# drop redundant post-barrier lgkmcnt(0) and back-to-back setprio 0/1 pairs in 56 GEMM phases
# baseline (speedup 1.0000x reference)
; #define PG8_STAGE(bufoff, gbase, voff) do { _Pragma("unroll") for (int _i = 0; _i < 2; ++_i) \
;         __builtin_amdgcn_global_load_lds((const unsigned*)((const char*)(gbase) + (voff)[_i]), (LAS unsigned*)(lds + (bufoff) + ldsw + _i * 8192), 16, 0, 0); } while (0)
; #define PG8_LDA(dst, b, h) do { _Pragma("unroll") for (int m = 0; m < 4; ++m) _Pragma("unroll") for (int k = 0; k < 2; ++k) dst[m][k] = *(const LAS bf16x8*)(lds + PG8_SA(b, h) + aoff + m * 2048 + k * 1024); } while (0)
; #define PG8_LDB(dst, b, h) do { _Pragma("unroll") for (int n = 0; n < 2; ++n) _Pragma("unroll") for (int k = 0; k < 2; ++k) dst[n][k] = *(const LAS bf16x8*)(lds + PG8_SB(b, h) + boff + n * 2048 + k * 1024); } while (0)
; #define PG8_MMA(ai, bj, At, Bt) do { __builtin_amdgcn_s_setprio(1); _Pragma("unroll") for (int m = 0; m < 4; ++m) _Pragma("unroll") for (int n = 0; n < 2; ++n) _Pragma("unroll") for (int k = 0; k < 2; ++k) \
;         acc[ai][bj][m][n] = __builtin_amdgcn_mfma_f32_16x16x32_bf16(Bt[n][k], At[m][k], acc[ai][bj][m][n], 0, 0, 0); __builtin_amdgcn_s_setprio(0); } while (0)
; #define PG8_WAIT_V(n) asm volatile("s_waitcnt vmcnt(" #n ")" ::: "memory")
; #define PG8_WAIT_L(n) asm volatile("s_waitcnt lgkmcnt(" #n ")" ::: "memory")
; #define PG8_BAR __builtin_amdgcn_s_barrier()
; #define PG8_SCHED __builtin_amdgcn_sched_barrier(0)
; template <class Epi>
; __device__ __forceinline__ void gemm_phase(LAS unsigned char* lds, const Gemm g, const StaticOrder& S, const Epi& E) {
;     ...
;             PG8_LDB(B0, 0, 0); PG8_LDB(B1, 0, 1); PG8_SCHED; PG8_LDA(At, 0, 0); PG8_STAGE(PG8_SA(1, 1), a1 + hstepA, voffA);
;             PG8_WAIT_V(8); PG8_WAIT_L(0); PG8_BAR; PG8_MMA(0, 0, At, B0); PG8_MMA(0, 1, At, B1); PG8_BAR; PG8_SCHED;
;             PG8_LDA(At, 0, 1); PG8_STAGE(PG8_SB(0, 0), b2, voffB); PG8_STAGE(PG8_SB(0, 1), b2 + hstepB, voffB); PG8_STAGE(PG8_SA(0, 0), a2, voffA);
;             PG8_WAIT_V(8); PG8_WAIT_L(0); PG8_BAR; PG8_MMA(1, 0, At, B0); PG8_MMA(1, 1, At, B1); PG8_BAR; PG8_SCHED;
;             PG8_LDB(B0, 1, 0); PG8_LDB(B1, 1, 1); PG8_SCHED; PG8_LDA(At, 1, 0); PG8_STAGE(PG8_SA(0, 1), a2 + hstepA, voffA);
.LBB0_163:
	s_add_u32 s22, s44, 0xfffc0080
	s_addc_u32 s23, s45, -1
	s_add_i32 s66, 0, 0x10000
	s_cmp_eq_u32 s65, 12
	s_cselect_b32 s47, s35, s23
	s_cselect_b32 s46, s61, s22
	v_add_u32_e32 v142, s66, v144
	s_cselect_b32 s23, s15, s64
	s_cselect_b32 s22, s62, s63
	s_add_i32 s68, 0, 0x14000
	ds_read_b128 v[148:151], v142
	ds_read_b128 v[152:155], v142 offset:1024
	ds_read_b128 v[156:159], v142 offset:2048
	ds_read_b128 v[160:163], v142 offset:3072
	v_add_u32_e32 v142, s68, v144
	ds_read_b128 v[164:167], v142
	ds_read_b128 v[168:171], v142 offset:1024
	ds_read_b128 v[172:175], v142 offset:2048
	ds_read_b128 v[176:179], v142 offset:3072
	v_lshl_add_u64 v[142:143], s[44:45], 0, v[138:139]
	s_add_i32 m0, s53, 0xc000
	ds_read_b128 v[180:183], v146
	ds_read_b128 v[184:187], v146 offset:1024
	ds_read_b128 v[188:191], v146 offset:2048
	ds_read_b128 v[192:195], v146 offset:3072
	ds_read_b128 v[210:213], v146 offset:4096
	ds_read_b128 v[214:217], v146 offset:5120
	ds_read_b128 v[218:221], v146 offset:6144
	ds_read_b128 v[222:225], v146 offset:7168
	global_load_lds_dwordx4 v[142:143], off
	v_lshl_add_u64 v[142:143], s[44:45], 0, v[140:141]
	s_add_i32 m0, s53, 0xe000
	s_nop 0
	global_load_lds_dwordx4 v[142:143], off
	s_waitcnt vmcnt(8)
	s_waitcnt lgkmcnt(0)
	s_barrier
	s_setprio 1
	v_mfma_f32_16x16x32_bf16 v[128:131], v[148:151], v[180:183], v[128:131]
	v_mfma_f32_16x16x32_bf16 v[120:123], v[156:159], v[180:183], v[120:123]
	v_mfma_f32_16x16x32_bf16 v[112:115], v[148:151], v[188:191], v[112:115]
	v_mfma_f32_16x16x32_bf16 v[100:103], v[156:159], v[188:191], v[100:103]
	v_mfma_f32_16x16x32_bf16 v[92:95], v[148:151], v[210:213], v[92:95]
	v_mfma_f32_16x16x32_bf16 v[84:87], v[156:159], v[210:213], v[84:87]
	v_mfma_f32_16x16x32_bf16 v[76:79], v[148:151], v[218:221], v[76:79]
	v_mfma_f32_16x16x32_bf16 v[68:71], v[156:159], v[218:221], v[68:71]
	v_mfma_f32_16x16x32_bf16 v[128:131], v[152:155], v[184:187], v[128:131]
	v_mfma_f32_16x16x32_bf16 v[120:123], v[160:163], v[184:187], v[120:123]
	v_mfma_f32_16x16x32_bf16 v[112:115], v[152:155], v[192:195], v[112:115]
	v_mfma_f32_16x16x32_bf16 v[100:103], v[160:163], v[192:195], v[100:103]
	v_mfma_f32_16x16x32_bf16 v[92:95], v[152:155], v[214:217], v[92:95]
	v_mfma_f32_16x16x32_bf16 v[84:87], v[160:163], v[214:217], v[84:87]
	v_mfma_f32_16x16x32_bf16 v[76:79], v[152:155], v[222:225], v[76:79]
	v_mfma_f32_16x16x32_bf16 v[68:71], v[160:163], v[222:225], v[68:71]
	v_mfma_f32_16x16x32_bf16 v[124:127], v[164:167], v[180:183], v[124:127]
	v_mfma_f32_16x16x32_bf16 v[116:119], v[172:175], v[180:183], v[116:119]
	v_mfma_f32_16x16x32_bf16 v[108:111], v[164:167], v[188:191], v[108:111]
	v_mfma_f32_16x16x32_bf16 v[104:107], v[172:175], v[188:191], v[104:107]
	v_mfma_f32_16x16x32_bf16 v[96:99], v[164:167], v[210:213], v[96:99]
	v_mfma_f32_16x16x32_bf16 v[88:91], v[172:175], v[210:213], v[88:91]
	v_mfma_f32_16x16x32_bf16 v[80:83], v[164:167], v[218:221], v[80:83]
	v_mfma_f32_16x16x32_bf16 v[72:75], v[172:175], v[218:221], v[72:75]
	v_mfma_f32_16x16x32_bf16 v[124:127], v[168:171], v[184:187], v[124:127]
	v_mfma_f32_16x16x32_bf16 v[116:119], v[176:179], v[184:187], v[116:119]
	v_mfma_f32_16x16x32_bf16 v[108:111], v[168:171], v[192:195], v[108:111]
	v_mfma_f32_16x16x32_bf16 v[104:107], v[176:179], v[192:195], v[104:107]
	v_mfma_f32_16x16x32_bf16 v[96:99], v[168:171], v[214:217], v[96:99]
	v_mfma_f32_16x16x32_bf16 v[88:91], v[176:179], v[214:217], v[88:91]
	v_mfma_f32_16x16x32_bf16 v[80:83], v[168:171], v[222:225], v[80:83]
	v_mfma_f32_16x16x32_bf16 v[72:75], v[176:179], v[222:225], v[72:75]
	s_setprio 0
	s_barrier
	s_add_i32 s66, s66, s52
	v_lshl_add_u64 v[142:143], s[22:23], 0, v[134:135]
	s_mov_b32 m0, s66
	ds_read_b128 v[180:183], v146 offset:16384
	ds_read_b128 v[184:187], v146 offset:17408
	ds_read_b128 v[188:191], v146 offset:18432
	ds_read_b128 v[192:195], v146 offset:19456
	ds_read_b128 v[210:213], v146 offset:20480
	ds_read_b128 v[214:217], v146 offset:21504
	ds_read_b128 v[218:221], v146 offset:22528
	ds_read_b128 v[222:225], v146 offset:23552
	global_load_lds_dwordx4 v[142:143], off
	s_add_i32 m0, s66, 0x2000
	s_add_u32 s66, s22, 0x10000
	v_lshl_add_u64 v[196:197], s[22:23], 0, v[0:1]
	s_addc_u32 s67, s23, 0
	s_add_i32 s68, s68, s52
	global_load_lds_dwordx4 v[196:197], off
	v_lshl_add_u64 v[198:199], s[66:67], 0, v[134:135]
	s_mov_b32 m0, s68
	v_lshl_add_u64 v[226:227], s[46:47], 0, v[132:133]
	global_load_lds_dwordx4 v[198:199], off
	v_lshl_add_u64 v[198:199], s[66:67], 0, v[0:1]
	s_add_i32 m0, s68, 0x2000
	s_nop 0
	global_load_lds_dwordx4 v[198:199], off
	v_lshl_add_u64 v[198:199], s[46:47], 0, v[136:137]
	s_mov_b32 m0, s53
	s_nop 0
	global_load_lds_dwordx4 v[198:199], off
	s_mov_b32 m0, s54
	s_nop 0
	global_load_lds_dwordx4 v[226:227], off
	s_waitcnt vmcnt(8)
	s_waitcnt lgkmcnt(0)
	s_barrier
; #define PG8_STAGE(bufoff, gbase, voff) do { _Pragma("unroll") for (int _i = 0; _i < 2; ++_i) \
;         __builtin_amdgcn_global_load_lds((const unsigned*)((const char*)(gbase) + (voff)[_i]), (LAS unsigned*)(lds + (bufoff) + ldsw + _i * 8192), 16, 0, 0); } while (0)
; #define PG8_LDA(dst, b, h) do { _Pragma("unroll") for (int m = 0; m < 4; ++m) _Pragma("unroll") for (int k = 0; k < 2; ++k) dst[m][k] = *(const LAS bf16x8*)(lds + PG8_SA(b, h) + aoff + m * 2048 + k * 1024); } while (0)
; #define PG8_LDB(dst, b, h) do { _Pragma("unroll") for (int n = 0; n < 2; ++n) _Pragma("unroll") for (int k = 0; k < 2; ++k) dst[n][k] = *(const LAS bf16x8*)(lds + PG8_SB(b, h) + boff + n * 2048 + k * 1024); } while (0)
; #define PG8_MMA(ai, bj, At, Bt) do { __builtin_amdgcn_s_setprio(1); _Pragma("unroll") for (int m = 0; m < 4; ++m) _Pragma("unroll") for (int n = 0; n < 2; ++n) _Pragma("unroll") for (int k = 0; k < 2; ++k) \
;         acc[ai][bj][m][n] = __builtin_amdgcn_mfma_f32_16x16x32_bf16(Bt[n][k], At[m][k], acc[ai][bj][m][n], 0, 0, 0); __builtin_amdgcn_s_setprio(0); } while (0)
; #define PG8_WAIT_V(n) asm volatile("s_waitcnt vmcnt(" #n ")" ::: "memory")
; #define PG8_WAIT_L(n) asm volatile("s_waitcnt lgkmcnt(" #n ")" ::: "memory")
; #define PG8_BAR __builtin_amdgcn_s_barrier()
; #define PG8_SCHED __builtin_amdgcn_sched_barrier(0)
; template <class Epi>
; __device__ __forceinline__ void gemm_phase(LAS unsigned char* lds, const Gemm g, const StaticOrder& S, const Epi& E) {
;     ...
;             PG8_WAIT_V(8); PG8_WAIT_L(0); PG8_BAR; PG8_MMA(1, 0, At, B0); PG8_MMA(1, 1, At, B1); PG8_BAR; PG8_SCHED;
;             PG8_LDB(B0, 1, 0); PG8_LDB(B1, 1, 1); PG8_SCHED; PG8_LDA(At, 1, 0); PG8_STAGE(PG8_SA(0, 1), a2 + hstepA, voffA);
;             PG8_WAIT_V(8); PG8_WAIT_L(0); PG8_BAR; PG8_MMA(0, 0, At, B0); PG8_MMA(0, 1, At, B1); PG8_BAR; PG8_SCHED;
;             PG8_LDA(At, 1, 1); PG8_STAGE(PG8_SB(1, 0), b3, voffB); PG8_STAGE(PG8_SB(1, 1), b3 + hstepB, voffB); PG8_STAGE(PG8_SA(1, 0), a3, voffA);
	s_setprio 1
	v_mfma_f32_16x16x32_bf16 v[60:63], v[148:151], v[180:183], v[60:63]
	v_mfma_f32_16x16x32_bf16 v[52:55], v[156:159], v[180:183], v[52:55]
	v_mfma_f32_16x16x32_bf16 v[44:47], v[148:151], v[188:191], v[44:47]
	v_mfma_f32_16x16x32_bf16 v[36:39], v[156:159], v[188:191], v[36:39]
	v_mfma_f32_16x16x32_bf16 v[28:31], v[148:151], v[210:213], v[28:31]
	v_mfma_f32_16x16x32_bf16 v[20:23], v[156:159], v[210:213], v[20:23]
	v_mfma_f32_16x16x32_bf16 v[4:7], v[148:151], v[218:221], v[4:7]
	v_mfma_f32_16x16x32_bf16 v[12:15], v[156:159], v[218:221], v[12:15]
	v_mfma_f32_16x16x32_bf16 v[60:63], v[152:155], v[184:187], v[60:63]
	v_mfma_f32_16x16x32_bf16 v[52:55], v[160:163], v[184:187], v[52:55]
	v_mfma_f32_16x16x32_bf16 v[44:47], v[152:155], v[192:195], v[44:47]
	v_mfma_f32_16x16x32_bf16 v[36:39], v[160:163], v[192:195], v[36:39]
	v_mfma_f32_16x16x32_bf16 v[28:31], v[152:155], v[214:217], v[28:31]
	v_mfma_f32_16x16x32_bf16 v[20:23], v[160:163], v[214:217], v[20:23]
	v_mfma_f32_16x16x32_bf16 v[4:7], v[152:155], v[222:225], v[4:7]
	v_mfma_f32_16x16x32_bf16 v[12:15], v[160:163], v[222:225], v[12:15]
	v_mfma_f32_16x16x32_bf16 v[64:67], v[164:167], v[180:183], v[64:67]
	v_mfma_f32_16x16x32_bf16 v[56:59], v[172:175], v[180:183], v[56:59]
	v_mfma_f32_16x16x32_bf16 v[48:51], v[164:167], v[188:191], v[48:51]
	v_mfma_f32_16x16x32_bf16 v[40:43], v[172:175], v[188:191], v[40:43]
	v_mfma_f32_16x16x32_bf16 v[32:35], v[164:167], v[210:213], v[32:35]
	v_mfma_f32_16x16x32_bf16 v[24:27], v[172:175], v[210:213], v[24:27]
	v_mfma_f32_16x16x32_bf16 v[8:11], v[164:167], v[218:221], v[8:11]
	v_mfma_f32_16x16x32_bf16 v[16:19], v[172:175], v[218:221], v[16:19]
	v_mfma_f32_16x16x32_bf16 v[64:67], v[168:171], v[184:187], v[64:67]
	v_mfma_f32_16x16x32_bf16 v[56:59], v[176:179], v[184:187], v[56:59]
	v_mfma_f32_16x16x32_bf16 v[48:51], v[168:171], v[192:195], v[48:51]
	v_mfma_f32_16x16x32_bf16 v[40:43], v[176:179], v[192:195], v[40:43]
	v_mfma_f32_16x16x32_bf16 v[32:35], v[168:171], v[214:217], v[32:35]
	v_mfma_f32_16x16x32_bf16 v[24:27], v[176:179], v[214:217], v[24:27]
	v_mfma_f32_16x16x32_bf16 v[8:11], v[168:171], v[222:225], v[8:11]
	v_mfma_f32_16x16x32_bf16 v[16:19], v[176:179], v[222:225], v[16:19]
	s_setprio 0
	s_barrier
	s_add_i32 s66, 0, 0x18000
	v_add_u32_e32 v147, s66, v144
	s_add_i32 s67, 0, 0x1c000
	ds_read_b128 v[148:151], v147
	ds_read_b128 v[152:155], v147 offset:1024
	ds_read_b128 v[156:159], v147 offset:2048
	ds_read_b128 v[160:163], v147 offset:3072
	v_add_u32_e32 v147, s67, v144
	ds_read_b128 v[164:167], v147
	ds_read_b128 v[168:171], v147 offset:1024
	ds_read_b128 v[172:175], v147 offset:2048
	ds_read_b128 v[176:179], v147 offset:3072
	s_add_u32 s46, s46, 0x40000
	s_addc_u32 s47, s47, 0
	s_mov_b32 m0, s55
	v_lshl_add_u64 v[228:229], s[46:47], 0, v[136:137]
	ds_read_b128 v[180:183], v146 offset:32768
	ds_read_b128 v[184:187], v146 offset:33792
	ds_read_b128 v[188:191], v146 offset:34816
	ds_read_b128 v[192:195], v146 offset:35840
	ds_read_b128 v[210:213], v146 offset:36864
	ds_read_b128 v[214:217], v146 offset:37888
	ds_read_b128 v[218:221], v146 offset:38912
	ds_read_b128 v[222:225], v146 offset:39936
	global_load_lds_dwordx4 v[228:229], off
	v_lshl_add_u64 v[228:229], s[46:47], 0, v[132:133]
	s_mov_b32 m0, s56
	s_nop 0
	global_load_lds_dwordx4 v[228:229], off
	s_waitcnt vmcnt(8)
	s_waitcnt lgkmcnt(0)
	s_barrier
	s_setprio 1
	v_mfma_f32_16x16x32_bf16 v[128:131], v[148:151], v[180:183], v[128:131]
	v_mfma_f32_16x16x32_bf16 v[120:123], v[156:159], v[180:183], v[120:123]
	v_mfma_f32_16x16x32_bf16 v[112:115], v[148:151], v[188:191], v[112:115]
	v_mfma_f32_16x16x32_bf16 v[100:103], v[156:159], v[188:191], v[100:103]
	v_mfma_f32_16x16x32_bf16 v[92:95], v[148:151], v[210:213], v[92:95]
	v_mfma_f32_16x16x32_bf16 v[84:87], v[156:159], v[210:213], v[84:87]
	v_mfma_f32_16x16x32_bf16 v[76:79], v[148:151], v[218:221], v[76:79]
	v_mfma_f32_16x16x32_bf16 v[68:71], v[156:159], v[218:221], v[68:71]
	v_mfma_f32_16x16x32_bf16 v[128:131], v[152:155], v[184:187], v[128:131]
	v_mfma_f32_16x16x32_bf16 v[120:123], v[160:163], v[184:187], v[120:123]
	v_mfma_f32_16x16x32_bf16 v[112:115], v[152:155], v[192:195], v[112:115]
	v_mfma_f32_16x16x32_bf16 v[100:103], v[160:163], v[192:195], v[100:103]
	v_mfma_f32_16x16x32_bf16 v[92:95], v[152:155], v[214:217], v[92:95]
	v_mfma_f32_16x16x32_bf16 v[84:87], v[160:163], v[214:217], v[84:87]
	v_mfma_f32_16x16x32_bf16 v[76:79], v[152:155], v[222:225], v[76:79]
	v_mfma_f32_16x16x32_bf16 v[68:71], v[160:163], v[222:225], v[68:71]
	v_mfma_f32_16x16x32_bf16 v[124:127], v[164:167], v[180:183], v[124:127]
	v_mfma_f32_16x16x32_bf16 v[116:119], v[172:175], v[180:183], v[116:119]
	v_mfma_f32_16x16x32_bf16 v[108:111], v[164:167], v[188:191], v[108:111]
	v_mfma_f32_16x16x32_bf16 v[104:107], v[172:175], v[188:191], v[104:107]
	v_mfma_f32_16x16x32_bf16 v[96:99], v[164:167], v[210:213], v[96:99]
	v_mfma_f32_16x16x32_bf16 v[88:91], v[172:175], v[210:213], v[88:91]
	v_mfma_f32_16x16x32_bf16 v[80:83], v[164:167], v[218:221], v[80:83]
	v_mfma_f32_16x16x32_bf16 v[72:75], v[172:175], v[218:221], v[72:75]
	v_mfma_f32_16x16x32_bf16 v[124:127], v[168:171], v[184:187], v[124:127]
	v_mfma_f32_16x16x32_bf16 v[116:119], v[176:179], v[184:187], v[116:119]
	v_mfma_f32_16x16x32_bf16 v[108:111], v[168:171], v[192:195], v[108:111]
	v_mfma_f32_16x16x32_bf16 v[104:107], v[176:179], v[192:195], v[104:107]
	v_mfma_f32_16x16x32_bf16 v[96:99], v[168:171], v[214:217], v[96:99]
	v_mfma_f32_16x16x32_bf16 v[88:91], v[176:179], v[214:217], v[88:91]
	v_mfma_f32_16x16x32_bf16 v[80:83], v[168:171], v[222:225], v[80:83]
	v_mfma_f32_16x16x32_bf16 v[72:75], v[176:179], v[222:225], v[72:75]
	s_setprio 0
	s_barrier
; #define PG8_STAGE(bufoff, gbase, voff) do { _Pragma("unroll") for (int _i = 0; _i < 2; ++_i) \
;         __builtin_amdgcn_global_load_lds((const unsigned*)((const char*)(gbase) + (voff)[_i]), (LAS unsigned*)(lds + (bufoff) + ldsw + _i * 8192), 16, 0, 0); } while (0)
; #define PG8_LDA(dst, b, h) do { _Pragma("unroll") for (int m = 0; m < 4; ++m) _Pragma("unroll") for (int k = 0; k < 2; ++k) dst[m][k] = *(const LAS bf16x8*)(lds + PG8_SA(b, h) + aoff + m * 2048 + k * 1024); } while (0)
; #define PG8_MMA(ai, bj, At, Bt) do { __builtin_amdgcn_s_setprio(1); _Pragma("unroll") for (int m = 0; m < 4; ++m) _Pragma("unroll") for (int n = 0; n < 2; ++n) _Pragma("unroll") for (int k = 0; k < 2; ++k) \
;         acc[ai][bj][m][n] = __builtin_amdgcn_mfma_f32_16x16x32_bf16(Bt[n][k], At[m][k], acc[ai][bj][m][n], 0, 0, 0); __builtin_amdgcn_s_setprio(0); } while (0)
; #define PG8_WAIT_V(n) asm volatile("s_waitcnt vmcnt(" #n ")" ::: "memory")
; #define PG8_WAIT_L(n) asm volatile("s_waitcnt lgkmcnt(" #n ")" ::: "memory")
; #define PG8_BAR __builtin_amdgcn_s_barrier()
; #define PG8_SCHED __builtin_amdgcn_sched_barrier(0)
; template <class Epi>
; __device__ __forceinline__ void gemm_phase(LAS unsigned char* lds, const Gemm g, const StaticOrder& S, const Epi& E) {
;     ...
;             PG8_WAIT_V(8); PG8_WAIT_L(0); PG8_BAR; PG8_MMA(0, 0, At, B0); PG8_MMA(0, 1, At, B1); PG8_BAR; PG8_SCHED;
;             PG8_LDA(At, 1, 1); PG8_STAGE(PG8_SB(1, 0), b3, voffB); PG8_STAGE(PG8_SB(1, 1), b3 + hstepB, voffB); PG8_STAGE(PG8_SA(1, 0), a3, voffA);
;             PG8_WAIT_V(8); PG8_WAIT_L(0); PG8_BAR; PG8_MMA(1, 0, At, B0); PG8_MMA(1, 1, At, B1); PG8_BAR; PG8_SCHED;
;         }
	s_add_i32 s46, s66, s52
	v_lshl_add_u64 v[142:143], v[142:143], 0, s[30:31]
	s_mov_b32 m0, s46
	ds_read_b128 v[180:183], v146 offset:49152
	ds_read_b128 v[184:187], v146 offset:50176
	ds_read_b128 v[188:191], v146 offset:51200
	ds_read_b128 v[192:195], v146 offset:52224
	ds_read_b128 v[210:213], v146 offset:53248
	ds_read_b128 v[214:217], v146 offset:54272
	ds_read_b128 v[218:221], v146 offset:55296
	ds_read_b128 v[222:225], v146 offset:56320
	global_load_lds_dwordx4 v[142:143], off
	s_add_i32 m0, s46, 0x2000
	s_add_u32 s22, s22, 0x10080
	v_lshl_add_u64 v[142:143], v[196:197], 0, s[30:31]
	s_addc_u32 s23, s23, 0
	s_add_i32 s46, s67, s52
	global_load_lds_dwordx4 v[142:143], off
	v_lshl_add_u64 v[142:143], s[22:23], 0, v[134:135]
	s_mov_b32 m0, s46
	s_nop 0
	global_load_lds_dwordx4 v[142:143], off
	v_lshl_add_u64 v[142:143], s[22:23], 0, v[0:1]
	s_add_i32 m0, s46, 0x2000
	s_nop 0
	global_load_lds_dwordx4 v[142:143], off
	v_lshl_add_u64 v[142:143], v[198:199], 0, s[30:31]
	s_mov_b32 m0, s28
	s_nop 0
	global_load_lds_dwordx4 v[142:143], off
	v_lshl_add_u64 v[142:143], v[226:227], 0, s[30:31]
	s_mov_b32 m0, s57
	s_nop 0
	global_load_lds_dwordx4 v[142:143], off
	s_waitcnt vmcnt(8)
	s_waitcnt lgkmcnt(0)
	s_barrier
	s_setprio 1
	v_mfma_f32_16x16x32_bf16 v[60:63], v[148:151], v[180:183], v[60:63]
	v_mfma_f32_16x16x32_bf16 v[52:55], v[156:159], v[180:183], v[52:55]
	v_mfma_f32_16x16x32_bf16 v[44:47], v[148:151], v[188:191], v[44:47]
	v_mfma_f32_16x16x32_bf16 v[36:39], v[156:159], v[188:191], v[36:39]
	v_mfma_f32_16x16x32_bf16 v[28:31], v[148:151], v[210:213], v[28:31]
	v_mfma_f32_16x16x32_bf16 v[20:23], v[156:159], v[210:213], v[20:23]
	v_mfma_f32_16x16x32_bf16 v[4:7], v[148:151], v[218:221], v[4:7]
	v_mfma_f32_16x16x32_bf16 v[12:15], v[156:159], v[218:221], v[12:15]
	v_mfma_f32_16x16x32_bf16 v[60:63], v[152:155], v[184:187], v[60:63]
	v_mfma_f32_16x16x32_bf16 v[52:55], v[160:163], v[184:187], v[52:55]
	v_mfma_f32_16x16x32_bf16 v[44:47], v[152:155], v[192:195], v[44:47]
	v_mfma_f32_16x16x32_bf16 v[36:39], v[160:163], v[192:195], v[36:39]
	v_mfma_f32_16x16x32_bf16 v[28:31], v[152:155], v[214:217], v[28:31]
	v_mfma_f32_16x16x32_bf16 v[20:23], v[160:163], v[214:217], v[20:23]
	v_mfma_f32_16x16x32_bf16 v[4:7], v[152:155], v[222:225], v[4:7]
	v_mfma_f32_16x16x32_bf16 v[12:15], v[160:163], v[222:225], v[12:15]
	v_mfma_f32_16x16x32_bf16 v[64:67], v[164:167], v[180:183], v[64:67]
	v_mfma_f32_16x16x32_bf16 v[56:59], v[172:175], v[180:183], v[56:59]
	v_mfma_f32_16x16x32_bf16 v[48:51], v[164:167], v[188:191], v[48:51]
	v_mfma_f32_16x16x32_bf16 v[40:43], v[172:175], v[188:191], v[40:43]
	v_mfma_f32_16x16x32_bf16 v[32:35], v[164:167], v[210:213], v[32:35]
	v_mfma_f32_16x16x32_bf16 v[24:27], v[172:175], v[210:213], v[24:27]
	v_mfma_f32_16x16x32_bf16 v[8:11], v[164:167], v[218:221], v[8:11]
	v_mfma_f32_16x16x32_bf16 v[16:19], v[172:175], v[218:221], v[16:19]
	v_mfma_f32_16x16x32_bf16 v[64:67], v[168:171], v[184:187], v[64:67]
	v_mfma_f32_16x16x32_bf16 v[56:59], v[176:179], v[184:187], v[56:59]
	v_mfma_f32_16x16x32_bf16 v[48:51], v[168:171], v[192:195], v[48:51]
	v_mfma_f32_16x16x32_bf16 v[40:43], v[176:179], v[192:195], v[40:43]
	v_mfma_f32_16x16x32_bf16 v[32:35], v[168:171], v[214:217], v[32:35]
	v_mfma_f32_16x16x32_bf16 v[24:27], v[176:179], v[214:217], v[24:27]
	v_mfma_f32_16x16x32_bf16 v[8:11], v[168:171], v[222:225], v[8:11]
	v_mfma_f32_16x16x32_bf16 v[16:19], v[176:179], v[222:225], v[16:19]
	s_setprio 0
	s_barrier
	s_add_i32 s65, s65, 2
	s_add_u32 s44, s44, 0x100
	s_addc_u32 s45, s45, 0
	s_add_u32 s63, s63, 0x100
	s_addc_u32 s64, s64, 0
	s_cmp_gt_u32 s65, 13
	s_cbranch_scc0 .LBB0_163
	s_and_b64 vcc, exec, s[12:13]
	s_cbranch_vccz .LBB0_166
	s_barrier

; #define PG8_STAGE(bufoff, gbase, voff) do { _Pragma("unroll") for (int _i = 0; _i < 2; ++_i) \
;         __builtin_amdgcn_global_load_lds((const unsigned*)((const char*)(gbase) + (voff)[_i]), (LAS unsigned*)(lds + (bufoff) + ldsw + _i * 8192), 16, 0, 0); } while (0)
; #define PG8_LDA(dst, b, h) do { _Pragma("unroll") for (int m = 0; m < 4; ++m) _Pragma("unroll") for (int k = 0; k < 2; ++k) dst[m][k] = *(const LAS bf16x8*)(lds + PG8_SA(b, h) + aoff + m * 2048 + k * 1024); } while (0)
; #define PG8_LDB(dst, b, h) do { _Pragma("unroll") for (int n = 0; n < 2; ++n) _Pragma("unroll") for (int k = 0; k < 2; ++k) dst[n][k] = *(const LAS bf16x8*)(lds + PG8_SB(b, h) + boff + n * 2048 + k * 1024); } while (0)
; #define PG8_MMA(ai, bj, At, Bt) do { __builtin_amdgcn_s_setprio(1); _Pragma("unroll") for (int m = 0; m < 4; ++m) _Pragma("unroll") for (int n = 0; n < 2; ++n) _Pragma("unroll") for (int k = 0; k < 2; ++k) \
;         acc[ai][bj][m][n] = __builtin_amdgcn_mfma_f32_16x16x32_bf16(Bt[n][k], At[m][k], acc[ai][bj][m][n], 0, 0, 0); __builtin_amdgcn_s_setprio(0); } while (0)
; #define PG8_WAIT_V(n) asm volatile("s_waitcnt vmcnt(" #n ")" ::: "memory")
; #define PG8_WAIT_L(n) asm volatile("s_waitcnt lgkmcnt(" #n ")" ::: "memory")
; #define PG8_BAR __builtin_amdgcn_s_barrier()
; #define PG8_SCHED __builtin_amdgcn_sched_barrier(0)
; template <class Epi>
; __device__ __forceinline__ void gemm_phase(LAS unsigned char* lds, const Gemm g, const StaticOrder& S, const Epi& E) {
;     ...
;             PG8_LDB(B0, 0, 0); PG8_LDB(B1, 0, 1); PG8_SCHED; PG8_LDA(At, 0, 0); PG8_STAGE(PG8_SA(1, 1), a1 + hstepA, voffA);
;             PG8_WAIT_V(8); PG8_WAIT_L(0); PG8_BAR; PG8_MMA(0, 0, At, B0); PG8_MMA(0, 1, At, B1); PG8_BAR; PG8_SCHED;
;             PG8_LDA(At, 0, 1); PG8_STAGE(PG8_SB(0, 0), b2, voffB); PG8_STAGE(PG8_SB(0, 1), b2 + hstepB, voffB); PG8_STAGE(PG8_SA(0, 0), a2, voffA);
;             PG8_WAIT_V(8); PG8_WAIT_L(0); PG8_BAR; PG8_MMA(1, 0, At, B0); PG8_MMA(1, 1, At, B1); PG8_BAR; PG8_SCHED;
;             PG8_LDB(B0, 1, 0); PG8_LDB(B1, 1, 1); PG8_SCHED; PG8_LDA(At, 1, 0); PG8_STAGE(PG8_SA(0, 1), a2 + hstepA, voffA);
.LBB0_240:
	s_add_u32 s48, s46, 0x100
	s_addc_u32 s49, s47, 0
	s_add_i32 s70, 0, 0x10000
	s_cmp_eq_u32 s69, 40
	s_cselect_b32 s51, s5, s49
	s_cselect_b32 s50, s4, s48
	s_cselect_b32 s23, s41, s68
	s_cselect_b32 s22, s40, s67
	s_add_i32 s71, 0, 0x14000
	v_add_u32_e32 v144, s70, v230
	v_add_u32_e32 v160, s71, v230
	ds_read_b128 v[132:135], v144
	ds_read_b128 v[136:139], v144 offset:1024
	ds_read_b128 v[140:143], v144 offset:2048
	ds_read_b128 v[144:147], v144 offset:3072
	ds_read_b128 v[148:151], v160
	ds_read_b128 v[152:155], v160 offset:1024
	ds_read_b128 v[156:159], v160 offset:2048
	ds_read_b128 v[160:163], v160 offset:3072
	v_lshl_add_u64 v[196:197], s[46:47], 0, v[194:195]
	s_add_i32 m0, s57, 0xc000
	ds_read_b128 v[164:167], v232
	ds_read_b128 v[168:171], v232 offset:1024
	ds_read_b128 v[172:175], v232 offset:2048
	ds_read_b128 v[176:179], v232 offset:3072
	ds_read_b128 v[180:183], v232 offset:4096
	ds_read_b128 v[184:187], v232 offset:5120
	ds_read_b128 v[212:215], v232 offset:6144
	ds_read_b128 v[216:219], v232 offset:7168
	global_load_lds_dwordx4 v[196:197], off
	v_lshl_add_u64 v[196:197], s[46:47], 0, v[210:211]
	s_add_i32 m0, s57, 0xe000
	s_nop 0
	global_load_lds_dwordx4 v[196:197], off
	s_waitcnt vmcnt(8)
	s_waitcnt lgkmcnt(0)
	s_barrier
	s_setprio 1
	v_mfma_f32_16x16x32_bf16 v[128:131], v[132:135], v[164:167], v[128:131]
	v_mfma_f32_16x16x32_bf16 v[124:127], v[140:143], v[164:167], v[124:127]
	v_mfma_f32_16x16x32_bf16 v[112:115], v[132:135], v[172:175], v[112:115]
	v_mfma_f32_16x16x32_bf16 v[108:111], v[140:143], v[172:175], v[108:111]
	v_mfma_f32_16x16x32_bf16 v[96:99], v[132:135], v[180:183], v[96:99]
	v_mfma_f32_16x16x32_bf16 v[92:95], v[140:143], v[180:183], v[92:95]
	v_mfma_f32_16x16x32_bf16 v[80:83], v[132:135], v[212:215], v[80:83]
	v_mfma_f32_16x16x32_bf16 v[76:79], v[140:143], v[212:215], v[76:79]
	v_mfma_f32_16x16x32_bf16 v[128:131], v[136:139], v[168:171], v[128:131]
	v_mfma_f32_16x16x32_bf16 v[124:127], v[144:147], v[168:171], v[124:127]
	v_mfma_f32_16x16x32_bf16 v[112:115], v[136:139], v[176:179], v[112:115]
	v_mfma_f32_16x16x32_bf16 v[108:111], v[144:147], v[176:179], v[108:111]
	v_mfma_f32_16x16x32_bf16 v[96:99], v[136:139], v[184:187], v[96:99]
	v_mfma_f32_16x16x32_bf16 v[92:95], v[144:147], v[184:187], v[92:95]
	v_mfma_f32_16x16x32_bf16 v[80:83], v[136:139], v[216:219], v[80:83]
	v_mfma_f32_16x16x32_bf16 v[76:79], v[144:147], v[216:219], v[76:79]
	v_mfma_f32_16x16x32_bf16 v[120:123], v[148:151], v[164:167], v[120:123]
	v_mfma_f32_16x16x32_bf16 v[116:119], v[156:159], v[164:167], v[116:119]
	v_mfma_f32_16x16x32_bf16 v[104:107], v[148:151], v[172:175], v[104:107]
	v_mfma_f32_16x16x32_bf16 v[100:103], v[156:159], v[172:175], v[100:103]
	v_mfma_f32_16x16x32_bf16 v[88:91], v[148:151], v[180:183], v[88:91]
	v_mfma_f32_16x16x32_bf16 v[84:87], v[156:159], v[180:183], v[84:87]
	v_mfma_f32_16x16x32_bf16 v[72:75], v[148:151], v[212:215], v[72:75]
	v_mfma_f32_16x16x32_bf16 v[68:71], v[156:159], v[212:215], v[68:71]
	v_mfma_f32_16x16x32_bf16 v[120:123], v[152:155], v[168:171], v[120:123]
	v_mfma_f32_16x16x32_bf16 v[116:119], v[160:163], v[168:171], v[116:119]
	v_mfma_f32_16x16x32_bf16 v[104:107], v[152:155], v[176:179], v[104:107]
	v_mfma_f32_16x16x32_bf16 v[100:103], v[160:163], v[176:179], v[100:103]
	v_mfma_f32_16x16x32_bf16 v[88:91], v[152:155], v[184:187], v[88:91]
	v_mfma_f32_16x16x32_bf16 v[84:87], v[160:163], v[184:187], v[84:87]
	v_mfma_f32_16x16x32_bf16 v[72:75], v[152:155], v[216:219], v[72:75]
	v_mfma_f32_16x16x32_bf16 v[68:71], v[160:163], v[216:219], v[68:71]
	s_setprio 0
	s_barrier
	s_add_i32 s46, s70, s54
	v_lshl_add_u64 v[196:197], s[22:23], 0, v[190:191]
	s_mov_b32 m0, s46
	ds_read_b128 v[164:167], v232 offset:16384
	ds_read_b128 v[168:171], v232 offset:17408
	ds_read_b128 v[172:175], v232 offset:18432
	ds_read_b128 v[176:179], v232 offset:19456
	ds_read_b128 v[180:183], v232 offset:20480
	ds_read_b128 v[184:187], v232 offset:21504
	ds_read_b128 v[212:215], v232 offset:22528
	ds_read_b128 v[216:219], v232 offset:23552
	global_load_lds_dwordx4 v[196:197], off
	s_add_i32 m0, s46, 0x2000
	s_add_u32 s46, s22, 0x2c000
	v_lshl_add_u64 v[198:199], s[22:23], 0, v[0:1]
	s_addc_u32 s47, s23, 0
	s_add_i32 s70, s71, s54
	global_load_lds_dwordx4 v[198:199], off
	v_lshl_add_u64 v[220:221], s[46:47], 0, v[190:191]
	s_mov_b32 m0, s70
	v_lshl_add_u64 v[222:223], s[50:51], 0, v[188:189]
	global_load_lds_dwordx4 v[220:221], off
	v_lshl_add_u64 v[220:221], s[46:47], 0, v[0:1]
	s_add_i32 m0, s70, 0x2000
	s_nop 0
	global_load_lds_dwordx4 v[220:221], off
	v_lshl_add_u64 v[220:221], s[50:51], 0, v[192:193]
	s_mov_b32 m0, s57
	s_nop 0
	global_load_lds_dwordx4 v[220:221], off
	s_mov_b32 m0, s58
	s_nop 0
	global_load_lds_dwordx4 v[222:223], off
	s_waitcnt vmcnt(8)
	s_waitcnt lgkmcnt(0)
	s_barrier
; #define PG8_STAGE(bufoff, gbase, voff) do { _Pragma("unroll") for (int _i = 0; _i < 2; ++_i) \
;         __builtin_amdgcn_global_load_lds((const unsigned*)((const char*)(gbase) + (voff)[_i]), (LAS unsigned*)(lds + (bufoff) + ldsw + _i * 8192), 16, 0, 0); } while (0)
; #define PG8_LDA(dst, b, h) do { _Pragma("unroll") for (int m = 0; m < 4; ++m) _Pragma("unroll") for (int k = 0; k < 2; ++k) dst[m][k] = *(const LAS bf16x8*)(lds + PG8_SA(b, h) + aoff + m * 2048 + k * 1024); } while (0)
; #define PG8_LDB(dst, b, h) do { _Pragma("unroll") for (int n = 0; n < 2; ++n) _Pragma("unroll") for (int k = 0; k < 2; ++k) dst[n][k] = *(const LAS bf16x8*)(lds + PG8_SB(b, h) + boff + n * 2048 + k * 1024); } while (0)
; #define PG8_MMA(ai, bj, At, Bt) do { __builtin_amdgcn_s_setprio(1); _Pragma("unroll") for (int m = 0; m < 4; ++m) _Pragma("unroll") for (int n = 0; n < 2; ++n) _Pragma("unroll") for (int k = 0; k < 2; ++k) \
;         acc[ai][bj][m][n] = __builtin_amdgcn_mfma_f32_16x16x32_bf16(Bt[n][k], At[m][k], acc[ai][bj][m][n], 0, 0, 0); __builtin_amdgcn_s_setprio(0); } while (0)
; #define PG8_WAIT_V(n) asm volatile("s_waitcnt vmcnt(" #n ")" ::: "memory")
; #define PG8_WAIT_L(n) asm volatile("s_waitcnt lgkmcnt(" #n ")" ::: "memory")
; #define PG8_BAR __builtin_amdgcn_s_barrier()
; #define PG8_SCHED __builtin_amdgcn_sched_barrier(0)
; template <class Epi>
; __device__ __forceinline__ void gemm_phase(LAS unsigned char* lds, const Gemm g, const StaticOrder& S, const Epi& E) {
;     ...
;             PG8_WAIT_V(8); PG8_WAIT_L(0); PG8_BAR; PG8_MMA(1, 0, At, B0); PG8_MMA(1, 1, At, B1); PG8_BAR; PG8_SCHED;
;             PG8_LDB(B0, 1, 0); PG8_LDB(B1, 1, 1); PG8_SCHED; PG8_LDA(At, 1, 0); PG8_STAGE(PG8_SA(0, 1), a2 + hstepA, voffA);
;             PG8_WAIT_V(8); PG8_WAIT_L(0); PG8_BAR; PG8_MMA(0, 0, At, B0); PG8_MMA(0, 1, At, B1); PG8_BAR; PG8_SCHED;
;             PG8_LDA(At, 1, 1); PG8_STAGE(PG8_SB(1, 0), b3, voffB); PG8_STAGE(PG8_SB(1, 1), b3 + hstepB, voffB); PG8_STAGE(PG8_SA(1, 0), a3, voffA);
	s_setprio 1
	v_mfma_f32_16x16x32_bf16 v[64:67], v[132:135], v[164:167], v[64:67]
	v_mfma_f32_16x16x32_bf16 v[60:63], v[140:143], v[164:167], v[60:63]
	v_mfma_f32_16x16x32_bf16 v[48:51], v[132:135], v[172:175], v[48:51]
	v_mfma_f32_16x16x32_bf16 v[44:47], v[140:143], v[172:175], v[44:47]
	v_mfma_f32_16x16x32_bf16 v[32:35], v[132:135], v[180:183], v[32:35]
	v_mfma_f32_16x16x32_bf16 v[28:31], v[140:143], v[180:183], v[28:31]
	v_mfma_f32_16x16x32_bf16 v[16:19], v[132:135], v[212:215], v[16:19]
	v_mfma_f32_16x16x32_bf16 v[12:15], v[140:143], v[212:215], v[12:15]
	v_mfma_f32_16x16x32_bf16 v[64:67], v[136:139], v[168:171], v[64:67]
	v_mfma_f32_16x16x32_bf16 v[60:63], v[144:147], v[168:171], v[60:63]
	v_mfma_f32_16x16x32_bf16 v[48:51], v[136:139], v[176:179], v[48:51]
	v_mfma_f32_16x16x32_bf16 v[44:47], v[144:147], v[176:179], v[44:47]
	v_mfma_f32_16x16x32_bf16 v[32:35], v[136:139], v[184:187], v[32:35]
	v_mfma_f32_16x16x32_bf16 v[28:31], v[144:147], v[184:187], v[28:31]
	v_mfma_f32_16x16x32_bf16 v[16:19], v[136:139], v[216:219], v[16:19]
	v_mfma_f32_16x16x32_bf16 v[12:15], v[144:147], v[216:219], v[12:15]
	v_mfma_f32_16x16x32_bf16 v[56:59], v[148:151], v[164:167], v[56:59]
	v_mfma_f32_16x16x32_bf16 v[52:55], v[156:159], v[164:167], v[52:55]
	v_mfma_f32_16x16x32_bf16 v[40:43], v[148:151], v[172:175], v[40:43]
	v_mfma_f32_16x16x32_bf16 v[36:39], v[156:159], v[172:175], v[36:39]
	v_mfma_f32_16x16x32_bf16 v[24:27], v[148:151], v[180:183], v[24:27]
	v_mfma_f32_16x16x32_bf16 v[20:23], v[156:159], v[180:183], v[20:23]
	v_mfma_f32_16x16x32_bf16 v[8:11], v[148:151], v[212:215], v[8:11]
	v_mfma_f32_16x16x32_bf16 v[4:7], v[156:159], v[212:215], v[4:7]
	v_mfma_f32_16x16x32_bf16 v[56:59], v[152:155], v[168:171], v[56:59]
	v_mfma_f32_16x16x32_bf16 v[52:55], v[160:163], v[168:171], v[52:55]
	v_mfma_f32_16x16x32_bf16 v[40:43], v[152:155], v[176:179], v[40:43]
	v_mfma_f32_16x16x32_bf16 v[36:39], v[160:163], v[176:179], v[36:39]
	v_mfma_f32_16x16x32_bf16 v[24:27], v[152:155], v[184:187], v[24:27]
	v_mfma_f32_16x16x32_bf16 v[20:23], v[160:163], v[184:187], v[20:23]
	v_mfma_f32_16x16x32_bf16 v[8:11], v[152:155], v[216:219], v[8:11]
	v_mfma_f32_16x16x32_bf16 v[4:7], v[160:163], v[216:219], v[4:7]
	s_setprio 0
	s_barrier
	s_add_i32 s70, 0, 0x18000
	s_add_i32 s71, 0, 0x1c000
	v_add_u32_e32 v144, s70, v230
	v_add_u32_e32 v160, s71, v230
	ds_read_b128 v[132:135], v144
	ds_read_b128 v[136:139], v144 offset:1024
	ds_read_b128 v[140:143], v144 offset:2048
	ds_read_b128 v[144:147], v144 offset:3072
	ds_read_b128 v[148:151], v160
	ds_read_b128 v[152:155], v160 offset:1024
	ds_read_b128 v[156:159], v160 offset:2048
	ds_read_b128 v[160:163], v160 offset:3072
	s_add_u32 s46, s50, 0xb0000
	s_addc_u32 s47, s51, 0
	s_mov_b32 m0, s59
	v_lshl_add_u64 v[224:225], s[46:47], 0, v[192:193]
	ds_read_b128 v[164:167], v232 offset:32768
	ds_read_b128 v[168:171], v232 offset:33792
	ds_read_b128 v[172:175], v232 offset:34816
	ds_read_b128 v[176:179], v232 offset:35840
	ds_read_b128 v[180:183], v232 offset:36864
	ds_read_b128 v[184:187], v232 offset:37888
	ds_read_b128 v[212:215], v232 offset:38912
	ds_read_b128 v[216:219], v232 offset:39936
	global_load_lds_dwordx4 v[224:225], off
	v_lshl_add_u64 v[224:225], s[46:47], 0, v[188:189]
	s_mov_b32 m0, s60
	s_nop 0
	global_load_lds_dwordx4 v[224:225], off
	s_waitcnt vmcnt(8)
	s_waitcnt lgkmcnt(0)
	s_barrier
	s_setprio 1
	v_mfma_f32_16x16x32_bf16 v[128:131], v[132:135], v[164:167], v[128:131]
	v_mfma_f32_16x16x32_bf16 v[124:127], v[140:143], v[164:167], v[124:127]
	v_mfma_f32_16x16x32_bf16 v[112:115], v[132:135], v[172:175], v[112:115]
	v_mfma_f32_16x16x32_bf16 v[108:111], v[140:143], v[172:175], v[108:111]
	v_mfma_f32_16x16x32_bf16 v[96:99], v[132:135], v[180:183], v[96:99]
	v_mfma_f32_16x16x32_bf16 v[92:95], v[140:143], v[180:183], v[92:95]
	v_mfma_f32_16x16x32_bf16 v[80:83], v[132:135], v[212:215], v[80:83]
	v_mfma_f32_16x16x32_bf16 v[76:79], v[140:143], v[212:215], v[76:79]
	v_mfma_f32_16x16x32_bf16 v[128:131], v[136:139], v[168:171], v[128:131]
	v_mfma_f32_16x16x32_bf16 v[124:127], v[144:147], v[168:171], v[124:127]
	v_mfma_f32_16x16x32_bf16 v[112:115], v[136:139], v[176:179], v[112:115]
	v_mfma_f32_16x16x32_bf16 v[108:111], v[144:147], v[176:179], v[108:111]
	v_mfma_f32_16x16x32_bf16 v[96:99], v[136:139], v[184:187], v[96:99]
	v_mfma_f32_16x16x32_bf16 v[92:95], v[144:147], v[184:187], v[92:95]
	v_mfma_f32_16x16x32_bf16 v[80:83], v[136:139], v[216:219], v[80:83]
	v_mfma_f32_16x16x32_bf16 v[76:79], v[144:147], v[216:219], v[76:79]
	v_mfma_f32_16x16x32_bf16 v[120:123], v[148:151], v[164:167], v[120:123]
	v_mfma_f32_16x16x32_bf16 v[116:119], v[156:159], v[164:167], v[116:119]
	v_mfma_f32_16x16x32_bf16 v[104:107], v[148:151], v[172:175], v[104:107]
	v_mfma_f32_16x16x32_bf16 v[100:103], v[156:159], v[172:175], v[100:103]
	v_mfma_f32_16x16x32_bf16 v[88:91], v[148:151], v[180:183], v[88:91]
	v_mfma_f32_16x16x32_bf16 v[84:87], v[156:159], v[180:183], v[84:87]
	v_mfma_f32_16x16x32_bf16 v[72:75], v[148:151], v[212:215], v[72:75]
	v_mfma_f32_16x16x32_bf16 v[68:71], v[156:159], v[212:215], v[68:71]
	v_mfma_f32_16x16x32_bf16 v[120:123], v[152:155], v[168:171], v[120:123]
	v_mfma_f32_16x16x32_bf16 v[116:119], v[160:163], v[168:171], v[116:119]
	v_mfma_f32_16x16x32_bf16 v[104:107], v[152:155], v[176:179], v[104:107]
	v_mfma_f32_16x16x32_bf16 v[100:103], v[160:163], v[176:179], v[100:103]
	v_mfma_f32_16x16x32_bf16 v[88:91], v[152:155], v[184:187], v[88:91]
	v_mfma_f32_16x16x32_bf16 v[84:87], v[160:163], v[184:187], v[84:87]
	v_mfma_f32_16x16x32_bf16 v[72:75], v[152:155], v[216:219], v[72:75]
	v_mfma_f32_16x16x32_bf16 v[68:71], v[160:163], v[216:219], v[68:71]
	s_setprio 0
	s_barrier
; #define PG8_STAGE(bufoff, gbase, voff) do { _Pragma("unroll") for (int _i = 0; _i < 2; ++_i) \
;         __builtin_amdgcn_global_load_lds((const unsigned*)((const char*)(gbase) + (voff)[_i]), (LAS unsigned*)(lds + (bufoff) + ldsw + _i * 8192), 16, 0, 0); } while (0)
; #define PG8_LDA(dst, b, h) do { _Pragma("unroll") for (int m = 0; m < 4; ++m) _Pragma("unroll") for (int k = 0; k < 2; ++k) dst[m][k] = *(const LAS bf16x8*)(lds + PG8_SA(b, h) + aoff + m * 2048 + k * 1024); } while (0)
; #define PG8_MMA(ai, bj, At, Bt) do { __builtin_amdgcn_s_setprio(1); _Pragma("unroll") for (int m = 0; m < 4; ++m) _Pragma("unroll") for (int n = 0; n < 2; ++n) _Pragma("unroll") for (int k = 0; k < 2; ++k) \
;         acc[ai][bj][m][n] = __builtin_amdgcn_mfma_f32_16x16x32_bf16(Bt[n][k], At[m][k], acc[ai][bj][m][n], 0, 0, 0); __builtin_amdgcn_s_setprio(0); } while (0)
; #define PG8_WAIT_V(n) asm volatile("s_waitcnt vmcnt(" #n ")" ::: "memory")
; #define PG8_WAIT_L(n) asm volatile("s_waitcnt lgkmcnt(" #n ")" ::: "memory")
; #define PG8_BAR __builtin_amdgcn_s_barrier()
; #define PG8_SCHED __builtin_amdgcn_sched_barrier(0)
; template <class Epi>
; __device__ __forceinline__ void gemm_phase(LAS unsigned char* lds, const Gemm g, const StaticOrder& S, const Epi& E) {
;     ...
;             PG8_WAIT_V(8); PG8_WAIT_L(0); PG8_BAR; PG8_MMA(0, 0, At, B0); PG8_MMA(0, 1, At, B1); PG8_BAR; PG8_SCHED;
;             PG8_LDA(At, 1, 1); PG8_STAGE(PG8_SB(1, 0), b3, voffB); PG8_STAGE(PG8_SB(1, 1), b3 + hstepB, voffB); PG8_STAGE(PG8_SA(1, 0), a3, voffA);
;             PG8_WAIT_V(8); PG8_WAIT_L(0); PG8_BAR; PG8_MMA(1, 0, At, B0); PG8_MMA(1, 1, At, B1); PG8_BAR; PG8_SCHED;
;         }
	s_add_i32 s46, s70, s54
	v_lshl_add_u64 v[196:197], v[196:197], 0, s[30:31]
	s_mov_b32 m0, s46
	ds_read_b128 v[164:167], v232 offset:49152
	ds_read_b128 v[168:171], v232 offset:50176
	ds_read_b128 v[172:175], v232 offset:51200
	ds_read_b128 v[176:179], v232 offset:52224
	ds_read_b128 v[180:183], v232 offset:53248
	ds_read_b128 v[184:187], v232 offset:54272
	ds_read_b128 v[212:215], v232 offset:55296
	ds_read_b128 v[216:219], v232 offset:56320
	global_load_lds_dwordx4 v[196:197], off
	s_add_i32 m0, s46, 0x2000
	s_add_u32 s22, s22, 0x2c080
	v_lshl_add_u64 v[196:197], v[198:199], 0, s[30:31]
	s_addc_u32 s23, s23, 0
	s_add_i32 s46, s71, s54
	global_load_lds_dwordx4 v[196:197], off
	v_lshl_add_u64 v[196:197], s[22:23], 0, v[190:191]
	s_mov_b32 m0, s46
	s_nop 0
	global_load_lds_dwordx4 v[196:197], off
	v_lshl_add_u64 v[196:197], s[22:23], 0, v[0:1]
	s_add_i32 m0, s46, 0x2000
	s_nop 0
	global_load_lds_dwordx4 v[196:197], off
	v_lshl_add_u64 v[196:197], v[220:221], 0, s[30:31]
	s_mov_b32 m0, s28
	s_nop 0
	global_load_lds_dwordx4 v[196:197], off
	v_lshl_add_u64 v[196:197], v[222:223], 0, s[30:31]
	s_mov_b32 m0, s61
	s_nop 0
	global_load_lds_dwordx4 v[196:197], off
	s_waitcnt vmcnt(8)
	s_waitcnt lgkmcnt(0)
	s_barrier
	s_setprio 1
	v_mfma_f32_16x16x32_bf16 v[64:67], v[132:135], v[164:167], v[64:67]
	v_mfma_f32_16x16x32_bf16 v[60:63], v[140:143], v[164:167], v[60:63]
	v_mfma_f32_16x16x32_bf16 v[48:51], v[132:135], v[172:175], v[48:51]
	v_mfma_f32_16x16x32_bf16 v[44:47], v[140:143], v[172:175], v[44:47]
	v_mfma_f32_16x16x32_bf16 v[32:35], v[132:135], v[180:183], v[32:35]
	v_mfma_f32_16x16x32_bf16 v[28:31], v[140:143], v[180:183], v[28:31]
	v_mfma_f32_16x16x32_bf16 v[16:19], v[132:135], v[212:215], v[16:19]
	v_mfma_f32_16x16x32_bf16 v[12:15], v[140:143], v[212:215], v[12:15]
	v_mfma_f32_16x16x32_bf16 v[64:67], v[136:139], v[168:171], v[64:67]
	v_mfma_f32_16x16x32_bf16 v[60:63], v[144:147], v[168:171], v[60:63]
	v_mfma_f32_16x16x32_bf16 v[48:51], v[136:139], v[176:179], v[48:51]
	v_mfma_f32_16x16x32_bf16 v[44:47], v[144:147], v[176:179], v[44:47]
	v_mfma_f32_16x16x32_bf16 v[32:35], v[136:139], v[184:187], v[32:35]
	v_mfma_f32_16x16x32_bf16 v[28:31], v[144:147], v[184:187], v[28:31]
	v_mfma_f32_16x16x32_bf16 v[16:19], v[136:139], v[216:219], v[16:19]
	v_mfma_f32_16x16x32_bf16 v[12:15], v[144:147], v[216:219], v[12:15]
	v_mfma_f32_16x16x32_bf16 v[56:59], v[148:151], v[164:167], v[56:59]
	v_mfma_f32_16x16x32_bf16 v[52:55], v[156:159], v[164:167], v[52:55]
	v_mfma_f32_16x16x32_bf16 v[40:43], v[148:151], v[172:175], v[40:43]
	v_mfma_f32_16x16x32_bf16 v[36:39], v[156:159], v[172:175], v[36:39]
	v_mfma_f32_16x16x32_bf16 v[24:27], v[148:151], v[180:183], v[24:27]
	v_mfma_f32_16x16x32_bf16 v[20:23], v[156:159], v[180:183], v[20:23]
	v_mfma_f32_16x16x32_bf16 v[8:11], v[148:151], v[212:215], v[8:11]
	v_mfma_f32_16x16x32_bf16 v[4:7], v[156:159], v[212:215], v[4:7]
	v_mfma_f32_16x16x32_bf16 v[56:59], v[152:155], v[168:171], v[56:59]
	v_mfma_f32_16x16x32_bf16 v[52:55], v[160:163], v[168:171], v[52:55]
	v_mfma_f32_16x16x32_bf16 v[40:43], v[152:155], v[176:179], v[40:43]
	v_mfma_f32_16x16x32_bf16 v[36:39], v[160:163], v[176:179], v[36:39]
	v_mfma_f32_16x16x32_bf16 v[24:27], v[152:155], v[184:187], v[24:27]
	v_mfma_f32_16x16x32_bf16 v[20:23], v[160:163], v[184:187], v[20:23]
	v_mfma_f32_16x16x32_bf16 v[8:11], v[152:155], v[216:219], v[8:11]
	v_mfma_f32_16x16x32_bf16 v[4:7], v[160:163], v[216:219], v[4:7]
	s_setprio 0
	s_barrier
	s_add_i32 s69, s69, 2
	s_add_u32 s67, s67, 0x100
	s_addc_u32 s68, s68, 0
	s_cmp_gt_u32 s69, 41
	s_mov_b64 s[46:47], s[48:49]
	s_cbranch_scc0 .LBB0_240
	v_mov_b64_e32 v[208:209], 0xaff
	s_and_b64 vcc, exec, s[38:39]
	s_cbranch_vccz .LBB0_243
	s_barrier

; #define PG8_STAGE(bufoff, gbase, voff) do { _Pragma("unroll") for (int _i = 0; _i < 2; ++_i) \
;         __builtin_amdgcn_global_load_lds((const unsigned*)((const char*)(gbase) + (voff)[_i]), (LAS unsigned*)(lds + (bufoff) + ldsw + _i * 8192), 16, 0, 0); } while (0)
; #define PG8_LDA(dst, b, h) do { _Pragma("unroll") for (int m = 0; m < 4; ++m) _Pragma("unroll") for (int k = 0; k < 2; ++k) dst[m][k] = *(const LAS bf16x8*)(lds + PG8_SA(b, h) + aoff + m * 2048 + k * 1024); } while (0)
; #define PG8_LDB(dst, b, h) do { _Pragma("unroll") for (int n = 0; n < 2; ++n) _Pragma("unroll") for (int k = 0; k < 2; ++k) dst[n][k] = *(const LAS bf16x8*)(lds + PG8_SB(b, h) + boff + n * 2048 + k * 1024); } while (0)
; #define PG8_MMA(ai, bj, At, Bt) do { __builtin_amdgcn_s_setprio(1); _Pragma("unroll") for (int m = 0; m < 4; ++m) _Pragma("unroll") for (int n = 0; n < 2; ++n) _Pragma("unroll") for (int k = 0; k < 2; ++k) \
;         acc[ai][bj][m][n] = __builtin_amdgcn_mfma_f32_16x16x32_bf16(Bt[n][k], At[m][k], acc[ai][bj][m][n], 0, 0, 0); __builtin_amdgcn_s_setprio(0); } while (0)
; #define PG8_WAIT_V(n) asm volatile("s_waitcnt vmcnt(" #n ")" ::: "memory")
; #define PG8_WAIT_L(n) asm volatile("s_waitcnt lgkmcnt(" #n ")" ::: "memory")
; #define PG8_BAR __builtin_amdgcn_s_barrier()
; #define PG8_SCHED __builtin_amdgcn_sched_barrier(0)
; template <class Epi>
; __device__ __forceinline__ void gemm_phase(LAS unsigned char* lds, const Gemm g, const StaticOrder& S, const Epi& E) {
;     ...
;             PG8_LDB(B0, 0, 0); PG8_LDB(B1, 0, 1); PG8_SCHED; PG8_LDA(At, 0, 0); PG8_STAGE(PG8_SA(1, 1), a1 + hstepA, voffA);
;             PG8_WAIT_V(8); PG8_WAIT_L(0); PG8_BAR; PG8_MMA(0, 0, At, B0); PG8_MMA(0, 1, At, B1); PG8_BAR; PG8_SCHED;
;             PG8_LDA(At, 0, 1); PG8_STAGE(PG8_SB(0, 0), b2, voffB); PG8_STAGE(PG8_SB(0, 1), b2 + hstepB, voffB); PG8_STAGE(PG8_SA(0, 0), a2, voffA);
;             PG8_WAIT_V(8); PG8_WAIT_L(0); PG8_BAR; PG8_MMA(1, 0, At, B0); PG8_MMA(1, 1, At, B1); PG8_BAR; PG8_SCHED;
;             PG8_LDB(B0, 1, 0); PG8_LDB(B1, 1, 1); PG8_SCHED; PG8_LDA(At, 1, 0); PG8_STAGE(PG8_SA(0, 1), a2 + hstepA, voffA);
.LBB0_323:
	s_add_u32 s22, s34, 0xfffc0080
	s_addc_u32 s23, s35, -1
	s_add_i32 s52, 0, 0x10000
	s_cmp_eq_u32 s51, 12
	s_cselect_b32 s39, s41, s23
	s_cselect_b32 s38, s46, s22
	s_cselect_b32 s23, s47, s50
	s_cselect_b32 s22, s48, s49
	s_add_i32 s54, 0, 0x14000
	v_add_u32_e32 v160, s52, v147
	v_add_u32_e32 v172, s54, v147
	ds_read_b128 v[132:135], v160
	ds_read_b128 v[136:139], v160 offset:1024
	ds_read_b128 v[156:159], v160 offset:2048
	ds_read_b128 v[160:163], v160 offset:3072
	ds_read_b128 v[164:167], v172
	ds_read_b128 v[168:171], v172 offset:1024
	ds_read_b128 v[176:179], v172 offset:2048
	ds_read_b128 v[180:183], v172 offset:3072
	v_lshl_add_u64 v[172:173], s[34:35], 0, v[152:153]
	s_add_i32 m0, s75, 0xc000
	ds_read_b128 v[184:187], v174
	ds_read_b128 v[188:191], v174 offset:1024
	ds_read_b128 v[192:195], v174 offset:2048
	ds_read_b128 v[210:213], v174 offset:3072
	ds_read_b128 v[214:217], v174 offset:4096
	ds_read_b128 v[218:221], v174 offset:5120
	ds_read_b128 v[222:225], v174 offset:6144
	ds_read_b128 v[226:229], v174 offset:7168
	global_load_lds_dwordx4 v[172:173], off
	v_lshl_add_u64 v[172:173], s[34:35], 0, v[154:155]
	s_add_i32 m0, s75, 0xe000
	s_nop 0
	global_load_lds_dwordx4 v[172:173], off
	s_waitcnt vmcnt(8)
	s_waitcnt lgkmcnt(0)
	s_barrier
	s_setprio 1
	v_mfma_f32_16x16x32_bf16 v[128:131], v[132:135], v[184:187], v[128:131]
	v_mfma_f32_16x16x32_bf16 v[124:127], v[156:159], v[184:187], v[124:127]
	v_mfma_f32_16x16x32_bf16 v[112:115], v[132:135], v[192:195], v[112:115]
	v_mfma_f32_16x16x32_bf16 v[108:111], v[156:159], v[192:195], v[108:111]
	v_mfma_f32_16x16x32_bf16 v[96:99], v[132:135], v[214:217], v[96:99]
	v_mfma_f32_16x16x32_bf16 v[92:95], v[156:159], v[214:217], v[92:95]
	v_mfma_f32_16x16x32_bf16 v[80:83], v[132:135], v[222:225], v[80:83]
	v_mfma_f32_16x16x32_bf16 v[76:79], v[156:159], v[222:225], v[76:79]
	v_mfma_f32_16x16x32_bf16 v[128:131], v[136:139], v[188:191], v[128:131]
	v_mfma_f32_16x16x32_bf16 v[124:127], v[160:163], v[188:191], v[124:127]
	v_mfma_f32_16x16x32_bf16 v[112:115], v[136:139], v[210:213], v[112:115]
	v_mfma_f32_16x16x32_bf16 v[108:111], v[160:163], v[210:213], v[108:111]
	v_mfma_f32_16x16x32_bf16 v[96:99], v[136:139], v[218:221], v[96:99]
	v_mfma_f32_16x16x32_bf16 v[92:95], v[160:163], v[218:221], v[92:95]
	v_mfma_f32_16x16x32_bf16 v[80:83], v[136:139], v[226:229], v[80:83]
	v_mfma_f32_16x16x32_bf16 v[76:79], v[160:163], v[226:229], v[76:79]
	v_mfma_f32_16x16x32_bf16 v[120:123], v[164:167], v[184:187], v[120:123]
	v_mfma_f32_16x16x32_bf16 v[116:119], v[176:179], v[184:187], v[116:119]
	v_mfma_f32_16x16x32_bf16 v[104:107], v[164:167], v[192:195], v[104:107]
	v_mfma_f32_16x16x32_bf16 v[100:103], v[176:179], v[192:195], v[100:103]
	v_mfma_f32_16x16x32_bf16 v[88:91], v[164:167], v[214:217], v[88:91]
	v_mfma_f32_16x16x32_bf16 v[84:87], v[176:179], v[214:217], v[84:87]
	v_mfma_f32_16x16x32_bf16 v[72:75], v[164:167], v[222:225], v[72:75]
	v_mfma_f32_16x16x32_bf16 v[68:71], v[176:179], v[222:225], v[68:71]
	v_mfma_f32_16x16x32_bf16 v[120:123], v[168:171], v[188:191], v[120:123]
	v_mfma_f32_16x16x32_bf16 v[116:119], v[180:183], v[188:191], v[116:119]
	v_mfma_f32_16x16x32_bf16 v[104:107], v[168:171], v[210:213], v[104:107]
	v_mfma_f32_16x16x32_bf16 v[100:103], v[180:183], v[210:213], v[100:103]
	v_mfma_f32_16x16x32_bf16 v[88:91], v[168:171], v[218:221], v[88:91]
	v_mfma_f32_16x16x32_bf16 v[84:87], v[180:183], v[218:221], v[84:87]
	v_mfma_f32_16x16x32_bf16 v[72:75], v[168:171], v[226:229], v[72:75]
	v_mfma_f32_16x16x32_bf16 v[68:71], v[180:183], v[226:229], v[68:71]
	s_setprio 0
	s_barrier
	s_add_i32 s52, s52, s74
	v_lshl_add_u64 v[172:173], s[22:23], 0, v[142:143]
	s_mov_b32 m0, s52
	ds_read_b128 v[184:187], v174 offset:16384
	ds_read_b128 v[188:191], v174 offset:17408
	ds_read_b128 v[192:195], v174 offset:18432
	ds_read_b128 v[210:213], v174 offset:19456
	ds_read_b128 v[214:217], v174 offset:20480
	ds_read_b128 v[218:221], v174 offset:21504
	ds_read_b128 v[222:225], v174 offset:22528
	ds_read_b128 v[226:229], v174 offset:23552
	global_load_lds_dwordx4 v[172:173], off
	s_add_i32 m0, s52, 0x2000
	s_add_u32 s52, s22, 0x10000
	v_lshl_add_u64 v[196:197], s[22:23], 0, v[0:1]
	s_addc_u32 s53, s23, 0
	s_add_i32 s54, s54, s74
	global_load_lds_dwordx4 v[196:197], off
	v_lshl_add_u64 v[198:199], s[52:53], 0, v[142:143]
	s_mov_b32 m0, s54
	v_lshl_add_u64 v[230:231], s[38:39], 0, v[140:141]
	global_load_lds_dwordx4 v[198:199], off
	v_lshl_add_u64 v[198:199], s[52:53], 0, v[0:1]
	s_add_i32 m0, s54, 0x2000
	s_nop 0
	global_load_lds_dwordx4 v[198:199], off
	v_lshl_add_u64 v[198:199], s[38:39], 0, v[144:145]
	s_mov_b32 m0, s75
	s_nop 0
	global_load_lds_dwordx4 v[198:199], off
	s_mov_b32 m0, s76
	s_nop 0
	global_load_lds_dwordx4 v[230:231], off
	s_waitcnt vmcnt(8)
	s_waitcnt lgkmcnt(0)
	s_barrier
; #define PG8_STAGE(bufoff, gbase, voff) do { _Pragma("unroll") for (int _i = 0; _i < 2; ++_i) \
;         __builtin_amdgcn_global_load_lds((const unsigned*)((const char*)(gbase) + (voff)[_i]), (LAS unsigned*)(lds + (bufoff) + ldsw + _i * 8192), 16, 0, 0); } while (0)
; #define PG8_LDA(dst, b, h) do { _Pragma("unroll") for (int m = 0; m < 4; ++m) _Pragma("unroll") for (int k = 0; k < 2; ++k) dst[m][k] = *(const LAS bf16x8*)(lds + PG8_SA(b, h) + aoff + m * 2048 + k * 1024); } while (0)
; #define PG8_LDB(dst, b, h) do { _Pragma("unroll") for (int n = 0; n < 2; ++n) _Pragma("unroll") for (int k = 0; k < 2; ++k) dst[n][k] = *(const LAS bf16x8*)(lds + PG8_SB(b, h) + boff + n * 2048 + k * 1024); } while (0)
; #define PG8_MMA(ai, bj, At, Bt) do { __builtin_amdgcn_s_setprio(1); _Pragma("unroll") for (int m = 0; m < 4; ++m) _Pragma("unroll") for (int n = 0; n < 2; ++n) _Pragma("unroll") for (int k = 0; k < 2; ++k) \
;         acc[ai][bj][m][n] = __builtin_amdgcn_mfma_f32_16x16x32_bf16(Bt[n][k], At[m][k], acc[ai][bj][m][n], 0, 0, 0); __builtin_amdgcn_s_setprio(0); } while (0)
; #define PG8_WAIT_V(n) asm volatile("s_waitcnt vmcnt(" #n ")" ::: "memory")
; #define PG8_WAIT_L(n) asm volatile("s_waitcnt lgkmcnt(" #n ")" ::: "memory")
; #define PG8_BAR __builtin_amdgcn_s_barrier()
; #define PG8_SCHED __builtin_amdgcn_sched_barrier(0)
; template <class Epi>
; __device__ __forceinline__ void gemm_phase(LAS unsigned char* lds, const Gemm g, const StaticOrder& S, const Epi& E) {
;     ...
;             PG8_WAIT_V(8); PG8_WAIT_L(0); PG8_BAR; PG8_MMA(1, 0, At, B0); PG8_MMA(1, 1, At, B1); PG8_BAR; PG8_SCHED;
;             PG8_LDB(B0, 1, 0); PG8_LDB(B1, 1, 1); PG8_SCHED; PG8_LDA(At, 1, 0); PG8_STAGE(PG8_SA(0, 1), a2 + hstepA, voffA);
;             PG8_WAIT_V(8); PG8_WAIT_L(0); PG8_BAR; PG8_MMA(0, 0, At, B0); PG8_MMA(0, 1, At, B1); PG8_BAR; PG8_SCHED;
	s_setprio 1
	v_mfma_f32_16x16x32_bf16 v[64:67], v[132:135], v[184:187], v[64:67]
	v_mfma_f32_16x16x32_bf16 v[60:63], v[156:159], v[184:187], v[60:63]
	v_mfma_f32_16x16x32_bf16 v[48:51], v[132:135], v[192:195], v[48:51]
	v_mfma_f32_16x16x32_bf16 v[44:47], v[156:159], v[192:195], v[44:47]
	v_mfma_f32_16x16x32_bf16 v[32:35], v[132:135], v[214:217], v[32:35]
	v_mfma_f32_16x16x32_bf16 v[28:31], v[156:159], v[214:217], v[28:31]
	v_mfma_f32_16x16x32_bf16 v[16:19], v[132:135], v[222:225], v[16:19]
	v_mfma_f32_16x16x32_bf16 v[12:15], v[156:159], v[222:225], v[12:15]
	v_mfma_f32_16x16x32_bf16 v[64:67], v[136:139], v[188:191], v[64:67]
	v_mfma_f32_16x16x32_bf16 v[60:63], v[160:163], v[188:191], v[60:63]
	v_mfma_f32_16x16x32_bf16 v[48:51], v[136:139], v[210:213], v[48:51]
	v_mfma_f32_16x16x32_bf16 v[44:47], v[160:163], v[210:213], v[44:47]
	v_mfma_f32_16x16x32_bf16 v[32:35], v[136:139], v[218:221], v[32:35]
	v_mfma_f32_16x16x32_bf16 v[28:31], v[160:163], v[218:221], v[28:31]
	v_mfma_f32_16x16x32_bf16 v[16:19], v[136:139], v[226:229], v[16:19]
	v_mfma_f32_16x16x32_bf16 v[12:15], v[160:163], v[226:229], v[12:15]
	v_mfma_f32_16x16x32_bf16 v[56:59], v[164:167], v[184:187], v[56:59]
	v_mfma_f32_16x16x32_bf16 v[52:55], v[176:179], v[184:187], v[52:55]
	v_mfma_f32_16x16x32_bf16 v[40:43], v[164:167], v[192:195], v[40:43]
	v_mfma_f32_16x16x32_bf16 v[36:39], v[176:179], v[192:195], v[36:39]
	v_mfma_f32_16x16x32_bf16 v[24:27], v[164:167], v[214:217], v[24:27]
	v_mfma_f32_16x16x32_bf16 v[20:23], v[176:179], v[214:217], v[20:23]
	v_mfma_f32_16x16x32_bf16 v[8:11], v[164:167], v[222:225], v[8:11]
	v_mfma_f32_16x16x32_bf16 v[4:7], v[176:179], v[222:225], v[4:7]
	v_mfma_f32_16x16x32_bf16 v[56:59], v[168:171], v[188:191], v[56:59]
	v_mfma_f32_16x16x32_bf16 v[52:55], v[180:183], v[188:191], v[52:55]
	v_mfma_f32_16x16x32_bf16 v[40:43], v[168:171], v[210:213], v[40:43]
	v_mfma_f32_16x16x32_bf16 v[36:39], v[180:183], v[210:213], v[36:39]
	v_mfma_f32_16x16x32_bf16 v[24:27], v[168:171], v[218:221], v[24:27]
	v_mfma_f32_16x16x32_bf16 v[20:23], v[180:183], v[218:221], v[20:23]
	v_mfma_f32_16x16x32_bf16 v[8:11], v[168:171], v[226:229], v[8:11]
	v_mfma_f32_16x16x32_bf16 v[4:7], v[180:183], v[226:229], v[4:7]
	s_setprio 0
	s_barrier
	s_add_i32 s52, 0, 0x18000
	s_add_i32 s53, 0, 0x1c000
	v_add_u32_e32 v160, s52, v147
	v_add_u32_e32 v175, s53, v147
	ds_read_b128 v[132:135], v160
	ds_read_b128 v[136:139], v160 offset:1024
	ds_read_b128 v[156:159], v160 offset:2048
	ds_read_b128 v[160:163], v160 offset:3072
	ds_read_b128 v[164:167], v175
	ds_read_b128 v[168:171], v175 offset:1024
	ds_read_b128 v[176:179], v175 offset:2048
	ds_read_b128 v[180:183], v175 offset:3072
	s_add_u32 s38, s38, 0x40000
	s_addc_u32 s39, s39, 0
	s_mov_b32 m0, s77
	v_lshl_add_u64 v[232:233], s[38:39], 0, v[144:145]
	ds_read_b128 v[184:187], v174 offset:32768
	ds_read_b128 v[188:191], v174 offset:33792
	ds_read_b128 v[192:195], v174 offset:34816
	ds_read_b128 v[210:213], v174 offset:35840
	ds_read_b128 v[214:217], v174 offset:36864
	ds_read_b128 v[218:221], v174 offset:37888
	ds_read_b128 v[222:225], v174 offset:38912
	ds_read_b128 v[226:229], v174 offset:39936
	global_load_lds_dwordx4 v[232:233], off
	v_lshl_add_u64 v[232:233], s[38:39], 0, v[140:141]
	s_mov_b32 m0, s78
	s_nop 0
	global_load_lds_dwordx4 v[232:233], off
	s_waitcnt vmcnt(8)
	s_waitcnt lgkmcnt(0)
	s_barrier
	s_setprio 1
	v_mfma_f32_16x16x32_bf16 v[128:131], v[132:135], v[184:187], v[128:131]
	v_mfma_f32_16x16x32_bf16 v[124:127], v[156:159], v[184:187], v[124:127]
	v_mfma_f32_16x16x32_bf16 v[112:115], v[132:135], v[192:195], v[112:115]
	v_mfma_f32_16x16x32_bf16 v[108:111], v[156:159], v[192:195], v[108:111]
	v_mfma_f32_16x16x32_bf16 v[96:99], v[132:135], v[214:217], v[96:99]
	v_mfma_f32_16x16x32_bf16 v[92:95], v[156:159], v[214:217], v[92:95]
	v_mfma_f32_16x16x32_bf16 v[80:83], v[132:135], v[222:225], v[80:83]
	v_mfma_f32_16x16x32_bf16 v[76:79], v[156:159], v[222:225], v[76:79]
	v_mfma_f32_16x16x32_bf16 v[128:131], v[136:139], v[188:191], v[128:131]
	v_mfma_f32_16x16x32_bf16 v[124:127], v[160:163], v[188:191], v[124:127]
	v_mfma_f32_16x16x32_bf16 v[112:115], v[136:139], v[210:213], v[112:115]
	v_mfma_f32_16x16x32_bf16 v[108:111], v[160:163], v[210:213], v[108:111]
	v_mfma_f32_16x16x32_bf16 v[96:99], v[136:139], v[218:221], v[96:99]
	v_mfma_f32_16x16x32_bf16 v[92:95], v[160:163], v[218:221], v[92:95]
	v_mfma_f32_16x16x32_bf16 v[80:83], v[136:139], v[226:229], v[80:83]
	v_mfma_f32_16x16x32_bf16 v[76:79], v[160:163], v[226:229], v[76:79]
	v_mfma_f32_16x16x32_bf16 v[120:123], v[164:167], v[184:187], v[120:123]
	v_mfma_f32_16x16x32_bf16 v[116:119], v[176:179], v[184:187], v[116:119]
	v_mfma_f32_16x16x32_bf16 v[104:107], v[164:167], v[192:195], v[104:107]
	v_mfma_f32_16x16x32_bf16 v[100:103], v[176:179], v[192:195], v[100:103]
	v_mfma_f32_16x16x32_bf16 v[88:91], v[164:167], v[214:217], v[88:91]
	v_mfma_f32_16x16x32_bf16 v[84:87], v[176:179], v[214:217], v[84:87]
	v_mfma_f32_16x16x32_bf16 v[72:75], v[164:167], v[222:225], v[72:75]
	v_mfma_f32_16x16x32_bf16 v[68:71], v[176:179], v[222:225], v[68:71]
	v_mfma_f32_16x16x32_bf16 v[120:123], v[168:171], v[188:191], v[120:123]
	v_mfma_f32_16x16x32_bf16 v[116:119], v[180:183], v[188:191], v[116:119]
	v_mfma_f32_16x16x32_bf16 v[104:107], v[168:171], v[210:213], v[104:107]
	v_mfma_f32_16x16x32_bf16 v[100:103], v[180:183], v[210:213], v[100:103]
	v_mfma_f32_16x16x32_bf16 v[88:91], v[168:171], v[218:221], v[88:91]
	v_mfma_f32_16x16x32_bf16 v[84:87], v[180:183], v[218:221], v[84:87]
	v_mfma_f32_16x16x32_bf16 v[72:75], v[168:171], v[226:229], v[72:75]
	v_mfma_f32_16x16x32_bf16 v[68:71], v[180:183], v[226:229], v[68:71]
	s_setprio 0
	s_barrier
; #define PG8_STAGE(bufoff, gbase, voff) do { _Pragma("unroll") for (int _i = 0; _i < 2; ++_i) \
;         __builtin_amdgcn_global_load_lds((const unsigned*)((const char*)(gbase) + (voff)[_i]), (LAS unsigned*)(lds + (bufoff) + ldsw + _i * 8192), 16, 0, 0); } while (0)
; #define PG8_LDA(dst, b, h) do { _Pragma("unroll") for (int m = 0; m < 4; ++m) _Pragma("unroll") for (int k = 0; k < 2; ++k) dst[m][k] = *(const LAS bf16x8*)(lds + PG8_SA(b, h) + aoff + m * 2048 + k * 1024); } while (0)
; #define PG8_MMA(ai, bj, At, Bt) do { __builtin_amdgcn_s_setprio(1); _Pragma("unroll") for (int m = 0; m < 4; ++m) _Pragma("unroll") for (int n = 0; n < 2; ++n) _Pragma("unroll") for (int k = 0; k < 2; ++k) \
;         acc[ai][bj][m][n] = __builtin_amdgcn_mfma_f32_16x16x32_bf16(Bt[n][k], At[m][k], acc[ai][bj][m][n], 0, 0, 0); __builtin_amdgcn_s_setprio(0); } while (0)
; #define PG8_WAIT_V(n) asm volatile("s_waitcnt vmcnt(" #n ")" ::: "memory")
; #define PG8_WAIT_L(n) asm volatile("s_waitcnt lgkmcnt(" #n ")" ::: "memory")
; #define PG8_BAR __builtin_amdgcn_s_barrier()
; #define PG8_SCHED __builtin_amdgcn_sched_barrier(0)
; template <class Epi>
; __device__ __forceinline__ void gemm_phase(LAS unsigned char* lds, const Gemm g, const StaticOrder& S, const Epi& E) {
;     ...
;             PG8_LDA(At, 1, 1); PG8_STAGE(PG8_SB(1, 0), b3, voffB); PG8_STAGE(PG8_SB(1, 1), b3 + hstepB, voffB); PG8_STAGE(PG8_SA(1, 0), a3, voffA);
;             PG8_WAIT_V(8); PG8_WAIT_L(0); PG8_BAR; PG8_MMA(1, 0, At, B0); PG8_MMA(1, 1, At, B1); PG8_BAR; PG8_SCHED;
;         }
;         if (wr == 0) PG8_BAR;
	s_add_i32 s38, s52, s74
	v_lshl_add_u64 v[172:173], v[172:173], 0, s[30:31]
	s_mov_b32 m0, s38
	ds_read_b128 v[184:187], v174 offset:49152
	ds_read_b128 v[188:191], v174 offset:50176
	ds_read_b128 v[192:195], v174 offset:51200
	ds_read_b128 v[210:213], v174 offset:52224
	ds_read_b128 v[214:217], v174 offset:53248
	ds_read_b128 v[218:221], v174 offset:54272
	ds_read_b128 v[222:225], v174 offset:55296
	ds_read_b128 v[226:229], v174 offset:56320
	global_load_lds_dwordx4 v[172:173], off
	s_add_i32 m0, s38, 0x2000
	s_add_u32 s22, s22, 0x10080
	v_lshl_add_u64 v[172:173], v[196:197], 0, s[30:31]
	s_addc_u32 s23, s23, 0
	s_add_i32 s38, s53, s74
	global_load_lds_dwordx4 v[172:173], off
	v_lshl_add_u64 v[172:173], s[22:23], 0, v[142:143]
	s_mov_b32 m0, s38
	s_nop 0
	global_load_lds_dwordx4 v[172:173], off
	v_lshl_add_u64 v[172:173], s[22:23], 0, v[0:1]
	s_add_i32 m0, s38, 0x2000
	s_nop 0
	global_load_lds_dwordx4 v[172:173], off
	v_lshl_add_u64 v[172:173], v[198:199], 0, s[30:31]
	s_mov_b32 m0, s85
	s_nop 0
	global_load_lds_dwordx4 v[172:173], off
	v_lshl_add_u64 v[172:173], v[230:231], 0, s[30:31]
	s_mov_b32 m0, s86
	s_nop 0
	global_load_lds_dwordx4 v[172:173], off
	s_waitcnt vmcnt(8)
	s_waitcnt lgkmcnt(0)
	s_barrier
	s_setprio 1
	v_mfma_f32_16x16x32_bf16 v[64:67], v[132:135], v[184:187], v[64:67]
	v_mfma_f32_16x16x32_bf16 v[60:63], v[156:159], v[184:187], v[60:63]
	v_mfma_f32_16x16x32_bf16 v[48:51], v[132:135], v[192:195], v[48:51]
	v_mfma_f32_16x16x32_bf16 v[44:47], v[156:159], v[192:195], v[44:47]
	v_mfma_f32_16x16x32_bf16 v[32:35], v[132:135], v[214:217], v[32:35]
	v_mfma_f32_16x16x32_bf16 v[28:31], v[156:159], v[214:217], v[28:31]
	v_mfma_f32_16x16x32_bf16 v[16:19], v[132:135], v[222:225], v[16:19]
	v_mfma_f32_16x16x32_bf16 v[12:15], v[156:159], v[222:225], v[12:15]
	v_mfma_f32_16x16x32_bf16 v[64:67], v[136:139], v[188:191], v[64:67]
	v_mfma_f32_16x16x32_bf16 v[60:63], v[160:163], v[188:191], v[60:63]
	v_mfma_f32_16x16x32_bf16 v[48:51], v[136:139], v[210:213], v[48:51]
	v_mfma_f32_16x16x32_bf16 v[44:47], v[160:163], v[210:213], v[44:47]
	v_mfma_f32_16x16x32_bf16 v[32:35], v[136:139], v[218:221], v[32:35]
	v_mfma_f32_16x16x32_bf16 v[28:31], v[160:163], v[218:221], v[28:31]
	v_mfma_f32_16x16x32_bf16 v[16:19], v[136:139], v[226:229], v[16:19]
	v_mfma_f32_16x16x32_bf16 v[12:15], v[160:163], v[226:229], v[12:15]
	v_mfma_f32_16x16x32_bf16 v[56:59], v[164:167], v[184:187], v[56:59]
	v_mfma_f32_16x16x32_bf16 v[52:55], v[176:179], v[184:187], v[52:55]
	v_mfma_f32_16x16x32_bf16 v[40:43], v[164:167], v[192:195], v[40:43]
	v_mfma_f32_16x16x32_bf16 v[36:39], v[176:179], v[192:195], v[36:39]
	v_mfma_f32_16x16x32_bf16 v[24:27], v[164:167], v[214:217], v[24:27]
	v_mfma_f32_16x16x32_bf16 v[20:23], v[176:179], v[214:217], v[20:23]
	v_mfma_f32_16x16x32_bf16 v[8:11], v[164:167], v[222:225], v[8:11]
	v_mfma_f32_16x16x32_bf16 v[4:7], v[176:179], v[222:225], v[4:7]
	v_mfma_f32_16x16x32_bf16 v[56:59], v[168:171], v[188:191], v[56:59]
	v_mfma_f32_16x16x32_bf16 v[52:55], v[180:183], v[188:191], v[52:55]
	v_mfma_f32_16x16x32_bf16 v[40:43], v[168:171], v[210:213], v[40:43]
	v_mfma_f32_16x16x32_bf16 v[36:39], v[180:183], v[210:213], v[36:39]
	v_mfma_f32_16x16x32_bf16 v[24:27], v[168:171], v[218:221], v[24:27]
	v_mfma_f32_16x16x32_bf16 v[20:23], v[180:183], v[218:221], v[20:23]
	v_mfma_f32_16x16x32_bf16 v[8:11], v[168:171], v[226:229], v[8:11]
	v_mfma_f32_16x16x32_bf16 v[4:7], v[180:183], v[226:229], v[4:7]
	s_setprio 0
	s_barrier
	s_add_i32 s51, s51, 2
	s_add_u32 s34, s34, 0x100
	s_addc_u32 s35, s35, 0
	s_add_u32 s49, s49, 0x100
	s_addc_u32 s50, s50, 0
	s_cmp_gt_u32 s51, 13
	s_cbranch_scc0 .LBB0_323
	s_and_b64 vcc, exec, s[14:15]
	s_cbranch_vccz .LBB0_326
	s_barrier

; #define PG8_STAGE(bufoff, gbase, voff) do { _Pragma("unroll") for (int _i = 0; _i < 2; ++_i) \
;         __builtin_amdgcn_global_load_lds((const unsigned*)((const char*)(gbase) + (voff)[_i]), (LAS unsigned*)(lds + (bufoff) + ldsw + _i * 8192), 16, 0, 0); } while (0)
; #define PG8_LDA(dst, b, h) do { _Pragma("unroll") for (int m = 0; m < 4; ++m) _Pragma("unroll") for (int k = 0; k < 2; ++k) dst[m][k] = *(const LAS bf16x8*)(lds + PG8_SA(b, h) + aoff + m * 2048 + k * 1024); } while (0)
; #define PG8_LDB(dst, b, h) do { _Pragma("unroll") for (int n = 0; n < 2; ++n) _Pragma("unroll") for (int k = 0; k < 2; ++k) dst[n][k] = *(const LAS bf16x8*)(lds + PG8_SB(b, h) + boff + n * 2048 + k * 1024); } while (0)
; #define PG8_MMA(ai, bj, At, Bt) do { __builtin_amdgcn_s_setprio(1); _Pragma("unroll") for (int m = 0; m < 4; ++m) _Pragma("unroll") for (int n = 0; n < 2; ++n) _Pragma("unroll") for (int k = 0; k < 2; ++k) \
;         acc[ai][bj][m][n] = __builtin_amdgcn_mfma_f32_16x16x32_bf16(Bt[n][k], At[m][k], acc[ai][bj][m][n], 0, 0, 0); __builtin_amdgcn_s_setprio(0); } while (0)
; #define PG8_WAIT_V(n) asm volatile("s_waitcnt vmcnt(" #n ")" ::: "memory")
; #define PG8_WAIT_L(n) asm volatile("s_waitcnt lgkmcnt(" #n ")" ::: "memory")
; #define PG8_BAR __builtin_amdgcn_s_barrier()
; #define PG8_SCHED __builtin_amdgcn_sched_barrier(0)
; template <class Epi>
; __device__ __forceinline__ void gemm_phase(LAS unsigned char* lds, const Gemm g, const StaticOrder& S, const Epi& E) {
;     ...
;             const bool last = (t == nt - 2);
;             const char* a1 = cA + (size_t)(t + 1) * kstep;
;             const char* a2 = last ? nA : cA + (size_t)(t + 2) * kstep; const char* b2 = last ? nB : cB + (size_t)(t + 2) * kstep;
;             const char* a3 = a2 + kstep; const char* b3 = b2 + kstep;
;             PG8_LDB(B0, 0, 0); PG8_LDB(B1, 0, 1); PG8_SCHED; PG8_LDA(At, 0, 0); PG8_STAGE(PG8_SA(1, 1), a1 + hstepA, voffA);
;             PG8_WAIT_V(8); PG8_WAIT_L(0); PG8_BAR; PG8_MMA(0, 0, At, B0); PG8_MMA(0, 1, At, B1); PG8_BAR; PG8_SCHED;
;             PG8_LDA(At, 0, 1); PG8_STAGE(PG8_SB(0, 0), b2, voffB); PG8_STAGE(PG8_SB(0, 1), b2 + hstepB, voffB); PG8_STAGE(PG8_SA(0, 0), a2, voffA);
;             PG8_WAIT_V(8); PG8_WAIT_L(0); PG8_BAR; PG8_MMA(1, 0, At, B0); PG8_MMA(1, 1, At, B1); PG8_BAR; PG8_SCHED;
.LBB0_551:
	s_add_u32 s22, s44, 0xfffc0080
	s_addc_u32 s23, s45, -1
	s_add_i32 s66, 0, 0x10000
	s_cmp_eq_u32 s65, 12
	s_cselect_b32 s47, s35, s23
	s_cselect_b32 s46, s61, s22
	v_add_u32_e32 v150, s66, v152
	s_cselect_b32 s23, s15, s64
	s_cselect_b32 s22, s62, s63
	s_add_i32 s68, 0, 0x14000
	ds_read_b128 v[142:145], v150
	ds_read_b128 v[146:149], v150 offset:1024
	ds_read_b128 v[156:159], v150 offset:2048
	ds_read_b128 v[160:163], v150 offset:3072
	v_add_u32_e32 v150, s68, v152
	ds_read_b128 v[164:167], v150
	ds_read_b128 v[168:171], v150 offset:1024
	ds_read_b128 v[172:175], v150 offset:2048
	ds_read_b128 v[176:179], v150 offset:3072
	v_lshl_add_u64 v[150:151], s[44:45], 0, v[138:139]
	s_add_i32 m0, s52, 0xc000
	ds_read_b128 v[180:183], v154
	ds_read_b128 v[184:187], v154 offset:1024
	ds_read_b128 v[188:191], v154 offset:2048
	ds_read_b128 v[192:195], v154 offset:3072
	ds_read_b128 v[210:213], v154 offset:4096
	ds_read_b128 v[214:217], v154 offset:5120
	ds_read_b128 v[218:221], v154 offset:6144
	ds_read_b128 v[222:225], v154 offset:7168
	global_load_lds_dwordx4 v[150:151], off
	v_lshl_add_u64 v[150:151], s[44:45], 0, v[140:141]
	s_add_i32 m0, s52, 0xe000
	s_nop 0
	global_load_lds_dwordx4 v[150:151], off
	s_waitcnt vmcnt(8)
	s_waitcnt lgkmcnt(0)
	s_barrier
	s_setprio 1
	v_mfma_f32_16x16x32_bf16 v[128:131], v[142:145], v[180:183], v[128:131]
	v_mfma_f32_16x16x32_bf16 v[124:127], v[156:159], v[180:183], v[124:127]
	v_mfma_f32_16x16x32_bf16 v[120:123], v[142:145], v[188:191], v[120:123]
	v_mfma_f32_16x16x32_bf16 v[116:119], v[156:159], v[188:191], v[116:119]
	v_mfma_f32_16x16x32_bf16 v[112:115], v[142:145], v[210:213], v[112:115]
	v_mfma_f32_16x16x32_bf16 v[108:111], v[156:159], v[210:213], v[108:111]
	v_mfma_f32_16x16x32_bf16 v[104:107], v[142:145], v[218:221], v[104:107]
	v_mfma_f32_16x16x32_bf16 v[100:103], v[156:159], v[218:221], v[100:103]
	v_mfma_f32_16x16x32_bf16 v[128:131], v[146:149], v[184:187], v[128:131]
	v_mfma_f32_16x16x32_bf16 v[124:127], v[160:163], v[184:187], v[124:127]
	v_mfma_f32_16x16x32_bf16 v[120:123], v[146:149], v[192:195], v[120:123]
	v_mfma_f32_16x16x32_bf16 v[116:119], v[160:163], v[192:195], v[116:119]
	v_mfma_f32_16x16x32_bf16 v[112:115], v[146:149], v[214:217], v[112:115]
	v_mfma_f32_16x16x32_bf16 v[108:111], v[160:163], v[214:217], v[108:111]
	v_mfma_f32_16x16x32_bf16 v[104:107], v[146:149], v[222:225], v[104:107]
	v_mfma_f32_16x16x32_bf16 v[100:103], v[160:163], v[222:225], v[100:103]
	v_mfma_f32_16x16x32_bf16 v[64:67], v[164:167], v[180:183], v[64:67]
	v_mfma_f32_16x16x32_bf16 v[60:63], v[172:175], v[180:183], v[60:63]
	v_mfma_f32_16x16x32_bf16 v[56:59], v[164:167], v[188:191], v[56:59]
	v_mfma_f32_16x16x32_bf16 v[52:55], v[172:175], v[188:191], v[52:55]
	v_mfma_f32_16x16x32_bf16 v[48:51], v[164:167], v[210:213], v[48:51]
	v_mfma_f32_16x16x32_bf16 v[44:47], v[172:175], v[210:213], v[44:47]
	v_mfma_f32_16x16x32_bf16 v[40:43], v[164:167], v[218:221], v[40:43]
	v_mfma_f32_16x16x32_bf16 v[36:39], v[172:175], v[218:221], v[36:39]
	v_mfma_f32_16x16x32_bf16 v[64:67], v[168:171], v[184:187], v[64:67]
	v_mfma_f32_16x16x32_bf16 v[60:63], v[176:179], v[184:187], v[60:63]
	v_mfma_f32_16x16x32_bf16 v[56:59], v[168:171], v[192:195], v[56:59]
	v_mfma_f32_16x16x32_bf16 v[52:55], v[176:179], v[192:195], v[52:55]
	v_mfma_f32_16x16x32_bf16 v[48:51], v[168:171], v[214:217], v[48:51]
	v_mfma_f32_16x16x32_bf16 v[44:47], v[176:179], v[214:217], v[44:47]
	v_mfma_f32_16x16x32_bf16 v[40:43], v[168:171], v[222:225], v[40:43]
	v_mfma_f32_16x16x32_bf16 v[36:39], v[176:179], v[222:225], v[36:39]
	s_setprio 0
	s_barrier
	s_add_i32 s66, s66, s51
	v_lshl_add_u64 v[150:151], s[22:23], 0, v[134:135]
	s_mov_b32 m0, s66
	ds_read_b128 v[180:183], v154 offset:16384
	ds_read_b128 v[184:187], v154 offset:17408
	ds_read_b128 v[188:191], v154 offset:18432
	ds_read_b128 v[192:195], v154 offset:19456
	ds_read_b128 v[210:213], v154 offset:20480
	ds_read_b128 v[214:217], v154 offset:21504
	ds_read_b128 v[218:221], v154 offset:22528
	ds_read_b128 v[222:225], v154 offset:23552
	global_load_lds_dwordx4 v[150:151], off
	s_add_i32 m0, s66, 0x2000
	s_add_u32 s66, s22, 0x10000
	v_lshl_add_u64 v[196:197], s[22:23], 0, v[0:1]
	s_addc_u32 s67, s23, 0
	s_add_i32 s68, s68, s51
	global_load_lds_dwordx4 v[196:197], off
	v_lshl_add_u64 v[198:199], s[66:67], 0, v[134:135]
	s_mov_b32 m0, s68
	v_lshl_add_u64 v[226:227], s[46:47], 0, v[132:133]
	global_load_lds_dwordx4 v[198:199], off
	v_lshl_add_u64 v[198:199], s[66:67], 0, v[0:1]
	s_add_i32 m0, s68, 0x2000
	s_nop 0
	global_load_lds_dwordx4 v[198:199], off
	v_lshl_add_u64 v[198:199], s[46:47], 0, v[136:137]
	s_mov_b32 m0, s52
	s_nop 0
	global_load_lds_dwordx4 v[198:199], off
	s_mov_b32 m0, s53
	s_nop 0
	global_load_lds_dwordx4 v[226:227], off
	s_waitcnt vmcnt(8)
	s_waitcnt lgkmcnt(0)
	s_barrier
; #define PG8_STAGE(bufoff, gbase, voff) do { _Pragma("unroll") for (int _i = 0; _i < 2; ++_i) \
;         __builtin_amdgcn_global_load_lds((const unsigned*)((const char*)(gbase) + (voff)[_i]), (LAS unsigned*)(lds + (bufoff) + ldsw + _i * 8192), 16, 0, 0); } while (0)
; #define PG8_LDA(dst, b, h) do { _Pragma("unroll") for (int m = 0; m < 4; ++m) _Pragma("unroll") for (int k = 0; k < 2; ++k) dst[m][k] = *(const LAS bf16x8*)(lds + PG8_SA(b, h) + aoff + m * 2048 + k * 1024); } while (0)
; #define PG8_LDB(dst, b, h) do { _Pragma("unroll") for (int n = 0; n < 2; ++n) _Pragma("unroll") for (int k = 0; k < 2; ++k) dst[n][k] = *(const LAS bf16x8*)(lds + PG8_SB(b, h) + boff + n * 2048 + k * 1024); } while (0)
; #define PG8_MMA(ai, bj, At, Bt) do { __builtin_amdgcn_s_setprio(1); _Pragma("unroll") for (int m = 0; m < 4; ++m) _Pragma("unroll") for (int n = 0; n < 2; ++n) _Pragma("unroll") for (int k = 0; k < 2; ++k) \
;         acc[ai][bj][m][n] = __builtin_amdgcn_mfma_f32_16x16x32_bf16(Bt[n][k], At[m][k], acc[ai][bj][m][n], 0, 0, 0); __builtin_amdgcn_s_setprio(0); } while (0)
; #define PG8_WAIT_V(n) asm volatile("s_waitcnt vmcnt(" #n ")" ::: "memory")
; #define PG8_WAIT_L(n) asm volatile("s_waitcnt lgkmcnt(" #n ")" ::: "memory")
; #define PG8_BAR __builtin_amdgcn_s_barrier()
; #define PG8_SCHED __builtin_amdgcn_sched_barrier(0)
; template <class Epi>
; __device__ __forceinline__ void gemm_phase(LAS unsigned char* lds, const Gemm g, const StaticOrder& S, const Epi& E) {
;     ...
;             PG8_WAIT_V(8); PG8_WAIT_L(0); PG8_BAR; PG8_MMA(1, 0, At, B0); PG8_MMA(1, 1, At, B1); PG8_BAR; PG8_SCHED;
;             PG8_LDB(B0, 1, 0); PG8_LDB(B1, 1, 1); PG8_SCHED; PG8_LDA(At, 1, 0); PG8_STAGE(PG8_SA(0, 1), a2 + hstepA, voffA);
;             PG8_WAIT_V(8); PG8_WAIT_L(0); PG8_BAR; PG8_MMA(0, 0, At, B0); PG8_MMA(0, 1, At, B1); PG8_BAR; PG8_SCHED;
	s_setprio 1
	v_mfma_f32_16x16x32_bf16 v[96:99], v[142:145], v[180:183], v[96:99]
	v_mfma_f32_16x16x32_bf16 v[92:95], v[156:159], v[180:183], v[92:95]
	v_mfma_f32_16x16x32_bf16 v[88:91], v[142:145], v[188:191], v[88:91]
	v_mfma_f32_16x16x32_bf16 v[84:87], v[156:159], v[188:191], v[84:87]
	v_mfma_f32_16x16x32_bf16 v[80:83], v[142:145], v[210:213], v[80:83]
	v_mfma_f32_16x16x32_bf16 v[76:79], v[156:159], v[210:213], v[76:79]
	v_mfma_f32_16x16x32_bf16 v[72:75], v[142:145], v[218:221], v[72:75]
	v_mfma_f32_16x16x32_bf16 v[68:71], v[156:159], v[218:221], v[68:71]
	v_mfma_f32_16x16x32_bf16 v[96:99], v[146:149], v[184:187], v[96:99]
	v_mfma_f32_16x16x32_bf16 v[92:95], v[160:163], v[184:187], v[92:95]
	v_mfma_f32_16x16x32_bf16 v[88:91], v[146:149], v[192:195], v[88:91]
	v_mfma_f32_16x16x32_bf16 v[84:87], v[160:163], v[192:195], v[84:87]
	v_mfma_f32_16x16x32_bf16 v[80:83], v[146:149], v[214:217], v[80:83]
	v_mfma_f32_16x16x32_bf16 v[76:79], v[160:163], v[214:217], v[76:79]
	v_mfma_f32_16x16x32_bf16 v[72:75], v[146:149], v[222:225], v[72:75]
	v_mfma_f32_16x16x32_bf16 v[68:71], v[160:163], v[222:225], v[68:71]
	v_mfma_f32_16x16x32_bf16 v[32:35], v[164:167], v[180:183], v[32:35]
	v_mfma_f32_16x16x32_bf16 v[28:31], v[172:175], v[180:183], v[28:31]
	v_mfma_f32_16x16x32_bf16 v[24:27], v[164:167], v[188:191], v[24:27]
	v_mfma_f32_16x16x32_bf16 v[20:23], v[172:175], v[188:191], v[20:23]
	v_mfma_f32_16x16x32_bf16 v[16:19], v[164:167], v[210:213], v[16:19]
	v_mfma_f32_16x16x32_bf16 v[12:15], v[172:175], v[210:213], v[12:15]
	v_mfma_f32_16x16x32_bf16 v[8:11], v[164:167], v[218:221], v[8:11]
	v_mfma_f32_16x16x32_bf16 v[4:7], v[172:175], v[218:221], v[4:7]
	v_mfma_f32_16x16x32_bf16 v[32:35], v[168:171], v[184:187], v[32:35]
	v_mfma_f32_16x16x32_bf16 v[28:31], v[176:179], v[184:187], v[28:31]
	v_mfma_f32_16x16x32_bf16 v[24:27], v[168:171], v[192:195], v[24:27]
	v_mfma_f32_16x16x32_bf16 v[20:23], v[176:179], v[192:195], v[20:23]
	v_mfma_f32_16x16x32_bf16 v[16:19], v[168:171], v[214:217], v[16:19]
	v_mfma_f32_16x16x32_bf16 v[12:15], v[176:179], v[214:217], v[12:15]
	v_mfma_f32_16x16x32_bf16 v[8:11], v[168:171], v[222:225], v[8:11]
	v_mfma_f32_16x16x32_bf16 v[4:7], v[176:179], v[222:225], v[4:7]
	s_setprio 0
	s_barrier
	s_add_i32 s66, 0, 0x18000
	v_add_u32_e32 v155, s66, v152
	s_add_i32 s67, 0, 0x1c000
	ds_read_b128 v[142:145], v155
	ds_read_b128 v[146:149], v155 offset:1024
	ds_read_b128 v[156:159], v155 offset:2048
	ds_read_b128 v[160:163], v155 offset:3072
	v_add_u32_e32 v155, s67, v152
	ds_read_b128 v[164:167], v155
	ds_read_b128 v[168:171], v155 offset:1024
	ds_read_b128 v[172:175], v155 offset:2048
	ds_read_b128 v[176:179], v155 offset:3072
	s_add_u32 s46, s46, 0x40000
	s_addc_u32 s47, s47, 0
	s_mov_b32 m0, s54
	v_lshl_add_u64 v[228:229], s[46:47], 0, v[136:137]
	ds_read_b128 v[180:183], v154 offset:32768
	ds_read_b128 v[184:187], v154 offset:33792
	ds_read_b128 v[188:191], v154 offset:34816
	ds_read_b128 v[192:195], v154 offset:35840
	ds_read_b128 v[210:213], v154 offset:36864
	ds_read_b128 v[214:217], v154 offset:37888
	ds_read_b128 v[218:221], v154 offset:38912
	ds_read_b128 v[222:225], v154 offset:39936
	global_load_lds_dwordx4 v[228:229], off
	v_lshl_add_u64 v[228:229], s[46:47], 0, v[132:133]
	s_mov_b32 m0, s55
	s_nop 0
	global_load_lds_dwordx4 v[228:229], off
	s_waitcnt vmcnt(8)
	s_waitcnt lgkmcnt(0)
	s_barrier
	s_setprio 1
	v_mfma_f32_16x16x32_bf16 v[128:131], v[142:145], v[180:183], v[128:131]
	v_mfma_f32_16x16x32_bf16 v[124:127], v[156:159], v[180:183], v[124:127]
	v_mfma_f32_16x16x32_bf16 v[120:123], v[142:145], v[188:191], v[120:123]
	v_mfma_f32_16x16x32_bf16 v[116:119], v[156:159], v[188:191], v[116:119]
	v_mfma_f32_16x16x32_bf16 v[112:115], v[142:145], v[210:213], v[112:115]
	v_mfma_f32_16x16x32_bf16 v[108:111], v[156:159], v[210:213], v[108:111]
	v_mfma_f32_16x16x32_bf16 v[104:107], v[142:145], v[218:221], v[104:107]
	v_mfma_f32_16x16x32_bf16 v[100:103], v[156:159], v[218:221], v[100:103]
	v_mfma_f32_16x16x32_bf16 v[128:131], v[146:149], v[184:187], v[128:131]
	v_mfma_f32_16x16x32_bf16 v[124:127], v[160:163], v[184:187], v[124:127]
	v_mfma_f32_16x16x32_bf16 v[120:123], v[146:149], v[192:195], v[120:123]
	v_mfma_f32_16x16x32_bf16 v[116:119], v[160:163], v[192:195], v[116:119]
	v_mfma_f32_16x16x32_bf16 v[112:115], v[146:149], v[214:217], v[112:115]
	v_mfma_f32_16x16x32_bf16 v[108:111], v[160:163], v[214:217], v[108:111]
	v_mfma_f32_16x16x32_bf16 v[104:107], v[146:149], v[222:225], v[104:107]
	v_mfma_f32_16x16x32_bf16 v[100:103], v[160:163], v[222:225], v[100:103]
	v_mfma_f32_16x16x32_bf16 v[64:67], v[164:167], v[180:183], v[64:67]
	v_mfma_f32_16x16x32_bf16 v[60:63], v[172:175], v[180:183], v[60:63]
	v_mfma_f32_16x16x32_bf16 v[56:59], v[164:167], v[188:191], v[56:59]
	v_mfma_f32_16x16x32_bf16 v[52:55], v[172:175], v[188:191], v[52:55]
	v_mfma_f32_16x16x32_bf16 v[48:51], v[164:167], v[210:213], v[48:51]
	v_mfma_f32_16x16x32_bf16 v[44:47], v[172:175], v[210:213], v[44:47]
	v_mfma_f32_16x16x32_bf16 v[40:43], v[164:167], v[218:221], v[40:43]
	v_mfma_f32_16x16x32_bf16 v[36:39], v[172:175], v[218:221], v[36:39]
	v_mfma_f32_16x16x32_bf16 v[64:67], v[168:171], v[184:187], v[64:67]
	v_mfma_f32_16x16x32_bf16 v[60:63], v[176:179], v[184:187], v[60:63]
	v_mfma_f32_16x16x32_bf16 v[56:59], v[168:171], v[192:195], v[56:59]
	v_mfma_f32_16x16x32_bf16 v[52:55], v[176:179], v[192:195], v[52:55]
	v_mfma_f32_16x16x32_bf16 v[48:51], v[168:171], v[214:217], v[48:51]
	v_mfma_f32_16x16x32_bf16 v[44:47], v[176:179], v[214:217], v[44:47]
	v_mfma_f32_16x16x32_bf16 v[40:43], v[168:171], v[222:225], v[40:43]
	v_mfma_f32_16x16x32_bf16 v[36:39], v[176:179], v[222:225], v[36:39]
	s_setprio 0
	s_barrier
; #define PG8_STAGE(bufoff, gbase, voff) do { _Pragma("unroll") for (int _i = 0; _i < 2; ++_i) \
;         __builtin_amdgcn_global_load_lds((const unsigned*)((const char*)(gbase) + (voff)[_i]), (LAS unsigned*)(lds + (bufoff) + ldsw + _i * 8192), 16, 0, 0); } while (0)
; #define PG8_LDA(dst, b, h) do { _Pragma("unroll") for (int m = 0; m < 4; ++m) _Pragma("unroll") for (int k = 0; k < 2; ++k) dst[m][k] = *(const LAS bf16x8*)(lds + PG8_SA(b, h) + aoff + m * 2048 + k * 1024); } while (0)
; #define PG8_MMA(ai, bj, At, Bt) do { __builtin_amdgcn_s_setprio(1); _Pragma("unroll") for (int m = 0; m < 4; ++m) _Pragma("unroll") for (int n = 0; n < 2; ++n) _Pragma("unroll") for (int k = 0; k < 2; ++k) \
;         acc[ai][bj][m][n] = __builtin_amdgcn_mfma_f32_16x16x32_bf16(Bt[n][k], At[m][k], acc[ai][bj][m][n], 0, 0, 0); __builtin_amdgcn_s_setprio(0); } while (0)
; #define PG8_WAIT_V(n) asm volatile("s_waitcnt vmcnt(" #n ")" ::: "memory")
; #define PG8_WAIT_L(n) asm volatile("s_waitcnt lgkmcnt(" #n ")" ::: "memory")
; #define PG8_BAR __builtin_amdgcn_s_barrier()
; #define PG8_SCHED __builtin_amdgcn_sched_barrier(0)
; template <class Epi>
; __device__ __forceinline__ void gemm_phase(LAS unsigned char* lds, const Gemm g, const StaticOrder& S, const Epi& E) {
;     ...
;             PG8_LDA(At, 1, 1); PG8_STAGE(PG8_SB(1, 0), b3, voffB); PG8_STAGE(PG8_SB(1, 1), b3 + hstepB, voffB); PG8_STAGE(PG8_SA(1, 0), a3, voffA);
;             PG8_WAIT_V(8); PG8_WAIT_L(0); PG8_BAR; PG8_MMA(1, 0, At, B0); PG8_MMA(1, 1, At, B1); PG8_BAR; PG8_SCHED;
;         }
;         if (wr == 0) PG8_BAR;
	s_add_i32 s46, s66, s51
	v_lshl_add_u64 v[150:151], v[150:151], 0, s[30:31]
	s_mov_b32 m0, s46
	ds_read_b128 v[180:183], v154 offset:49152
	ds_read_b128 v[184:187], v154 offset:50176
	ds_read_b128 v[188:191], v154 offset:51200
	ds_read_b128 v[192:195], v154 offset:52224
	ds_read_b128 v[210:213], v154 offset:53248
	ds_read_b128 v[214:217], v154 offset:54272
	ds_read_b128 v[218:221], v154 offset:55296
	ds_read_b128 v[222:225], v154 offset:56320
	global_load_lds_dwordx4 v[150:151], off
	s_add_i32 m0, s46, 0x2000
	s_add_u32 s22, s22, 0x10080
	v_lshl_add_u64 v[150:151], v[196:197], 0, s[30:31]
	s_addc_u32 s23, s23, 0
	s_add_i32 s46, s67, s51
	global_load_lds_dwordx4 v[150:151], off
	v_lshl_add_u64 v[150:151], s[22:23], 0, v[134:135]
	s_mov_b32 m0, s46
	s_nop 0
	global_load_lds_dwordx4 v[150:151], off
	v_lshl_add_u64 v[150:151], s[22:23], 0, v[0:1]
	s_add_i32 m0, s46, 0x2000
	s_nop 0
	global_load_lds_dwordx4 v[150:151], off
	v_lshl_add_u64 v[150:151], v[198:199], 0, s[30:31]
	s_mov_b32 m0, s56
	s_nop 0
	global_load_lds_dwordx4 v[150:151], off
	v_lshl_add_u64 v[150:151], v[226:227], 0, s[30:31]
	s_mov_b32 m0, s57
	s_nop 0
	global_load_lds_dwordx4 v[150:151], off
	s_waitcnt vmcnt(8)
	s_waitcnt lgkmcnt(0)
	s_barrier
	s_setprio 1
	v_mfma_f32_16x16x32_bf16 v[96:99], v[142:145], v[180:183], v[96:99]
	v_mfma_f32_16x16x32_bf16 v[92:95], v[156:159], v[180:183], v[92:95]
	v_mfma_f32_16x16x32_bf16 v[88:91], v[142:145], v[188:191], v[88:91]
	v_mfma_f32_16x16x32_bf16 v[84:87], v[156:159], v[188:191], v[84:87]
	v_mfma_f32_16x16x32_bf16 v[80:83], v[142:145], v[210:213], v[80:83]
	v_mfma_f32_16x16x32_bf16 v[76:79], v[156:159], v[210:213], v[76:79]
	v_mfma_f32_16x16x32_bf16 v[72:75], v[142:145], v[218:221], v[72:75]
	v_mfma_f32_16x16x32_bf16 v[68:71], v[156:159], v[218:221], v[68:71]
	v_mfma_f32_16x16x32_bf16 v[96:99], v[146:149], v[184:187], v[96:99]
	v_mfma_f32_16x16x32_bf16 v[92:95], v[160:163], v[184:187], v[92:95]
	v_mfma_f32_16x16x32_bf16 v[88:91], v[146:149], v[192:195], v[88:91]
	v_mfma_f32_16x16x32_bf16 v[84:87], v[160:163], v[192:195], v[84:87]
	v_mfma_f32_16x16x32_bf16 v[80:83], v[146:149], v[214:217], v[80:83]
	v_mfma_f32_16x16x32_bf16 v[76:79], v[160:163], v[214:217], v[76:79]
	v_mfma_f32_16x16x32_bf16 v[72:75], v[146:149], v[222:225], v[72:75]
	v_mfma_f32_16x16x32_bf16 v[68:71], v[160:163], v[222:225], v[68:71]
	v_mfma_f32_16x16x32_bf16 v[32:35], v[164:167], v[180:183], v[32:35]
	v_mfma_f32_16x16x32_bf16 v[28:31], v[172:175], v[180:183], v[28:31]
	v_mfma_f32_16x16x32_bf16 v[24:27], v[164:167], v[188:191], v[24:27]
	v_mfma_f32_16x16x32_bf16 v[20:23], v[172:175], v[188:191], v[20:23]
	v_mfma_f32_16x16x32_bf16 v[16:19], v[164:167], v[210:213], v[16:19]
	v_mfma_f32_16x16x32_bf16 v[12:15], v[172:175], v[210:213], v[12:15]
	v_mfma_f32_16x16x32_bf16 v[8:11], v[164:167], v[218:221], v[8:11]
	v_mfma_f32_16x16x32_bf16 v[4:7], v[172:175], v[218:221], v[4:7]
	v_mfma_f32_16x16x32_bf16 v[32:35], v[168:171], v[184:187], v[32:35]
	v_mfma_f32_16x16x32_bf16 v[28:31], v[176:179], v[184:187], v[28:31]
	v_mfma_f32_16x16x32_bf16 v[24:27], v[168:171], v[192:195], v[24:27]
	v_mfma_f32_16x16x32_bf16 v[20:23], v[176:179], v[192:195], v[20:23]
	v_mfma_f32_16x16x32_bf16 v[16:19], v[168:171], v[214:217], v[16:19]
	v_mfma_f32_16x16x32_bf16 v[12:15], v[176:179], v[214:217], v[12:15]
	v_mfma_f32_16x16x32_bf16 v[8:11], v[168:171], v[222:225], v[8:11]
	v_mfma_f32_16x16x32_bf16 v[4:7], v[176:179], v[222:225], v[4:7]
	s_setprio 0
	s_barrier
	s_add_i32 s65, s65, 2
	s_add_u32 s44, s44, 0x100
	s_addc_u32 s45, s45, 0
	s_add_u32 s63, s63, 0x100
	s_addc_u32 s64, s64, 0
	s_cmp_gt_u32 s65, 13
	s_cbranch_scc0 .LBB0_551
	v_readlane_b32 s64, v252, 28
	s_and_b64 vcc, exec, s[12:13]
	v_readlane_b32 s65, v252, 29
	s_cbranch_vccz .LBB0_554
	s_barrier

; #define PG8_STAGE(bufoff, gbase, voff) do { _Pragma("unroll") for (int _i = 0; _i < 2; ++_i) \
;         __builtin_amdgcn_global_load_lds((const unsigned*)((const char*)(gbase) + (voff)[_i]), (LAS unsigned*)(lds + (bufoff) + ldsw + _i * 8192), 16, 0, 0); } while (0)
; #define PG8_LDA(dst, b, h) do { _Pragma("unroll") for (int m = 0; m < 4; ++m) _Pragma("unroll") for (int k = 0; k < 2; ++k) dst[m][k] = *(const LAS bf16x8*)(lds + PG8_SA(b, h) + aoff + m * 2048 + k * 1024); } while (0)
; #define PG8_LDB(dst, b, h) do { _Pragma("unroll") for (int n = 0; n < 2; ++n) _Pragma("unroll") for (int k = 0; k < 2; ++k) dst[n][k] = *(const LAS bf16x8*)(lds + PG8_SB(b, h) + boff + n * 2048 + k * 1024); } while (0)
; #define PG8_MMA(ai, bj, At, Bt) do { __builtin_amdgcn_s_setprio(1); _Pragma("unroll") for (int m = 0; m < 4; ++m) _Pragma("unroll") for (int n = 0; n < 2; ++n) _Pragma("unroll") for (int k = 0; k < 2; ++k) \
;         acc[ai][bj][m][n] = __builtin_amdgcn_mfma_f32_16x16x32_bf16(Bt[n][k], At[m][k], acc[ai][bj][m][n], 0, 0, 0); __builtin_amdgcn_s_setprio(0); } while (0)
; #define PG8_WAIT_V(n) asm volatile("s_waitcnt vmcnt(" #n ")" ::: "memory")
; #define PG8_WAIT_L(n) asm volatile("s_waitcnt lgkmcnt(" #n ")" ::: "memory")
; #define PG8_BAR __builtin_amdgcn_s_barrier()
; #define PG8_SCHED __builtin_amdgcn_sched_barrier(0)
; template <class Epi>
; __device__ __forceinline__ void gemm_phase(LAS unsigned char* lds, const Gemm g, const StaticOrder& S, const Epi& E) {
;     ...
;             const bool last = (t == nt - 2);
;             const char* a1 = cA + (size_t)(t + 1) * kstep;
;             const char* a2 = last ? nA : cA + (size_t)(t + 2) * kstep; const char* b2 = last ? nB : cB + (size_t)(t + 2) * kstep;
;             const char* a3 = a2 + kstep; const char* b3 = b2 + kstep;
;             PG8_LDB(B0, 0, 0); PG8_LDB(B1, 0, 1); PG8_SCHED; PG8_LDA(At, 0, 0); PG8_STAGE(PG8_SA(1, 1), a1 + hstepA, voffA);
;             PG8_WAIT_V(8); PG8_WAIT_L(0); PG8_BAR; PG8_MMA(0, 0, At, B0); PG8_MMA(0, 1, At, B1); PG8_BAR; PG8_SCHED;
;             PG8_LDA(At, 0, 1); PG8_STAGE(PG8_SB(0, 0), b2, voffB); PG8_STAGE(PG8_SB(0, 1), b2 + hstepB, voffB); PG8_STAGE(PG8_SA(0, 0), a2, voffA);
;             PG8_WAIT_V(8); PG8_WAIT_L(0); PG8_BAR; PG8_MMA(1, 0, At, B0); PG8_MMA(1, 1, At, B1); PG8_BAR; PG8_SCHED;
.LBB0_660:
	s_add_u32 s38, s34, 0x100
	s_addc_u32 s39, s35, 0
	s_add_i32 s63, 0, 0x10000
	s_cmp_eq_u32 s62, 2
	s_cselect_b32 s41, s5, s39
	s_cselect_b32 s40, s4, s38
	s_cselect_b32 s23, s15, s61
	s_cselect_b32 s22, s14, s60
	s_add_i32 s64, 0, 0x14000
	v_add_u32_e32 v158, s63, v170
	v_add_u32_e32 v173, s64, v170
	ds_read_b128 v[146:149], v158
	ds_read_b128 v[150:153], v158 offset:1024
	ds_read_b128 v[154:157], v158 offset:2048
	ds_read_b128 v[158:161], v158 offset:3072
	ds_read_b128 v[162:165], v173
	ds_read_b128 v[166:169], v173 offset:1024
	ds_read_b128 v[174:177], v173 offset:2048
	ds_read_b128 v[178:181], v173 offset:3072
	v_lshl_add_u64 v[194:195], s[34:35], 0, v[142:143]
	s_add_i32 m0, s51, 0xc000
	ds_read_b128 v[182:185], v172
	ds_read_b128 v[186:189], v172 offset:1024
	ds_read_b128 v[190:193], v172 offset:2048
	ds_read_b128 v[210:213], v172 offset:3072
	ds_read_b128 v[214:217], v172 offset:4096
	ds_read_b128 v[218:221], v172 offset:5120
	ds_read_b128 v[222:225], v172 offset:6144
	ds_read_b128 v[226:229], v172 offset:7168
	global_load_lds_dwordx4 v[194:195], off
	v_lshl_add_u64 v[194:195], s[34:35], 0, v[144:145]
	s_add_i32 m0, s51, 0xe000
	s_nop 0
	global_load_lds_dwordx4 v[194:195], off
	s_waitcnt vmcnt(8)
	s_waitcnt lgkmcnt(0)
	s_barrier
	s_setprio 1
	v_mfma_f32_16x16x32_bf16 v[128:131], v[146:149], v[182:185], v[128:131]
	v_mfma_f32_16x16x32_bf16 v[124:127], v[154:157], v[182:185], v[124:127]
	v_mfma_f32_16x16x32_bf16 v[112:115], v[146:149], v[190:193], v[112:115]
	v_mfma_f32_16x16x32_bf16 v[108:111], v[154:157], v[190:193], v[108:111]
	v_mfma_f32_16x16x32_bf16 v[96:99], v[146:149], v[214:217], v[96:99]
	v_mfma_f32_16x16x32_bf16 v[92:95], v[154:157], v[214:217], v[92:95]
	v_mfma_f32_16x16x32_bf16 v[80:83], v[146:149], v[222:225], v[80:83]
	v_mfma_f32_16x16x32_bf16 v[76:79], v[154:157], v[222:225], v[76:79]
	v_mfma_f32_16x16x32_bf16 v[128:131], v[150:153], v[186:189], v[128:131]
	v_mfma_f32_16x16x32_bf16 v[124:127], v[158:161], v[186:189], v[124:127]
	v_mfma_f32_16x16x32_bf16 v[112:115], v[150:153], v[210:213], v[112:115]
	v_mfma_f32_16x16x32_bf16 v[108:111], v[158:161], v[210:213], v[108:111]
	v_mfma_f32_16x16x32_bf16 v[96:99], v[150:153], v[218:221], v[96:99]
	v_mfma_f32_16x16x32_bf16 v[92:95], v[158:161], v[218:221], v[92:95]
	v_mfma_f32_16x16x32_bf16 v[80:83], v[150:153], v[226:229], v[80:83]
	v_mfma_f32_16x16x32_bf16 v[76:79], v[158:161], v[226:229], v[76:79]
	v_mfma_f32_16x16x32_bf16 v[120:123], v[162:165], v[182:185], v[120:123]
	v_mfma_f32_16x16x32_bf16 v[116:119], v[174:177], v[182:185], v[116:119]
	v_mfma_f32_16x16x32_bf16 v[104:107], v[162:165], v[190:193], v[104:107]
	v_mfma_f32_16x16x32_bf16 v[100:103], v[174:177], v[190:193], v[100:103]
	v_mfma_f32_16x16x32_bf16 v[88:91], v[162:165], v[214:217], v[88:91]
	v_mfma_f32_16x16x32_bf16 v[84:87], v[174:177], v[214:217], v[84:87]
	v_mfma_f32_16x16x32_bf16 v[72:75], v[162:165], v[222:225], v[72:75]
	v_mfma_f32_16x16x32_bf16 v[68:71], v[174:177], v[222:225], v[68:71]
	v_mfma_f32_16x16x32_bf16 v[120:123], v[166:169], v[186:189], v[120:123]
	v_mfma_f32_16x16x32_bf16 v[116:119], v[178:181], v[186:189], v[116:119]
	v_mfma_f32_16x16x32_bf16 v[104:107], v[166:169], v[210:213], v[104:107]
	v_mfma_f32_16x16x32_bf16 v[100:103], v[178:181], v[210:213], v[100:103]
	v_mfma_f32_16x16x32_bf16 v[88:91], v[166:169], v[218:221], v[88:91]
	v_mfma_f32_16x16x32_bf16 v[84:87], v[178:181], v[218:221], v[84:87]
	v_mfma_f32_16x16x32_bf16 v[72:75], v[166:169], v[226:229], v[72:75]
	v_mfma_f32_16x16x32_bf16 v[68:71], v[178:181], v[226:229], v[68:71]
	s_setprio 0
	s_barrier
	s_add_i32 s34, s63, s50
	v_lshl_add_u64 v[194:195], s[22:23], 0, v[134:135]
	s_mov_b32 m0, s34
	ds_read_b128 v[182:185], v172 offset:16384
	ds_read_b128 v[186:189], v172 offset:17408
	ds_read_b128 v[190:193], v172 offset:18432
	ds_read_b128 v[210:213], v172 offset:19456
	ds_read_b128 v[214:217], v172 offset:20480
	ds_read_b128 v[218:221], v172 offset:21504
	ds_read_b128 v[222:225], v172 offset:22528
	ds_read_b128 v[226:229], v172 offset:23552
	global_load_lds_dwordx4 v[194:195], off
	s_add_i32 m0, s34, 0x2000
	s_add_u32 s34, s22, 0x6000
	v_lshl_add_u64 v[196:197], s[22:23], 0, v[0:1]
	s_addc_u32 s35, s23, 0
	s_add_i32 s63, s64, s50
	global_load_lds_dwordx4 v[196:197], off
	v_lshl_add_u64 v[198:199], s[34:35], 0, v[134:135]
	s_mov_b32 m0, s63
	v_lshl_add_u64 v[230:231], s[40:41], 0, v[132:133]
	global_load_lds_dwordx4 v[198:199], off
	v_lshl_add_u64 v[198:199], s[34:35], 0, v[0:1]
	s_add_i32 m0, s63, 0x2000
	s_nop 0
	global_load_lds_dwordx4 v[198:199], off
	v_lshl_add_u64 v[198:199], s[40:41], 0, v[136:137]
	s_mov_b32 m0, s51
	s_nop 0
	global_load_lds_dwordx4 v[198:199], off
	s_mov_b32 m0, s52
	s_nop 0
	global_load_lds_dwordx4 v[230:231], off
	s_waitcnt vmcnt(8)
	s_waitcnt lgkmcnt(0)
	s_barrier
; #define PG8_STAGE(bufoff, gbase, voff) do { _Pragma("unroll") for (int _i = 0; _i < 2; ++_i) \
;         __builtin_amdgcn_global_load_lds((const unsigned*)((const char*)(gbase) + (voff)[_i]), (LAS unsigned*)(lds + (bufoff) + ldsw + _i * 8192), 16, 0, 0); } while (0)
; #define PG8_LDA(dst, b, h) do { _Pragma("unroll") for (int m = 0; m < 4; ++m) _Pragma("unroll") for (int k = 0; k < 2; ++k) dst[m][k] = *(const LAS bf16x8*)(lds + PG8_SA(b, h) + aoff + m * 2048 + k * 1024); } while (0)
; #define PG8_LDB(dst, b, h) do { _Pragma("unroll") for (int n = 0; n < 2; ++n) _Pragma("unroll") for (int k = 0; k < 2; ++k) dst[n][k] = *(const LAS bf16x8*)(lds + PG8_SB(b, h) + boff + n * 2048 + k * 1024); } while (0)
; #define PG8_MMA(ai, bj, At, Bt) do { __builtin_amdgcn_s_setprio(1); _Pragma("unroll") for (int m = 0; m < 4; ++m) _Pragma("unroll") for (int n = 0; n < 2; ++n) _Pragma("unroll") for (int k = 0; k < 2; ++k) \
;         acc[ai][bj][m][n] = __builtin_amdgcn_mfma_f32_16x16x32_bf16(Bt[n][k], At[m][k], acc[ai][bj][m][n], 0, 0, 0); __builtin_amdgcn_s_setprio(0); } while (0)
; #define PG8_WAIT_V(n) asm volatile("s_waitcnt vmcnt(" #n ")" ::: "memory")
; #define PG8_WAIT_L(n) asm volatile("s_waitcnt lgkmcnt(" #n ")" ::: "memory")
; #define PG8_BAR __builtin_amdgcn_s_barrier()
; #define PG8_SCHED __builtin_amdgcn_sched_barrier(0)
; template <class Epi>
; __device__ __forceinline__ void gemm_phase(LAS unsigned char* lds, const Gemm g, const StaticOrder& S, const Epi& E) {
;     ...
;             PG8_WAIT_V(8); PG8_WAIT_L(0); PG8_BAR; PG8_MMA(1, 0, At, B0); PG8_MMA(1, 1, At, B1); PG8_BAR; PG8_SCHED;
;             PG8_LDB(B0, 1, 0); PG8_LDB(B1, 1, 1); PG8_SCHED; PG8_LDA(At, 1, 0); PG8_STAGE(PG8_SA(0, 1), a2 + hstepA, voffA);
;             PG8_WAIT_V(8); PG8_WAIT_L(0); PG8_BAR; PG8_MMA(0, 0, At, B0); PG8_MMA(0, 1, At, B1); PG8_BAR; PG8_SCHED;
	s_setprio 1
	v_mfma_f32_16x16x32_bf16 v[64:67], v[146:149], v[182:185], v[64:67]
	v_mfma_f32_16x16x32_bf16 v[60:63], v[154:157], v[182:185], v[60:63]
	v_mfma_f32_16x16x32_bf16 v[48:51], v[146:149], v[190:193], v[48:51]
	v_mfma_f32_16x16x32_bf16 v[44:47], v[154:157], v[190:193], v[44:47]
	v_mfma_f32_16x16x32_bf16 v[32:35], v[146:149], v[214:217], v[32:35]
	v_mfma_f32_16x16x32_bf16 v[28:31], v[154:157], v[214:217], v[28:31]
	v_mfma_f32_16x16x32_bf16 v[16:19], v[146:149], v[222:225], v[16:19]
	v_mfma_f32_16x16x32_bf16 v[12:15], v[154:157], v[222:225], v[12:15]
	v_mfma_f32_16x16x32_bf16 v[64:67], v[150:153], v[186:189], v[64:67]
	v_mfma_f32_16x16x32_bf16 v[60:63], v[158:161], v[186:189], v[60:63]
	v_mfma_f32_16x16x32_bf16 v[48:51], v[150:153], v[210:213], v[48:51]
	v_mfma_f32_16x16x32_bf16 v[44:47], v[158:161], v[210:213], v[44:47]
	v_mfma_f32_16x16x32_bf16 v[32:35], v[150:153], v[218:221], v[32:35]
	v_mfma_f32_16x16x32_bf16 v[28:31], v[158:161], v[218:221], v[28:31]
	v_mfma_f32_16x16x32_bf16 v[16:19], v[150:153], v[226:229], v[16:19]
	v_mfma_f32_16x16x32_bf16 v[12:15], v[158:161], v[226:229], v[12:15]
	v_mfma_f32_16x16x32_bf16 v[56:59], v[162:165], v[182:185], v[56:59]
	v_mfma_f32_16x16x32_bf16 v[52:55], v[174:177], v[182:185], v[52:55]
	v_mfma_f32_16x16x32_bf16 v[40:43], v[162:165], v[190:193], v[40:43]
	v_mfma_f32_16x16x32_bf16 v[36:39], v[174:177], v[190:193], v[36:39]
	v_mfma_f32_16x16x32_bf16 v[24:27], v[162:165], v[214:217], v[24:27]
	v_mfma_f32_16x16x32_bf16 v[20:23], v[174:177], v[214:217], v[20:23]
	v_mfma_f32_16x16x32_bf16 v[8:11], v[162:165], v[222:225], v[8:11]
	v_mfma_f32_16x16x32_bf16 v[4:7], v[174:177], v[222:225], v[4:7]
	v_mfma_f32_16x16x32_bf16 v[56:59], v[166:169], v[186:189], v[56:59]
	v_mfma_f32_16x16x32_bf16 v[52:55], v[178:181], v[186:189], v[52:55]
	v_mfma_f32_16x16x32_bf16 v[40:43], v[166:169], v[210:213], v[40:43]
	v_mfma_f32_16x16x32_bf16 v[36:39], v[178:181], v[210:213], v[36:39]
	v_mfma_f32_16x16x32_bf16 v[24:27], v[166:169], v[218:221], v[24:27]
	v_mfma_f32_16x16x32_bf16 v[20:23], v[178:181], v[218:221], v[20:23]
	v_mfma_f32_16x16x32_bf16 v[8:11], v[166:169], v[226:229], v[8:11]
	v_mfma_f32_16x16x32_bf16 v[4:7], v[178:181], v[226:229], v[4:7]
	s_setprio 0
	s_barrier
	s_add_i32 s63, 0, 0x18000
	s_add_i32 s64, 0, 0x1c000
	v_add_u32_e32 v158, s63, v170
	v_add_u32_e32 v173, s64, v170
	ds_read_b128 v[146:149], v158
	ds_read_b128 v[150:153], v158 offset:1024
	ds_read_b128 v[154:157], v158 offset:2048
	ds_read_b128 v[158:161], v158 offset:3072
	ds_read_b128 v[162:165], v173
	ds_read_b128 v[166:169], v173 offset:1024
	ds_read_b128 v[174:177], v173 offset:2048
	ds_read_b128 v[178:181], v173 offset:3072
	s_add_u32 s34, s40, 0xea000
	s_addc_u32 s35, s41, 0
	s_mov_b32 m0, s53
	v_lshl_add_u64 v[232:233], s[34:35], 0, v[136:137]
	ds_read_b128 v[182:185], v172 offset:32768
	ds_read_b128 v[186:189], v172 offset:33792
	ds_read_b128 v[190:193], v172 offset:34816
	ds_read_b128 v[210:213], v172 offset:35840
	ds_read_b128 v[214:217], v172 offset:36864
	ds_read_b128 v[218:221], v172 offset:37888
	ds_read_b128 v[222:225], v172 offset:38912
	ds_read_b128 v[226:229], v172 offset:39936
	global_load_lds_dwordx4 v[232:233], off
	v_lshl_add_u64 v[232:233], s[34:35], 0, v[132:133]
	s_mov_b32 m0, s54
	s_nop 0
	global_load_lds_dwordx4 v[232:233], off
	s_waitcnt vmcnt(8)
	s_waitcnt lgkmcnt(0)
	s_barrier
	s_setprio 1
	v_mfma_f32_16x16x32_bf16 v[128:131], v[146:149], v[182:185], v[128:131]
	v_mfma_f32_16x16x32_bf16 v[124:127], v[154:157], v[182:185], v[124:127]
	v_mfma_f32_16x16x32_bf16 v[112:115], v[146:149], v[190:193], v[112:115]
	v_mfma_f32_16x16x32_bf16 v[108:111], v[154:157], v[190:193], v[108:111]
	v_mfma_f32_16x16x32_bf16 v[96:99], v[146:149], v[214:217], v[96:99]
	v_mfma_f32_16x16x32_bf16 v[92:95], v[154:157], v[214:217], v[92:95]
	v_mfma_f32_16x16x32_bf16 v[80:83], v[146:149], v[222:225], v[80:83]
	v_mfma_f32_16x16x32_bf16 v[76:79], v[154:157], v[222:225], v[76:79]
	v_mfma_f32_16x16x32_bf16 v[128:131], v[150:153], v[186:189], v[128:131]
	v_mfma_f32_16x16x32_bf16 v[124:127], v[158:161], v[186:189], v[124:127]
	v_mfma_f32_16x16x32_bf16 v[112:115], v[150:153], v[210:213], v[112:115]
	v_mfma_f32_16x16x32_bf16 v[108:111], v[158:161], v[210:213], v[108:111]
	v_mfma_f32_16x16x32_bf16 v[96:99], v[150:153], v[218:221], v[96:99]
	v_mfma_f32_16x16x32_bf16 v[92:95], v[158:161], v[218:221], v[92:95]
	v_mfma_f32_16x16x32_bf16 v[80:83], v[150:153], v[226:229], v[80:83]
	v_mfma_f32_16x16x32_bf16 v[76:79], v[158:161], v[226:229], v[76:79]
	v_mfma_f32_16x16x32_bf16 v[120:123], v[162:165], v[182:185], v[120:123]
	v_mfma_f32_16x16x32_bf16 v[116:119], v[174:177], v[182:185], v[116:119]
	v_mfma_f32_16x16x32_bf16 v[104:107], v[162:165], v[190:193], v[104:107]
	v_mfma_f32_16x16x32_bf16 v[100:103], v[174:177], v[190:193], v[100:103]
	v_mfma_f32_16x16x32_bf16 v[88:91], v[162:165], v[214:217], v[88:91]
	v_mfma_f32_16x16x32_bf16 v[84:87], v[174:177], v[214:217], v[84:87]
	v_mfma_f32_16x16x32_bf16 v[72:75], v[162:165], v[222:225], v[72:75]
	v_mfma_f32_16x16x32_bf16 v[68:71], v[174:177], v[222:225], v[68:71]
	v_mfma_f32_16x16x32_bf16 v[120:123], v[166:169], v[186:189], v[120:123]
	v_mfma_f32_16x16x32_bf16 v[116:119], v[178:181], v[186:189], v[116:119]
	v_mfma_f32_16x16x32_bf16 v[104:107], v[166:169], v[210:213], v[104:107]
	v_mfma_f32_16x16x32_bf16 v[100:103], v[178:181], v[210:213], v[100:103]
	v_mfma_f32_16x16x32_bf16 v[88:91], v[166:169], v[218:221], v[88:91]
	v_mfma_f32_16x16x32_bf16 v[84:87], v[178:181], v[218:221], v[84:87]
	v_mfma_f32_16x16x32_bf16 v[72:75], v[166:169], v[226:229], v[72:75]
	v_mfma_f32_16x16x32_bf16 v[68:71], v[178:181], v[226:229], v[68:71]
	s_setprio 0
	s_barrier
; #define PG8_STAGE(bufoff, gbase, voff) do { _Pragma("unroll") for (int _i = 0; _i < 2; ++_i) \
;         __builtin_amdgcn_global_load_lds((const unsigned*)((const char*)(gbase) + (voff)[_i]), (LAS unsigned*)(lds + (bufoff) + ldsw + _i * 8192), 16, 0, 0); } while (0)
; #define PG8_LDA(dst, b, h) do { _Pragma("unroll") for (int m = 0; m < 4; ++m) _Pragma("unroll") for (int k = 0; k < 2; ++k) dst[m][k] = *(const LAS bf16x8*)(lds + PG8_SA(b, h) + aoff + m * 2048 + k * 1024); } while (0)
; #define PG8_MMA(ai, bj, At, Bt) do { __builtin_amdgcn_s_setprio(1); _Pragma("unroll") for (int m = 0; m < 4; ++m) _Pragma("unroll") for (int n = 0; n < 2; ++n) _Pragma("unroll") for (int k = 0; k < 2; ++k) \
;         acc[ai][bj][m][n] = __builtin_amdgcn_mfma_f32_16x16x32_bf16(Bt[n][k], At[m][k], acc[ai][bj][m][n], 0, 0, 0); __builtin_amdgcn_s_setprio(0); } while (0)
; #define PG8_WAIT_V(n) asm volatile("s_waitcnt vmcnt(" #n ")" ::: "memory")
; #define PG8_WAIT_L(n) asm volatile("s_waitcnt lgkmcnt(" #n ")" ::: "memory")
; #define PG8_BAR __builtin_amdgcn_s_barrier()
; #define PG8_SCHED __builtin_amdgcn_sched_barrier(0)
; template <class Epi>
; __device__ __forceinline__ void gemm_phase(LAS unsigned char* lds, const Gemm g, const StaticOrder& S, const Epi& E) {
;     ...
;             PG8_LDA(At, 1, 1); PG8_STAGE(PG8_SB(1, 0), b3, voffB); PG8_STAGE(PG8_SB(1, 1), b3 + hstepB, voffB); PG8_STAGE(PG8_SA(1, 0), a3, voffA);
;             PG8_WAIT_V(8); PG8_WAIT_L(0); PG8_BAR; PG8_MMA(1, 0, At, B0); PG8_MMA(1, 1, At, B1); PG8_BAR; PG8_SCHED;
;         }
;         if (wr == 0) PG8_BAR;
	s_add_i32 s34, s63, s50
	v_lshl_add_u64 v[194:195], v[194:195], 0, s[30:31]
	s_mov_b32 m0, s34
	ds_read_b128 v[182:185], v172 offset:49152
	ds_read_b128 v[186:189], v172 offset:50176
	ds_read_b128 v[190:193], v172 offset:51200
	ds_read_b128 v[210:213], v172 offset:52224
	ds_read_b128 v[214:217], v172 offset:53248
	ds_read_b128 v[218:221], v172 offset:54272
	ds_read_b128 v[222:225], v172 offset:55296
	ds_read_b128 v[226:229], v172 offset:56320
	global_load_lds_dwordx4 v[194:195], off
	s_add_i32 m0, s34, 0x2000
	s_add_u32 s22, s22, 0x6080
	v_lshl_add_u64 v[194:195], v[196:197], 0, s[30:31]
	s_addc_u32 s23, s23, 0
	s_add_i32 s34, s64, s50
	global_load_lds_dwordx4 v[194:195], off
	v_lshl_add_u64 v[194:195], s[22:23], 0, v[134:135]
	s_mov_b32 m0, s34
	s_nop 0
	global_load_lds_dwordx4 v[194:195], off
	v_lshl_add_u64 v[194:195], s[22:23], 0, v[0:1]
	s_add_i32 m0, s34, 0x2000
	s_nop 0
	global_load_lds_dwordx4 v[194:195], off
	v_lshl_add_u64 v[194:195], v[198:199], 0, s[30:31]
	s_mov_b32 m0, s55
	s_nop 0
	global_load_lds_dwordx4 v[194:195], off
	v_lshl_add_u64 v[194:195], v[230:231], 0, s[30:31]
	s_mov_b32 m0, s56
	s_nop 0
	global_load_lds_dwordx4 v[194:195], off
	s_waitcnt vmcnt(8)
	s_waitcnt lgkmcnt(0)
	s_barrier
	s_setprio 1
	v_mfma_f32_16x16x32_bf16 v[64:67], v[146:149], v[182:185], v[64:67]
	v_mfma_f32_16x16x32_bf16 v[60:63], v[154:157], v[182:185], v[60:63]
	v_mfma_f32_16x16x32_bf16 v[48:51], v[146:149], v[190:193], v[48:51]
	v_mfma_f32_16x16x32_bf16 v[44:47], v[154:157], v[190:193], v[44:47]
	v_mfma_f32_16x16x32_bf16 v[32:35], v[146:149], v[214:217], v[32:35]
	v_mfma_f32_16x16x32_bf16 v[28:31], v[154:157], v[214:217], v[28:31]
	v_mfma_f32_16x16x32_bf16 v[16:19], v[146:149], v[222:225], v[16:19]
	v_mfma_f32_16x16x32_bf16 v[12:15], v[154:157], v[222:225], v[12:15]
	v_mfma_f32_16x16x32_bf16 v[64:67], v[150:153], v[186:189], v[64:67]
	v_mfma_f32_16x16x32_bf16 v[60:63], v[158:161], v[186:189], v[60:63]
	v_mfma_f32_16x16x32_bf16 v[48:51], v[150:153], v[210:213], v[48:51]
	v_mfma_f32_16x16x32_bf16 v[44:47], v[158:161], v[210:213], v[44:47]
	v_mfma_f32_16x16x32_bf16 v[32:35], v[150:153], v[218:221], v[32:35]
	v_mfma_f32_16x16x32_bf16 v[28:31], v[158:161], v[218:221], v[28:31]
	v_mfma_f32_16x16x32_bf16 v[16:19], v[150:153], v[226:229], v[16:19]
	v_mfma_f32_16x16x32_bf16 v[12:15], v[158:161], v[226:229], v[12:15]
	v_mfma_f32_16x16x32_bf16 v[56:59], v[162:165], v[182:185], v[56:59]
	v_mfma_f32_16x16x32_bf16 v[52:55], v[174:177], v[182:185], v[52:55]
	v_mfma_f32_16x16x32_bf16 v[40:43], v[162:165], v[190:193], v[40:43]
	v_mfma_f32_16x16x32_bf16 v[36:39], v[174:177], v[190:193], v[36:39]
	v_mfma_f32_16x16x32_bf16 v[24:27], v[162:165], v[214:217], v[24:27]
	v_mfma_f32_16x16x32_bf16 v[20:23], v[174:177], v[214:217], v[20:23]
	v_mfma_f32_16x16x32_bf16 v[8:11], v[162:165], v[222:225], v[8:11]
	v_mfma_f32_16x16x32_bf16 v[4:7], v[174:177], v[222:225], v[4:7]
	v_mfma_f32_16x16x32_bf16 v[56:59], v[166:169], v[186:189], v[56:59]
	v_mfma_f32_16x16x32_bf16 v[52:55], v[178:181], v[186:189], v[52:55]
	v_mfma_f32_16x16x32_bf16 v[40:43], v[166:169], v[210:213], v[40:43]
	v_mfma_f32_16x16x32_bf16 v[36:39], v[178:181], v[210:213], v[36:39]
	v_mfma_f32_16x16x32_bf16 v[24:27], v[166:169], v[218:221], v[24:27]
	v_mfma_f32_16x16x32_bf16 v[20:23], v[178:181], v[218:221], v[20:23]
	v_mfma_f32_16x16x32_bf16 v[8:11], v[166:169], v[226:229], v[8:11]
	v_mfma_f32_16x16x32_bf16 v[4:7], v[178:181], v[226:229], v[4:7]
	s_setprio 0
	s_barrier
	s_add_i32 s62, s62, 2
	s_add_u32 s60, s60, 0x100
	s_addc_u32 s61, s61, 0
	s_cmp_gt_u32 s62, 3
	s_mov_b64 s[34:35], s[38:39]
	s_cbranch_scc0 .LBB0_660
	s_and_b64 vcc, exec, s[12:13]
	s_cbranch_vccz .LBB0_663
	s_barrier

; #define PG8_STAGE(bufoff, gbase, voff) do { _Pragma("unroll") for (int _i = 0; _i < 2; ++_i) \
;         __builtin_amdgcn_global_load_lds((const unsigned*)((const char*)(gbase) + (voff)[_i]), (LAS unsigned*)(lds + (bufoff) + ldsw + _i * 8192), 16, 0, 0); } while (0)
; #define PG8_LDA(dst, b, h) do { _Pragma("unroll") for (int m = 0; m < 4; ++m) _Pragma("unroll") for (int k = 0; k < 2; ++k) dst[m][k] = *(const LAS bf16x8*)(lds + PG8_SA(b, h) + aoff + m * 2048 + k * 1024); } while (0)
; #define PG8_LDB(dst, b, h) do { _Pragma("unroll") for (int n = 0; n < 2; ++n) _Pragma("unroll") for (int k = 0; k < 2; ++k) dst[n][k] = *(const LAS bf16x8*)(lds + PG8_SB(b, h) + boff + n * 2048 + k * 1024); } while (0)
; #define PG8_MMA(ai, bj, At, Bt) do { __builtin_amdgcn_s_setprio(1); _Pragma("unroll") for (int m = 0; m < 4; ++m) _Pragma("unroll") for (int n = 0; n < 2; ++n) _Pragma("unroll") for (int k = 0; k < 2; ++k) \
;         acc[ai][bj][m][n] = __builtin_amdgcn_mfma_f32_16x16x32_bf16(Bt[n][k], At[m][k], acc[ai][bj][m][n], 0, 0, 0); __builtin_amdgcn_s_setprio(0); } while (0)
; #define PG8_WAIT_V(n) asm volatile("s_waitcnt vmcnt(" #n ")" ::: "memory")
; #define PG8_WAIT_L(n) asm volatile("s_waitcnt lgkmcnt(" #n ")" ::: "memory")
; #define PG8_BAR __builtin_amdgcn_s_barrier()
; #define PG8_SCHED __builtin_amdgcn_sched_barrier(0)
; template <class Epi>
; __device__ __forceinline__ void gemm_phase(LAS unsigned char* lds, const Gemm g, const StaticOrder& S, const Epi& E) {
;     ...
;             const bool last = (t == nt - 2);
;             const char* a1 = cA + (size_t)(t + 1) * kstep;
;             const char* a2 = last ? nA : cA + (size_t)(t + 2) * kstep; const char* b2 = last ? nB : cB + (size_t)(t + 2) * kstep;
;             const char* a3 = a2 + kstep; const char* b3 = b2 + kstep;
;             PG8_LDB(B0, 0, 0); PG8_LDB(B1, 0, 1); PG8_SCHED; PG8_LDA(At, 0, 0); PG8_STAGE(PG8_SA(1, 1), a1 + hstepA, voffA);
;             PG8_WAIT_V(8); PG8_WAIT_L(0); PG8_BAR; PG8_MMA(0, 0, At, B0); PG8_MMA(0, 1, At, B1); PG8_BAR; PG8_SCHED;
;             PG8_LDA(At, 0, 1); PG8_STAGE(PG8_SB(0, 0), b2, voffB); PG8_STAGE(PG8_SB(0, 1), b2 + hstepB, voffB); PG8_STAGE(PG8_SA(0, 0), a2, voffA);
;             PG8_WAIT_V(8); PG8_WAIT_L(0); PG8_BAR; PG8_MMA(1, 0, At, B0); PG8_MMA(1, 1, At, B1); PG8_BAR; PG8_SCHED;
.LBB0_710:
	s_add_u32 s52, s42, s22
	s_addc_u32 s53, s43, 0
	s_add_u32 s23, s52, 0x100
	s_addc_u32 s50, s53, 0
	s_and_b64 s[48:49], s[46:47], exec
	s_cselect_b32 s49, s35, s50
	s_cselect_b32 s48, s34, s23
	s_add_u32 s22, s40, s22
	s_addc_u32 s23, s41, 0
	s_add_u32 s50, s22, 0x100
	s_addc_u32 s51, s23, 0
	s_add_i32 s80, 0, 0x10000
	s_and_b64 s[22:23], s[46:47], exec
	s_cselect_b32 s51, s15, s51
	s_cselect_b32 s50, s71, s50
	s_add_i32 s47, 0, 0x14000
	s_add_u32 s54, s52, 0xea080
	s_addc_u32 s55, s53, 0
	s_add_i32 s79, s80, s60
	s_add_i32 m0, s61, 0xc000
	s_add_i32 s82, s61, 0xe000
	s_add_i32 s76, s79, 0x2000
	v_add_u32_e32 v146, s80, v148
	s_add_u32 s52, s50, 0x4000
	ds_read_b128 v[138:141], v146
	ds_read_b128 v[142:145], v146 offset:1024
	ds_read_b128 v[152:155], v146 offset:2048
	ds_read_b128 v[156:159], v146 offset:3072
	v_add_u32_e32 v146, s47, v148
	s_addc_u32 s53, s51, 0
	s_add_i32 s78, s47, s60
	ds_read_b128 v[160:163], v146
	ds_read_b128 v[164:167], v146 offset:1024
	ds_read_b128 v[168:171], v146 offset:2048
	ds_read_b128 v[172:175], v146 offset:3072
	s_add_i32 s77, s78, 0x2000
	s_add_i32 s75, 0, 0x18000
	s_add_i32 s74, 0, 0x1c000
	s_add_u32 s22, s48, 0xea000
	s_addc_u32 s23, s49, 0
	s_add_i32 s73, s75, s60
	s_add_i32 s72, s73, 0x2000
	s_add_u32 s46, s50, 0x4080
	s_addc_u32 s47, s51, 0
	s_add_i32 s81, s74, s60
	s_add_i32 s80, s81, 0x2000
	v_lshl_add_u64 v[146:147], s[54:55], 0, v[136:137]
	ds_read_b128 v[176:179], v150
	ds_read_b128 v[180:183], v150 offset:1024
	ds_read_b128 v[184:187], v150 offset:2048
	ds_read_b128 v[188:191], v150 offset:3072
	ds_read_b128 v[192:195], v150 offset:4096
	ds_read_b128 v[210:213], v150 offset:5120
	ds_read_b128 v[214:217], v150 offset:6144
	ds_read_b128 v[218:221], v150 offset:7168
	global_load_lds_dwordx4 v[146:147], off
	v_lshl_add_u64 v[146:147], s[54:55], 0, v[132:133]
	s_mov_b32 m0, s82
	s_nop 0
	global_load_lds_dwordx4 v[146:147], off
	s_waitcnt vmcnt(8)
	s_waitcnt lgkmcnt(0)
	s_barrier
	s_setprio 1
	v_mfma_f32_16x16x32_bf16 v[128:131], v[138:141], v[176:179], v[128:131]
	v_mfma_f32_16x16x32_bf16 v[124:127], v[152:155], v[176:179], v[124:127]
	v_mfma_f32_16x16x32_bf16 v[112:115], v[138:141], v[184:187], v[112:115]
	v_mfma_f32_16x16x32_bf16 v[108:111], v[152:155], v[184:187], v[108:111]
	v_mfma_f32_16x16x32_bf16 v[96:99], v[138:141], v[192:195], v[96:99]
	v_mfma_f32_16x16x32_bf16 v[92:95], v[152:155], v[192:195], v[92:95]
	v_mfma_f32_16x16x32_bf16 v[80:83], v[138:141], v[214:217], v[80:83]
	v_mfma_f32_16x16x32_bf16 v[76:79], v[152:155], v[214:217], v[76:79]
	v_mfma_f32_16x16x32_bf16 v[128:131], v[142:145], v[180:183], v[128:131]
	v_mfma_f32_16x16x32_bf16 v[124:127], v[156:159], v[180:183], v[124:127]
	v_mfma_f32_16x16x32_bf16 v[112:115], v[142:145], v[188:191], v[112:115]
	v_mfma_f32_16x16x32_bf16 v[108:111], v[156:159], v[188:191], v[108:111]
	v_mfma_f32_16x16x32_bf16 v[96:99], v[142:145], v[210:213], v[96:99]
	v_mfma_f32_16x16x32_bf16 v[92:95], v[156:159], v[210:213], v[92:95]
	v_mfma_f32_16x16x32_bf16 v[80:83], v[142:145], v[218:221], v[80:83]
	v_mfma_f32_16x16x32_bf16 v[76:79], v[156:159], v[218:221], v[76:79]
	v_mfma_f32_16x16x32_bf16 v[120:123], v[160:163], v[176:179], v[120:123]
	v_mfma_f32_16x16x32_bf16 v[116:119], v[168:171], v[176:179], v[116:119]
	v_mfma_f32_16x16x32_bf16 v[104:107], v[160:163], v[184:187], v[104:107]
	v_mfma_f32_16x16x32_bf16 v[100:103], v[168:171], v[184:187], v[100:103]
	v_mfma_f32_16x16x32_bf16 v[88:91], v[160:163], v[192:195], v[88:91]
	v_mfma_f32_16x16x32_bf16 v[84:87], v[168:171], v[192:195], v[84:87]
	v_mfma_f32_16x16x32_bf16 v[72:75], v[160:163], v[214:217], v[72:75]
	v_mfma_f32_16x16x32_bf16 v[68:71], v[168:171], v[214:217], v[68:71]
	v_mfma_f32_16x16x32_bf16 v[120:123], v[164:167], v[180:183], v[120:123]
	v_mfma_f32_16x16x32_bf16 v[116:119], v[172:175], v[180:183], v[116:119]
	v_mfma_f32_16x16x32_bf16 v[104:107], v[164:167], v[188:191], v[104:107]
	v_mfma_f32_16x16x32_bf16 v[100:103], v[172:175], v[188:191], v[100:103]
	v_mfma_f32_16x16x32_bf16 v[88:91], v[164:167], v[210:213], v[88:91]
	v_mfma_f32_16x16x32_bf16 v[84:87], v[172:175], v[210:213], v[84:87]
	v_mfma_f32_16x16x32_bf16 v[72:75], v[164:167], v[218:221], v[72:75]
	v_mfma_f32_16x16x32_bf16 v[68:71], v[172:175], v[218:221], v[68:71]
	s_setprio 0
	s_barrier
	s_mov_b32 m0, s79
	v_lshl_add_u64 v[146:147], s[50:51], 0, v[134:135]
	ds_read_b128 v[176:179], v150 offset:16384
	ds_read_b128 v[180:183], v150 offset:17408
	ds_read_b128 v[184:187], v150 offset:18432
	ds_read_b128 v[188:191], v150 offset:19456
	ds_read_b128 v[192:195], v150 offset:20480
	ds_read_b128 v[210:213], v150 offset:21504
	ds_read_b128 v[214:217], v150 offset:22528
	ds_read_b128 v[218:221], v150 offset:23552
	global_load_lds_dwordx4 v[146:147], off
	v_lshl_add_u64 v[196:197], s[50:51], 0, v[0:1]
	s_mov_b32 m0, s76
	v_lshl_add_u64 v[198:199], s[52:53], 0, v[134:135]
	global_load_lds_dwordx4 v[196:197], off
	s_mov_b32 m0, s78
	v_lshl_add_u64 v[222:223], s[48:49], 0, v[132:133]
	global_load_lds_dwordx4 v[198:199], off
	v_lshl_add_u64 v[198:199], s[52:53], 0, v[0:1]
	s_mov_b32 m0, s77
	s_nop 0
	global_load_lds_dwordx4 v[198:199], off
	v_lshl_add_u64 v[198:199], s[48:49], 0, v[136:137]
	s_mov_b32 m0, s61
	s_nop 0
	global_load_lds_dwordx4 v[198:199], off
	s_mov_b32 m0, s62
	s_nop 0
	global_load_lds_dwordx4 v[222:223], off
	s_waitcnt vmcnt(8)
	s_waitcnt lgkmcnt(0)
	s_barrier
; #define PG8_STAGE(bufoff, gbase, voff) do { _Pragma("unroll") for (int _i = 0; _i < 2; ++_i) \
;         __builtin_amdgcn_global_load_lds((const unsigned*)((const char*)(gbase) + (voff)[_i]), (LAS unsigned*)(lds + (bufoff) + ldsw + _i * 8192), 16, 0, 0); } while (0)
; #define PG8_LDA(dst, b, h) do { _Pragma("unroll") for (int m = 0; m < 4; ++m) _Pragma("unroll") for (int k = 0; k < 2; ++k) dst[m][k] = *(const LAS bf16x8*)(lds + PG8_SA(b, h) + aoff + m * 2048 + k * 1024); } while (0)
; #define PG8_LDB(dst, b, h) do { _Pragma("unroll") for (int n = 0; n < 2; ++n) _Pragma("unroll") for (int k = 0; k < 2; ++k) dst[n][k] = *(const LAS bf16x8*)(lds + PG8_SB(b, h) + boff + n * 2048 + k * 1024); } while (0)
; #define PG8_MMA(ai, bj, At, Bt) do { __builtin_amdgcn_s_setprio(1); _Pragma("unroll") for (int m = 0; m < 4; ++m) _Pragma("unroll") for (int n = 0; n < 2; ++n) _Pragma("unroll") for (int k = 0; k < 2; ++k) \
;         acc[ai][bj][m][n] = __builtin_amdgcn_mfma_f32_16x16x32_bf16(Bt[n][k], At[m][k], acc[ai][bj][m][n], 0, 0, 0); __builtin_amdgcn_s_setprio(0); } while (0)
; #define PG8_WAIT_V(n) asm volatile("s_waitcnt vmcnt(" #n ")" ::: "memory")
; #define PG8_WAIT_L(n) asm volatile("s_waitcnt lgkmcnt(" #n ")" ::: "memory")
; #define PG8_BAR __builtin_amdgcn_s_barrier()
; #define PG8_SCHED __builtin_amdgcn_sched_barrier(0)
; template <class Epi>
; __device__ __forceinline__ void gemm_phase(LAS unsigned char* lds, const Gemm g, const StaticOrder& S, const Epi& E) {
;     ...
;             PG8_WAIT_V(8); PG8_WAIT_L(0); PG8_BAR; PG8_MMA(1, 0, At, B0); PG8_MMA(1, 1, At, B1); PG8_BAR; PG8_SCHED;
;             PG8_LDB(B0, 1, 0); PG8_LDB(B1, 1, 1); PG8_SCHED; PG8_LDA(At, 1, 0); PG8_STAGE(PG8_SA(0, 1), a2 + hstepA, voffA);
;             PG8_WAIT_V(8); PG8_WAIT_L(0); PG8_BAR; PG8_MMA(0, 0, At, B0); PG8_MMA(0, 1, At, B1); PG8_BAR; PG8_SCHED;
	s_setprio 1
	v_mfma_f32_16x16x32_bf16 v[64:67], v[138:141], v[176:179], v[64:67]
	v_mfma_f32_16x16x32_bf16 v[60:63], v[152:155], v[176:179], v[60:63]
	v_mfma_f32_16x16x32_bf16 v[48:51], v[138:141], v[184:187], v[48:51]
	v_mfma_f32_16x16x32_bf16 v[44:47], v[152:155], v[184:187], v[44:47]
	v_mfma_f32_16x16x32_bf16 v[32:35], v[138:141], v[192:195], v[32:35]
	v_mfma_f32_16x16x32_bf16 v[28:31], v[152:155], v[192:195], v[28:31]
	v_mfma_f32_16x16x32_bf16 v[16:19], v[138:141], v[214:217], v[16:19]
	v_mfma_f32_16x16x32_bf16 v[12:15], v[152:155], v[214:217], v[12:15]
	v_mfma_f32_16x16x32_bf16 v[64:67], v[142:145], v[180:183], v[64:67]
	v_mfma_f32_16x16x32_bf16 v[60:63], v[156:159], v[180:183], v[60:63]
	v_mfma_f32_16x16x32_bf16 v[48:51], v[142:145], v[188:191], v[48:51]
	v_mfma_f32_16x16x32_bf16 v[44:47], v[156:159], v[188:191], v[44:47]
	v_mfma_f32_16x16x32_bf16 v[32:35], v[142:145], v[210:213], v[32:35]
	v_mfma_f32_16x16x32_bf16 v[28:31], v[156:159], v[210:213], v[28:31]
	v_mfma_f32_16x16x32_bf16 v[16:19], v[142:145], v[218:221], v[16:19]
	v_mfma_f32_16x16x32_bf16 v[12:15], v[156:159], v[218:221], v[12:15]
	v_mfma_f32_16x16x32_bf16 v[56:59], v[160:163], v[176:179], v[56:59]
	v_mfma_f32_16x16x32_bf16 v[52:55], v[168:171], v[176:179], v[52:55]
	v_mfma_f32_16x16x32_bf16 v[40:43], v[160:163], v[184:187], v[40:43]
	v_mfma_f32_16x16x32_bf16 v[36:39], v[168:171], v[184:187], v[36:39]
	v_mfma_f32_16x16x32_bf16 v[24:27], v[160:163], v[192:195], v[24:27]
	v_mfma_f32_16x16x32_bf16 v[20:23], v[168:171], v[192:195], v[20:23]
	v_mfma_f32_16x16x32_bf16 v[8:11], v[160:163], v[214:217], v[8:11]
	v_mfma_f32_16x16x32_bf16 v[4:7], v[168:171], v[214:217], v[4:7]
	v_mfma_f32_16x16x32_bf16 v[56:59], v[164:167], v[180:183], v[56:59]
	v_mfma_f32_16x16x32_bf16 v[52:55], v[172:175], v[180:183], v[52:55]
	v_mfma_f32_16x16x32_bf16 v[40:43], v[164:167], v[188:191], v[40:43]
	v_mfma_f32_16x16x32_bf16 v[36:39], v[172:175], v[188:191], v[36:39]
	v_mfma_f32_16x16x32_bf16 v[24:27], v[164:167], v[210:213], v[24:27]
	v_mfma_f32_16x16x32_bf16 v[20:23], v[172:175], v[210:213], v[20:23]
	v_mfma_f32_16x16x32_bf16 v[8:11], v[164:167], v[218:221], v[8:11]
	v_mfma_f32_16x16x32_bf16 v[4:7], v[172:175], v[218:221], v[4:7]
	s_setprio 0
	s_barrier
	v_add_u32_e32 v151, s75, v148
	ds_read_b128 v[138:141], v151
	ds_read_b128 v[142:145], v151 offset:1024
	ds_read_b128 v[152:155], v151 offset:2048
	ds_read_b128 v[156:159], v151 offset:3072
	v_add_u32_e32 v151, s74, v148
	ds_read_b128 v[160:163], v151
	ds_read_b128 v[164:167], v151 offset:1024
	ds_read_b128 v[168:171], v151 offset:2048
	ds_read_b128 v[172:175], v151 offset:3072
	s_mov_b32 m0, s63
	v_lshl_add_u64 v[224:225], s[22:23], 0, v[136:137]
	ds_read_b128 v[176:179], v150 offset:32768
	ds_read_b128 v[180:183], v150 offset:33792
	ds_read_b128 v[184:187], v150 offset:34816
	ds_read_b128 v[188:191], v150 offset:35840
	ds_read_b128 v[192:195], v150 offset:36864
	ds_read_b128 v[210:213], v150 offset:37888
	ds_read_b128 v[214:217], v150 offset:38912
	ds_read_b128 v[218:221], v150 offset:39936
	global_load_lds_dwordx4 v[224:225], off
	v_lshl_add_u64 v[224:225], s[22:23], 0, v[132:133]
	s_mov_b32 m0, s64
	s_nop 0
	global_load_lds_dwordx4 v[224:225], off
	s_waitcnt vmcnt(8)
	s_waitcnt lgkmcnt(0)
	s_barrier
	s_setprio 1
	v_mfma_f32_16x16x32_bf16 v[128:131], v[138:141], v[176:179], v[128:131]
	v_mfma_f32_16x16x32_bf16 v[124:127], v[152:155], v[176:179], v[124:127]
	v_mfma_f32_16x16x32_bf16 v[112:115], v[138:141], v[184:187], v[112:115]
	v_mfma_f32_16x16x32_bf16 v[108:111], v[152:155], v[184:187], v[108:111]
	v_mfma_f32_16x16x32_bf16 v[96:99], v[138:141], v[192:195], v[96:99]
	v_mfma_f32_16x16x32_bf16 v[92:95], v[152:155], v[192:195], v[92:95]
	v_mfma_f32_16x16x32_bf16 v[80:83], v[138:141], v[214:217], v[80:83]
	v_mfma_f32_16x16x32_bf16 v[76:79], v[152:155], v[214:217], v[76:79]
	v_mfma_f32_16x16x32_bf16 v[128:131], v[142:145], v[180:183], v[128:131]
	v_mfma_f32_16x16x32_bf16 v[124:127], v[156:159], v[180:183], v[124:127]
	v_mfma_f32_16x16x32_bf16 v[112:115], v[142:145], v[188:191], v[112:115]
	v_mfma_f32_16x16x32_bf16 v[108:111], v[156:159], v[188:191], v[108:111]
	v_mfma_f32_16x16x32_bf16 v[96:99], v[142:145], v[210:213], v[96:99]
	v_mfma_f32_16x16x32_bf16 v[92:95], v[156:159], v[210:213], v[92:95]
	v_mfma_f32_16x16x32_bf16 v[80:83], v[142:145], v[218:221], v[80:83]
	v_mfma_f32_16x16x32_bf16 v[76:79], v[156:159], v[218:221], v[76:79]
	v_mfma_f32_16x16x32_bf16 v[120:123], v[160:163], v[176:179], v[120:123]
	v_mfma_f32_16x16x32_bf16 v[116:119], v[168:171], v[176:179], v[116:119]
	v_mfma_f32_16x16x32_bf16 v[104:107], v[160:163], v[184:187], v[104:107]
	v_mfma_f32_16x16x32_bf16 v[100:103], v[168:171], v[184:187], v[100:103]
	v_mfma_f32_16x16x32_bf16 v[88:91], v[160:163], v[192:195], v[88:91]
	v_mfma_f32_16x16x32_bf16 v[84:87], v[168:171], v[192:195], v[84:87]
	v_mfma_f32_16x16x32_bf16 v[72:75], v[160:163], v[214:217], v[72:75]
	v_mfma_f32_16x16x32_bf16 v[68:71], v[168:171], v[214:217], v[68:71]
	v_mfma_f32_16x16x32_bf16 v[120:123], v[164:167], v[180:183], v[120:123]
	v_mfma_f32_16x16x32_bf16 v[116:119], v[172:175], v[180:183], v[116:119]
	v_mfma_f32_16x16x32_bf16 v[104:107], v[164:167], v[188:191], v[104:107]
	v_mfma_f32_16x16x32_bf16 v[100:103], v[172:175], v[188:191], v[100:103]
	v_mfma_f32_16x16x32_bf16 v[88:91], v[164:167], v[210:213], v[88:91]
	v_mfma_f32_16x16x32_bf16 v[84:87], v[172:175], v[210:213], v[84:87]
	v_mfma_f32_16x16x32_bf16 v[72:75], v[164:167], v[218:221], v[72:75]
	v_mfma_f32_16x16x32_bf16 v[68:71], v[172:175], v[218:221], v[68:71]
	s_setprio 0
	s_barrier
; #define PG8_STAGE(bufoff, gbase, voff) do { _Pragma("unroll") for (int _i = 0; _i < 2; ++_i) \
;         __builtin_amdgcn_global_load_lds((const unsigned*)((const char*)(gbase) + (voff)[_i]), (LAS unsigned*)(lds + (bufoff) + ldsw + _i * 8192), 16, 0, 0); } while (0)
; #define PG8_LDA(dst, b, h) do { _Pragma("unroll") for (int m = 0; m < 4; ++m) _Pragma("unroll") for (int k = 0; k < 2; ++k) dst[m][k] = *(const LAS bf16x8*)(lds + PG8_SA(b, h) + aoff + m * 2048 + k * 1024); } while (0)
; #define PG8_MMA(ai, bj, At, Bt) do { __builtin_amdgcn_s_setprio(1); _Pragma("unroll") for (int m = 0; m < 4; ++m) _Pragma("unroll") for (int n = 0; n < 2; ++n) _Pragma("unroll") for (int k = 0; k < 2; ++k) \
;         acc[ai][bj][m][n] = __builtin_amdgcn_mfma_f32_16x16x32_bf16(Bt[n][k], At[m][k], acc[ai][bj][m][n], 0, 0, 0); __builtin_amdgcn_s_setprio(0); } while (0)
; #define PG8_WAIT_V(n) asm volatile("s_waitcnt vmcnt(" #n ")" ::: "memory")
; #define PG8_WAIT_L(n) asm volatile("s_waitcnt lgkmcnt(" #n ")" ::: "memory")
; #define PG8_BAR __builtin_amdgcn_s_barrier()
; #define PG8_SCHED __builtin_amdgcn_sched_barrier(0)
; template <class Epi>
; __device__ __forceinline__ void gemm_phase(LAS unsigned char* lds, const Gemm g, const StaticOrder& S, const Epi& E) {
;     ...
;             PG8_LDA(At, 1, 1); PG8_STAGE(PG8_SB(1, 0), b3, voffB); PG8_STAGE(PG8_SB(1, 1), b3 + hstepB, voffB); PG8_STAGE(PG8_SA(1, 0), a3, voffA);
;             PG8_WAIT_V(8); PG8_WAIT_L(0); PG8_BAR; PG8_MMA(1, 0, At, B0); PG8_MMA(1, 1, At, B1); PG8_BAR; PG8_SCHED;
;         }
;         if (wr == 0) PG8_BAR;
	s_mov_b32 m0, s73
	v_lshl_add_u64 v[146:147], v[146:147], 0, s[30:31]
	ds_read_b128 v[176:179], v150 offset:49152
	ds_read_b128 v[180:183], v150 offset:50176
	ds_read_b128 v[184:187], v150 offset:51200
	ds_read_b128 v[188:191], v150 offset:52224
	ds_read_b128 v[192:195], v150 offset:53248
	ds_read_b128 v[210:213], v150 offset:54272
	ds_read_b128 v[214:217], v150 offset:55296
	ds_read_b128 v[218:221], v150 offset:56320
	global_load_lds_dwordx4 v[146:147], off
	v_lshl_add_u64 v[146:147], v[196:197], 0, s[30:31]
	s_mov_b32 m0, s72
	s_nop 0
	global_load_lds_dwordx4 v[146:147], off
	v_lshl_add_u64 v[146:147], s[46:47], 0, v[134:135]
	s_mov_b32 m0, s81
	s_nop 0
	global_load_lds_dwordx4 v[146:147], off
	v_lshl_add_u64 v[146:147], s[46:47], 0, v[0:1]
	s_mov_b32 m0, s80
	s_nop 0
	global_load_lds_dwordx4 v[146:147], off
	v_lshl_add_u64 v[146:147], v[198:199], 0, s[30:31]
	s_mov_b32 m0, s65
	s_nop 0
	global_load_lds_dwordx4 v[146:147], off
	v_lshl_add_u64 v[146:147], v[222:223], 0, s[30:31]
	s_mov_b32 m0, s66
	s_nop 0
	global_load_lds_dwordx4 v[146:147], off
	s_waitcnt vmcnt(8)
	s_waitcnt lgkmcnt(0)
	s_barrier
	s_setprio 1
	v_mfma_f32_16x16x32_bf16 v[64:67], v[138:141], v[176:179], v[64:67]
	v_mfma_f32_16x16x32_bf16 v[60:63], v[152:155], v[176:179], v[60:63]
	v_mfma_f32_16x16x32_bf16 v[48:51], v[138:141], v[184:187], v[48:51]
	v_mfma_f32_16x16x32_bf16 v[44:47], v[152:155], v[184:187], v[44:47]
	v_mfma_f32_16x16x32_bf16 v[32:35], v[138:141], v[192:195], v[32:35]
	v_mfma_f32_16x16x32_bf16 v[28:31], v[152:155], v[192:195], v[28:31]
	v_mfma_f32_16x16x32_bf16 v[16:19], v[138:141], v[214:217], v[16:19]
	v_mfma_f32_16x16x32_bf16 v[12:15], v[152:155], v[214:217], v[12:15]
	v_mfma_f32_16x16x32_bf16 v[64:67], v[142:145], v[180:183], v[64:67]
	v_mfma_f32_16x16x32_bf16 v[60:63], v[156:159], v[180:183], v[60:63]
	v_mfma_f32_16x16x32_bf16 v[48:51], v[142:145], v[188:191], v[48:51]
	v_mfma_f32_16x16x32_bf16 v[44:47], v[156:159], v[188:191], v[44:47]
	v_mfma_f32_16x16x32_bf16 v[32:35], v[142:145], v[210:213], v[32:35]
	v_mfma_f32_16x16x32_bf16 v[28:31], v[156:159], v[210:213], v[28:31]
	v_mfma_f32_16x16x32_bf16 v[16:19], v[142:145], v[218:221], v[16:19]
	v_mfma_f32_16x16x32_bf16 v[12:15], v[156:159], v[218:221], v[12:15]
	v_mfma_f32_16x16x32_bf16 v[56:59], v[160:163], v[176:179], v[56:59]
	v_mfma_f32_16x16x32_bf16 v[52:55], v[168:171], v[176:179], v[52:55]
	v_mfma_f32_16x16x32_bf16 v[40:43], v[160:163], v[184:187], v[40:43]
	v_mfma_f32_16x16x32_bf16 v[36:39], v[168:171], v[184:187], v[36:39]
	v_mfma_f32_16x16x32_bf16 v[24:27], v[160:163], v[192:195], v[24:27]
	v_mfma_f32_16x16x32_bf16 v[20:23], v[168:171], v[192:195], v[20:23]
	v_mfma_f32_16x16x32_bf16 v[8:11], v[160:163], v[214:217], v[8:11]
	v_mfma_f32_16x16x32_bf16 v[4:7], v[168:171], v[214:217], v[4:7]
	v_mfma_f32_16x16x32_bf16 v[56:59], v[164:167], v[180:183], v[56:59]
	v_mfma_f32_16x16x32_bf16 v[52:55], v[172:175], v[180:183], v[52:55]
	v_mfma_f32_16x16x32_bf16 v[40:43], v[164:167], v[188:191], v[40:43]
	v_mfma_f32_16x16x32_bf16 v[36:39], v[172:175], v[188:191], v[36:39]
	v_mfma_f32_16x16x32_bf16 v[24:27], v[164:167], v[210:213], v[24:27]
	v_mfma_f32_16x16x32_bf16 v[20:23], v[172:175], v[210:213], v[20:23]
	v_mfma_f32_16x16x32_bf16 v[8:11], v[164:167], v[218:221], v[8:11]
	v_mfma_f32_16x16x32_bf16 v[4:7], v[172:175], v[218:221], v[4:7]
	s_setprio 0
	s_barrier
	s_movk_i32 s22, 0x100
	s_andn2_b64 vcc, exec, s[4:5]
	s_mov_b64 s[46:47], -1
	s_mov_b64 s[4:5], 0
	s_cbranch_vccz .LBB0_710
	s_and_b64 vcc, exec, s[12:13]
	s_cbranch_vccz .LBB0_713
	s_barrier

; #define PG8_STAGE(bufoff, gbase, voff) do { _Pragma("unroll") for (int _i = 0; _i < 2; ++_i) \
;         __builtin_amdgcn_global_load_lds((const unsigned*)((const char*)(gbase) + (voff)[_i]), (LAS unsigned*)(lds + (bufoff) + ldsw + _i * 8192), 16, 0, 0); } while (0)
; #define PG8_LDA(dst, b, h) do { _Pragma("unroll") for (int m = 0; m < 4; ++m) _Pragma("unroll") for (int k = 0; k < 2; ++k) dst[m][k] = *(const LAS bf16x8*)(lds + PG8_SA(b, h) + aoff + m * 2048 + k * 1024); } while (0)
; #define PG8_LDB(dst, b, h) do { _Pragma("unroll") for (int n = 0; n < 2; ++n) _Pragma("unroll") for (int k = 0; k < 2; ++k) dst[n][k] = *(const LAS bf16x8*)(lds + PG8_SB(b, h) + boff + n * 2048 + k * 1024); } while (0)
; #define PG8_MMA(ai, bj, At, Bt) do { __builtin_amdgcn_s_setprio(1); _Pragma("unroll") for (int m = 0; m < 4; ++m) _Pragma("unroll") for (int n = 0; n < 2; ++n) _Pragma("unroll") for (int k = 0; k < 2; ++k) \
;         acc[ai][bj][m][n] = __builtin_amdgcn_mfma_f32_16x16x32_bf16(Bt[n][k], At[m][k], acc[ai][bj][m][n], 0, 0, 0); __builtin_amdgcn_s_setprio(0); } while (0)
; #define PG8_WAIT_V(n) asm volatile("s_waitcnt vmcnt(" #n ")" ::: "memory")
; #define PG8_WAIT_L(n) asm volatile("s_waitcnt lgkmcnt(" #n ")" ::: "memory")
; #define PG8_BAR __builtin_amdgcn_s_barrier()
; #define PG8_SCHED __builtin_amdgcn_sched_barrier(0)
; template <class Epi>
; __device__ __forceinline__ void gemm_phase(LAS unsigned char* lds, const Gemm g, const StaticOrder& S, const Epi& E) {
;     ...
;             const bool last = (t == nt - 2);
;             const char* a1 = cA + (size_t)(t + 1) * kstep;
;             const char* a2 = last ? nA : cA + (size_t)(t + 2) * kstep; const char* b2 = last ? nB : cB + (size_t)(t + 2) * kstep;
;             const char* a3 = a2 + kstep; const char* b3 = b2 + kstep;
;             PG8_LDB(B0, 0, 0); PG8_LDB(B1, 0, 1); PG8_SCHED; PG8_LDA(At, 0, 0); PG8_STAGE(PG8_SA(1, 1), a1 + hstepA, voffA);
;             PG8_WAIT_V(8); PG8_WAIT_L(0); PG8_BAR; PG8_MMA(0, 0, At, B0); PG8_MMA(0, 1, At, B1); PG8_BAR; PG8_SCHED;
;             PG8_LDA(At, 0, 1); PG8_STAGE(PG8_SB(0, 0), b2, voffB); PG8_STAGE(PG8_SB(0, 1), b2 + hstepB, voffB); PG8_STAGE(PG8_SA(0, 0), a2, voffA);
;             PG8_WAIT_V(8); PG8_WAIT_L(0); PG8_BAR; PG8_MMA(1, 0, At, B0); PG8_MMA(1, 1, At, B1); PG8_BAR; PG8_SCHED;
.LBB0_732:
	s_add_u32 s52, s42, s22
	s_addc_u32 s53, s43, 0
	s_add_u32 s23, s52, 0x100
	s_addc_u32 s50, s53, 0
	s_and_b64 s[48:49], s[46:47], exec
	s_cselect_b32 s49, s15, s50
	s_cselect_b32 s48, s70, s23
	s_add_u32 s22, s40, s22
	s_addc_u32 s23, s41, 0
	s_add_u32 s50, s22, 0x100
	s_addc_u32 s51, s23, 0
	s_add_i32 s79, 0, 0x10000
	s_and_b64 s[22:23], s[46:47], exec
	s_cselect_b32 s51, s35, s51
	s_cselect_b32 s50, s34, s50
	s_add_i32 s47, 0, 0x14000
	s_add_u32 s54, s52, 0x10080
	s_addc_u32 s55, s53, 0
	s_add_i32 s78, s79, s60
	s_add_i32 m0, s61, 0xc000
	s_add_i32 s81, s61, 0xe000
	s_add_i32 s75, s78, 0x2000
	v_add_u32_e32 v146, s79, v148
	s_add_u32 s52, s50, 0x3a800
	ds_read_b128 v[138:141], v146
	ds_read_b128 v[142:145], v146 offset:1024
	ds_read_b128 v[152:155], v146 offset:2048
	ds_read_b128 v[156:159], v146 offset:3072
	v_add_u32_e32 v146, s47, v148
	s_addc_u32 s53, s51, 0
	s_add_i32 s77, s47, s60
	ds_read_b128 v[160:163], v146
	ds_read_b128 v[164:167], v146 offset:1024
	ds_read_b128 v[168:171], v146 offset:2048
	ds_read_b128 v[172:175], v146 offset:3072
	s_add_i32 s76, s77, 0x2000
	s_add_i32 s74, 0, 0x18000
	s_add_i32 s73, 0, 0x1c000
	s_add_u32 s22, s48, 0x10000
	s_addc_u32 s23, s49, 0
	s_add_i32 s72, s74, s60
	s_add_i32 s71, s72, 0x2000
	s_add_u32 s46, s50, 0x3a880
	s_addc_u32 s47, s51, 0
	s_add_i32 s80, s73, s60
	s_add_i32 s79, s80, 0x2000
	v_lshl_add_u64 v[146:147], s[54:55], 0, v[136:137]
	ds_read_b128 v[176:179], v150
	ds_read_b128 v[180:183], v150 offset:1024
	ds_read_b128 v[184:187], v150 offset:2048
	ds_read_b128 v[188:191], v150 offset:3072
	ds_read_b128 v[192:195], v150 offset:4096
	ds_read_b128 v[210:213], v150 offset:5120
	ds_read_b128 v[214:217], v150 offset:6144
	ds_read_b128 v[218:221], v150 offset:7168
	global_load_lds_dwordx4 v[146:147], off
	v_lshl_add_u64 v[146:147], s[54:55], 0, v[132:133]
	s_mov_b32 m0, s81
	s_nop 0
	global_load_lds_dwordx4 v[146:147], off
	s_waitcnt vmcnt(8)
	s_waitcnt lgkmcnt(0)
	s_barrier
	s_setprio 1
	v_mfma_f32_16x16x32_bf16 v[128:131], v[138:141], v[176:179], v[128:131]
	v_mfma_f32_16x16x32_bf16 v[124:127], v[152:155], v[176:179], v[124:127]
	v_mfma_f32_16x16x32_bf16 v[120:123], v[138:141], v[184:187], v[120:123]
	v_mfma_f32_16x16x32_bf16 v[116:119], v[152:155], v[184:187], v[116:119]
	v_mfma_f32_16x16x32_bf16 v[112:115], v[138:141], v[192:195], v[112:115]
	v_mfma_f32_16x16x32_bf16 v[108:111], v[152:155], v[192:195], v[108:111]
	v_mfma_f32_16x16x32_bf16 v[104:107], v[138:141], v[214:217], v[104:107]
	v_mfma_f32_16x16x32_bf16 v[100:103], v[152:155], v[214:217], v[100:103]
	v_mfma_f32_16x16x32_bf16 v[128:131], v[142:145], v[180:183], v[128:131]
	v_mfma_f32_16x16x32_bf16 v[124:127], v[156:159], v[180:183], v[124:127]
	v_mfma_f32_16x16x32_bf16 v[120:123], v[142:145], v[188:191], v[120:123]
	v_mfma_f32_16x16x32_bf16 v[116:119], v[156:159], v[188:191], v[116:119]
	v_mfma_f32_16x16x32_bf16 v[112:115], v[142:145], v[210:213], v[112:115]
	v_mfma_f32_16x16x32_bf16 v[108:111], v[156:159], v[210:213], v[108:111]
	v_mfma_f32_16x16x32_bf16 v[104:107], v[142:145], v[218:221], v[104:107]
	v_mfma_f32_16x16x32_bf16 v[100:103], v[156:159], v[218:221], v[100:103]
	v_mfma_f32_16x16x32_bf16 v[64:67], v[160:163], v[176:179], v[64:67]
	v_mfma_f32_16x16x32_bf16 v[60:63], v[168:171], v[176:179], v[60:63]
	v_mfma_f32_16x16x32_bf16 v[56:59], v[160:163], v[184:187], v[56:59]
	v_mfma_f32_16x16x32_bf16 v[52:55], v[168:171], v[184:187], v[52:55]
	v_mfma_f32_16x16x32_bf16 v[48:51], v[160:163], v[192:195], v[48:51]
	v_mfma_f32_16x16x32_bf16 v[44:47], v[168:171], v[192:195], v[44:47]
	v_mfma_f32_16x16x32_bf16 v[40:43], v[160:163], v[214:217], v[40:43]
	v_mfma_f32_16x16x32_bf16 v[36:39], v[168:171], v[214:217], v[36:39]
	v_mfma_f32_16x16x32_bf16 v[64:67], v[164:167], v[180:183], v[64:67]
	v_mfma_f32_16x16x32_bf16 v[60:63], v[172:175], v[180:183], v[60:63]
	v_mfma_f32_16x16x32_bf16 v[56:59], v[164:167], v[188:191], v[56:59]
	v_mfma_f32_16x16x32_bf16 v[52:55], v[172:175], v[188:191], v[52:55]
	v_mfma_f32_16x16x32_bf16 v[48:51], v[164:167], v[210:213], v[48:51]
	v_mfma_f32_16x16x32_bf16 v[44:47], v[172:175], v[210:213], v[44:47]
	v_mfma_f32_16x16x32_bf16 v[40:43], v[164:167], v[218:221], v[40:43]
	v_mfma_f32_16x16x32_bf16 v[36:39], v[172:175], v[218:221], v[36:39]
	s_setprio 0
	s_barrier
	s_mov_b32 m0, s78
	v_lshl_add_u64 v[146:147], s[50:51], 0, v[134:135]
	ds_read_b128 v[176:179], v150 offset:16384
	ds_read_b128 v[180:183], v150 offset:17408
	ds_read_b128 v[184:187], v150 offset:18432
	ds_read_b128 v[188:191], v150 offset:19456
	ds_read_b128 v[192:195], v150 offset:20480
	ds_read_b128 v[210:213], v150 offset:21504
	ds_read_b128 v[214:217], v150 offset:22528
	ds_read_b128 v[218:221], v150 offset:23552
	global_load_lds_dwordx4 v[146:147], off
	v_lshl_add_u64 v[196:197], s[50:51], 0, v[0:1]
	s_mov_b32 m0, s75
	v_lshl_add_u64 v[198:199], s[52:53], 0, v[134:135]
	global_load_lds_dwordx4 v[196:197], off
	s_mov_b32 m0, s77
	v_lshl_add_u64 v[222:223], s[48:49], 0, v[132:133]
	global_load_lds_dwordx4 v[198:199], off
	v_lshl_add_u64 v[198:199], s[52:53], 0, v[0:1]
	s_mov_b32 m0, s76
	s_nop 0
	global_load_lds_dwordx4 v[198:199], off
	v_lshl_add_u64 v[198:199], s[48:49], 0, v[136:137]
	s_mov_b32 m0, s61
	s_nop 0
	global_load_lds_dwordx4 v[198:199], off
	s_mov_b32 m0, s62
	s_nop 0
	global_load_lds_dwordx4 v[222:223], off
	s_waitcnt vmcnt(8)
	s_waitcnt lgkmcnt(0)
	s_barrier
; #define PG8_STAGE(bufoff, gbase, voff) do { _Pragma("unroll") for (int _i = 0; _i < 2; ++_i) \
;         __builtin_amdgcn_global_load_lds((const unsigned*)((const char*)(gbase) + (voff)[_i]), (LAS unsigned*)(lds + (bufoff) + ldsw + _i * 8192), 16, 0, 0); } while (0)
; #define PG8_LDA(dst, b, h) do { _Pragma("unroll") for (int m = 0; m < 4; ++m) _Pragma("unroll") for (int k = 0; k < 2; ++k) dst[m][k] = *(const LAS bf16x8*)(lds + PG8_SA(b, h) + aoff + m * 2048 + k * 1024); } while (0)
; #define PG8_LDB(dst, b, h) do { _Pragma("unroll") for (int n = 0; n < 2; ++n) _Pragma("unroll") for (int k = 0; k < 2; ++k) dst[n][k] = *(const LAS bf16x8*)(lds + PG8_SB(b, h) + boff + n * 2048 + k * 1024); } while (0)
; #define PG8_MMA(ai, bj, At, Bt) do { __builtin_amdgcn_s_setprio(1); _Pragma("unroll") for (int m = 0; m < 4; ++m) _Pragma("unroll") for (int n = 0; n < 2; ++n) _Pragma("unroll") for (int k = 0; k < 2; ++k) \
;         acc[ai][bj][m][n] = __builtin_amdgcn_mfma_f32_16x16x32_bf16(Bt[n][k], At[m][k], acc[ai][bj][m][n], 0, 0, 0); __builtin_amdgcn_s_setprio(0); } while (0)
; #define PG8_WAIT_V(n) asm volatile("s_waitcnt vmcnt(" #n ")" ::: "memory")
; #define PG8_WAIT_L(n) asm volatile("s_waitcnt lgkmcnt(" #n ")" ::: "memory")
; #define PG8_BAR __builtin_amdgcn_s_barrier()
; #define PG8_SCHED __builtin_amdgcn_sched_barrier(0)
; template <class Epi>
; __device__ __forceinline__ void gemm_phase(LAS unsigned char* lds, const Gemm g, const StaticOrder& S, const Epi& E) {
;     ...
;             PG8_WAIT_V(8); PG8_WAIT_L(0); PG8_BAR; PG8_MMA(1, 0, At, B0); PG8_MMA(1, 1, At, B1); PG8_BAR; PG8_SCHED;
;             PG8_LDB(B0, 1, 0); PG8_LDB(B1, 1, 1); PG8_SCHED; PG8_LDA(At, 1, 0); PG8_STAGE(PG8_SA(0, 1), a2 + hstepA, voffA);
;             PG8_WAIT_V(8); PG8_WAIT_L(0); PG8_BAR; PG8_MMA(0, 0, At, B0); PG8_MMA(0, 1, At, B1); PG8_BAR; PG8_SCHED;
	s_setprio 1
	v_mfma_f32_16x16x32_bf16 v[96:99], v[138:141], v[176:179], v[96:99]
	v_mfma_f32_16x16x32_bf16 v[92:95], v[152:155], v[176:179], v[92:95]
	v_mfma_f32_16x16x32_bf16 v[88:91], v[138:141], v[184:187], v[88:91]
	v_mfma_f32_16x16x32_bf16 v[84:87], v[152:155], v[184:187], v[84:87]
	v_mfma_f32_16x16x32_bf16 v[80:83], v[138:141], v[192:195], v[80:83]
	v_mfma_f32_16x16x32_bf16 v[76:79], v[152:155], v[192:195], v[76:79]
	v_mfma_f32_16x16x32_bf16 v[72:75], v[138:141], v[214:217], v[72:75]
	v_mfma_f32_16x16x32_bf16 v[68:71], v[152:155], v[214:217], v[68:71]
	v_mfma_f32_16x16x32_bf16 v[96:99], v[142:145], v[180:183], v[96:99]
	v_mfma_f32_16x16x32_bf16 v[92:95], v[156:159], v[180:183], v[92:95]
	v_mfma_f32_16x16x32_bf16 v[88:91], v[142:145], v[188:191], v[88:91]
	v_mfma_f32_16x16x32_bf16 v[84:87], v[156:159], v[188:191], v[84:87]
	v_mfma_f32_16x16x32_bf16 v[80:83], v[142:145], v[210:213], v[80:83]
	v_mfma_f32_16x16x32_bf16 v[76:79], v[156:159], v[210:213], v[76:79]
	v_mfma_f32_16x16x32_bf16 v[72:75], v[142:145], v[218:221], v[72:75]
	v_mfma_f32_16x16x32_bf16 v[68:71], v[156:159], v[218:221], v[68:71]
	v_mfma_f32_16x16x32_bf16 v[32:35], v[160:163], v[176:179], v[32:35]
	v_mfma_f32_16x16x32_bf16 v[28:31], v[168:171], v[176:179], v[28:31]
	v_mfma_f32_16x16x32_bf16 v[24:27], v[160:163], v[184:187], v[24:27]
	v_mfma_f32_16x16x32_bf16 v[20:23], v[168:171], v[184:187], v[20:23]
	v_mfma_f32_16x16x32_bf16 v[16:19], v[160:163], v[192:195], v[16:19]
	v_mfma_f32_16x16x32_bf16 v[12:15], v[168:171], v[192:195], v[12:15]
	v_mfma_f32_16x16x32_bf16 v[8:11], v[160:163], v[214:217], v[8:11]
	v_mfma_f32_16x16x32_bf16 v[4:7], v[168:171], v[214:217], v[4:7]
	v_mfma_f32_16x16x32_bf16 v[32:35], v[164:167], v[180:183], v[32:35]
	v_mfma_f32_16x16x32_bf16 v[28:31], v[172:175], v[180:183], v[28:31]
	v_mfma_f32_16x16x32_bf16 v[24:27], v[164:167], v[188:191], v[24:27]
	v_mfma_f32_16x16x32_bf16 v[20:23], v[172:175], v[188:191], v[20:23]
	v_mfma_f32_16x16x32_bf16 v[16:19], v[164:167], v[210:213], v[16:19]
	v_mfma_f32_16x16x32_bf16 v[12:15], v[172:175], v[210:213], v[12:15]
	v_mfma_f32_16x16x32_bf16 v[8:11], v[164:167], v[218:221], v[8:11]
	v_mfma_f32_16x16x32_bf16 v[4:7], v[172:175], v[218:221], v[4:7]
	s_setprio 0
	s_barrier
	v_add_u32_e32 v151, s74, v148
	ds_read_b128 v[138:141], v151
	ds_read_b128 v[142:145], v151 offset:1024
	ds_read_b128 v[152:155], v151 offset:2048
	ds_read_b128 v[156:159], v151 offset:3072
	v_add_u32_e32 v151, s73, v148
	ds_read_b128 v[160:163], v151
	ds_read_b128 v[164:167], v151 offset:1024
	ds_read_b128 v[168:171], v151 offset:2048
	ds_read_b128 v[172:175], v151 offset:3072
	s_mov_b32 m0, s63
	v_lshl_add_u64 v[224:225], s[22:23], 0, v[136:137]
	ds_read_b128 v[176:179], v150 offset:32768
	ds_read_b128 v[180:183], v150 offset:33792
	ds_read_b128 v[184:187], v150 offset:34816
	ds_read_b128 v[188:191], v150 offset:35840
	ds_read_b128 v[192:195], v150 offset:36864
	ds_read_b128 v[210:213], v150 offset:37888
	ds_read_b128 v[214:217], v150 offset:38912
	ds_read_b128 v[218:221], v150 offset:39936
	global_load_lds_dwordx4 v[224:225], off
	v_lshl_add_u64 v[224:225], s[22:23], 0, v[132:133]
	s_mov_b32 m0, s64
	s_nop 0
	global_load_lds_dwordx4 v[224:225], off
	s_waitcnt vmcnt(8)
	s_waitcnt lgkmcnt(0)
	s_barrier
	s_setprio 1
	v_mfma_f32_16x16x32_bf16 v[128:131], v[138:141], v[176:179], v[128:131]
	v_mfma_f32_16x16x32_bf16 v[124:127], v[152:155], v[176:179], v[124:127]
	v_mfma_f32_16x16x32_bf16 v[120:123], v[138:141], v[184:187], v[120:123]
	v_mfma_f32_16x16x32_bf16 v[116:119], v[152:155], v[184:187], v[116:119]
	v_mfma_f32_16x16x32_bf16 v[112:115], v[138:141], v[192:195], v[112:115]
	v_mfma_f32_16x16x32_bf16 v[108:111], v[152:155], v[192:195], v[108:111]
	v_mfma_f32_16x16x32_bf16 v[104:107], v[138:141], v[214:217], v[104:107]
	v_mfma_f32_16x16x32_bf16 v[100:103], v[152:155], v[214:217], v[100:103]
	v_mfma_f32_16x16x32_bf16 v[128:131], v[142:145], v[180:183], v[128:131]
	v_mfma_f32_16x16x32_bf16 v[124:127], v[156:159], v[180:183], v[124:127]
	v_mfma_f32_16x16x32_bf16 v[120:123], v[142:145], v[188:191], v[120:123]
	v_mfma_f32_16x16x32_bf16 v[116:119], v[156:159], v[188:191], v[116:119]
	v_mfma_f32_16x16x32_bf16 v[112:115], v[142:145], v[210:213], v[112:115]
	v_mfma_f32_16x16x32_bf16 v[108:111], v[156:159], v[210:213], v[108:111]
	v_mfma_f32_16x16x32_bf16 v[104:107], v[142:145], v[218:221], v[104:107]
	v_mfma_f32_16x16x32_bf16 v[100:103], v[156:159], v[218:221], v[100:103]
	v_mfma_f32_16x16x32_bf16 v[64:67], v[160:163], v[176:179], v[64:67]
	v_mfma_f32_16x16x32_bf16 v[60:63], v[168:171], v[176:179], v[60:63]
	v_mfma_f32_16x16x32_bf16 v[56:59], v[160:163], v[184:187], v[56:59]
	v_mfma_f32_16x16x32_bf16 v[52:55], v[168:171], v[184:187], v[52:55]
	v_mfma_f32_16x16x32_bf16 v[48:51], v[160:163], v[192:195], v[48:51]
	v_mfma_f32_16x16x32_bf16 v[44:47], v[168:171], v[192:195], v[44:47]
	v_mfma_f32_16x16x32_bf16 v[40:43], v[160:163], v[214:217], v[40:43]
	v_mfma_f32_16x16x32_bf16 v[36:39], v[168:171], v[214:217], v[36:39]
	v_mfma_f32_16x16x32_bf16 v[64:67], v[164:167], v[180:183], v[64:67]
	v_mfma_f32_16x16x32_bf16 v[60:63], v[172:175], v[180:183], v[60:63]
	v_mfma_f32_16x16x32_bf16 v[56:59], v[164:167], v[188:191], v[56:59]
	v_mfma_f32_16x16x32_bf16 v[52:55], v[172:175], v[188:191], v[52:55]
	v_mfma_f32_16x16x32_bf16 v[48:51], v[164:167], v[210:213], v[48:51]
	v_mfma_f32_16x16x32_bf16 v[44:47], v[172:175], v[210:213], v[44:47]
	v_mfma_f32_16x16x32_bf16 v[40:43], v[164:167], v[218:221], v[40:43]
	v_mfma_f32_16x16x32_bf16 v[36:39], v[172:175], v[218:221], v[36:39]
	s_setprio 0
	s_barrier
; #define PG8_STAGE(bufoff, gbase, voff) do { _Pragma("unroll") for (int _i = 0; _i < 2; ++_i) \
;         __builtin_amdgcn_global_load_lds((const unsigned*)((const char*)(gbase) + (voff)[_i]), (LAS unsigned*)(lds + (bufoff) + ldsw + _i * 8192), 16, 0, 0); } while (0)
; #define PG8_LDA(dst, b, h) do { _Pragma("unroll") for (int m = 0; m < 4; ++m) _Pragma("unroll") for (int k = 0; k < 2; ++k) dst[m][k] = *(const LAS bf16x8*)(lds + PG8_SA(b, h) + aoff + m * 2048 + k * 1024); } while (0)
; #define PG8_MMA(ai, bj, At, Bt) do { __builtin_amdgcn_s_setprio(1); _Pragma("unroll") for (int m = 0; m < 4; ++m) _Pragma("unroll") for (int n = 0; n < 2; ++n) _Pragma("unroll") for (int k = 0; k < 2; ++k) \
;         acc[ai][bj][m][n] = __builtin_amdgcn_mfma_f32_16x16x32_bf16(Bt[n][k], At[m][k], acc[ai][bj][m][n], 0, 0, 0); __builtin_amdgcn_s_setprio(0); } while (0)
; #define PG8_WAIT_V(n) asm volatile("s_waitcnt vmcnt(" #n ")" ::: "memory")
; #define PG8_WAIT_L(n) asm volatile("s_waitcnt lgkmcnt(" #n ")" ::: "memory")
; #define PG8_BAR __builtin_amdgcn_s_barrier()
; #define PG8_SCHED __builtin_amdgcn_sched_barrier(0)
; template <class Epi>
; __device__ __forceinline__ void gemm_phase(LAS unsigned char* lds, const Gemm g, const StaticOrder& S, const Epi& E) {
;     ...
;             PG8_LDA(At, 1, 1); PG8_STAGE(PG8_SB(1, 0), b3, voffB); PG8_STAGE(PG8_SB(1, 1), b3 + hstepB, voffB); PG8_STAGE(PG8_SA(1, 0), a3, voffA);
;             PG8_WAIT_V(8); PG8_WAIT_L(0); PG8_BAR; PG8_MMA(1, 0, At, B0); PG8_MMA(1, 1, At, B1); PG8_BAR; PG8_SCHED;
;         }
;         if (wr == 0) PG8_BAR;
	s_mov_b32 m0, s72
	v_lshl_add_u64 v[146:147], v[146:147], 0, s[30:31]
	ds_read_b128 v[176:179], v150 offset:49152
	ds_read_b128 v[180:183], v150 offset:50176
	ds_read_b128 v[184:187], v150 offset:51200
	ds_read_b128 v[188:191], v150 offset:52224
	ds_read_b128 v[192:195], v150 offset:53248
	ds_read_b128 v[210:213], v150 offset:54272
	ds_read_b128 v[214:217], v150 offset:55296
	ds_read_b128 v[218:221], v150 offset:56320
	global_load_lds_dwordx4 v[146:147], off
	v_lshl_add_u64 v[146:147], v[196:197], 0, s[30:31]
	s_mov_b32 m0, s71
	s_nop 0
	global_load_lds_dwordx4 v[146:147], off
	v_lshl_add_u64 v[146:147], s[46:47], 0, v[134:135]
	s_mov_b32 m0, s80
	s_nop 0
	global_load_lds_dwordx4 v[146:147], off
	v_lshl_add_u64 v[146:147], s[46:47], 0, v[0:1]
	s_mov_b32 m0, s79
	s_nop 0
	global_load_lds_dwordx4 v[146:147], off
	v_lshl_add_u64 v[146:147], v[198:199], 0, s[30:31]
	s_mov_b32 m0, s28
	s_nop 0
	global_load_lds_dwordx4 v[146:147], off
	v_lshl_add_u64 v[146:147], v[222:223], 0, s[30:31]
	s_mov_b32 m0, s65
	s_nop 0
	global_load_lds_dwordx4 v[146:147], off
	s_waitcnt vmcnt(8)
	s_waitcnt lgkmcnt(0)
	s_barrier
	s_setprio 1
	v_mfma_f32_16x16x32_bf16 v[96:99], v[138:141], v[176:179], v[96:99]
	v_mfma_f32_16x16x32_bf16 v[92:95], v[152:155], v[176:179], v[92:95]
	v_mfma_f32_16x16x32_bf16 v[88:91], v[138:141], v[184:187], v[88:91]
	v_mfma_f32_16x16x32_bf16 v[84:87], v[152:155], v[184:187], v[84:87]
	v_mfma_f32_16x16x32_bf16 v[80:83], v[138:141], v[192:195], v[80:83]
	v_mfma_f32_16x16x32_bf16 v[76:79], v[152:155], v[192:195], v[76:79]
	v_mfma_f32_16x16x32_bf16 v[72:75], v[138:141], v[214:217], v[72:75]
	v_mfma_f32_16x16x32_bf16 v[68:71], v[152:155], v[214:217], v[68:71]
	v_mfma_f32_16x16x32_bf16 v[96:99], v[142:145], v[180:183], v[96:99]
	v_mfma_f32_16x16x32_bf16 v[92:95], v[156:159], v[180:183], v[92:95]
	v_mfma_f32_16x16x32_bf16 v[88:91], v[142:145], v[188:191], v[88:91]
	v_mfma_f32_16x16x32_bf16 v[84:87], v[156:159], v[188:191], v[84:87]
	v_mfma_f32_16x16x32_bf16 v[80:83], v[142:145], v[210:213], v[80:83]
	v_mfma_f32_16x16x32_bf16 v[76:79], v[156:159], v[210:213], v[76:79]
	v_mfma_f32_16x16x32_bf16 v[72:75], v[142:145], v[218:221], v[72:75]
	v_mfma_f32_16x16x32_bf16 v[68:71], v[156:159], v[218:221], v[68:71]
	v_mfma_f32_16x16x32_bf16 v[32:35], v[160:163], v[176:179], v[32:35]
	v_mfma_f32_16x16x32_bf16 v[28:31], v[168:171], v[176:179], v[28:31]
	v_mfma_f32_16x16x32_bf16 v[24:27], v[160:163], v[184:187], v[24:27]
	v_mfma_f32_16x16x32_bf16 v[20:23], v[168:171], v[184:187], v[20:23]
	v_mfma_f32_16x16x32_bf16 v[16:19], v[160:163], v[192:195], v[16:19]
	v_mfma_f32_16x16x32_bf16 v[12:15], v[168:171], v[192:195], v[12:15]
	v_mfma_f32_16x16x32_bf16 v[8:11], v[160:163], v[214:217], v[8:11]
	v_mfma_f32_16x16x32_bf16 v[4:7], v[168:171], v[214:217], v[4:7]
	v_mfma_f32_16x16x32_bf16 v[32:35], v[164:167], v[180:183], v[32:35]
	v_mfma_f32_16x16x32_bf16 v[28:31], v[172:175], v[180:183], v[28:31]
	v_mfma_f32_16x16x32_bf16 v[24:27], v[164:167], v[188:191], v[24:27]
	v_mfma_f32_16x16x32_bf16 v[20:23], v[172:175], v[188:191], v[20:23]
	v_mfma_f32_16x16x32_bf16 v[16:19], v[164:167], v[210:213], v[16:19]
	v_mfma_f32_16x16x32_bf16 v[12:15], v[172:175], v[210:213], v[12:15]
	v_mfma_f32_16x16x32_bf16 v[8:11], v[164:167], v[218:221], v[8:11]
	v_mfma_f32_16x16x32_bf16 v[4:7], v[172:175], v[218:221], v[4:7]
	s_setprio 0
	s_barrier
	s_movk_i32 s22, 0x100
	s_andn2_b64 vcc, exec, s[4:5]
	s_mov_b64 s[46:47], -1
	s_mov_b64 s[4:5], 0
	s_cbranch_vccz .LBB0_732
	s_and_b64 vcc, exec, s[12:13]
	s_cbranch_vccz .LBB0_735
	s_barrier

; #define PG8_STAGE(bufoff, gbase, voff) do { _Pragma("unroll") for (int _i = 0; _i < 2; ++_i) \
;         __builtin_amdgcn_global_load_lds((const unsigned*)((const char*)(gbase) + (voff)[_i]), (LAS unsigned*)(lds + (bufoff) + ldsw + _i * 8192), 16, 0, 0); } while (0)
; #define PG8_LDA(dst, b, h) do { _Pragma("unroll") for (int m = 0; m < 4; ++m) _Pragma("unroll") for (int k = 0; k < 2; ++k) dst[m][k] = *(const LAS bf16x8*)(lds + PG8_SA(b, h) + aoff + m * 2048 + k * 1024); } while (0)
; #define PG8_LDB(dst, b, h) do { _Pragma("unroll") for (int n = 0; n < 2; ++n) _Pragma("unroll") for (int k = 0; k < 2; ++k) dst[n][k] = *(const LAS bf16x8*)(lds + PG8_SB(b, h) + boff + n * 2048 + k * 1024); } while (0)
; #define PG8_MMA(ai, bj, At, Bt) do { __builtin_amdgcn_s_setprio(1); _Pragma("unroll") for (int m = 0; m < 4; ++m) _Pragma("unroll") for (int n = 0; n < 2; ++n) _Pragma("unroll") for (int k = 0; k < 2; ++k) \
;         acc[ai][bj][m][n] = __builtin_amdgcn_mfma_f32_16x16x32_bf16(Bt[n][k], At[m][k], acc[ai][bj][m][n], 0, 0, 0); __builtin_amdgcn_s_setprio(0); } while (0)
; #define PG8_WAIT_V(n) asm volatile("s_waitcnt vmcnt(" #n ")" ::: "memory")
; #define PG8_WAIT_L(n) asm volatile("s_waitcnt lgkmcnt(" #n ")" ::: "memory")
; #define PG8_BAR __builtin_amdgcn_s_barrier()
; #define PG8_SCHED __builtin_amdgcn_sched_barrier(0)
; template <class Epi>
; __device__ __forceinline__ void gemm_phase(LAS unsigned char* lds, const Gemm g, const StaticOrder& S, const Epi& E) {
;     ...
;             const bool last = (t == nt - 2);
;             const char* a1 = cA + (size_t)(t + 1) * kstep;
;             const char* a2 = last ? nA : cA + (size_t)(t + 2) * kstep; const char* b2 = last ? nB : cB + (size_t)(t + 2) * kstep;
;             const char* a3 = a2 + kstep; const char* b3 = b2 + kstep;
;             PG8_LDB(B0, 0, 0); PG8_LDB(B1, 0, 1); PG8_SCHED; PG8_LDA(At, 0, 0); PG8_STAGE(PG8_SA(1, 1), a1 + hstepA, voffA);
;             PG8_WAIT_V(8); PG8_WAIT_L(0); PG8_BAR; PG8_MMA(0, 0, At, B0); PG8_MMA(0, 1, At, B1); PG8_BAR; PG8_SCHED;
;             PG8_LDA(At, 0, 1); PG8_STAGE(PG8_SB(0, 0), b2, voffB); PG8_STAGE(PG8_SB(0, 1), b2 + hstepB, voffB); PG8_STAGE(PG8_SA(0, 0), a2, voffA);
;             PG8_WAIT_V(8); PG8_WAIT_L(0); PG8_BAR; PG8_MMA(1, 0, At, B0); PG8_MMA(1, 1, At, B1); PG8_BAR; PG8_SCHED;
.LBB0_880:
	s_add_u32 s22, s48, 0xfffc0080
	s_addc_u32 s23, s49, -1
	s_add_i32 s72, 0, 0x10000
	s_cmp_eq_u32 s71, 12
	s_cselect_b32 s51, s39, s23
	s_cselect_b32 s50, s67, s22
	v_add_u32_e32 v150, s72, v152
	s_cselect_b32 s23, s35, s70
	s_cselect_b32 s22, s68, s69
	s_add_i32 s74, 0, 0x14000
	ds_read_b128 v[142:145], v150
	ds_read_b128 v[146:149], v150 offset:1024
	ds_read_b128 v[156:159], v150 offset:2048
	ds_read_b128 v[160:163], v150 offset:3072
	v_add_u32_e32 v150, s74, v152
	ds_read_b128 v[164:167], v150
	ds_read_b128 v[168:171], v150 offset:1024
	ds_read_b128 v[172:175], v150 offset:2048
	ds_read_b128 v[176:179], v150 offset:3072
	v_lshl_add_u64 v[150:151], s[48:49], 0, v[138:139]
	s_add_i32 m0, s58, 0xc000
	ds_read_b128 v[180:183], v154
	ds_read_b128 v[184:187], v154 offset:1024
	ds_read_b128 v[188:191], v154 offset:2048
	ds_read_b128 v[192:195], v154 offset:3072
	ds_read_b128 v[210:213], v154 offset:4096
	ds_read_b128 v[214:217], v154 offset:5120
	ds_read_b128 v[218:221], v154 offset:6144
	ds_read_b128 v[222:225], v154 offset:7168
	global_load_lds_dwordx4 v[150:151], off
	v_lshl_add_u64 v[150:151], s[48:49], 0, v[140:141]
	s_add_i32 m0, s58, 0xe000
	s_nop 0
	global_load_lds_dwordx4 v[150:151], off
	s_waitcnt vmcnt(8)
	s_waitcnt lgkmcnt(0)
	s_barrier
	s_setprio 1
	v_mfma_f32_16x16x32_bf16 v[128:131], v[142:145], v[180:183], v[128:131]
	v_mfma_f32_16x16x32_bf16 v[124:127], v[156:159], v[180:183], v[124:127]
	v_mfma_f32_16x16x32_bf16 v[112:115], v[142:145], v[188:191], v[112:115]
	v_mfma_f32_16x16x32_bf16 v[108:111], v[156:159], v[188:191], v[108:111]
	v_mfma_f32_16x16x32_bf16 v[96:99], v[142:145], v[210:213], v[96:99]
	v_mfma_f32_16x16x32_bf16 v[92:95], v[156:159], v[210:213], v[92:95]
	v_mfma_f32_16x16x32_bf16 v[80:83], v[142:145], v[218:221], v[80:83]
	v_mfma_f32_16x16x32_bf16 v[76:79], v[156:159], v[218:221], v[76:79]
	v_mfma_f32_16x16x32_bf16 v[128:131], v[146:149], v[184:187], v[128:131]
	v_mfma_f32_16x16x32_bf16 v[124:127], v[160:163], v[184:187], v[124:127]
	v_mfma_f32_16x16x32_bf16 v[112:115], v[146:149], v[192:195], v[112:115]
	v_mfma_f32_16x16x32_bf16 v[108:111], v[160:163], v[192:195], v[108:111]
	v_mfma_f32_16x16x32_bf16 v[96:99], v[146:149], v[214:217], v[96:99]
	v_mfma_f32_16x16x32_bf16 v[92:95], v[160:163], v[214:217], v[92:95]
	v_mfma_f32_16x16x32_bf16 v[80:83], v[146:149], v[222:225], v[80:83]
	v_mfma_f32_16x16x32_bf16 v[76:79], v[160:163], v[222:225], v[76:79]
	v_mfma_f32_16x16x32_bf16 v[120:123], v[164:167], v[180:183], v[120:123]
	v_mfma_f32_16x16x32_bf16 v[116:119], v[172:175], v[180:183], v[116:119]
	v_mfma_f32_16x16x32_bf16 v[104:107], v[164:167], v[188:191], v[104:107]
	v_mfma_f32_16x16x32_bf16 v[100:103], v[172:175], v[188:191], v[100:103]
	v_mfma_f32_16x16x32_bf16 v[88:91], v[164:167], v[210:213], v[88:91]
	v_mfma_f32_16x16x32_bf16 v[84:87], v[172:175], v[210:213], v[84:87]
	v_mfma_f32_16x16x32_bf16 v[72:75], v[164:167], v[218:221], v[72:75]
	v_mfma_f32_16x16x32_bf16 v[68:71], v[172:175], v[218:221], v[68:71]
	v_mfma_f32_16x16x32_bf16 v[120:123], v[168:171], v[184:187], v[120:123]
	v_mfma_f32_16x16x32_bf16 v[116:119], v[176:179], v[184:187], v[116:119]
	v_mfma_f32_16x16x32_bf16 v[104:107], v[168:171], v[192:195], v[104:107]
	v_mfma_f32_16x16x32_bf16 v[100:103], v[176:179], v[192:195], v[100:103]
	v_mfma_f32_16x16x32_bf16 v[88:91], v[168:171], v[214:217], v[88:91]
	v_mfma_f32_16x16x32_bf16 v[84:87], v[176:179], v[214:217], v[84:87]
	v_mfma_f32_16x16x32_bf16 v[72:75], v[168:171], v[222:225], v[72:75]
	v_mfma_f32_16x16x32_bf16 v[68:71], v[176:179], v[222:225], v[68:71]
	s_setprio 0
	s_barrier
	s_add_i32 s72, s72, s57
	v_lshl_add_u64 v[150:151], s[22:23], 0, v[134:135]
	s_mov_b32 m0, s72
	ds_read_b128 v[180:183], v154 offset:16384
	ds_read_b128 v[184:187], v154 offset:17408
	ds_read_b128 v[188:191], v154 offset:18432
	ds_read_b128 v[192:195], v154 offset:19456
	ds_read_b128 v[210:213], v154 offset:20480
	ds_read_b128 v[214:217], v154 offset:21504
	ds_read_b128 v[218:221], v154 offset:22528
	ds_read_b128 v[222:225], v154 offset:23552
	global_load_lds_dwordx4 v[150:151], off
	s_add_i32 m0, s72, 0x2000
	s_add_u32 s72, s22, 0x10000
	v_lshl_add_u64 v[196:197], s[22:23], 0, v[0:1]
	s_addc_u32 s73, s23, 0
	s_add_i32 s74, s74, s57
	global_load_lds_dwordx4 v[196:197], off
	v_lshl_add_u64 v[198:199], s[72:73], 0, v[134:135]
	s_mov_b32 m0, s74
	v_lshl_add_u64 v[226:227], s[50:51], 0, v[132:133]
	global_load_lds_dwordx4 v[198:199], off
	v_lshl_add_u64 v[198:199], s[72:73], 0, v[0:1]
	s_add_i32 m0, s74, 0x2000
	s_nop 0
	global_load_lds_dwordx4 v[198:199], off
	v_lshl_add_u64 v[198:199], s[50:51], 0, v[136:137]
	s_mov_b32 m0, s58
	s_nop 0
	global_load_lds_dwordx4 v[198:199], off
	s_mov_b32 m0, s59
	s_nop 0
	global_load_lds_dwordx4 v[226:227], off
	s_waitcnt vmcnt(8)
	s_waitcnt lgkmcnt(0)
	s_barrier
; #define PG8_STAGE(bufoff, gbase, voff) do { _Pragma("unroll") for (int _i = 0; _i < 2; ++_i) \
;         __builtin_amdgcn_global_load_lds((const unsigned*)((const char*)(gbase) + (voff)[_i]), (LAS unsigned*)(lds + (bufoff) + ldsw + _i * 8192), 16, 0, 0); } while (0)
; #define PG8_LDA(dst, b, h) do { _Pragma("unroll") for (int m = 0; m < 4; ++m) _Pragma("unroll") for (int k = 0; k < 2; ++k) dst[m][k] = *(const LAS bf16x8*)(lds + PG8_SA(b, h) + aoff + m * 2048 + k * 1024); } while (0)
; #define PG8_LDB(dst, b, h) do { _Pragma("unroll") for (int n = 0; n < 2; ++n) _Pragma("unroll") for (int k = 0; k < 2; ++k) dst[n][k] = *(const LAS bf16x8*)(lds + PG8_SB(b, h) + boff + n * 2048 + k * 1024); } while (0)
; #define PG8_MMA(ai, bj, At, Bt) do { __builtin_amdgcn_s_setprio(1); _Pragma("unroll") for (int m = 0; m < 4; ++m) _Pragma("unroll") for (int n = 0; n < 2; ++n) _Pragma("unroll") for (int k = 0; k < 2; ++k) \
;         acc[ai][bj][m][n] = __builtin_amdgcn_mfma_f32_16x16x32_bf16(Bt[n][k], At[m][k], acc[ai][bj][m][n], 0, 0, 0); __builtin_amdgcn_s_setprio(0); } while (0)
; #define PG8_WAIT_V(n) asm volatile("s_waitcnt vmcnt(" #n ")" ::: "memory")
; #define PG8_WAIT_L(n) asm volatile("s_waitcnt lgkmcnt(" #n ")" ::: "memory")
; #define PG8_BAR __builtin_amdgcn_s_barrier()
; #define PG8_SCHED __builtin_amdgcn_sched_barrier(0)
; template <class Epi>
; __device__ __forceinline__ void gemm_phase(LAS unsigned char* lds, const Gemm g, const StaticOrder& S, const Epi& E) {
;     ...
;             PG8_WAIT_V(8); PG8_WAIT_L(0); PG8_BAR; PG8_MMA(1, 0, At, B0); PG8_MMA(1, 1, At, B1); PG8_BAR; PG8_SCHED;
;             PG8_LDB(B0, 1, 0); PG8_LDB(B1, 1, 1); PG8_SCHED; PG8_LDA(At, 1, 0); PG8_STAGE(PG8_SA(0, 1), a2 + hstepA, voffA);
;             PG8_WAIT_V(8); PG8_WAIT_L(0); PG8_BAR; PG8_MMA(0, 0, At, B0); PG8_MMA(0, 1, At, B1); PG8_BAR; PG8_SCHED;
	s_setprio 1
	v_mfma_f32_16x16x32_bf16 v[64:67], v[142:145], v[180:183], v[64:67]
	v_mfma_f32_16x16x32_bf16 v[60:63], v[156:159], v[180:183], v[60:63]
	v_mfma_f32_16x16x32_bf16 v[48:51], v[142:145], v[188:191], v[48:51]
	v_mfma_f32_16x16x32_bf16 v[44:47], v[156:159], v[188:191], v[44:47]
	v_mfma_f32_16x16x32_bf16 v[32:35], v[142:145], v[210:213], v[32:35]
	v_mfma_f32_16x16x32_bf16 v[28:31], v[156:159], v[210:213], v[28:31]
	v_mfma_f32_16x16x32_bf16 v[16:19], v[142:145], v[218:221], v[16:19]
	v_mfma_f32_16x16x32_bf16 v[12:15], v[156:159], v[218:221], v[12:15]
	v_mfma_f32_16x16x32_bf16 v[64:67], v[146:149], v[184:187], v[64:67]
	v_mfma_f32_16x16x32_bf16 v[60:63], v[160:163], v[184:187], v[60:63]
	v_mfma_f32_16x16x32_bf16 v[48:51], v[146:149], v[192:195], v[48:51]
	v_mfma_f32_16x16x32_bf16 v[44:47], v[160:163], v[192:195], v[44:47]
	v_mfma_f32_16x16x32_bf16 v[32:35], v[146:149], v[214:217], v[32:35]
	v_mfma_f32_16x16x32_bf16 v[28:31], v[160:163], v[214:217], v[28:31]
	v_mfma_f32_16x16x32_bf16 v[16:19], v[146:149], v[222:225], v[16:19]
	v_mfma_f32_16x16x32_bf16 v[12:15], v[160:163], v[222:225], v[12:15]
	v_mfma_f32_16x16x32_bf16 v[56:59], v[164:167], v[180:183], v[56:59]
	v_mfma_f32_16x16x32_bf16 v[52:55], v[172:175], v[180:183], v[52:55]
	v_mfma_f32_16x16x32_bf16 v[40:43], v[164:167], v[188:191], v[40:43]
	v_mfma_f32_16x16x32_bf16 v[36:39], v[172:175], v[188:191], v[36:39]
	v_mfma_f32_16x16x32_bf16 v[24:27], v[164:167], v[210:213], v[24:27]
	v_mfma_f32_16x16x32_bf16 v[20:23], v[172:175], v[210:213], v[20:23]
	v_mfma_f32_16x16x32_bf16 v[8:11], v[164:167], v[218:221], v[8:11]
	v_mfma_f32_16x16x32_bf16 v[4:7], v[172:175], v[218:221], v[4:7]
	v_mfma_f32_16x16x32_bf16 v[56:59], v[168:171], v[184:187], v[56:59]
	v_mfma_f32_16x16x32_bf16 v[52:55], v[176:179], v[184:187], v[52:55]
	v_mfma_f32_16x16x32_bf16 v[40:43], v[168:171], v[192:195], v[40:43]
	v_mfma_f32_16x16x32_bf16 v[36:39], v[176:179], v[192:195], v[36:39]
	v_mfma_f32_16x16x32_bf16 v[24:27], v[168:171], v[214:217], v[24:27]
	v_mfma_f32_16x16x32_bf16 v[20:23], v[176:179], v[214:217], v[20:23]
	v_mfma_f32_16x16x32_bf16 v[8:11], v[168:171], v[222:225], v[8:11]
	v_mfma_f32_16x16x32_bf16 v[4:7], v[176:179], v[222:225], v[4:7]
	s_setprio 0
	s_barrier
	s_add_i32 s72, 0, 0x18000
	v_add_u32_e32 v155, s72, v152
	s_add_i32 s73, 0, 0x1c000
	ds_read_b128 v[142:145], v155
	ds_read_b128 v[146:149], v155 offset:1024
	ds_read_b128 v[156:159], v155 offset:2048
	ds_read_b128 v[160:163], v155 offset:3072
	v_add_u32_e32 v155, s73, v152
	ds_read_b128 v[164:167], v155
	ds_read_b128 v[168:171], v155 offset:1024
	ds_read_b128 v[172:175], v155 offset:2048
	ds_read_b128 v[176:179], v155 offset:3072
	s_add_u32 s50, s50, 0x40000
	s_addc_u32 s51, s51, 0
	s_mov_b32 m0, s60
	v_lshl_add_u64 v[228:229], s[50:51], 0, v[136:137]
	ds_read_b128 v[180:183], v154 offset:32768
	ds_read_b128 v[184:187], v154 offset:33792
	ds_read_b128 v[188:191], v154 offset:34816
	ds_read_b128 v[192:195], v154 offset:35840
	ds_read_b128 v[210:213], v154 offset:36864
	ds_read_b128 v[214:217], v154 offset:37888
	ds_read_b128 v[218:221], v154 offset:38912
	ds_read_b128 v[222:225], v154 offset:39936
	global_load_lds_dwordx4 v[228:229], off
	v_lshl_add_u64 v[228:229], s[50:51], 0, v[132:133]
	s_mov_b32 m0, s61
	s_nop 0
	global_load_lds_dwordx4 v[228:229], off
	s_waitcnt vmcnt(8)
	s_waitcnt lgkmcnt(0)
	s_barrier
	s_setprio 1
	v_mfma_f32_16x16x32_bf16 v[128:131], v[142:145], v[180:183], v[128:131]
	v_mfma_f32_16x16x32_bf16 v[124:127], v[156:159], v[180:183], v[124:127]
	v_mfma_f32_16x16x32_bf16 v[112:115], v[142:145], v[188:191], v[112:115]
	v_mfma_f32_16x16x32_bf16 v[108:111], v[156:159], v[188:191], v[108:111]
	v_mfma_f32_16x16x32_bf16 v[96:99], v[142:145], v[210:213], v[96:99]
	v_mfma_f32_16x16x32_bf16 v[92:95], v[156:159], v[210:213], v[92:95]
	v_mfma_f32_16x16x32_bf16 v[80:83], v[142:145], v[218:221], v[80:83]
	v_mfma_f32_16x16x32_bf16 v[76:79], v[156:159], v[218:221], v[76:79]
	v_mfma_f32_16x16x32_bf16 v[128:131], v[146:149], v[184:187], v[128:131]
	v_mfma_f32_16x16x32_bf16 v[124:127], v[160:163], v[184:187], v[124:127]
	v_mfma_f32_16x16x32_bf16 v[112:115], v[146:149], v[192:195], v[112:115]
	v_mfma_f32_16x16x32_bf16 v[108:111], v[160:163], v[192:195], v[108:111]
	v_mfma_f32_16x16x32_bf16 v[96:99], v[146:149], v[214:217], v[96:99]
	v_mfma_f32_16x16x32_bf16 v[92:95], v[160:163], v[214:217], v[92:95]
	v_mfma_f32_16x16x32_bf16 v[80:83], v[146:149], v[222:225], v[80:83]
	v_mfma_f32_16x16x32_bf16 v[76:79], v[160:163], v[222:225], v[76:79]
	v_mfma_f32_16x16x32_bf16 v[120:123], v[164:167], v[180:183], v[120:123]
	v_mfma_f32_16x16x32_bf16 v[116:119], v[172:175], v[180:183], v[116:119]
	v_mfma_f32_16x16x32_bf16 v[104:107], v[164:167], v[188:191], v[104:107]
	v_mfma_f32_16x16x32_bf16 v[100:103], v[172:175], v[188:191], v[100:103]
	v_mfma_f32_16x16x32_bf16 v[88:91], v[164:167], v[210:213], v[88:91]
	v_mfma_f32_16x16x32_bf16 v[84:87], v[172:175], v[210:213], v[84:87]
	v_mfma_f32_16x16x32_bf16 v[72:75], v[164:167], v[218:221], v[72:75]
	v_mfma_f32_16x16x32_bf16 v[68:71], v[172:175], v[218:221], v[68:71]
	v_mfma_f32_16x16x32_bf16 v[120:123], v[168:171], v[184:187], v[120:123]
	v_mfma_f32_16x16x32_bf16 v[116:119], v[176:179], v[184:187], v[116:119]
	v_mfma_f32_16x16x32_bf16 v[104:107], v[168:171], v[192:195], v[104:107]
	v_mfma_f32_16x16x32_bf16 v[100:103], v[176:179], v[192:195], v[100:103]
	v_mfma_f32_16x16x32_bf16 v[88:91], v[168:171], v[214:217], v[88:91]
	v_mfma_f32_16x16x32_bf16 v[84:87], v[176:179], v[214:217], v[84:87]
	v_mfma_f32_16x16x32_bf16 v[72:75], v[168:171], v[222:225], v[72:75]
	v_mfma_f32_16x16x32_bf16 v[68:71], v[176:179], v[222:225], v[68:71]
	s_setprio 0
	s_barrier
; #define PG8_STAGE(bufoff, gbase, voff) do { _Pragma("unroll") for (int _i = 0; _i < 2; ++_i) \
;         __builtin_amdgcn_global_load_lds((const unsigned*)((const char*)(gbase) + (voff)[_i]), (LAS unsigned*)(lds + (bufoff) + ldsw + _i * 8192), 16, 0, 0); } while (0)
; #define PG8_LDA(dst, b, h) do { _Pragma("unroll") for (int m = 0; m < 4; ++m) _Pragma("unroll") for (int k = 0; k < 2; ++k) dst[m][k] = *(const LAS bf16x8*)(lds + PG8_SA(b, h) + aoff + m * 2048 + k * 1024); } while (0)
; #define PG8_MMA(ai, bj, At, Bt) do { __builtin_amdgcn_s_setprio(1); _Pragma("unroll") for (int m = 0; m < 4; ++m) _Pragma("unroll") for (int n = 0; n < 2; ++n) _Pragma("unroll") for (int k = 0; k < 2; ++k) \
;         acc[ai][bj][m][n] = __builtin_amdgcn_mfma_f32_16x16x32_bf16(Bt[n][k], At[m][k], acc[ai][bj][m][n], 0, 0, 0); __builtin_amdgcn_s_setprio(0); } while (0)
; #define PG8_WAIT_V(n) asm volatile("s_waitcnt vmcnt(" #n ")" ::: "memory")
; #define PG8_WAIT_L(n) asm volatile("s_waitcnt lgkmcnt(" #n ")" ::: "memory")
; #define PG8_BAR __builtin_amdgcn_s_barrier()
; #define PG8_SCHED __builtin_amdgcn_sched_barrier(0)
; template <class Epi>
; __device__ __forceinline__ void gemm_phase(LAS unsigned char* lds, const Gemm g, const StaticOrder& S, const Epi& E) {
;     ...
;             PG8_LDA(At, 1, 1); PG8_STAGE(PG8_SB(1, 0), b3, voffB); PG8_STAGE(PG8_SB(1, 1), b3 + hstepB, voffB); PG8_STAGE(PG8_SA(1, 0), a3, voffA);
;             PG8_WAIT_V(8); PG8_WAIT_L(0); PG8_BAR; PG8_MMA(1, 0, At, B0); PG8_MMA(1, 1, At, B1); PG8_BAR; PG8_SCHED;
;         }
;         if (wr == 0) PG8_BAR;
	s_add_i32 s50, s72, s57
	v_lshl_add_u64 v[150:151], v[150:151], 0, s[30:31]
	s_mov_b32 m0, s50
	ds_read_b128 v[180:183], v154 offset:49152
	ds_read_b128 v[184:187], v154 offset:50176
	ds_read_b128 v[188:191], v154 offset:51200
	ds_read_b128 v[192:195], v154 offset:52224
	ds_read_b128 v[210:213], v154 offset:53248
	ds_read_b128 v[214:217], v154 offset:54272
	ds_read_b128 v[218:221], v154 offset:55296
	ds_read_b128 v[222:225], v154 offset:56320
	global_load_lds_dwordx4 v[150:151], off
	s_add_i32 m0, s50, 0x2000
	s_add_u32 s22, s22, 0x10080
	v_lshl_add_u64 v[150:151], v[196:197], 0, s[30:31]
	s_addc_u32 s23, s23, 0
	s_add_i32 s50, s73, s57
	global_load_lds_dwordx4 v[150:151], off
	v_lshl_add_u64 v[150:151], s[22:23], 0, v[134:135]
	s_mov_b32 m0, s50
	s_nop 0
	global_load_lds_dwordx4 v[150:151], off
	v_lshl_add_u64 v[150:151], s[22:23], 0, v[0:1]
	s_add_i32 m0, s50, 0x2000
	s_nop 0
	global_load_lds_dwordx4 v[150:151], off
	v_lshl_add_u64 v[150:151], v[198:199], 0, s[30:31]
	s_mov_b32 m0, s62
	s_nop 0
	global_load_lds_dwordx4 v[150:151], off
	v_lshl_add_u64 v[150:151], v[226:227], 0, s[30:31]
	s_mov_b32 m0, s63
	s_nop 0
	global_load_lds_dwordx4 v[150:151], off
	s_waitcnt vmcnt(8)
	s_waitcnt lgkmcnt(0)
	s_barrier
	s_setprio 1
	v_mfma_f32_16x16x32_bf16 v[64:67], v[142:145], v[180:183], v[64:67]
	v_mfma_f32_16x16x32_bf16 v[60:63], v[156:159], v[180:183], v[60:63]
	v_mfma_f32_16x16x32_bf16 v[48:51], v[142:145], v[188:191], v[48:51]
	v_mfma_f32_16x16x32_bf16 v[44:47], v[156:159], v[188:191], v[44:47]
	v_mfma_f32_16x16x32_bf16 v[32:35], v[142:145], v[210:213], v[32:35]
	v_mfma_f32_16x16x32_bf16 v[28:31], v[156:159], v[210:213], v[28:31]
	v_mfma_f32_16x16x32_bf16 v[16:19], v[142:145], v[218:221], v[16:19]
	v_mfma_f32_16x16x32_bf16 v[12:15], v[156:159], v[218:221], v[12:15]
	v_mfma_f32_16x16x32_bf16 v[64:67], v[146:149], v[184:187], v[64:67]
	v_mfma_f32_16x16x32_bf16 v[60:63], v[160:163], v[184:187], v[60:63]
	v_mfma_f32_16x16x32_bf16 v[48:51], v[146:149], v[192:195], v[48:51]
	v_mfma_f32_16x16x32_bf16 v[44:47], v[160:163], v[192:195], v[44:47]
	v_mfma_f32_16x16x32_bf16 v[32:35], v[146:149], v[214:217], v[32:35]
	v_mfma_f32_16x16x32_bf16 v[28:31], v[160:163], v[214:217], v[28:31]
	v_mfma_f32_16x16x32_bf16 v[16:19], v[146:149], v[222:225], v[16:19]
	v_mfma_f32_16x16x32_bf16 v[12:15], v[160:163], v[222:225], v[12:15]
	v_mfma_f32_16x16x32_bf16 v[56:59], v[164:167], v[180:183], v[56:59]
	v_mfma_f32_16x16x32_bf16 v[52:55], v[172:175], v[180:183], v[52:55]
	v_mfma_f32_16x16x32_bf16 v[40:43], v[164:167], v[188:191], v[40:43]
	v_mfma_f32_16x16x32_bf16 v[36:39], v[172:175], v[188:191], v[36:39]
	v_mfma_f32_16x16x32_bf16 v[24:27], v[164:167], v[210:213], v[24:27]
	v_mfma_f32_16x16x32_bf16 v[20:23], v[172:175], v[210:213], v[20:23]
	v_mfma_f32_16x16x32_bf16 v[8:11], v[164:167], v[218:221], v[8:11]
	v_mfma_f32_16x16x32_bf16 v[4:7], v[172:175], v[218:221], v[4:7]
	v_mfma_f32_16x16x32_bf16 v[56:59], v[168:171], v[184:187], v[56:59]
	v_mfma_f32_16x16x32_bf16 v[52:55], v[176:179], v[184:187], v[52:55]
	v_mfma_f32_16x16x32_bf16 v[40:43], v[168:171], v[192:195], v[40:43]
	v_mfma_f32_16x16x32_bf16 v[36:39], v[176:179], v[192:195], v[36:39]
	v_mfma_f32_16x16x32_bf16 v[24:27], v[168:171], v[214:217], v[24:27]
	v_mfma_f32_16x16x32_bf16 v[20:23], v[176:179], v[214:217], v[20:23]
	v_mfma_f32_16x16x32_bf16 v[8:11], v[168:171], v[222:225], v[8:11]
	v_mfma_f32_16x16x32_bf16 v[4:7], v[176:179], v[222:225], v[4:7]
	s_setprio 0
	s_barrier
	s_add_i32 s71, s71, 2
	s_add_u32 s48, s48, 0x100
	s_addc_u32 s49, s49, 0
	s_add_u32 s69, s69, 0x100
	s_addc_u32 s70, s70, 0
	s_cmp_gt_u32 s71, 13
	s_cbranch_scc0 .LBB0_880
	s_and_b64 vcc, exec, s[14:15]
	s_cbranch_vccz .LBB0_883
	s_barrier

; #define PG8_STAGE(bufoff, gbase, voff) do { _Pragma("unroll") for (int _i = 0; _i < 2; ++_i) \
;         __builtin_amdgcn_global_load_lds((const unsigned*)((const char*)(gbase) + (voff)[_i]), (LAS unsigned*)(lds + (bufoff) + ldsw + _i * 8192), 16, 0, 0); } while (0)
; #define PG8_LDA(dst, b, h) do { _Pragma("unroll") for (int m = 0; m < 4; ++m) _Pragma("unroll") for (int k = 0; k < 2; ++k) dst[m][k] = *(const LAS bf16x8*)(lds + PG8_SA(b, h) + aoff + m * 2048 + k * 1024); } while (0)
; #define PG8_LDB(dst, b, h) do { _Pragma("unroll") for (int n = 0; n < 2; ++n) _Pragma("unroll") for (int k = 0; k < 2; ++k) dst[n][k] = *(const LAS bf16x8*)(lds + PG8_SB(b, h) + boff + n * 2048 + k * 1024); } while (0)
; #define PG8_MMA(ai, bj, At, Bt) do { __builtin_amdgcn_s_setprio(1); _Pragma("unroll") for (int m = 0; m < 4; ++m) _Pragma("unroll") for (int n = 0; n < 2; ++n) _Pragma("unroll") for (int k = 0; k < 2; ++k) \
;         acc[ai][bj][m][n] = __builtin_amdgcn_mfma_f32_16x16x32_bf16(Bt[n][k], At[m][k], acc[ai][bj][m][n], 0, 0, 0); __builtin_amdgcn_s_setprio(0); } while (0)
; #define PG8_WAIT_V(n) asm volatile("s_waitcnt vmcnt(" #n ")" ::: "memory")
; #define PG8_WAIT_L(n) asm volatile("s_waitcnt lgkmcnt(" #n ")" ::: "memory")
; #define PG8_BAR __builtin_amdgcn_s_barrier()
; #define PG8_SCHED __builtin_amdgcn_sched_barrier(0)
; template <class Epi>
; __device__ __forceinline__ void gemm_phase(LAS unsigned char* lds, const Gemm g, const StaticOrder& S, const Epi& E) {
;     ...
;             const bool last = (t == nt - 2);
;             const char* a1 = cA + (size_t)(t + 1) * kstep;
;             const char* a2 = last ? nA : cA + (size_t)(t + 2) * kstep; const char* b2 = last ? nB : cB + (size_t)(t + 2) * kstep;
;             const char* a3 = a2 + kstep; const char* b3 = b2 + kstep;
;             PG8_LDB(B0, 0, 0); PG8_LDB(B1, 0, 1); PG8_SCHED; PG8_LDA(At, 0, 0); PG8_STAGE(PG8_SA(1, 1), a1 + hstepA, voffA);
;             PG8_WAIT_V(8); PG8_WAIT_L(0); PG8_BAR; PG8_MMA(0, 0, At, B0); PG8_MMA(0, 1, At, B1); PG8_BAR; PG8_SCHED;
;             PG8_LDA(At, 0, 1); PG8_STAGE(PG8_SB(0, 0), b2, voffB); PG8_STAGE(PG8_SB(0, 1), b2 + hstepB, voffB); PG8_STAGE(PG8_SA(0, 0), a2, voffA);
;             PG8_WAIT_V(8); PG8_WAIT_L(0); PG8_BAR; PG8_MMA(1, 0, At, B0); PG8_MMA(1, 1, At, B1); PG8_BAR; PG8_SCHED;
.LBB0_902:
	s_add_u32 s22, s50, s4
	s_addc_u32 s23, s51, s5
	s_add_u32 s22, s22, 0x100
	s_addc_u32 s23, s23, 0
	s_add_u32 s73, s70, s4
	s_addc_u32 s74, s71, s5
	s_add_i32 s75, 0, 0x10000
	s_cmpk_eq_i32 s4, 0x300
	s_cselect_b32 s53, s47, s23
	s_cselect_b32 s52, s46, s22
	s_cselect_b32 s23, s41, s74
	s_cselect_b32 s22, s45, s73
	s_add_i32 s73, 0, 0x14000
	v_add_u32_e32 v148, s75, v242
	v_add_u32_e32 v164, s73, v242
	ds_read_b128 v[136:139], v148
	ds_read_b128 v[140:143], v148 offset:1024
	ds_read_b128 v[144:147], v148 offset:2048
	ds_read_b128 v[148:151], v148 offset:3072
	ds_read_b128 v[152:155], v164
	ds_read_b128 v[156:159], v164 offset:1024
	ds_read_b128 v[160:163], v164 offset:2048
	ds_read_b128 v[164:167], v164 offset:3072
	v_lshl_add_u64 v[196:197], v[134:135], 0, s[4:5]
	s_add_i32 m0, s61, 0xc000
	ds_read_b128 v[168:171], v244
	ds_read_b128 v[172:175], v244 offset:1024
	ds_read_b128 v[176:179], v244 offset:2048
	ds_read_b128 v[180:183], v244 offset:3072
	ds_read_b128 v[184:187], v244 offset:4096
	ds_read_b128 v[188:191], v244 offset:5120
	ds_read_b128 v[192:195], v244 offset:6144
	ds_read_b128 v[220:223], v244 offset:7168
	global_load_lds_dwordx4 v[196:197], off
	v_lshl_add_u64 v[196:197], v[132:133], 0, s[4:5]
	s_add_i32 m0, s61, 0xe000
	s_nop 0
	global_load_lds_dwordx4 v[196:197], off
	s_waitcnt vmcnt(8)
	s_waitcnt lgkmcnt(0)
	s_barrier
	s_setprio 1
	v_mfma_f32_16x16x32_bf16 v[128:131], v[136:139], v[168:171], v[128:131]
	v_mfma_f32_16x16x32_bf16 v[124:127], v[144:147], v[168:171], v[124:127]
	v_mfma_f32_16x16x32_bf16 v[112:115], v[136:139], v[176:179], v[112:115]
	v_mfma_f32_16x16x32_bf16 v[108:111], v[144:147], v[176:179], v[108:111]
	v_mfma_f32_16x16x32_bf16 v[96:99], v[136:139], v[184:187], v[96:99]
	v_mfma_f32_16x16x32_bf16 v[92:95], v[144:147], v[184:187], v[92:95]
	v_mfma_f32_16x16x32_bf16 v[80:83], v[136:139], v[192:195], v[80:83]
	v_mfma_f32_16x16x32_bf16 v[76:79], v[144:147], v[192:195], v[76:79]
	v_mfma_f32_16x16x32_bf16 v[128:131], v[140:143], v[172:175], v[128:131]
	v_mfma_f32_16x16x32_bf16 v[124:127], v[148:151], v[172:175], v[124:127]
	v_mfma_f32_16x16x32_bf16 v[112:115], v[140:143], v[180:183], v[112:115]
	v_mfma_f32_16x16x32_bf16 v[108:111], v[148:151], v[180:183], v[108:111]
	v_mfma_f32_16x16x32_bf16 v[96:99], v[140:143], v[188:191], v[96:99]
	v_mfma_f32_16x16x32_bf16 v[92:95], v[148:151], v[188:191], v[92:95]
	v_mfma_f32_16x16x32_bf16 v[80:83], v[140:143], v[220:223], v[80:83]
	v_mfma_f32_16x16x32_bf16 v[76:79], v[148:151], v[220:223], v[76:79]
	v_mfma_f32_16x16x32_bf16 v[120:123], v[152:155], v[168:171], v[120:123]
	v_mfma_f32_16x16x32_bf16 v[116:119], v[160:163], v[168:171], v[116:119]
	v_mfma_f32_16x16x32_bf16 v[104:107], v[152:155], v[176:179], v[104:107]
	v_mfma_f32_16x16x32_bf16 v[100:103], v[160:163], v[176:179], v[100:103]
	v_mfma_f32_16x16x32_bf16 v[88:91], v[152:155], v[184:187], v[88:91]
	v_mfma_f32_16x16x32_bf16 v[84:87], v[160:163], v[184:187], v[84:87]
	v_mfma_f32_16x16x32_bf16 v[72:75], v[152:155], v[192:195], v[72:75]
	v_mfma_f32_16x16x32_bf16 v[68:71], v[160:163], v[192:195], v[68:71]
	v_mfma_f32_16x16x32_bf16 v[120:123], v[156:159], v[172:175], v[120:123]
	v_mfma_f32_16x16x32_bf16 v[116:119], v[164:167], v[172:175], v[116:119]
	v_mfma_f32_16x16x32_bf16 v[104:107], v[156:159], v[180:183], v[104:107]
	v_mfma_f32_16x16x32_bf16 v[100:103], v[164:167], v[180:183], v[100:103]
	v_mfma_f32_16x16x32_bf16 v[88:91], v[156:159], v[188:191], v[88:91]
	v_mfma_f32_16x16x32_bf16 v[84:87], v[164:167], v[188:191], v[84:87]
	v_mfma_f32_16x16x32_bf16 v[72:75], v[156:159], v[220:223], v[72:75]
	v_mfma_f32_16x16x32_bf16 v[68:71], v[164:167], v[220:223], v[68:71]
	s_setprio 0
	s_barrier
	s_add_i32 s74, s75, s60
	v_lshl_add_u64 v[196:197], s[22:23], 0, v[212:213]
	s_mov_b32 m0, s74
	ds_read_b128 v[168:171], v244 offset:16384
	ds_read_b128 v[172:175], v244 offset:17408
	ds_read_b128 v[176:179], v244 offset:18432
	ds_read_b128 v[180:183], v244 offset:19456
	ds_read_b128 v[184:187], v244 offset:20480
	ds_read_b128 v[188:191], v244 offset:21504
	ds_read_b128 v[192:195], v244 offset:22528
	ds_read_b128 v[220:223], v244 offset:23552
	global_load_lds_dwordx4 v[196:197], off
	s_add_i32 m0, s74, 0x2000
	s_add_u32 s74, s22, 0x8000
	v_lshl_add_u64 v[198:199], s[22:23], 0, v[0:1]
	s_addc_u32 s75, s23, 0
	s_add_i32 s73, s73, s60
	global_load_lds_dwordx4 v[198:199], off
	v_lshl_add_u64 v[224:225], s[74:75], 0, v[212:213]
	s_mov_b32 m0, s73
	v_lshl_add_u64 v[226:227], s[52:53], 0, v[210:211]
	global_load_lds_dwordx4 v[224:225], off
	v_lshl_add_u64 v[224:225], s[74:75], 0, v[0:1]
	s_add_i32 m0, s73, 0x2000
	s_nop 0
	global_load_lds_dwordx4 v[224:225], off
	v_lshl_add_u64 v[224:225], s[52:53], 0, v[214:215]
	s_mov_b32 m0, s61
	s_nop 0
	global_load_lds_dwordx4 v[224:225], off
	s_mov_b32 m0, s62
	s_nop 0
	global_load_lds_dwordx4 v[226:227], off
	s_waitcnt vmcnt(8)
	s_waitcnt lgkmcnt(0)
	s_barrier
; #define PG8_STAGE(bufoff, gbase, voff) do { _Pragma("unroll") for (int _i = 0; _i < 2; ++_i) \
;         __builtin_amdgcn_global_load_lds((const unsigned*)((const char*)(gbase) + (voff)[_i]), (LAS unsigned*)(lds + (bufoff) + ldsw + _i * 8192), 16, 0, 0); } while (0)
; #define PG8_LDA(dst, b, h) do { _Pragma("unroll") for (int m = 0; m < 4; ++m) _Pragma("unroll") for (int k = 0; k < 2; ++k) dst[m][k] = *(const LAS bf16x8*)(lds + PG8_SA(b, h) + aoff + m * 2048 + k * 1024); } while (0)
; #define PG8_LDB(dst, b, h) do { _Pragma("unroll") for (int n = 0; n < 2; ++n) _Pragma("unroll") for (int k = 0; k < 2; ++k) dst[n][k] = *(const LAS bf16x8*)(lds + PG8_SB(b, h) + boff + n * 2048 + k * 1024); } while (0)
; #define PG8_MMA(ai, bj, At, Bt) do { __builtin_amdgcn_s_setprio(1); _Pragma("unroll") for (int m = 0; m < 4; ++m) _Pragma("unroll") for (int n = 0; n < 2; ++n) _Pragma("unroll") for (int k = 0; k < 2; ++k) \
;         acc[ai][bj][m][n] = __builtin_amdgcn_mfma_f32_16x16x32_bf16(Bt[n][k], At[m][k], acc[ai][bj][m][n], 0, 0, 0); __builtin_amdgcn_s_setprio(0); } while (0)
; #define PG8_WAIT_V(n) asm volatile("s_waitcnt vmcnt(" #n ")" ::: "memory")
; #define PG8_WAIT_L(n) asm volatile("s_waitcnt lgkmcnt(" #n ")" ::: "memory")
; #define PG8_BAR __builtin_amdgcn_s_barrier()
; #define PG8_SCHED __builtin_amdgcn_sched_barrier(0)
; template <class Epi>
; __device__ __forceinline__ void gemm_phase(LAS unsigned char* lds, const Gemm g, const StaticOrder& S, const Epi& E) {
;     ...
;             PG8_WAIT_V(8); PG8_WAIT_L(0); PG8_BAR; PG8_MMA(1, 0, At, B0); PG8_MMA(1, 1, At, B1); PG8_BAR; PG8_SCHED;
;             PG8_LDB(B0, 1, 0); PG8_LDB(B1, 1, 1); PG8_SCHED; PG8_LDA(At, 1, 0); PG8_STAGE(PG8_SA(0, 1), a2 + hstepA, voffA);
;             PG8_WAIT_V(8); PG8_WAIT_L(0); PG8_BAR; PG8_MMA(0, 0, At, B0); PG8_MMA(0, 1, At, B1); PG8_BAR; PG8_SCHED;
	s_setprio 1
	v_mfma_f32_16x16x32_bf16 v[64:67], v[136:139], v[168:171], v[64:67]
	v_mfma_f32_16x16x32_bf16 v[60:63], v[144:147], v[168:171], v[60:63]
	v_mfma_f32_16x16x32_bf16 v[48:51], v[136:139], v[176:179], v[48:51]
	v_mfma_f32_16x16x32_bf16 v[44:47], v[144:147], v[176:179], v[44:47]
	v_mfma_f32_16x16x32_bf16 v[32:35], v[136:139], v[184:187], v[32:35]
	v_mfma_f32_16x16x32_bf16 v[28:31], v[144:147], v[184:187], v[28:31]
	v_mfma_f32_16x16x32_bf16 v[16:19], v[136:139], v[192:195], v[16:19]
	v_mfma_f32_16x16x32_bf16 v[12:15], v[144:147], v[192:195], v[12:15]
	v_mfma_f32_16x16x32_bf16 v[64:67], v[140:143], v[172:175], v[64:67]
	v_mfma_f32_16x16x32_bf16 v[60:63], v[148:151], v[172:175], v[60:63]
	v_mfma_f32_16x16x32_bf16 v[48:51], v[140:143], v[180:183], v[48:51]
	v_mfma_f32_16x16x32_bf16 v[44:47], v[148:151], v[180:183], v[44:47]
	v_mfma_f32_16x16x32_bf16 v[32:35], v[140:143], v[188:191], v[32:35]
	v_mfma_f32_16x16x32_bf16 v[28:31], v[148:151], v[188:191], v[28:31]
	v_mfma_f32_16x16x32_bf16 v[16:19], v[140:143], v[220:223], v[16:19]
	v_mfma_f32_16x16x32_bf16 v[12:15], v[148:151], v[220:223], v[12:15]
	v_mfma_f32_16x16x32_bf16 v[56:59], v[152:155], v[168:171], v[56:59]
	v_mfma_f32_16x16x32_bf16 v[52:55], v[160:163], v[168:171], v[52:55]
	v_mfma_f32_16x16x32_bf16 v[40:43], v[152:155], v[176:179], v[40:43]
	v_mfma_f32_16x16x32_bf16 v[36:39], v[160:163], v[176:179], v[36:39]
	v_mfma_f32_16x16x32_bf16 v[24:27], v[152:155], v[184:187], v[24:27]
	v_mfma_f32_16x16x32_bf16 v[20:23], v[160:163], v[184:187], v[20:23]
	v_mfma_f32_16x16x32_bf16 v[8:11], v[152:155], v[192:195], v[8:11]
	v_mfma_f32_16x16x32_bf16 v[4:7], v[160:163], v[192:195], v[4:7]
	v_mfma_f32_16x16x32_bf16 v[56:59], v[156:159], v[172:175], v[56:59]
	v_mfma_f32_16x16x32_bf16 v[52:55], v[164:167], v[172:175], v[52:55]
	v_mfma_f32_16x16x32_bf16 v[40:43], v[156:159], v[180:183], v[40:43]
	v_mfma_f32_16x16x32_bf16 v[36:39], v[164:167], v[180:183], v[36:39]
	v_mfma_f32_16x16x32_bf16 v[24:27], v[156:159], v[188:191], v[24:27]
	v_mfma_f32_16x16x32_bf16 v[20:23], v[164:167], v[188:191], v[20:23]
	v_mfma_f32_16x16x32_bf16 v[8:11], v[156:159], v[220:223], v[8:11]
	v_mfma_f32_16x16x32_bf16 v[4:7], v[164:167], v[220:223], v[4:7]
	s_setprio 0
	s_barrier
	s_add_i32 s73, 0, 0x18000
	s_add_i32 s74, 0, 0x1c000
	v_add_u32_e32 v148, s73, v242
	v_add_u32_e32 v164, s74, v242
	ds_read_b128 v[136:139], v148
	ds_read_b128 v[140:143], v148 offset:1024
	ds_read_b128 v[144:147], v148 offset:2048
	ds_read_b128 v[148:151], v148 offset:3072
	ds_read_b128 v[152:155], v164
	ds_read_b128 v[156:159], v164 offset:1024
	ds_read_b128 v[160:163], v164 offset:2048
	ds_read_b128 v[164:167], v164 offset:3072
	s_add_u32 s52, s52, s28
	s_addc_u32 s53, s53, 0
	s_mov_b32 m0, s63
	v_lshl_add_u64 v[228:229], s[52:53], 0, v[214:215]
	ds_read_b128 v[168:171], v244 offset:32768
	ds_read_b128 v[172:175], v244 offset:33792
	ds_read_b128 v[176:179], v244 offset:34816
	ds_read_b128 v[180:183], v244 offset:35840
	ds_read_b128 v[184:187], v244 offset:36864
	ds_read_b128 v[188:191], v244 offset:37888
	ds_read_b128 v[192:195], v244 offset:38912
	ds_read_b128 v[220:223], v244 offset:39936
	global_load_lds_dwordx4 v[228:229], off
	v_lshl_add_u64 v[228:229], s[52:53], 0, v[210:211]
	s_mov_b32 m0, s64
	s_nop 0
	global_load_lds_dwordx4 v[228:229], off
	s_waitcnt vmcnt(8)
	s_waitcnt lgkmcnt(0)
	s_barrier
	s_setprio 1
	v_mfma_f32_16x16x32_bf16 v[128:131], v[136:139], v[168:171], v[128:131]
	v_mfma_f32_16x16x32_bf16 v[124:127], v[144:147], v[168:171], v[124:127]
	v_mfma_f32_16x16x32_bf16 v[112:115], v[136:139], v[176:179], v[112:115]
	v_mfma_f32_16x16x32_bf16 v[108:111], v[144:147], v[176:179], v[108:111]
	v_mfma_f32_16x16x32_bf16 v[96:99], v[136:139], v[184:187], v[96:99]
	v_mfma_f32_16x16x32_bf16 v[92:95], v[144:147], v[184:187], v[92:95]
	v_mfma_f32_16x16x32_bf16 v[80:83], v[136:139], v[192:195], v[80:83]
	v_mfma_f32_16x16x32_bf16 v[76:79], v[144:147], v[192:195], v[76:79]
	v_mfma_f32_16x16x32_bf16 v[128:131], v[140:143], v[172:175], v[128:131]
	v_mfma_f32_16x16x32_bf16 v[124:127], v[148:151], v[172:175], v[124:127]
	v_mfma_f32_16x16x32_bf16 v[112:115], v[140:143], v[180:183], v[112:115]
	v_mfma_f32_16x16x32_bf16 v[108:111], v[148:151], v[180:183], v[108:111]
	v_mfma_f32_16x16x32_bf16 v[96:99], v[140:143], v[188:191], v[96:99]
	v_mfma_f32_16x16x32_bf16 v[92:95], v[148:151], v[188:191], v[92:95]
	v_mfma_f32_16x16x32_bf16 v[80:83], v[140:143], v[220:223], v[80:83]
	v_mfma_f32_16x16x32_bf16 v[76:79], v[148:151], v[220:223], v[76:79]
	v_mfma_f32_16x16x32_bf16 v[120:123], v[152:155], v[168:171], v[120:123]
	v_mfma_f32_16x16x32_bf16 v[116:119], v[160:163], v[168:171], v[116:119]
	v_mfma_f32_16x16x32_bf16 v[104:107], v[152:155], v[176:179], v[104:107]
	v_mfma_f32_16x16x32_bf16 v[100:103], v[160:163], v[176:179], v[100:103]
	v_mfma_f32_16x16x32_bf16 v[88:91], v[152:155], v[184:187], v[88:91]
	v_mfma_f32_16x16x32_bf16 v[84:87], v[160:163], v[184:187], v[84:87]
	v_mfma_f32_16x16x32_bf16 v[72:75], v[152:155], v[192:195], v[72:75]
	v_mfma_f32_16x16x32_bf16 v[68:71], v[160:163], v[192:195], v[68:71]
	v_mfma_f32_16x16x32_bf16 v[120:123], v[156:159], v[172:175], v[120:123]
	v_mfma_f32_16x16x32_bf16 v[116:119], v[164:167], v[172:175], v[116:119]
	v_mfma_f32_16x16x32_bf16 v[104:107], v[156:159], v[180:183], v[104:107]
	v_mfma_f32_16x16x32_bf16 v[100:103], v[164:167], v[180:183], v[100:103]
	v_mfma_f32_16x16x32_bf16 v[88:91], v[156:159], v[188:191], v[88:91]
	v_mfma_f32_16x16x32_bf16 v[84:87], v[164:167], v[188:191], v[84:87]
	v_mfma_f32_16x16x32_bf16 v[72:75], v[156:159], v[220:223], v[72:75]
	v_mfma_f32_16x16x32_bf16 v[68:71], v[164:167], v[220:223], v[68:71]
	s_setprio 0
	s_barrier
; #define PG8_STAGE(bufoff, gbase, voff) do { _Pragma("unroll") for (int _i = 0; _i < 2; ++_i) \
;         __builtin_amdgcn_global_load_lds((const unsigned*)((const char*)(gbase) + (voff)[_i]), (LAS unsigned*)(lds + (bufoff) + ldsw + _i * 8192), 16, 0, 0); } while (0)
; #define PG8_LDA(dst, b, h) do { _Pragma("unroll") for (int m = 0; m < 4; ++m) _Pragma("unroll") for (int k = 0; k < 2; ++k) dst[m][k] = *(const LAS bf16x8*)(lds + PG8_SA(b, h) + aoff + m * 2048 + k * 1024); } while (0)
; #define PG8_MMA(ai, bj, At, Bt) do { __builtin_amdgcn_s_setprio(1); _Pragma("unroll") for (int m = 0; m < 4; ++m) _Pragma("unroll") for (int n = 0; n < 2; ++n) _Pragma("unroll") for (int k = 0; k < 2; ++k) \
;         acc[ai][bj][m][n] = __builtin_amdgcn_mfma_f32_16x16x32_bf16(Bt[n][k], At[m][k], acc[ai][bj][m][n], 0, 0, 0); __builtin_amdgcn_s_setprio(0); } while (0)
; #define PG8_WAIT_V(n) asm volatile("s_waitcnt vmcnt(" #n ")" ::: "memory")
; #define PG8_WAIT_L(n) asm volatile("s_waitcnt lgkmcnt(" #n ")" ::: "memory")
; #define PG8_BAR __builtin_amdgcn_s_barrier()
; #define PG8_SCHED __builtin_amdgcn_sched_barrier(0)
; template <class Epi>
; __device__ __forceinline__ void gemm_phase(LAS unsigned char* lds, const Gemm g, const StaticOrder& S, const Epi& E) {
;     ...
;             PG8_LDA(At, 1, 1); PG8_STAGE(PG8_SB(1, 0), b3, voffB); PG8_STAGE(PG8_SB(1, 1), b3 + hstepB, voffB); PG8_STAGE(PG8_SA(1, 0), a3, voffA);
;             PG8_WAIT_V(8); PG8_WAIT_L(0); PG8_BAR; PG8_MMA(1, 0, At, B0); PG8_MMA(1, 1, At, B1); PG8_BAR; PG8_SCHED;
;         }
;         if (wr == 0) PG8_BAR;
	s_add_i32 s52, s73, s60
	v_lshl_add_u64 v[196:197], v[196:197], 0, s[30:31]
	s_mov_b32 m0, s52
	ds_read_b128 v[168:171], v244 offset:49152
	ds_read_b128 v[172:175], v244 offset:50176
	ds_read_b128 v[176:179], v244 offset:51200
	ds_read_b128 v[180:183], v244 offset:52224
	ds_read_b128 v[184:187], v244 offset:53248
	ds_read_b128 v[188:191], v244 offset:54272
	ds_read_b128 v[192:195], v244 offset:55296
	ds_read_b128 v[220:223], v244 offset:56320
	global_load_lds_dwordx4 v[196:197], off
	s_add_i32 m0, s52, 0x2000
	s_add_u32 s22, s22, 0x8080
	v_lshl_add_u64 v[196:197], v[198:199], 0, s[30:31]
	s_addc_u32 s23, s23, 0
	s_add_i32 s52, s74, s60
	global_load_lds_dwordx4 v[196:197], off
	v_lshl_add_u64 v[196:197], s[22:23], 0, v[212:213]
	s_mov_b32 m0, s52
	s_nop 0
	global_load_lds_dwordx4 v[196:197], off
	v_lshl_add_u64 v[196:197], s[22:23], 0, v[0:1]
	s_add_i32 m0, s52, 0x2000
	s_nop 0
	global_load_lds_dwordx4 v[196:197], off
	v_lshl_add_u64 v[196:197], v[224:225], 0, s[30:31]
	s_mov_b32 m0, s65
	s_nop 0
	global_load_lds_dwordx4 v[196:197], off
	v_lshl_add_u64 v[196:197], v[226:227], 0, s[30:31]
	s_mov_b32 m0, s66
	s_nop 0
	global_load_lds_dwordx4 v[196:197], off
	s_waitcnt vmcnt(8)
	s_waitcnt lgkmcnt(0)
	s_barrier
	s_setprio 1
	v_mfma_f32_16x16x32_bf16 v[64:67], v[136:139], v[168:171], v[64:67]
	v_mfma_f32_16x16x32_bf16 v[60:63], v[144:147], v[168:171], v[60:63]
	v_mfma_f32_16x16x32_bf16 v[48:51], v[136:139], v[176:179], v[48:51]
	v_mfma_f32_16x16x32_bf16 v[44:47], v[144:147], v[176:179], v[44:47]
	v_mfma_f32_16x16x32_bf16 v[32:35], v[136:139], v[184:187], v[32:35]
	v_mfma_f32_16x16x32_bf16 v[28:31], v[144:147], v[184:187], v[28:31]
	v_mfma_f32_16x16x32_bf16 v[16:19], v[136:139], v[192:195], v[16:19]
	v_mfma_f32_16x16x32_bf16 v[12:15], v[144:147], v[192:195], v[12:15]
	v_mfma_f32_16x16x32_bf16 v[64:67], v[140:143], v[172:175], v[64:67]
	v_mfma_f32_16x16x32_bf16 v[60:63], v[148:151], v[172:175], v[60:63]
	v_mfma_f32_16x16x32_bf16 v[48:51], v[140:143], v[180:183], v[48:51]
	v_mfma_f32_16x16x32_bf16 v[44:47], v[148:151], v[180:183], v[44:47]
	v_mfma_f32_16x16x32_bf16 v[32:35], v[140:143], v[188:191], v[32:35]
	v_mfma_f32_16x16x32_bf16 v[28:31], v[148:151], v[188:191], v[28:31]
	v_mfma_f32_16x16x32_bf16 v[16:19], v[140:143], v[220:223], v[16:19]
	v_mfma_f32_16x16x32_bf16 v[12:15], v[148:151], v[220:223], v[12:15]
	v_mfma_f32_16x16x32_bf16 v[56:59], v[152:155], v[168:171], v[56:59]
	v_mfma_f32_16x16x32_bf16 v[52:55], v[160:163], v[168:171], v[52:55]
	v_mfma_f32_16x16x32_bf16 v[40:43], v[152:155], v[176:179], v[40:43]
	v_mfma_f32_16x16x32_bf16 v[36:39], v[160:163], v[176:179], v[36:39]
	v_mfma_f32_16x16x32_bf16 v[24:27], v[152:155], v[184:187], v[24:27]
	v_mfma_f32_16x16x32_bf16 v[20:23], v[160:163], v[184:187], v[20:23]
	v_mfma_f32_16x16x32_bf16 v[8:11], v[152:155], v[192:195], v[8:11]
	v_mfma_f32_16x16x32_bf16 v[4:7], v[160:163], v[192:195], v[4:7]
	v_mfma_f32_16x16x32_bf16 v[56:59], v[156:159], v[172:175], v[56:59]
	v_mfma_f32_16x16x32_bf16 v[52:55], v[164:167], v[172:175], v[52:55]
	v_mfma_f32_16x16x32_bf16 v[40:43], v[156:159], v[180:183], v[40:43]
	v_mfma_f32_16x16x32_bf16 v[36:39], v[164:167], v[180:183], v[36:39]
	v_mfma_f32_16x16x32_bf16 v[24:27], v[156:159], v[188:191], v[24:27]
	v_mfma_f32_16x16x32_bf16 v[20:23], v[164:167], v[188:191], v[20:23]
	v_mfma_f32_16x16x32_bf16 v[8:11], v[156:159], v[220:223], v[8:11]
	v_mfma_f32_16x16x32_bf16 v[4:7], v[164:167], v[220:223], v[4:7]
	s_setprio 0
	s_barrier
	s_add_i32 s72, s72, 2
	s_add_u32 s4, s4, 0x100
	s_addc_u32 s5, s5, 0
	s_cmp_gt_u32 s72, 5
	s_cbranch_scc0 .LBB0_902
	s_and_b64 vcc, exec, s[38:39]
	s_cbranch_vccz .LBB0_905
	s_barrier

; #define PG8_STAGE(bufoff, gbase, voff) do { _Pragma("unroll") for (int _i = 0; _i < 2; ++_i) \
;         __builtin_amdgcn_global_load_lds((const unsigned*)((const char*)(gbase) + (voff)[_i]), (LAS unsigned*)(lds + (bufoff) + ldsw + _i * 8192), 16, 0, 0); } while (0)
; #define PG8_LDA(dst, b, h) do { _Pragma("unroll") for (int m = 0; m < 4; ++m) _Pragma("unroll") for (int k = 0; k < 2; ++k) dst[m][k] = *(const LAS bf16x8*)(lds + PG8_SA(b, h) + aoff + m * 2048 + k * 1024); } while (0)
; #define PG8_LDB(dst, b, h) do { _Pragma("unroll") for (int n = 0; n < 2; ++n) _Pragma("unroll") for (int k = 0; k < 2; ++k) dst[n][k] = *(const LAS bf16x8*)(lds + PG8_SB(b, h) + boff + n * 2048 + k * 1024); } while (0)
; #define PG8_MMA(ai, bj, At, Bt) do { __builtin_amdgcn_s_setprio(1); _Pragma("unroll") for (int m = 0; m < 4; ++m) _Pragma("unroll") for (int n = 0; n < 2; ++n) _Pragma("unroll") for (int k = 0; k < 2; ++k) \
;         acc[ai][bj][m][n] = __builtin_amdgcn_mfma_f32_16x16x32_bf16(Bt[n][k], At[m][k], acc[ai][bj][m][n], 0, 0, 0); __builtin_amdgcn_s_setprio(0); } while (0)
; #define PG8_WAIT_V(n) asm volatile("s_waitcnt vmcnt(" #n ")" ::: "memory")
; #define PG8_WAIT_L(n) asm volatile("s_waitcnt lgkmcnt(" #n ")" ::: "memory")
; #define PG8_BAR __builtin_amdgcn_s_barrier()
; #define PG8_SCHED __builtin_amdgcn_sched_barrier(0)
; template <class Epi>
; __device__ __forceinline__ void gemm_phase(LAS unsigned char* lds, const Gemm g, const StaticOrder& S, const Epi& E) {
;     ...
;             const bool last = (t == nt - 2);
;             const char* a1 = cA + (size_t)(t + 1) * kstep;
;             const char* a2 = last ? nA : cA + (size_t)(t + 2) * kstep; const char* b2 = last ? nB : cB + (size_t)(t + 2) * kstep;
;             const char* a3 = a2 + kstep; const char* b3 = b2 + kstep;
;             PG8_LDB(B0, 0, 0); PG8_LDB(B1, 0, 1); PG8_SCHED; PG8_LDA(At, 0, 0); PG8_STAGE(PG8_SA(1, 1), a1 + hstepA, voffA);
;             PG8_WAIT_V(8); PG8_WAIT_L(0); PG8_BAR; PG8_MMA(0, 0, At, B0); PG8_MMA(0, 1, At, B1); PG8_BAR; PG8_SCHED;
;             PG8_LDA(At, 0, 1); PG8_STAGE(PG8_SB(0, 0), b2, voffB); PG8_STAGE(PG8_SB(0, 1), b2 + hstepB, voffB); PG8_STAGE(PG8_SA(0, 0), a2, voffA);
;             PG8_WAIT_V(8); PG8_WAIT_L(0); PG8_BAR; PG8_MMA(1, 0, At, B0); PG8_MMA(1, 1, At, B1); PG8_BAR; PG8_SCHED;
.LBB0_1005:
	s_add_u32 s22, s50, 0xfffc0080
	s_addc_u32 s23, s51, -1
	s_add_i32 s72, 0, 0x10000
	s_cmp_eq_u32 s71, 12
	s_cselect_b32 s53, s39, s23
	s_cselect_b32 s52, s67, s22
	s_cselect_b32 s23, s35, s70
	s_cselect_b32 s22, s68, s69
	s_add_i32 s74, 0, 0x14000
	v_add_u32_e32 v144, s72, v232
	v_add_u32_e32 v160, s74, v232
	ds_read_b128 v[132:135], v144
	ds_read_b128 v[136:139], v144 offset:1024
	ds_read_b128 v[140:143], v144 offset:2048
	ds_read_b128 v[144:147], v144 offset:3072
	ds_read_b128 v[148:151], v160
	ds_read_b128 v[152:155], v160 offset:1024
	ds_read_b128 v[156:159], v160 offset:2048
	ds_read_b128 v[160:163], v160 offset:3072
	v_lshl_add_u64 v[196:197], s[50:51], 0, v[194:195]
	s_add_i32 m0, s59, 0xc000
	ds_read_b128 v[164:167], v242
	ds_read_b128 v[168:171], v242 offset:1024
	ds_read_b128 v[172:175], v242 offset:2048
	ds_read_b128 v[176:179], v242 offset:3072
	ds_read_b128 v[180:183], v242 offset:4096
	ds_read_b128 v[184:187], v242 offset:5120
	ds_read_b128 v[212:215], v242 offset:6144
	ds_read_b128 v[216:219], v242 offset:7168
	global_load_lds_dwordx4 v[196:197], off
	v_lshl_add_u64 v[196:197], s[50:51], 0, v[210:211]
	s_add_i32 m0, s59, 0xe000
	s_nop 0
	global_load_lds_dwordx4 v[196:197], off
	s_waitcnt vmcnt(8)
	s_waitcnt lgkmcnt(0)
	s_barrier
	s_setprio 1
	v_mfma_f32_16x16x32_bf16 v[128:131], v[132:135], v[164:167], v[128:131]
	v_mfma_f32_16x16x32_bf16 v[124:127], v[140:143], v[164:167], v[124:127]
	v_mfma_f32_16x16x32_bf16 v[112:115], v[132:135], v[172:175], v[112:115]
	v_mfma_f32_16x16x32_bf16 v[108:111], v[140:143], v[172:175], v[108:111]
	v_mfma_f32_16x16x32_bf16 v[96:99], v[132:135], v[180:183], v[96:99]
	v_mfma_f32_16x16x32_bf16 v[92:95], v[140:143], v[180:183], v[92:95]
	v_mfma_f32_16x16x32_bf16 v[80:83], v[132:135], v[212:215], v[80:83]
	v_mfma_f32_16x16x32_bf16 v[76:79], v[140:143], v[212:215], v[76:79]
	v_mfma_f32_16x16x32_bf16 v[128:131], v[136:139], v[168:171], v[128:131]
	v_mfma_f32_16x16x32_bf16 v[124:127], v[144:147], v[168:171], v[124:127]
	v_mfma_f32_16x16x32_bf16 v[112:115], v[136:139], v[176:179], v[112:115]
	v_mfma_f32_16x16x32_bf16 v[108:111], v[144:147], v[176:179], v[108:111]
	v_mfma_f32_16x16x32_bf16 v[96:99], v[136:139], v[184:187], v[96:99]
	v_mfma_f32_16x16x32_bf16 v[92:95], v[144:147], v[184:187], v[92:95]
	v_mfma_f32_16x16x32_bf16 v[80:83], v[136:139], v[216:219], v[80:83]
	v_mfma_f32_16x16x32_bf16 v[76:79], v[144:147], v[216:219], v[76:79]
	v_mfma_f32_16x16x32_bf16 v[120:123], v[148:151], v[164:167], v[120:123]
	v_mfma_f32_16x16x32_bf16 v[116:119], v[156:159], v[164:167], v[116:119]
	v_mfma_f32_16x16x32_bf16 v[104:107], v[148:151], v[172:175], v[104:107]
	v_mfma_f32_16x16x32_bf16 v[100:103], v[156:159], v[172:175], v[100:103]
	v_mfma_f32_16x16x32_bf16 v[88:91], v[148:151], v[180:183], v[88:91]
	v_mfma_f32_16x16x32_bf16 v[84:87], v[156:159], v[180:183], v[84:87]
	v_mfma_f32_16x16x32_bf16 v[72:75], v[148:151], v[212:215], v[72:75]
	v_mfma_f32_16x16x32_bf16 v[68:71], v[156:159], v[212:215], v[68:71]
	v_mfma_f32_16x16x32_bf16 v[120:123], v[152:155], v[168:171], v[120:123]
	v_mfma_f32_16x16x32_bf16 v[116:119], v[160:163], v[168:171], v[116:119]
	v_mfma_f32_16x16x32_bf16 v[104:107], v[152:155], v[176:179], v[104:107]
	v_mfma_f32_16x16x32_bf16 v[100:103], v[160:163], v[176:179], v[100:103]
	v_mfma_f32_16x16x32_bf16 v[88:91], v[152:155], v[184:187], v[88:91]
	v_mfma_f32_16x16x32_bf16 v[84:87], v[160:163], v[184:187], v[84:87]
	v_mfma_f32_16x16x32_bf16 v[72:75], v[152:155], v[216:219], v[72:75]
	v_mfma_f32_16x16x32_bf16 v[68:71], v[160:163], v[216:219], v[68:71]
	s_setprio 0
	s_barrier
	s_add_i32 s72, s72, s58
	v_lshl_add_u64 v[196:197], s[22:23], 0, v[190:191]
	s_mov_b32 m0, s72
	ds_read_b128 v[164:167], v242 offset:16384
	ds_read_b128 v[168:171], v242 offset:17408
	ds_read_b128 v[172:175], v242 offset:18432
	ds_read_b128 v[176:179], v242 offset:19456
	ds_read_b128 v[180:183], v242 offset:20480
	ds_read_b128 v[184:187], v242 offset:21504
	ds_read_b128 v[212:215], v242 offset:22528
	ds_read_b128 v[216:219], v242 offset:23552
	global_load_lds_dwordx4 v[196:197], off
	s_add_i32 m0, s72, 0x2000
	s_add_u32 s72, s22, 0x10000
	v_lshl_add_u64 v[198:199], s[22:23], 0, v[0:1]
	s_addc_u32 s73, s23, 0
	s_add_i32 s74, s74, s58
	global_load_lds_dwordx4 v[198:199], off
	v_lshl_add_u64 v[220:221], s[72:73], 0, v[190:191]
	s_mov_b32 m0, s74
	v_lshl_add_u64 v[222:223], s[52:53], 0, v[188:189]
	global_load_lds_dwordx4 v[220:221], off
	v_lshl_add_u64 v[220:221], s[72:73], 0, v[0:1]
	s_add_i32 m0, s74, 0x2000
	s_nop 0
	global_load_lds_dwordx4 v[220:221], off
	v_lshl_add_u64 v[220:221], s[52:53], 0, v[192:193]
	s_mov_b32 m0, s59
	s_nop 0
	global_load_lds_dwordx4 v[220:221], off
	s_mov_b32 m0, s60
	s_nop 0
	global_load_lds_dwordx4 v[222:223], off
	s_waitcnt vmcnt(8)
	s_waitcnt lgkmcnt(0)
	s_barrier
; #define PG8_STAGE(bufoff, gbase, voff) do { _Pragma("unroll") for (int _i = 0; _i < 2; ++_i) \
;         __builtin_amdgcn_global_load_lds((const unsigned*)((const char*)(gbase) + (voff)[_i]), (LAS unsigned*)(lds + (bufoff) + ldsw + _i * 8192), 16, 0, 0); } while (0)
; #define PG8_LDA(dst, b, h) do { _Pragma("unroll") for (int m = 0; m < 4; ++m) _Pragma("unroll") for (int k = 0; k < 2; ++k) dst[m][k] = *(const LAS bf16x8*)(lds + PG8_SA(b, h) + aoff + m * 2048 + k * 1024); } while (0)
; #define PG8_LDB(dst, b, h) do { _Pragma("unroll") for (int n = 0; n < 2; ++n) _Pragma("unroll") for (int k = 0; k < 2; ++k) dst[n][k] = *(const LAS bf16x8*)(lds + PG8_SB(b, h) + boff + n * 2048 + k * 1024); } while (0)
; #define PG8_MMA(ai, bj, At, Bt) do { __builtin_amdgcn_s_setprio(1); _Pragma("unroll") for (int m = 0; m < 4; ++m) _Pragma("unroll") for (int n = 0; n < 2; ++n) _Pragma("unroll") for (int k = 0; k < 2; ++k) \
;         acc[ai][bj][m][n] = __builtin_amdgcn_mfma_f32_16x16x32_bf16(Bt[n][k], At[m][k], acc[ai][bj][m][n], 0, 0, 0); __builtin_amdgcn_s_setprio(0); } while (0)
; #define PG8_WAIT_V(n) asm volatile("s_waitcnt vmcnt(" #n ")" ::: "memory")
; #define PG8_WAIT_L(n) asm volatile("s_waitcnt lgkmcnt(" #n ")" ::: "memory")
; #define PG8_BAR __builtin_amdgcn_s_barrier()
; #define PG8_SCHED __builtin_amdgcn_sched_barrier(0)
; template <class Epi>
; __device__ __forceinline__ void gemm_phase(LAS unsigned char* lds, const Gemm g, const StaticOrder& S, const Epi& E) {
;     ...
;             PG8_WAIT_V(8); PG8_WAIT_L(0); PG8_BAR; PG8_MMA(1, 0, At, B0); PG8_MMA(1, 1, At, B1); PG8_BAR; PG8_SCHED;
;             PG8_LDB(B0, 1, 0); PG8_LDB(B1, 1, 1); PG8_SCHED; PG8_LDA(At, 1, 0); PG8_STAGE(PG8_SA(0, 1), a2 + hstepA, voffA);
;             PG8_WAIT_V(8); PG8_WAIT_L(0); PG8_BAR; PG8_MMA(0, 0, At, B0); PG8_MMA(0, 1, At, B1); PG8_BAR; PG8_SCHED;
	s_setprio 1
	v_mfma_f32_16x16x32_bf16 v[64:67], v[132:135], v[164:167], v[64:67]
	v_mfma_f32_16x16x32_bf16 v[60:63], v[140:143], v[164:167], v[60:63]
	v_mfma_f32_16x16x32_bf16 v[48:51], v[132:135], v[172:175], v[48:51]
	v_mfma_f32_16x16x32_bf16 v[44:47], v[140:143], v[172:175], v[44:47]
	v_mfma_f32_16x16x32_bf16 v[32:35], v[132:135], v[180:183], v[32:35]
	v_mfma_f32_16x16x32_bf16 v[28:31], v[140:143], v[180:183], v[28:31]
	v_mfma_f32_16x16x32_bf16 v[16:19], v[132:135], v[212:215], v[16:19]
	v_mfma_f32_16x16x32_bf16 v[12:15], v[140:143], v[212:215], v[12:15]
	v_mfma_f32_16x16x32_bf16 v[64:67], v[136:139], v[168:171], v[64:67]
	v_mfma_f32_16x16x32_bf16 v[60:63], v[144:147], v[168:171], v[60:63]
	v_mfma_f32_16x16x32_bf16 v[48:51], v[136:139], v[176:179], v[48:51]
	v_mfma_f32_16x16x32_bf16 v[44:47], v[144:147], v[176:179], v[44:47]
	v_mfma_f32_16x16x32_bf16 v[32:35], v[136:139], v[184:187], v[32:35]
	v_mfma_f32_16x16x32_bf16 v[28:31], v[144:147], v[184:187], v[28:31]
	v_mfma_f32_16x16x32_bf16 v[16:19], v[136:139], v[216:219], v[16:19]
	v_mfma_f32_16x16x32_bf16 v[12:15], v[144:147], v[216:219], v[12:15]
	v_mfma_f32_16x16x32_bf16 v[56:59], v[148:151], v[164:167], v[56:59]
	v_mfma_f32_16x16x32_bf16 v[52:55], v[156:159], v[164:167], v[52:55]
	v_mfma_f32_16x16x32_bf16 v[40:43], v[148:151], v[172:175], v[40:43]
	v_mfma_f32_16x16x32_bf16 v[36:39], v[156:159], v[172:175], v[36:39]
	v_mfma_f32_16x16x32_bf16 v[24:27], v[148:151], v[180:183], v[24:27]
	v_mfma_f32_16x16x32_bf16 v[20:23], v[156:159], v[180:183], v[20:23]
	v_mfma_f32_16x16x32_bf16 v[8:11], v[148:151], v[212:215], v[8:11]
	v_mfma_f32_16x16x32_bf16 v[4:7], v[156:159], v[212:215], v[4:7]
	v_mfma_f32_16x16x32_bf16 v[56:59], v[152:155], v[168:171], v[56:59]
	v_mfma_f32_16x16x32_bf16 v[52:55], v[160:163], v[168:171], v[52:55]
	v_mfma_f32_16x16x32_bf16 v[40:43], v[152:155], v[176:179], v[40:43]
	v_mfma_f32_16x16x32_bf16 v[36:39], v[160:163], v[176:179], v[36:39]
	v_mfma_f32_16x16x32_bf16 v[24:27], v[152:155], v[184:187], v[24:27]
	v_mfma_f32_16x16x32_bf16 v[20:23], v[160:163], v[184:187], v[20:23]
	v_mfma_f32_16x16x32_bf16 v[8:11], v[152:155], v[216:219], v[8:11]
	v_mfma_f32_16x16x32_bf16 v[4:7], v[160:163], v[216:219], v[4:7]
	s_setprio 0
	s_barrier
	s_add_i32 s72, 0, 0x18000
	s_add_i32 s73, 0, 0x1c000
	v_add_u32_e32 v144, s72, v232
	v_add_u32_e32 v160, s73, v232
	ds_read_b128 v[132:135], v144
	ds_read_b128 v[136:139], v144 offset:1024
	ds_read_b128 v[140:143], v144 offset:2048
	ds_read_b128 v[144:147], v144 offset:3072
	ds_read_b128 v[148:151], v160
	ds_read_b128 v[152:155], v160 offset:1024
	ds_read_b128 v[156:159], v160 offset:2048
	ds_read_b128 v[160:163], v160 offset:3072
	s_add_u32 s52, s52, 0x40000
	s_addc_u32 s53, s53, 0
	s_mov_b32 m0, s61
	v_lshl_add_u64 v[224:225], s[52:53], 0, v[192:193]
	ds_read_b128 v[164:167], v242 offset:32768
	ds_read_b128 v[168:171], v242 offset:33792
	ds_read_b128 v[172:175], v242 offset:34816
	ds_read_b128 v[176:179], v242 offset:35840
	ds_read_b128 v[180:183], v242 offset:36864
	ds_read_b128 v[184:187], v242 offset:37888
	ds_read_b128 v[212:215], v242 offset:38912
	ds_read_b128 v[216:219], v242 offset:39936
	global_load_lds_dwordx4 v[224:225], off
	v_lshl_add_u64 v[224:225], s[52:53], 0, v[188:189]
	s_mov_b32 m0, s62
	s_nop 0
	global_load_lds_dwordx4 v[224:225], off
	s_waitcnt vmcnt(8)
	s_waitcnt lgkmcnt(0)
	s_barrier
	s_setprio 1
	v_mfma_f32_16x16x32_bf16 v[128:131], v[132:135], v[164:167], v[128:131]
	v_mfma_f32_16x16x32_bf16 v[124:127], v[140:143], v[164:167], v[124:127]
	v_mfma_f32_16x16x32_bf16 v[112:115], v[132:135], v[172:175], v[112:115]
	v_mfma_f32_16x16x32_bf16 v[108:111], v[140:143], v[172:175], v[108:111]
	v_mfma_f32_16x16x32_bf16 v[96:99], v[132:135], v[180:183], v[96:99]
	v_mfma_f32_16x16x32_bf16 v[92:95], v[140:143], v[180:183], v[92:95]
	v_mfma_f32_16x16x32_bf16 v[80:83], v[132:135], v[212:215], v[80:83]
	v_mfma_f32_16x16x32_bf16 v[76:79], v[140:143], v[212:215], v[76:79]
	v_mfma_f32_16x16x32_bf16 v[128:131], v[136:139], v[168:171], v[128:131]
	v_mfma_f32_16x16x32_bf16 v[124:127], v[144:147], v[168:171], v[124:127]
	v_mfma_f32_16x16x32_bf16 v[112:115], v[136:139], v[176:179], v[112:115]
	v_mfma_f32_16x16x32_bf16 v[108:111], v[144:147], v[176:179], v[108:111]
	v_mfma_f32_16x16x32_bf16 v[96:99], v[136:139], v[184:187], v[96:99]
	v_mfma_f32_16x16x32_bf16 v[92:95], v[144:147], v[184:187], v[92:95]
	v_mfma_f32_16x16x32_bf16 v[80:83], v[136:139], v[216:219], v[80:83]
	v_mfma_f32_16x16x32_bf16 v[76:79], v[144:147], v[216:219], v[76:79]
	v_mfma_f32_16x16x32_bf16 v[120:123], v[148:151], v[164:167], v[120:123]
	v_mfma_f32_16x16x32_bf16 v[116:119], v[156:159], v[164:167], v[116:119]
	v_mfma_f32_16x16x32_bf16 v[104:107], v[148:151], v[172:175], v[104:107]
	v_mfma_f32_16x16x32_bf16 v[100:103], v[156:159], v[172:175], v[100:103]
	v_mfma_f32_16x16x32_bf16 v[88:91], v[148:151], v[180:183], v[88:91]
	v_mfma_f32_16x16x32_bf16 v[84:87], v[156:159], v[180:183], v[84:87]
	v_mfma_f32_16x16x32_bf16 v[72:75], v[148:151], v[212:215], v[72:75]
	v_mfma_f32_16x16x32_bf16 v[68:71], v[156:159], v[212:215], v[68:71]
	v_mfma_f32_16x16x32_bf16 v[120:123], v[152:155], v[168:171], v[120:123]
	v_mfma_f32_16x16x32_bf16 v[116:119], v[160:163], v[168:171], v[116:119]
	v_mfma_f32_16x16x32_bf16 v[104:107], v[152:155], v[176:179], v[104:107]
	v_mfma_f32_16x16x32_bf16 v[100:103], v[160:163], v[176:179], v[100:103]
	v_mfma_f32_16x16x32_bf16 v[88:91], v[152:155], v[184:187], v[88:91]
	v_mfma_f32_16x16x32_bf16 v[84:87], v[160:163], v[184:187], v[84:87]
	v_mfma_f32_16x16x32_bf16 v[72:75], v[152:155], v[216:219], v[72:75]
	v_mfma_f32_16x16x32_bf16 v[68:71], v[160:163], v[216:219], v[68:71]
	s_setprio 0
	s_barrier
; #define PG8_STAGE(bufoff, gbase, voff) do { _Pragma("unroll") for (int _i = 0; _i < 2; ++_i) \
;         __builtin_amdgcn_global_load_lds((const unsigned*)((const char*)(gbase) + (voff)[_i]), (LAS unsigned*)(lds + (bufoff) + ldsw + _i * 8192), 16, 0, 0); } while (0)
; #define PG8_LDA(dst, b, h) do { _Pragma("unroll") for (int m = 0; m < 4; ++m) _Pragma("unroll") for (int k = 0; k < 2; ++k) dst[m][k] = *(const LAS bf16x8*)(lds + PG8_SA(b, h) + aoff + m * 2048 + k * 1024); } while (0)
; #define PG8_MMA(ai, bj, At, Bt) do { __builtin_amdgcn_s_setprio(1); _Pragma("unroll") for (int m = 0; m < 4; ++m) _Pragma("unroll") for (int n = 0; n < 2; ++n) _Pragma("unroll") for (int k = 0; k < 2; ++k) \
;         acc[ai][bj][m][n] = __builtin_amdgcn_mfma_f32_16x16x32_bf16(Bt[n][k], At[m][k], acc[ai][bj][m][n], 0, 0, 0); __builtin_amdgcn_s_setprio(0); } while (0)
; #define PG8_WAIT_V(n) asm volatile("s_waitcnt vmcnt(" #n ")" ::: "memory")
; #define PG8_WAIT_L(n) asm volatile("s_waitcnt lgkmcnt(" #n ")" ::: "memory")
; #define PG8_BAR __builtin_amdgcn_s_barrier()
; #define PG8_SCHED __builtin_amdgcn_sched_barrier(0)
; template <class Epi>
; __device__ __forceinline__ void gemm_phase(LAS unsigned char* lds, const Gemm g, const StaticOrder& S, const Epi& E) {
;     ...
;             PG8_LDA(At, 1, 1); PG8_STAGE(PG8_SB(1, 0), b3, voffB); PG8_STAGE(PG8_SB(1, 1), b3 + hstepB, voffB); PG8_STAGE(PG8_SA(1, 0), a3, voffA);
;             PG8_WAIT_V(8); PG8_WAIT_L(0); PG8_BAR; PG8_MMA(1, 0, At, B0); PG8_MMA(1, 1, At, B1); PG8_BAR; PG8_SCHED;
;         }
;         if (wr == 0) PG8_BAR;
	s_add_i32 s52, s72, s58
	v_lshl_add_u64 v[196:197], v[196:197], 0, s[30:31]
	s_mov_b32 m0, s52
	ds_read_b128 v[164:167], v242 offset:49152
	ds_read_b128 v[168:171], v242 offset:50176
	ds_read_b128 v[172:175], v242 offset:51200
	ds_read_b128 v[176:179], v242 offset:52224
	ds_read_b128 v[180:183], v242 offset:53248
	ds_read_b128 v[184:187], v242 offset:54272
	ds_read_b128 v[212:215], v242 offset:55296
	ds_read_b128 v[216:219], v242 offset:56320
	global_load_lds_dwordx4 v[196:197], off
	s_add_i32 m0, s52, 0x2000
	s_add_u32 s22, s22, 0x10080
	v_lshl_add_u64 v[196:197], v[198:199], 0, s[30:31]
	s_addc_u32 s23, s23, 0
	s_add_i32 s52, s73, s58
	global_load_lds_dwordx4 v[196:197], off
	v_lshl_add_u64 v[196:197], s[22:23], 0, v[190:191]
	s_mov_b32 m0, s52
	s_nop 0
	global_load_lds_dwordx4 v[196:197], off
	v_lshl_add_u64 v[196:197], s[22:23], 0, v[0:1]
	s_add_i32 m0, s52, 0x2000
	s_nop 0
	global_load_lds_dwordx4 v[196:197], off
	v_lshl_add_u64 v[196:197], v[220:221], 0, s[30:31]
	s_mov_b32 m0, s28
	s_nop 0
	global_load_lds_dwordx4 v[196:197], off
	v_lshl_add_u64 v[196:197], v[222:223], 0, s[30:31]
	s_mov_b32 m0, s63
	s_nop 0
	global_load_lds_dwordx4 v[196:197], off
	s_waitcnt vmcnt(8)
	s_waitcnt lgkmcnt(0)
	s_barrier
	s_setprio 1
	v_mfma_f32_16x16x32_bf16 v[64:67], v[132:135], v[164:167], v[64:67]
	v_mfma_f32_16x16x32_bf16 v[60:63], v[140:143], v[164:167], v[60:63]
	v_mfma_f32_16x16x32_bf16 v[48:51], v[132:135], v[172:175], v[48:51]
	v_mfma_f32_16x16x32_bf16 v[44:47], v[140:143], v[172:175], v[44:47]
	v_mfma_f32_16x16x32_bf16 v[32:35], v[132:135], v[180:183], v[32:35]
	v_mfma_f32_16x16x32_bf16 v[28:31], v[140:143], v[180:183], v[28:31]
	v_mfma_f32_16x16x32_bf16 v[16:19], v[132:135], v[212:215], v[16:19]
	v_mfma_f32_16x16x32_bf16 v[12:15], v[140:143], v[212:215], v[12:15]
	v_mfma_f32_16x16x32_bf16 v[64:67], v[136:139], v[168:171], v[64:67]
	v_mfma_f32_16x16x32_bf16 v[60:63], v[144:147], v[168:171], v[60:63]
	v_mfma_f32_16x16x32_bf16 v[48:51], v[136:139], v[176:179], v[48:51]
	v_mfma_f32_16x16x32_bf16 v[44:47], v[144:147], v[176:179], v[44:47]
	v_mfma_f32_16x16x32_bf16 v[32:35], v[136:139], v[184:187], v[32:35]
	v_mfma_f32_16x16x32_bf16 v[28:31], v[144:147], v[184:187], v[28:31]
	v_mfma_f32_16x16x32_bf16 v[16:19], v[136:139], v[216:219], v[16:19]
	v_mfma_f32_16x16x32_bf16 v[12:15], v[144:147], v[216:219], v[12:15]
	v_mfma_f32_16x16x32_bf16 v[56:59], v[148:151], v[164:167], v[56:59]
	v_mfma_f32_16x16x32_bf16 v[52:55], v[156:159], v[164:167], v[52:55]
	v_mfma_f32_16x16x32_bf16 v[40:43], v[148:151], v[172:175], v[40:43]
	v_mfma_f32_16x16x32_bf16 v[36:39], v[156:159], v[172:175], v[36:39]
	v_mfma_f32_16x16x32_bf16 v[24:27], v[148:151], v[180:183], v[24:27]
	v_mfma_f32_16x16x32_bf16 v[20:23], v[156:159], v[180:183], v[20:23]
	v_mfma_f32_16x16x32_bf16 v[8:11], v[148:151], v[212:215], v[8:11]
	v_mfma_f32_16x16x32_bf16 v[4:7], v[156:159], v[212:215], v[4:7]
	v_mfma_f32_16x16x32_bf16 v[56:59], v[152:155], v[168:171], v[56:59]
	v_mfma_f32_16x16x32_bf16 v[52:55], v[160:163], v[168:171], v[52:55]
	v_mfma_f32_16x16x32_bf16 v[40:43], v[152:155], v[176:179], v[40:43]
	v_mfma_f32_16x16x32_bf16 v[36:39], v[160:163], v[176:179], v[36:39]
	v_mfma_f32_16x16x32_bf16 v[24:27], v[152:155], v[184:187], v[24:27]
	v_mfma_f32_16x16x32_bf16 v[20:23], v[160:163], v[184:187], v[20:23]
	v_mfma_f32_16x16x32_bf16 v[8:11], v[152:155], v[216:219], v[8:11]
	v_mfma_f32_16x16x32_bf16 v[4:7], v[160:163], v[216:219], v[4:7]
	s_setprio 0
	s_barrier
	s_add_i32 s71, s71, 2
	s_add_u32 s50, s50, 0x100
	s_addc_u32 s51, s51, 0
	s_add_u32 s69, s69, 0x100
	s_addc_u32 s70, s70, 0
	s_cmp_gt_u32 s71, 13
	s_cbranch_scc0 .LBB0_1005
	s_and_b64 vcc, exec, s[14:15]
	s_cbranch_vccz .LBB0_1008
	s_barrier

; #define PG8_STAGE(bufoff, gbase, voff) do { _Pragma("unroll") for (int _i = 0; _i < 2; ++_i) \
;         __builtin_amdgcn_global_load_lds((const unsigned*)((const char*)(gbase) + (voff)[_i]), (LAS unsigned*)(lds + (bufoff) + ldsw + _i * 8192), 16, 0, 0); } while (0)
; #define PG8_LDA(dst, b, h) do { _Pragma("unroll") for (int m = 0; m < 4; ++m) _Pragma("unroll") for (int k = 0; k < 2; ++k) dst[m][k] = *(const LAS bf16x8*)(lds + PG8_SA(b, h) + aoff + m * 2048 + k * 1024); } while (0)
; #define PG8_LDB(dst, b, h) do { _Pragma("unroll") for (int n = 0; n < 2; ++n) _Pragma("unroll") for (int k = 0; k < 2; ++k) dst[n][k] = *(const LAS bf16x8*)(lds + PG8_SB(b, h) + boff + n * 2048 + k * 1024); } while (0)
; #define PG8_MMA(ai, bj, At, Bt) do { __builtin_amdgcn_s_setprio(1); _Pragma("unroll") for (int m = 0; m < 4; ++m) _Pragma("unroll") for (int n = 0; n < 2; ++n) _Pragma("unroll") for (int k = 0; k < 2; ++k) \
;         acc[ai][bj][m][n] = __builtin_amdgcn_mfma_f32_16x16x32_bf16(Bt[n][k], At[m][k], acc[ai][bj][m][n], 0, 0, 0); __builtin_amdgcn_s_setprio(0); } while (0)
; #define PG8_WAIT_V(n) asm volatile("s_waitcnt vmcnt(" #n ")" ::: "memory")
; #define PG8_WAIT_L(n) asm volatile("s_waitcnt lgkmcnt(" #n ")" ::: "memory")
; #define PG8_BAR __builtin_amdgcn_s_barrier()
; #define PG8_SCHED __builtin_amdgcn_sched_barrier(0)
; template <class Epi>
; __device__ __forceinline__ void gemm_phase(LAS unsigned char* lds, const Gemm g, const StaticOrder& S, const Epi& E) {
;     ...
;             const bool last = (t == nt - 2);
;             const char* a1 = cA + (size_t)(t + 1) * kstep;
;             const char* a2 = last ? nA : cA + (size_t)(t + 2) * kstep; const char* b2 = last ? nB : cB + (size_t)(t + 2) * kstep;
;             const char* a3 = a2 + kstep; const char* b3 = b2 + kstep;
;             PG8_LDB(B0, 0, 0); PG8_LDB(B1, 0, 1); PG8_SCHED; PG8_LDA(At, 0, 0); PG8_STAGE(PG8_SA(1, 1), a1 + hstepA, voffA);
;             PG8_WAIT_V(8); PG8_WAIT_L(0); PG8_BAR; PG8_MMA(0, 0, At, B0); PG8_MMA(0, 1, At, B1); PG8_BAR; PG8_SCHED;
;             PG8_LDA(At, 0, 1); PG8_STAGE(PG8_SB(0, 0), b2, voffB); PG8_STAGE(PG8_SB(0, 1), b2 + hstepB, voffB); PG8_STAGE(PG8_SA(0, 0), a2, voffA);
;             PG8_WAIT_V(8); PG8_WAIT_L(0); PG8_BAR; PG8_MMA(1, 0, At, B0); PG8_MMA(1, 1, At, B1); PG8_BAR; PG8_SCHED;
.LBB0_1088:
	s_add_u32 s22, s46, 0xfffc0080
	s_addc_u32 s23, s47, -1
	s_add_i32 s68, 0, 0x10000
	s_cmp_eq_u32 s67, 12
	s_cselect_b32 s49, s35, s23
	s_cselect_b32 s48, s63, s22
	s_cselect_b32 s23, s15, s66
	s_cselect_b32 s22, s64, s65
	s_add_i32 s70, 0, 0x14000
	v_add_u32_e32 v154, s68, v158
	v_add_u32_e32 v161, s70, v158
	ds_read_b128 v[142:145], v154
	ds_read_b128 v[146:149], v154 offset:1024
	ds_read_b128 v[150:153], v154 offset:2048
	ds_read_b128 v[154:157], v154 offset:3072
	ds_read_b128 v[162:165], v161
	ds_read_b128 v[166:169], v161 offset:1024
	ds_read_b128 v[170:173], v161 offset:2048
	ds_read_b128 v[174:177], v161 offset:3072
	v_lshl_add_u64 v[198:199], s[46:47], 0, v[138:139]
	s_add_i32 m0, s55, 0xc000
	ds_read_b128 v[178:181], v160
	ds_read_b128 v[182:185], v160 offset:1024
	ds_read_b128 v[186:189], v160 offset:2048
	ds_read_b128 v[190:193], v160 offset:3072
	ds_read_b128 v[194:197], v160 offset:4096
	ds_read_b128 v[210:213], v160 offset:5120
	ds_read_b128 v[214:217], v160 offset:6144
	ds_read_b128 v[218:221], v160 offset:7168
	global_load_lds_dwordx4 v[198:199], off
	v_lshl_add_u64 v[198:199], s[46:47], 0, v[140:141]
	s_add_i32 m0, s55, 0xe000
	s_nop 0
	global_load_lds_dwordx4 v[198:199], off
	s_waitcnt vmcnt(8)
	s_waitcnt lgkmcnt(0)
	s_barrier
	s_setprio 1
	v_mfma_f32_16x16x32_bf16 v[128:131], v[142:145], v[178:181], v[128:131]
	v_mfma_f32_16x16x32_bf16 v[120:123], v[150:153], v[178:181], v[120:123]
	v_mfma_f32_16x16x32_bf16 v[108:111], v[142:145], v[186:189], v[108:111]
	v_mfma_f32_16x16x32_bf16 v[100:103], v[150:153], v[186:189], v[100:103]
	v_mfma_f32_16x16x32_bf16 v[92:95], v[142:145], v[194:197], v[92:95]
	v_mfma_f32_16x16x32_bf16 v[84:87], v[150:153], v[194:197], v[84:87]
	v_mfma_f32_16x16x32_bf16 v[76:79], v[142:145], v[214:217], v[76:79]
	v_mfma_f32_16x16x32_bf16 v[68:71], v[150:153], v[214:217], v[68:71]
	v_mfma_f32_16x16x32_bf16 v[128:131], v[146:149], v[182:185], v[128:131]
	v_mfma_f32_16x16x32_bf16 v[120:123], v[154:157], v[182:185], v[120:123]
	v_mfma_f32_16x16x32_bf16 v[108:111], v[146:149], v[190:193], v[108:111]
	v_mfma_f32_16x16x32_bf16 v[100:103], v[154:157], v[190:193], v[100:103]
	v_mfma_f32_16x16x32_bf16 v[92:95], v[146:149], v[210:213], v[92:95]
	v_mfma_f32_16x16x32_bf16 v[84:87], v[154:157], v[210:213], v[84:87]
	v_mfma_f32_16x16x32_bf16 v[76:79], v[146:149], v[218:221], v[76:79]
	v_mfma_f32_16x16x32_bf16 v[68:71], v[154:157], v[218:221], v[68:71]
	v_mfma_f32_16x16x32_bf16 v[124:127], v[162:165], v[178:181], v[124:127]
	v_mfma_f32_16x16x32_bf16 v[116:119], v[170:173], v[178:181], v[116:119]
	v_mfma_f32_16x16x32_bf16 v[112:115], v[162:165], v[186:189], v[112:115]
	v_mfma_f32_16x16x32_bf16 v[104:107], v[170:173], v[186:189], v[104:107]
	v_mfma_f32_16x16x32_bf16 v[96:99], v[162:165], v[194:197], v[96:99]
	v_mfma_f32_16x16x32_bf16 v[88:91], v[170:173], v[194:197], v[88:91]
	v_mfma_f32_16x16x32_bf16 v[80:83], v[162:165], v[214:217], v[80:83]
	v_mfma_f32_16x16x32_bf16 v[72:75], v[170:173], v[214:217], v[72:75]
	v_mfma_f32_16x16x32_bf16 v[124:127], v[166:169], v[182:185], v[124:127]
	v_mfma_f32_16x16x32_bf16 v[116:119], v[174:177], v[182:185], v[116:119]
	v_mfma_f32_16x16x32_bf16 v[112:115], v[166:169], v[190:193], v[112:115]
	v_mfma_f32_16x16x32_bf16 v[104:107], v[174:177], v[190:193], v[104:107]
	v_mfma_f32_16x16x32_bf16 v[96:99], v[166:169], v[210:213], v[96:99]
	v_mfma_f32_16x16x32_bf16 v[88:91], v[174:177], v[210:213], v[88:91]
	v_mfma_f32_16x16x32_bf16 v[80:83], v[166:169], v[218:221], v[80:83]
	v_mfma_f32_16x16x32_bf16 v[72:75], v[174:177], v[218:221], v[72:75]
	s_setprio 0
	s_barrier
	s_add_i32 s68, s68, s54
	v_lshl_add_u64 v[198:199], s[22:23], 0, v[134:135]
	s_mov_b32 m0, s68
	ds_read_b128 v[178:181], v160 offset:16384
	ds_read_b128 v[182:185], v160 offset:17408
	ds_read_b128 v[186:189], v160 offset:18432
	ds_read_b128 v[190:193], v160 offset:19456
	ds_read_b128 v[194:197], v160 offset:20480
	ds_read_b128 v[210:213], v160 offset:21504
	ds_read_b128 v[214:217], v160 offset:22528
	ds_read_b128 v[218:221], v160 offset:23552
	global_load_lds_dwordx4 v[198:199], off
	s_add_i32 m0, s68, 0x2000
	s_add_u32 s68, s22, 0x10000
	v_lshl_add_u64 v[222:223], s[22:23], 0, v[0:1]
	s_addc_u32 s69, s23, 0
	s_add_i32 s70, s70, s54
	global_load_lds_dwordx4 v[222:223], off
	v_lshl_add_u64 v[224:225], s[68:69], 0, v[134:135]
	s_mov_b32 m0, s70
	v_lshl_add_u64 v[226:227], s[48:49], 0, v[132:133]
	global_load_lds_dwordx4 v[224:225], off
	v_lshl_add_u64 v[224:225], s[68:69], 0, v[0:1]
	s_add_i32 m0, s70, 0x2000
	s_nop 0
	global_load_lds_dwordx4 v[224:225], off
	v_lshl_add_u64 v[224:225], s[48:49], 0, v[136:137]
	s_mov_b32 m0, s55
	s_nop 0
	global_load_lds_dwordx4 v[224:225], off
	s_mov_b32 m0, s56
	s_nop 0
	global_load_lds_dwordx4 v[226:227], off
	s_waitcnt vmcnt(8)
	s_waitcnt lgkmcnt(0)
	s_barrier
; #define PG8_STAGE(bufoff, gbase, voff) do { _Pragma("unroll") for (int _i = 0; _i < 2; ++_i) \
;         __builtin_amdgcn_global_load_lds((const unsigned*)((const char*)(gbase) + (voff)[_i]), (LAS unsigned*)(lds + (bufoff) + ldsw + _i * 8192), 16, 0, 0); } while (0)
; #define PG8_LDA(dst, b, h) do { _Pragma("unroll") for (int m = 0; m < 4; ++m) _Pragma("unroll") for (int k = 0; k < 2; ++k) dst[m][k] = *(const LAS bf16x8*)(lds + PG8_SA(b, h) + aoff + m * 2048 + k * 1024); } while (0)
; #define PG8_LDB(dst, b, h) do { _Pragma("unroll") for (int n = 0; n < 2; ++n) _Pragma("unroll") for (int k = 0; k < 2; ++k) dst[n][k] = *(const LAS bf16x8*)(lds + PG8_SB(b, h) + boff + n * 2048 + k * 1024); } while (0)
; #define PG8_MMA(ai, bj, At, Bt) do { __builtin_amdgcn_s_setprio(1); _Pragma("unroll") for (int m = 0; m < 4; ++m) _Pragma("unroll") for (int n = 0; n < 2; ++n) _Pragma("unroll") for (int k = 0; k < 2; ++k) \
;         acc[ai][bj][m][n] = __builtin_amdgcn_mfma_f32_16x16x32_bf16(Bt[n][k], At[m][k], acc[ai][bj][m][n], 0, 0, 0); __builtin_amdgcn_s_setprio(0); } while (0)
; #define PG8_WAIT_V(n) asm volatile("s_waitcnt vmcnt(" #n ")" ::: "memory")
; #define PG8_WAIT_L(n) asm volatile("s_waitcnt lgkmcnt(" #n ")" ::: "memory")
; #define PG8_BAR __builtin_amdgcn_s_barrier()
; #define PG8_SCHED __builtin_amdgcn_sched_barrier(0)
; template <class Epi>
; __device__ __forceinline__ void gemm_phase(LAS unsigned char* lds, const Gemm g, const StaticOrder& S, const Epi& E) {
;     ...
;             PG8_WAIT_V(8); PG8_WAIT_L(0); PG8_BAR; PG8_MMA(1, 0, At, B0); PG8_MMA(1, 1, At, B1); PG8_BAR; PG8_SCHED;
;             PG8_LDB(B0, 1, 0); PG8_LDB(B1, 1, 1); PG8_SCHED; PG8_LDA(At, 1, 0); PG8_STAGE(PG8_SA(0, 1), a2 + hstepA, voffA);
;             PG8_WAIT_V(8); PG8_WAIT_L(0); PG8_BAR; PG8_MMA(0, 0, At, B0); PG8_MMA(0, 1, At, B1); PG8_BAR; PG8_SCHED;
	s_setprio 1
	v_mfma_f32_16x16x32_bf16 v[60:63], v[142:145], v[178:181], v[60:63]
	v_mfma_f32_16x16x32_bf16 v[52:55], v[150:153], v[178:181], v[52:55]
	v_mfma_f32_16x16x32_bf16 v[44:47], v[142:145], v[186:189], v[44:47]
	v_mfma_f32_16x16x32_bf16 v[36:39], v[150:153], v[186:189], v[36:39]
	v_mfma_f32_16x16x32_bf16 v[28:31], v[142:145], v[194:197], v[28:31]
	v_mfma_f32_16x16x32_bf16 v[20:23], v[150:153], v[194:197], v[20:23]
	v_mfma_f32_16x16x32_bf16 v[4:7], v[142:145], v[214:217], v[4:7]
	v_mfma_f32_16x16x32_bf16 v[12:15], v[150:153], v[214:217], v[12:15]
	v_mfma_f32_16x16x32_bf16 v[60:63], v[146:149], v[182:185], v[60:63]
	v_mfma_f32_16x16x32_bf16 v[52:55], v[154:157], v[182:185], v[52:55]
	v_mfma_f32_16x16x32_bf16 v[44:47], v[146:149], v[190:193], v[44:47]
	v_mfma_f32_16x16x32_bf16 v[36:39], v[154:157], v[190:193], v[36:39]
	v_mfma_f32_16x16x32_bf16 v[28:31], v[146:149], v[210:213], v[28:31]
	v_mfma_f32_16x16x32_bf16 v[20:23], v[154:157], v[210:213], v[20:23]
	v_mfma_f32_16x16x32_bf16 v[4:7], v[146:149], v[218:221], v[4:7]
	v_mfma_f32_16x16x32_bf16 v[12:15], v[154:157], v[218:221], v[12:15]
	v_mfma_f32_16x16x32_bf16 v[64:67], v[162:165], v[178:181], v[64:67]
	v_mfma_f32_16x16x32_bf16 v[56:59], v[170:173], v[178:181], v[56:59]
	v_mfma_f32_16x16x32_bf16 v[48:51], v[162:165], v[186:189], v[48:51]
	v_mfma_f32_16x16x32_bf16 v[40:43], v[170:173], v[186:189], v[40:43]
	v_mfma_f32_16x16x32_bf16 v[32:35], v[162:165], v[194:197], v[32:35]
	v_mfma_f32_16x16x32_bf16 v[24:27], v[170:173], v[194:197], v[24:27]
	v_mfma_f32_16x16x32_bf16 v[8:11], v[162:165], v[214:217], v[8:11]
	v_mfma_f32_16x16x32_bf16 v[16:19], v[170:173], v[214:217], v[16:19]
	v_mfma_f32_16x16x32_bf16 v[64:67], v[166:169], v[182:185], v[64:67]
	v_mfma_f32_16x16x32_bf16 v[56:59], v[174:177], v[182:185], v[56:59]
	v_mfma_f32_16x16x32_bf16 v[48:51], v[166:169], v[190:193], v[48:51]
	v_mfma_f32_16x16x32_bf16 v[40:43], v[174:177], v[190:193], v[40:43]
	v_mfma_f32_16x16x32_bf16 v[32:35], v[166:169], v[210:213], v[32:35]
	v_mfma_f32_16x16x32_bf16 v[24:27], v[174:177], v[210:213], v[24:27]
	v_mfma_f32_16x16x32_bf16 v[8:11], v[166:169], v[218:221], v[8:11]
	v_mfma_f32_16x16x32_bf16 v[16:19], v[174:177], v[218:221], v[16:19]
	s_setprio 0
	s_barrier
	s_add_i32 s68, 0, 0x18000
	s_add_i32 s69, 0, 0x1c000
	v_add_u32_e32 v154, s68, v158
	v_add_u32_e32 v161, s69, v158
	ds_read_b128 v[142:145], v154
	ds_read_b128 v[146:149], v154 offset:1024
	ds_read_b128 v[150:153], v154 offset:2048
	ds_read_b128 v[154:157], v154 offset:3072
	ds_read_b128 v[162:165], v161
	ds_read_b128 v[166:169], v161 offset:1024
	ds_read_b128 v[170:173], v161 offset:2048
	ds_read_b128 v[174:177], v161 offset:3072
	s_add_u32 s48, s48, 0x40000
	s_addc_u32 s49, s49, 0
	s_mov_b32 m0, s57
	v_lshl_add_u64 v[228:229], s[48:49], 0, v[136:137]
	ds_read_b128 v[178:181], v160 offset:32768
	ds_read_b128 v[182:185], v160 offset:33792
	ds_read_b128 v[186:189], v160 offset:34816
	ds_read_b128 v[190:193], v160 offset:35840
	ds_read_b128 v[194:197], v160 offset:36864
	ds_read_b128 v[210:213], v160 offset:37888
	ds_read_b128 v[214:217], v160 offset:38912
	ds_read_b128 v[218:221], v160 offset:39936
	global_load_lds_dwordx4 v[228:229], off
	v_lshl_add_u64 v[228:229], s[48:49], 0, v[132:133]
	s_mov_b32 m0, s58
	s_nop 0
	global_load_lds_dwordx4 v[228:229], off
	s_waitcnt vmcnt(8)
	s_waitcnt lgkmcnt(0)
	s_barrier
	s_setprio 1
	v_mfma_f32_16x16x32_bf16 v[128:131], v[142:145], v[178:181], v[128:131]
	v_mfma_f32_16x16x32_bf16 v[120:123], v[150:153], v[178:181], v[120:123]
	v_mfma_f32_16x16x32_bf16 v[108:111], v[142:145], v[186:189], v[108:111]
	v_mfma_f32_16x16x32_bf16 v[100:103], v[150:153], v[186:189], v[100:103]
	v_mfma_f32_16x16x32_bf16 v[92:95], v[142:145], v[194:197], v[92:95]
	v_mfma_f32_16x16x32_bf16 v[84:87], v[150:153], v[194:197], v[84:87]
	v_mfma_f32_16x16x32_bf16 v[76:79], v[142:145], v[214:217], v[76:79]
	v_mfma_f32_16x16x32_bf16 v[68:71], v[150:153], v[214:217], v[68:71]
	v_mfma_f32_16x16x32_bf16 v[128:131], v[146:149], v[182:185], v[128:131]
	v_mfma_f32_16x16x32_bf16 v[120:123], v[154:157], v[182:185], v[120:123]
	v_mfma_f32_16x16x32_bf16 v[108:111], v[146:149], v[190:193], v[108:111]
	v_mfma_f32_16x16x32_bf16 v[100:103], v[154:157], v[190:193], v[100:103]
	v_mfma_f32_16x16x32_bf16 v[92:95], v[146:149], v[210:213], v[92:95]
	v_mfma_f32_16x16x32_bf16 v[84:87], v[154:157], v[210:213], v[84:87]
	v_mfma_f32_16x16x32_bf16 v[76:79], v[146:149], v[218:221], v[76:79]
	v_mfma_f32_16x16x32_bf16 v[68:71], v[154:157], v[218:221], v[68:71]
	v_mfma_f32_16x16x32_bf16 v[124:127], v[162:165], v[178:181], v[124:127]
	v_mfma_f32_16x16x32_bf16 v[116:119], v[170:173], v[178:181], v[116:119]
	v_mfma_f32_16x16x32_bf16 v[112:115], v[162:165], v[186:189], v[112:115]
	v_mfma_f32_16x16x32_bf16 v[104:107], v[170:173], v[186:189], v[104:107]
	v_mfma_f32_16x16x32_bf16 v[96:99], v[162:165], v[194:197], v[96:99]
	v_mfma_f32_16x16x32_bf16 v[88:91], v[170:173], v[194:197], v[88:91]
	v_mfma_f32_16x16x32_bf16 v[80:83], v[162:165], v[214:217], v[80:83]
	v_mfma_f32_16x16x32_bf16 v[72:75], v[170:173], v[214:217], v[72:75]
	v_mfma_f32_16x16x32_bf16 v[124:127], v[166:169], v[182:185], v[124:127]
	v_mfma_f32_16x16x32_bf16 v[116:119], v[174:177], v[182:185], v[116:119]
	v_mfma_f32_16x16x32_bf16 v[112:115], v[166:169], v[190:193], v[112:115]
	v_mfma_f32_16x16x32_bf16 v[104:107], v[174:177], v[190:193], v[104:107]
	v_mfma_f32_16x16x32_bf16 v[96:99], v[166:169], v[210:213], v[96:99]
	v_mfma_f32_16x16x32_bf16 v[88:91], v[174:177], v[210:213], v[88:91]
	v_mfma_f32_16x16x32_bf16 v[80:83], v[166:169], v[218:221], v[80:83]
	v_mfma_f32_16x16x32_bf16 v[72:75], v[174:177], v[218:221], v[72:75]
	s_setprio 0
	s_barrier
; #define PG8_STAGE(bufoff, gbase, voff) do { _Pragma("unroll") for (int _i = 0; _i < 2; ++_i) \
;         __builtin_amdgcn_global_load_lds((const unsigned*)((const char*)(gbase) + (voff)[_i]), (LAS unsigned*)(lds + (bufoff) + ldsw + _i * 8192), 16, 0, 0); } while (0)
; #define PG8_LDA(dst, b, h) do { _Pragma("unroll") for (int m = 0; m < 4; ++m) _Pragma("unroll") for (int k = 0; k < 2; ++k) dst[m][k] = *(const LAS bf16x8*)(lds + PG8_SA(b, h) + aoff + m * 2048 + k * 1024); } while (0)
; #define PG8_MMA(ai, bj, At, Bt) do { __builtin_amdgcn_s_setprio(1); _Pragma("unroll") for (int m = 0; m < 4; ++m) _Pragma("unroll") for (int n = 0; n < 2; ++n) _Pragma("unroll") for (int k = 0; k < 2; ++k) \
;         acc[ai][bj][m][n] = __builtin_amdgcn_mfma_f32_16x16x32_bf16(Bt[n][k], At[m][k], acc[ai][bj][m][n], 0, 0, 0); __builtin_amdgcn_s_setprio(0); } while (0)
; #define PG8_WAIT_V(n) asm volatile("s_waitcnt vmcnt(" #n ")" ::: "memory")
; #define PG8_WAIT_L(n) asm volatile("s_waitcnt lgkmcnt(" #n ")" ::: "memory")
; #define PG8_BAR __builtin_amdgcn_s_barrier()
; #define PG8_SCHED __builtin_amdgcn_sched_barrier(0)
; template <class Epi>
; __device__ __forceinline__ void gemm_phase(LAS unsigned char* lds, const Gemm g, const StaticOrder& S, const Epi& E) {
;     ...
;             PG8_LDA(At, 1, 1); PG8_STAGE(PG8_SB(1, 0), b3, voffB); PG8_STAGE(PG8_SB(1, 1), b3 + hstepB, voffB); PG8_STAGE(PG8_SA(1, 0), a3, voffA);
;             PG8_WAIT_V(8); PG8_WAIT_L(0); PG8_BAR; PG8_MMA(1, 0, At, B0); PG8_MMA(1, 1, At, B1); PG8_BAR; PG8_SCHED;
;         }
;         if (wr == 0) PG8_BAR;
	s_add_i32 s48, s68, s54
	v_lshl_add_u64 v[198:199], v[198:199], 0, s[30:31]
	s_mov_b32 m0, s48
	ds_read_b128 v[178:181], v160 offset:49152
	ds_read_b128 v[182:185], v160 offset:50176
	ds_read_b128 v[186:189], v160 offset:51200
	ds_read_b128 v[190:193], v160 offset:52224
	ds_read_b128 v[194:197], v160 offset:53248
	ds_read_b128 v[210:213], v160 offset:54272
	ds_read_b128 v[214:217], v160 offset:55296
	ds_read_b128 v[218:221], v160 offset:56320
	global_load_lds_dwordx4 v[198:199], off
	s_add_i32 m0, s48, 0x2000
	s_add_u32 s22, s22, 0x10080
	v_lshl_add_u64 v[198:199], v[222:223], 0, s[30:31]
	s_addc_u32 s23, s23, 0
	s_add_i32 s48, s69, s54
	global_load_lds_dwordx4 v[198:199], off
	v_lshl_add_u64 v[198:199], s[22:23], 0, v[134:135]
	s_mov_b32 m0, s48
	s_nop 0
	global_load_lds_dwordx4 v[198:199], off
	v_lshl_add_u64 v[198:199], s[22:23], 0, v[0:1]
	s_add_i32 m0, s48, 0x2000
	s_nop 0
	global_load_lds_dwordx4 v[198:199], off
	v_lshl_add_u64 v[198:199], v[224:225], 0, s[30:31]
	s_mov_b32 m0, s28
	s_nop 0
	global_load_lds_dwordx4 v[198:199], off
	v_lshl_add_u64 v[198:199], v[226:227], 0, s[30:31]
	s_mov_b32 m0, s59
	s_nop 0
	global_load_lds_dwordx4 v[198:199], off
	s_waitcnt vmcnt(8)
	s_waitcnt lgkmcnt(0)
	s_barrier
	s_setprio 1
	v_mfma_f32_16x16x32_bf16 v[60:63], v[142:145], v[178:181], v[60:63]
	v_mfma_f32_16x16x32_bf16 v[52:55], v[150:153], v[178:181], v[52:55]
	v_mfma_f32_16x16x32_bf16 v[44:47], v[142:145], v[186:189], v[44:47]
	v_mfma_f32_16x16x32_bf16 v[36:39], v[150:153], v[186:189], v[36:39]
	v_mfma_f32_16x16x32_bf16 v[28:31], v[142:145], v[194:197], v[28:31]
	v_mfma_f32_16x16x32_bf16 v[20:23], v[150:153], v[194:197], v[20:23]
	v_mfma_f32_16x16x32_bf16 v[4:7], v[142:145], v[214:217], v[4:7]
	v_mfma_f32_16x16x32_bf16 v[12:15], v[150:153], v[214:217], v[12:15]
	v_mfma_f32_16x16x32_bf16 v[60:63], v[146:149], v[182:185], v[60:63]
	v_mfma_f32_16x16x32_bf16 v[52:55], v[154:157], v[182:185], v[52:55]
	v_mfma_f32_16x16x32_bf16 v[44:47], v[146:149], v[190:193], v[44:47]
	v_mfma_f32_16x16x32_bf16 v[36:39], v[154:157], v[190:193], v[36:39]
	v_mfma_f32_16x16x32_bf16 v[28:31], v[146:149], v[210:213], v[28:31]
	v_mfma_f32_16x16x32_bf16 v[20:23], v[154:157], v[210:213], v[20:23]
	v_mfma_f32_16x16x32_bf16 v[4:7], v[146:149], v[218:221], v[4:7]
	v_mfma_f32_16x16x32_bf16 v[12:15], v[154:157], v[218:221], v[12:15]
	v_mfma_f32_16x16x32_bf16 v[64:67], v[162:165], v[178:181], v[64:67]
	v_mfma_f32_16x16x32_bf16 v[56:59], v[170:173], v[178:181], v[56:59]
	v_mfma_f32_16x16x32_bf16 v[48:51], v[162:165], v[186:189], v[48:51]
	v_mfma_f32_16x16x32_bf16 v[40:43], v[170:173], v[186:189], v[40:43]
	v_mfma_f32_16x16x32_bf16 v[32:35], v[162:165], v[194:197], v[32:35]
	v_mfma_f32_16x16x32_bf16 v[24:27], v[170:173], v[194:197], v[24:27]
	v_mfma_f32_16x16x32_bf16 v[8:11], v[162:165], v[214:217], v[8:11]
	v_mfma_f32_16x16x32_bf16 v[16:19], v[170:173], v[214:217], v[16:19]
	v_mfma_f32_16x16x32_bf16 v[64:67], v[166:169], v[182:185], v[64:67]
	v_mfma_f32_16x16x32_bf16 v[56:59], v[174:177], v[182:185], v[56:59]
	v_mfma_f32_16x16x32_bf16 v[48:51], v[166:169], v[190:193], v[48:51]
	v_mfma_f32_16x16x32_bf16 v[40:43], v[174:177], v[190:193], v[40:43]
	v_mfma_f32_16x16x32_bf16 v[32:35], v[166:169], v[210:213], v[32:35]
	v_mfma_f32_16x16x32_bf16 v[24:27], v[174:177], v[210:213], v[24:27]
	v_mfma_f32_16x16x32_bf16 v[8:11], v[166:169], v[218:221], v[8:11]
	v_mfma_f32_16x16x32_bf16 v[16:19], v[174:177], v[218:221], v[16:19]
	s_setprio 0
	s_barrier
	s_add_i32 s67, s67, 2
	s_add_u32 s46, s46, 0x100
	s_addc_u32 s47, s47, 0
	s_add_u32 s65, s65, 0x100
	s_addc_u32 s66, s66, 0
	s_cmp_gt_u32 s67, 13
	s_cbranch_scc0 .LBB0_1088
	s_and_b64 vcc, exec, s[12:13]
	s_cbranch_vccz .LBB0_1091
	s_barrier

; #define PG8_STAGE(bufoff, gbase, voff) do { _Pragma("unroll") for (int _i = 0; _i < 2; ++_i) \
;         __builtin_amdgcn_global_load_lds((const unsigned*)((const char*)(gbase) + (voff)[_i]), (LAS unsigned*)(lds + (bufoff) + ldsw + _i * 8192), 16, 0, 0); } while (0)
; #define PG8_LDA(dst, b, h) do { _Pragma("unroll") for (int m = 0; m < 4; ++m) _Pragma("unroll") for (int k = 0; k < 2; ++k) dst[m][k] = *(const LAS bf16x8*)(lds + PG8_SA(b, h) + aoff + m * 2048 + k * 1024); } while (0)
; #define PG8_LDB(dst, b, h) do { _Pragma("unroll") for (int n = 0; n < 2; ++n) _Pragma("unroll") for (int k = 0; k < 2; ++k) dst[n][k] = *(const LAS bf16x8*)(lds + PG8_SB(b, h) + boff + n * 2048 + k * 1024); } while (0)
; #define PG8_MMA(ai, bj, At, Bt) do { __builtin_amdgcn_s_setprio(1); _Pragma("unroll") for (int m = 0; m < 4; ++m) _Pragma("unroll") for (int n = 0; n < 2; ++n) _Pragma("unroll") for (int k = 0; k < 2; ++k) \
;         acc[ai][bj][m][n] = __builtin_amdgcn_mfma_f32_16x16x32_bf16(Bt[n][k], At[m][k], acc[ai][bj][m][n], 0, 0, 0); __builtin_amdgcn_s_setprio(0); } while (0)
; #define PG8_WAIT_V(n) asm volatile("s_waitcnt vmcnt(" #n ")" ::: "memory")
; #define PG8_WAIT_L(n) asm volatile("s_waitcnt lgkmcnt(" #n ")" ::: "memory")
; #define PG8_BAR __builtin_amdgcn_s_barrier()
; #define PG8_SCHED __builtin_amdgcn_sched_barrier(0)
; template <class Epi>
; __device__ __forceinline__ void gemm_phase(LAS unsigned char* lds, const Gemm g, const StaticOrder& S, const Epi& E) {
;     ...
;         for (int t = 0; t < nt; t += 2) {
;             const bool last = (t == nt - 2);
;             const char* a1 = cA + (size_t)(t + 1) * kstep;
;             const char* a2 = last ? nA : cA + (size_t)(t + 2) * kstep; const char* b2 = last ? nB : cB + (size_t)(t + 2) * kstep;
;             const char* a3 = a2 + kstep; const char* b3 = b2 + kstep;
;             PG8_LDB(B0, 0, 0); PG8_LDB(B1, 0, 1); PG8_SCHED; PG8_LDA(At, 0, 0); PG8_STAGE(PG8_SA(1, 1), a1 + hstepA, voffA);
;             PG8_WAIT_V(8); PG8_WAIT_L(0); PG8_BAR; PG8_MMA(0, 0, At, B0); PG8_MMA(0, 1, At, B1); PG8_BAR; PG8_SCHED;
;             PG8_LDA(At, 0, 1); PG8_STAGE(PG8_SB(0, 0), b2, voffB); PG8_STAGE(PG8_SB(0, 1), b2 + hstepB, voffB); PG8_STAGE(PG8_SA(0, 0), a2, voffA);
;             PG8_WAIT_V(8); PG8_WAIT_L(0); PG8_BAR; PG8_MMA(1, 0, At, B0); PG8_MMA(1, 1, At, B1); PG8_BAR; PG8_SCHED;
.LBB0_1163:
	s_add_u32 s48, s46, 0x100
	s_addc_u32 s49, s47, 0
	s_add_i32 s70, 0, 0x10000
	s_cmp_eq_u32 s69, 40
	s_cselect_b32 s51, s5, s49
	s_cselect_b32 s50, s4, s48
	s_cselect_b32 s23, s39, s68
	s_cselect_b32 s22, s38, s67
	s_add_i32 s71, 0, 0x14000
	v_add_u32_e32 v144, s70, v232
	v_add_u32_e32 v160, s71, v232
	ds_read_b128 v[132:135], v144
	ds_read_b128 v[136:139], v144 offset:1024
	ds_read_b128 v[140:143], v144 offset:2048
	ds_read_b128 v[144:147], v144 offset:3072
	ds_read_b128 v[148:151], v160
	ds_read_b128 v[152:155], v160 offset:1024
	ds_read_b128 v[156:159], v160 offset:2048
	ds_read_b128 v[160:163], v160 offset:3072
	v_lshl_add_u64 v[216:217], s[46:47], 0, v[194:195]
	s_add_i32 m0, s57, 0xc000
	ds_read_b128 v[164:167], v242
	ds_read_b128 v[168:171], v242 offset:1024
	ds_read_b128 v[172:175], v242 offset:2048
	ds_read_b128 v[176:179], v242 offset:3072
	ds_read_b128 v[180:183], v242 offset:4096
	ds_read_b128 v[184:187], v242 offset:5120
	ds_read_b128 v[196:199], v242 offset:6144
	ds_read_b128 v[212:215], v242 offset:7168
	global_load_lds_dwordx4 v[216:217], off
	v_lshl_add_u64 v[216:217], s[46:47], 0, v[210:211]
	s_add_i32 m0, s57, 0xe000
	s_nop 0
	global_load_lds_dwordx4 v[216:217], off
	s_waitcnt vmcnt(8)
	s_waitcnt lgkmcnt(0)
	s_barrier
	s_setprio 1
	v_mfma_f32_16x16x32_bf16 v[128:131], v[132:135], v[164:167], v[128:131]
	v_mfma_f32_16x16x32_bf16 v[124:127], v[140:143], v[164:167], v[124:127]
	v_mfma_f32_16x16x32_bf16 v[112:115], v[132:135], v[172:175], v[112:115]
	v_mfma_f32_16x16x32_bf16 v[108:111], v[140:143], v[172:175], v[108:111]
	v_mfma_f32_16x16x32_bf16 v[96:99], v[132:135], v[180:183], v[96:99]
	v_mfma_f32_16x16x32_bf16 v[92:95], v[140:143], v[180:183], v[92:95]
	v_mfma_f32_16x16x32_bf16 v[80:83], v[132:135], v[196:199], v[80:83]
	v_mfma_f32_16x16x32_bf16 v[76:79], v[140:143], v[196:199], v[76:79]
	v_mfma_f32_16x16x32_bf16 v[128:131], v[136:139], v[168:171], v[128:131]
	v_mfma_f32_16x16x32_bf16 v[124:127], v[144:147], v[168:171], v[124:127]
	v_mfma_f32_16x16x32_bf16 v[112:115], v[136:139], v[176:179], v[112:115]
	v_mfma_f32_16x16x32_bf16 v[108:111], v[144:147], v[176:179], v[108:111]
	v_mfma_f32_16x16x32_bf16 v[96:99], v[136:139], v[184:187], v[96:99]
	v_mfma_f32_16x16x32_bf16 v[92:95], v[144:147], v[184:187], v[92:95]
	v_mfma_f32_16x16x32_bf16 v[80:83], v[136:139], v[212:215], v[80:83]
	v_mfma_f32_16x16x32_bf16 v[76:79], v[144:147], v[212:215], v[76:79]
	v_mfma_f32_16x16x32_bf16 v[120:123], v[148:151], v[164:167], v[120:123]
	v_mfma_f32_16x16x32_bf16 v[116:119], v[156:159], v[164:167], v[116:119]
	v_mfma_f32_16x16x32_bf16 v[104:107], v[148:151], v[172:175], v[104:107]
	v_mfma_f32_16x16x32_bf16 v[100:103], v[156:159], v[172:175], v[100:103]
	v_mfma_f32_16x16x32_bf16 v[88:91], v[148:151], v[180:183], v[88:91]
	v_mfma_f32_16x16x32_bf16 v[84:87], v[156:159], v[180:183], v[84:87]
	v_mfma_f32_16x16x32_bf16 v[72:75], v[148:151], v[196:199], v[72:75]
	v_mfma_f32_16x16x32_bf16 v[68:71], v[156:159], v[196:199], v[68:71]
	v_mfma_f32_16x16x32_bf16 v[120:123], v[152:155], v[168:171], v[120:123]
	v_mfma_f32_16x16x32_bf16 v[116:119], v[160:163], v[168:171], v[116:119]
	v_mfma_f32_16x16x32_bf16 v[104:107], v[152:155], v[176:179], v[104:107]
	v_mfma_f32_16x16x32_bf16 v[100:103], v[160:163], v[176:179], v[100:103]
	v_mfma_f32_16x16x32_bf16 v[88:91], v[152:155], v[184:187], v[88:91]
	v_mfma_f32_16x16x32_bf16 v[84:87], v[160:163], v[184:187], v[84:87]
	v_mfma_f32_16x16x32_bf16 v[72:75], v[152:155], v[212:215], v[72:75]
	v_mfma_f32_16x16x32_bf16 v[68:71], v[160:163], v[212:215], v[68:71]
	s_setprio 0
	s_barrier
	s_add_i32 s46, s70, s56
	v_lshl_add_u64 v[216:217], s[22:23], 0, v[190:191]
	s_mov_b32 m0, s46
	ds_read_b128 v[164:167], v242 offset:16384
	ds_read_b128 v[168:171], v242 offset:17408
	ds_read_b128 v[172:175], v242 offset:18432
	ds_read_b128 v[176:179], v242 offset:19456
	ds_read_b128 v[180:183], v242 offset:20480
	ds_read_b128 v[184:187], v242 offset:21504
	ds_read_b128 v[196:199], v242 offset:22528
	ds_read_b128 v[212:215], v242 offset:23552
	global_load_lds_dwordx4 v[216:217], off
	s_add_i32 m0, s46, 0x2000
	s_add_u32 s46, s22, 0x2c000
	v_lshl_add_u64 v[218:219], s[22:23], 0, v[0:1]
	s_addc_u32 s47, s23, 0
	s_add_i32 s70, s71, s56
	global_load_lds_dwordx4 v[218:219], off
	v_lshl_add_u64 v[220:221], s[46:47], 0, v[190:191]
	s_mov_b32 m0, s70
	v_lshl_add_u64 v[222:223], s[50:51], 0, v[188:189]
	global_load_lds_dwordx4 v[220:221], off
	v_lshl_add_u64 v[220:221], s[46:47], 0, v[0:1]
	s_add_i32 m0, s70, 0x2000
	s_nop 0
	global_load_lds_dwordx4 v[220:221], off
	v_lshl_add_u64 v[220:221], s[50:51], 0, v[192:193]
	s_mov_b32 m0, s57
	s_nop 0
	global_load_lds_dwordx4 v[220:221], off
	s_mov_b32 m0, s58
	s_nop 0
	global_load_lds_dwordx4 v[222:223], off
	s_waitcnt vmcnt(8)
	s_waitcnt lgkmcnt(0)
	s_barrier
; #define PG8_STAGE(bufoff, gbase, voff) do { _Pragma("unroll") for (int _i = 0; _i < 2; ++_i) \
;         __builtin_amdgcn_global_load_lds((const unsigned*)((const char*)(gbase) + (voff)[_i]), (LAS unsigned*)(lds + (bufoff) + ldsw + _i * 8192), 16, 0, 0); } while (0)
; #define PG8_LDA(dst, b, h) do { _Pragma("unroll") for (int m = 0; m < 4; ++m) _Pragma("unroll") for (int k = 0; k < 2; ++k) dst[m][k] = *(const LAS bf16x8*)(lds + PG8_SA(b, h) + aoff + m * 2048 + k * 1024); } while (0)
; #define PG8_LDB(dst, b, h) do { _Pragma("unroll") for (int n = 0; n < 2; ++n) _Pragma("unroll") for (int k = 0; k < 2; ++k) dst[n][k] = *(const LAS bf16x8*)(lds + PG8_SB(b, h) + boff + n * 2048 + k * 1024); } while (0)
; #define PG8_MMA(ai, bj, At, Bt) do { __builtin_amdgcn_s_setprio(1); _Pragma("unroll") for (int m = 0; m < 4; ++m) _Pragma("unroll") for (int n = 0; n < 2; ++n) _Pragma("unroll") for (int k = 0; k < 2; ++k) \
;         acc[ai][bj][m][n] = __builtin_amdgcn_mfma_f32_16x16x32_bf16(Bt[n][k], At[m][k], acc[ai][bj][m][n], 0, 0, 0); __builtin_amdgcn_s_setprio(0); } while (0)
; #define PG8_WAIT_V(n) asm volatile("s_waitcnt vmcnt(" #n ")" ::: "memory")
; #define PG8_WAIT_L(n) asm volatile("s_waitcnt lgkmcnt(" #n ")" ::: "memory")
; #define PG8_BAR __builtin_amdgcn_s_barrier()
; #define PG8_SCHED __builtin_amdgcn_sched_barrier(0)
; template <class Epi>
; __device__ __forceinline__ void gemm_phase(LAS unsigned char* lds, const Gemm g, const StaticOrder& S, const Epi& E) {
;     ...
;             PG8_WAIT_V(8); PG8_WAIT_L(0); PG8_BAR; PG8_MMA(1, 0, At, B0); PG8_MMA(1, 1, At, B1); PG8_BAR; PG8_SCHED;
;             PG8_LDB(B0, 1, 0); PG8_LDB(B1, 1, 1); PG8_SCHED; PG8_LDA(At, 1, 0); PG8_STAGE(PG8_SA(0, 1), a2 + hstepA, voffA);
;             PG8_WAIT_V(8); PG8_WAIT_L(0); PG8_BAR; PG8_MMA(0, 0, At, B0); PG8_MMA(0, 1, At, B1); PG8_BAR; PG8_SCHED;
	s_setprio 1
	v_mfma_f32_16x16x32_bf16 v[64:67], v[132:135], v[164:167], v[64:67]
	v_mfma_f32_16x16x32_bf16 v[60:63], v[140:143], v[164:167], v[60:63]
	v_mfma_f32_16x16x32_bf16 v[48:51], v[132:135], v[172:175], v[48:51]
	v_mfma_f32_16x16x32_bf16 v[44:47], v[140:143], v[172:175], v[44:47]
	v_mfma_f32_16x16x32_bf16 v[32:35], v[132:135], v[180:183], v[32:35]
	v_mfma_f32_16x16x32_bf16 v[28:31], v[140:143], v[180:183], v[28:31]
	v_mfma_f32_16x16x32_bf16 v[16:19], v[132:135], v[196:199], v[16:19]
	v_mfma_f32_16x16x32_bf16 v[12:15], v[140:143], v[196:199], v[12:15]
	v_mfma_f32_16x16x32_bf16 v[64:67], v[136:139], v[168:171], v[64:67]
	v_mfma_f32_16x16x32_bf16 v[60:63], v[144:147], v[168:171], v[60:63]
	v_mfma_f32_16x16x32_bf16 v[48:51], v[136:139], v[176:179], v[48:51]
	v_mfma_f32_16x16x32_bf16 v[44:47], v[144:147], v[176:179], v[44:47]
	v_mfma_f32_16x16x32_bf16 v[32:35], v[136:139], v[184:187], v[32:35]
	v_mfma_f32_16x16x32_bf16 v[28:31], v[144:147], v[184:187], v[28:31]
	v_mfma_f32_16x16x32_bf16 v[16:19], v[136:139], v[212:215], v[16:19]
	v_mfma_f32_16x16x32_bf16 v[12:15], v[144:147], v[212:215], v[12:15]
	v_mfma_f32_16x16x32_bf16 v[56:59], v[148:151], v[164:167], v[56:59]
	v_mfma_f32_16x16x32_bf16 v[52:55], v[156:159], v[164:167], v[52:55]
	v_mfma_f32_16x16x32_bf16 v[40:43], v[148:151], v[172:175], v[40:43]
	v_mfma_f32_16x16x32_bf16 v[36:39], v[156:159], v[172:175], v[36:39]
	v_mfma_f32_16x16x32_bf16 v[24:27], v[148:151], v[180:183], v[24:27]
	v_mfma_f32_16x16x32_bf16 v[20:23], v[156:159], v[180:183], v[20:23]
	v_mfma_f32_16x16x32_bf16 v[8:11], v[148:151], v[196:199], v[8:11]
	v_mfma_f32_16x16x32_bf16 v[4:7], v[156:159], v[196:199], v[4:7]
	v_mfma_f32_16x16x32_bf16 v[56:59], v[152:155], v[168:171], v[56:59]
	v_mfma_f32_16x16x32_bf16 v[52:55], v[160:163], v[168:171], v[52:55]
	v_mfma_f32_16x16x32_bf16 v[40:43], v[152:155], v[176:179], v[40:43]
	v_mfma_f32_16x16x32_bf16 v[36:39], v[160:163], v[176:179], v[36:39]
	v_mfma_f32_16x16x32_bf16 v[24:27], v[152:155], v[184:187], v[24:27]
	v_mfma_f32_16x16x32_bf16 v[20:23], v[160:163], v[184:187], v[20:23]
	v_mfma_f32_16x16x32_bf16 v[8:11], v[152:155], v[212:215], v[8:11]
	v_mfma_f32_16x16x32_bf16 v[4:7], v[160:163], v[212:215], v[4:7]
	s_setprio 0
	s_barrier
	s_add_i32 s70, 0, 0x18000
	s_add_i32 s71, 0, 0x1c000
	v_add_u32_e32 v144, s70, v232
	v_add_u32_e32 v160, s71, v232
	ds_read_b128 v[132:135], v144
	ds_read_b128 v[136:139], v144 offset:1024
	ds_read_b128 v[140:143], v144 offset:2048
	ds_read_b128 v[144:147], v144 offset:3072
	ds_read_b128 v[148:151], v160
	ds_read_b128 v[152:155], v160 offset:1024
	ds_read_b128 v[156:159], v160 offset:2048
	ds_read_b128 v[160:163], v160 offset:3072
	s_add_u32 s46, s50, 0xb0000
	s_addc_u32 s47, s51, 0
	s_mov_b32 m0, s59
	v_lshl_add_u64 v[224:225], s[46:47], 0, v[192:193]
	ds_read_b128 v[164:167], v242 offset:32768
	ds_read_b128 v[168:171], v242 offset:33792
	ds_read_b128 v[172:175], v242 offset:34816
	ds_read_b128 v[176:179], v242 offset:35840
	ds_read_b128 v[180:183], v242 offset:36864
	ds_read_b128 v[184:187], v242 offset:37888
	ds_read_b128 v[196:199], v242 offset:38912
	ds_read_b128 v[212:215], v242 offset:39936
	global_load_lds_dwordx4 v[224:225], off
	v_lshl_add_u64 v[224:225], s[46:47], 0, v[188:189]
	s_mov_b32 m0, s60
	s_nop 0
	global_load_lds_dwordx4 v[224:225], off
	s_waitcnt vmcnt(8)
	s_waitcnt lgkmcnt(0)
	s_barrier
	s_setprio 1
	v_mfma_f32_16x16x32_bf16 v[128:131], v[132:135], v[164:167], v[128:131]
	v_mfma_f32_16x16x32_bf16 v[124:127], v[140:143], v[164:167], v[124:127]
	v_mfma_f32_16x16x32_bf16 v[112:115], v[132:135], v[172:175], v[112:115]
	v_mfma_f32_16x16x32_bf16 v[108:111], v[140:143], v[172:175], v[108:111]
	v_mfma_f32_16x16x32_bf16 v[96:99], v[132:135], v[180:183], v[96:99]
	v_mfma_f32_16x16x32_bf16 v[92:95], v[140:143], v[180:183], v[92:95]
	v_mfma_f32_16x16x32_bf16 v[80:83], v[132:135], v[196:199], v[80:83]
	v_mfma_f32_16x16x32_bf16 v[76:79], v[140:143], v[196:199], v[76:79]
	v_mfma_f32_16x16x32_bf16 v[128:131], v[136:139], v[168:171], v[128:131]
	v_mfma_f32_16x16x32_bf16 v[124:127], v[144:147], v[168:171], v[124:127]
	v_mfma_f32_16x16x32_bf16 v[112:115], v[136:139], v[176:179], v[112:115]
	v_mfma_f32_16x16x32_bf16 v[108:111], v[144:147], v[176:179], v[108:111]
	v_mfma_f32_16x16x32_bf16 v[96:99], v[136:139], v[184:187], v[96:99]
	v_mfma_f32_16x16x32_bf16 v[92:95], v[144:147], v[184:187], v[92:95]
	v_mfma_f32_16x16x32_bf16 v[80:83], v[136:139], v[212:215], v[80:83]
	v_mfma_f32_16x16x32_bf16 v[76:79], v[144:147], v[212:215], v[76:79]
	v_mfma_f32_16x16x32_bf16 v[120:123], v[148:151], v[164:167], v[120:123]
	v_mfma_f32_16x16x32_bf16 v[116:119], v[156:159], v[164:167], v[116:119]
	v_mfma_f32_16x16x32_bf16 v[104:107], v[148:151], v[172:175], v[104:107]
	v_mfma_f32_16x16x32_bf16 v[100:103], v[156:159], v[172:175], v[100:103]
	v_mfma_f32_16x16x32_bf16 v[88:91], v[148:151], v[180:183], v[88:91]
	v_mfma_f32_16x16x32_bf16 v[84:87], v[156:159], v[180:183], v[84:87]
	v_mfma_f32_16x16x32_bf16 v[72:75], v[148:151], v[196:199], v[72:75]
	v_mfma_f32_16x16x32_bf16 v[68:71], v[156:159], v[196:199], v[68:71]
	v_mfma_f32_16x16x32_bf16 v[120:123], v[152:155], v[168:171], v[120:123]
	v_mfma_f32_16x16x32_bf16 v[116:119], v[160:163], v[168:171], v[116:119]
	v_mfma_f32_16x16x32_bf16 v[104:107], v[152:155], v[176:179], v[104:107]
	v_mfma_f32_16x16x32_bf16 v[100:103], v[160:163], v[176:179], v[100:103]
	v_mfma_f32_16x16x32_bf16 v[88:91], v[152:155], v[184:187], v[88:91]
	v_mfma_f32_16x16x32_bf16 v[84:87], v[160:163], v[184:187], v[84:87]
	v_mfma_f32_16x16x32_bf16 v[72:75], v[152:155], v[212:215], v[72:75]
	v_mfma_f32_16x16x32_bf16 v[68:71], v[160:163], v[212:215], v[68:71]
	s_setprio 0
	s_barrier
; #define PG8_STAGE(bufoff, gbase, voff) do { _Pragma("unroll") for (int _i = 0; _i < 2; ++_i) \
;         __builtin_amdgcn_global_load_lds((const unsigned*)((const char*)(gbase) + (voff)[_i]), (LAS unsigned*)(lds + (bufoff) + ldsw + _i * 8192), 16, 0, 0); } while (0)
; #define PG8_LDA(dst, b, h) do { _Pragma("unroll") for (int m = 0; m < 4; ++m) _Pragma("unroll") for (int k = 0; k < 2; ++k) dst[m][k] = *(const LAS bf16x8*)(lds + PG8_SA(b, h) + aoff + m * 2048 + k * 1024); } while (0)
; #define PG8_MMA(ai, bj, At, Bt) do { __builtin_amdgcn_s_setprio(1); _Pragma("unroll") for (int m = 0; m < 4; ++m) _Pragma("unroll") for (int n = 0; n < 2; ++n) _Pragma("unroll") for (int k = 0; k < 2; ++k) \
;         acc[ai][bj][m][n] = __builtin_amdgcn_mfma_f32_16x16x32_bf16(Bt[n][k], At[m][k], acc[ai][bj][m][n], 0, 0, 0); __builtin_amdgcn_s_setprio(0); } while (0)
; #define PG8_WAIT_V(n) asm volatile("s_waitcnt vmcnt(" #n ")" ::: "memory")
; #define PG8_WAIT_L(n) asm volatile("s_waitcnt lgkmcnt(" #n ")" ::: "memory")
; #define PG8_BAR __builtin_amdgcn_s_barrier()
; #define PG8_SCHED __builtin_amdgcn_sched_barrier(0)
; template <class Epi>
; __device__ __forceinline__ void gemm_phase(LAS unsigned char* lds, const Gemm g, const StaticOrder& S, const Epi& E) {
;     ...
;             PG8_LDA(At, 1, 1); PG8_STAGE(PG8_SB(1, 0), b3, voffB); PG8_STAGE(PG8_SB(1, 1), b3 + hstepB, voffB); PG8_STAGE(PG8_SA(1, 0), a3, voffA);
;             PG8_WAIT_V(8); PG8_WAIT_L(0); PG8_BAR; PG8_MMA(1, 0, At, B0); PG8_MMA(1, 1, At, B1); PG8_BAR; PG8_SCHED;
;         }
;         if (wr == 0) PG8_BAR;
	s_add_i32 s46, s70, s56
	v_lshl_add_u64 v[216:217], v[216:217], 0, s[30:31]
	s_mov_b32 m0, s46
	ds_read_b128 v[164:167], v242 offset:49152
	ds_read_b128 v[168:171], v242 offset:50176
	ds_read_b128 v[172:175], v242 offset:51200
	ds_read_b128 v[176:179], v242 offset:52224
	ds_read_b128 v[180:183], v242 offset:53248
	ds_read_b128 v[184:187], v242 offset:54272
	ds_read_b128 v[196:199], v242 offset:55296
	ds_read_b128 v[212:215], v242 offset:56320
	global_load_lds_dwordx4 v[216:217], off
	s_add_i32 m0, s46, 0x2000
	s_add_u32 s22, s22, 0x2c080
	v_lshl_add_u64 v[216:217], v[218:219], 0, s[30:31]
	s_addc_u32 s23, s23, 0
	s_add_i32 s46, s71, s56
	global_load_lds_dwordx4 v[216:217], off
	v_lshl_add_u64 v[216:217], s[22:23], 0, v[190:191]
	s_mov_b32 m0, s46
	s_nop 0
	global_load_lds_dwordx4 v[216:217], off
	v_lshl_add_u64 v[216:217], s[22:23], 0, v[0:1]
	s_add_i32 m0, s46, 0x2000
	s_nop 0
	global_load_lds_dwordx4 v[216:217], off
	v_lshl_add_u64 v[216:217], v[220:221], 0, s[30:31]
	s_mov_b32 m0, s28
	s_nop 0
	global_load_lds_dwordx4 v[216:217], off
	v_lshl_add_u64 v[216:217], v[222:223], 0, s[30:31]
	s_mov_b32 m0, s61
	s_nop 0
	global_load_lds_dwordx4 v[216:217], off
	s_waitcnt vmcnt(8)
	s_waitcnt lgkmcnt(0)
	s_barrier
	s_setprio 1
	v_mfma_f32_16x16x32_bf16 v[64:67], v[132:135], v[164:167], v[64:67]
	v_mfma_f32_16x16x32_bf16 v[60:63], v[140:143], v[164:167], v[60:63]
	v_mfma_f32_16x16x32_bf16 v[48:51], v[132:135], v[172:175], v[48:51]
	v_mfma_f32_16x16x32_bf16 v[44:47], v[140:143], v[172:175], v[44:47]
	v_mfma_f32_16x16x32_bf16 v[32:35], v[132:135], v[180:183], v[32:35]
	v_mfma_f32_16x16x32_bf16 v[28:31], v[140:143], v[180:183], v[28:31]
	v_mfma_f32_16x16x32_bf16 v[16:19], v[132:135], v[196:199], v[16:19]
	v_mfma_f32_16x16x32_bf16 v[12:15], v[140:143], v[196:199], v[12:15]
	v_mfma_f32_16x16x32_bf16 v[64:67], v[136:139], v[168:171], v[64:67]
	v_mfma_f32_16x16x32_bf16 v[60:63], v[144:147], v[168:171], v[60:63]
	v_mfma_f32_16x16x32_bf16 v[48:51], v[136:139], v[176:179], v[48:51]
	v_mfma_f32_16x16x32_bf16 v[44:47], v[144:147], v[176:179], v[44:47]
	v_mfma_f32_16x16x32_bf16 v[32:35], v[136:139], v[184:187], v[32:35]
	v_mfma_f32_16x16x32_bf16 v[28:31], v[144:147], v[184:187], v[28:31]
	v_mfma_f32_16x16x32_bf16 v[16:19], v[136:139], v[212:215], v[16:19]
	v_mfma_f32_16x16x32_bf16 v[12:15], v[144:147], v[212:215], v[12:15]
	v_mfma_f32_16x16x32_bf16 v[56:59], v[148:151], v[164:167], v[56:59]
	v_mfma_f32_16x16x32_bf16 v[52:55], v[156:159], v[164:167], v[52:55]
	v_mfma_f32_16x16x32_bf16 v[40:43], v[148:151], v[172:175], v[40:43]
	v_mfma_f32_16x16x32_bf16 v[36:39], v[156:159], v[172:175], v[36:39]
	v_mfma_f32_16x16x32_bf16 v[24:27], v[148:151], v[180:183], v[24:27]
	v_mfma_f32_16x16x32_bf16 v[20:23], v[156:159], v[180:183], v[20:23]
	v_mfma_f32_16x16x32_bf16 v[8:11], v[148:151], v[196:199], v[8:11]
	v_mfma_f32_16x16x32_bf16 v[4:7], v[156:159], v[196:199], v[4:7]
	v_mfma_f32_16x16x32_bf16 v[56:59], v[152:155], v[168:171], v[56:59]
	v_mfma_f32_16x16x32_bf16 v[52:55], v[160:163], v[168:171], v[52:55]
	v_mfma_f32_16x16x32_bf16 v[40:43], v[152:155], v[176:179], v[40:43]
	v_mfma_f32_16x16x32_bf16 v[36:39], v[160:163], v[176:179], v[36:39]
	v_mfma_f32_16x16x32_bf16 v[24:27], v[152:155], v[184:187], v[24:27]
	v_mfma_f32_16x16x32_bf16 v[20:23], v[160:163], v[184:187], v[20:23]
	v_mfma_f32_16x16x32_bf16 v[8:11], v[152:155], v[212:215], v[8:11]
	v_mfma_f32_16x16x32_bf16 v[4:7], v[160:163], v[212:215], v[4:7]
	s_setprio 0
	s_barrier
	s_add_i32 s69, s69, 2
	s_add_u32 s67, s67, 0x100
	s_addc_u32 s68, s68, 0
	s_cmp_gt_u32 s69, 41
	s_mov_b64 s[46:47], s[48:49]
	s_cbranch_scc0 .LBB0_1163
	s_and_b64 vcc, exec, s[34:35]
	s_cbranch_vccz .LBB0_1166
	s_barrier

; #define PG8_STAGE(bufoff, gbase, voff) do { _Pragma("unroll") for (int _i = 0; _i < 2; ++_i) \
;         __builtin_amdgcn_global_load_lds((const unsigned*)((const char*)(gbase) + (voff)[_i]), (LAS unsigned*)(lds + (bufoff) + ldsw + _i * 8192), 16, 0, 0); } while (0)
; #define PG8_LDA(dst, b, h) do { _Pragma("unroll") for (int m = 0; m < 4; ++m) _Pragma("unroll") for (int k = 0; k < 2; ++k) dst[m][k] = *(const LAS bf16x8*)(lds + PG8_SA(b, h) + aoff + m * 2048 + k * 1024); } while (0)
; #define PG8_LDB(dst, b, h) do { _Pragma("unroll") for (int n = 0; n < 2; ++n) _Pragma("unroll") for (int k = 0; k < 2; ++k) dst[n][k] = *(const LAS bf16x8*)(lds + PG8_SB(b, h) + boff + n * 2048 + k * 1024); } while (0)
; #define PG8_MMA(ai, bj, At, Bt) do { __builtin_amdgcn_s_setprio(1); _Pragma("unroll") for (int m = 0; m < 4; ++m) _Pragma("unroll") for (int n = 0; n < 2; ++n) _Pragma("unroll") for (int k = 0; k < 2; ++k) \
;         acc[ai][bj][m][n] = __builtin_amdgcn_mfma_f32_16x16x32_bf16(Bt[n][k], At[m][k], acc[ai][bj][m][n], 0, 0, 0); __builtin_amdgcn_s_setprio(0); } while (0)
; #define PG8_WAIT_V(n) asm volatile("s_waitcnt vmcnt(" #n ")" ::: "memory")
; #define PG8_WAIT_L(n) asm volatile("s_waitcnt lgkmcnt(" #n ")" ::: "memory")
; template <class Epi>
; __device__ __forceinline__ void gemm_phase(LAS unsigned char* lds, const Gemm g, const StaticOrder& S, const Epi& E) {
;     ...
;         const bool has_next = S.next(ui + 1, nxt);
;         const char* nA = has_next ? (const char*)g.A + (size_t)nxt.pm * tstepA : cA; const char* nB = has_next ? (const char*)g.Bt + (size_t)nxt.pn * tstepB : cB;
; #pragma unroll 1
;         for (int t = 0; t < nt; t += 2) {
;             const bool last = (t == nt - 2);
;             const char* a1 = cA + (size_t)(t + 1) * kstep;
;             const char* a2 = last ? nA : cA + (size_t)(t + 2) * kstep; const char* b2 = last ? nB : cB + (size_t)(t + 2) * kstep;
;             const char* a3 = a2 + kstep; const char* b3 = b2 + kstep;
;             PG8_LDB(B0, 0, 0); PG8_LDB(B1, 0, 1); PG8_SCHED; PG8_LDA(At, 0, 0); PG8_STAGE(PG8_SA(1, 1), a1 + hstepA, voffA);
;             PG8_WAIT_V(8); PG8_WAIT_L(0); PG8_BAR; PG8_MMA(0, 0, At, B0); PG8_MMA(0, 1, At, B1); PG8_BAR; PG8_SCHED;
;             PG8_LDA(At, 0, 1); PG8_STAGE(PG8_SB(0, 0), b2, voffB); PG8_STAGE(PG8_SB(0, 1), b2 + hstepB, voffB); PG8_STAGE(PG8_SA(0, 0), a2, voffA);
.LBB0_1250:
	s_add_u32 s56, s38, s22
	s_addc_u32 s57, s39, 0
	s_add_u32 s23, s56, 0x100
	s_addc_u32 s54, s57, 0
	s_and_b64 s[52:53], s[50:51], exec
	s_cselect_b32 s53, s35, s54
	s_cselect_b32 s52, s74, s23
	s_add_u32 s22, s12, s22
	s_addc_u32 s23, s13, 0
	s_add_u32 s54, s22, 0x100
	s_addc_u32 s55, s23, 0
	s_add_i32 s84, 0, 0x10000
	s_and_b64 s[22:23], s[50:51], exec
	s_cselect_b32 s55, s15, s55
	s_cselect_b32 s54, s75, s54
	s_add_i32 s51, 0, 0x14000
	s_add_u32 s58, s56, 0x10080
	s_addc_u32 s59, s57, 0
	s_add_i32 s83, s84, s64
	s_add_i32 m0, s65, 0xc000
	s_add_i32 s86, s65, 0xe000
	s_add_i32 s80, s83, 0x2000
	v_add_u32_e32 v141, s84, v138
	s_add_u32 s56, s54, 0x4000
	ds_read_b128 v[142:145], v141
	ds_read_b128 v[146:149], v141 offset:1024
	ds_read_b128 v[150:153], v141 offset:2048
	ds_read_b128 v[154:157], v141 offset:3072
	v_add_u32_e32 v141, s51, v138
	s_addc_u32 s57, s55, 0
	s_add_i32 s82, s51, s64
	ds_read_b128 v[158:161], v141
	ds_read_b128 v[162:165], v141 offset:1024
	ds_read_b128 v[166:169], v141 offset:2048
	ds_read_b128 v[170:173], v141 offset:3072
	s_add_i32 s81, s82, 0x2000
	s_add_i32 s79, 0, 0x18000
	s_add_i32 s78, 0, 0x1c000
	s_add_u32 s22, s52, 0x10000
	s_addc_u32 s23, s53, 0
	s_add_i32 s77, s79, s64
	s_add_i32 s76, s77, 0x2000
	s_add_u32 s50, s54, 0x4080
	s_addc_u32 s51, s55, 0
	s_add_i32 s85, s78, s64
	s_add_i32 s84, s85, 0x2000
	v_lshl_add_u64 v[198:199], s[58:59], 0, v[136:137]
	ds_read_b128 v[174:177], v140
	ds_read_b128 v[178:181], v140 offset:1024
	ds_read_b128 v[182:185], v140 offset:2048
	ds_read_b128 v[186:189], v140 offset:3072
	ds_read_b128 v[190:193], v140 offset:4096
	ds_read_b128 v[194:197], v140 offset:5120
	ds_read_b128 v[210:213], v140 offset:6144
	ds_read_b128 v[214:217], v140 offset:7168
	global_load_lds_dwordx4 v[198:199], off
	v_lshl_add_u64 v[198:199], s[58:59], 0, v[132:133]
	s_mov_b32 m0, s86
	s_nop 0
	global_load_lds_dwordx4 v[198:199], off
	s_waitcnt vmcnt(8)
	s_waitcnt lgkmcnt(0)
	s_barrier
	s_setprio 1
	v_mfma_f32_16x16x32_bf16 v[128:131], v[142:145], v[174:177], v[128:131]
	v_mfma_f32_16x16x32_bf16 v[124:127], v[150:153], v[174:177], v[124:127]
	v_mfma_f32_16x16x32_bf16 v[120:123], v[142:145], v[182:185], v[120:123]
	v_mfma_f32_16x16x32_bf16 v[116:119], v[150:153], v[182:185], v[116:119]
	v_mfma_f32_16x16x32_bf16 v[104:107], v[142:145], v[190:193], v[104:107]
	v_mfma_f32_16x16x32_bf16 v[100:103], v[150:153], v[190:193], v[100:103]
	v_mfma_f32_16x16x32_bf16 v[88:91], v[142:145], v[210:213], v[88:91]
	v_mfma_f32_16x16x32_bf16 v[84:87], v[150:153], v[210:213], v[84:87]
	v_mfma_f32_16x16x32_bf16 v[128:131], v[146:149], v[178:181], v[128:131]
	v_mfma_f32_16x16x32_bf16 v[124:127], v[154:157], v[178:181], v[124:127]
	v_mfma_f32_16x16x32_bf16 v[120:123], v[146:149], v[186:189], v[120:123]
	v_mfma_f32_16x16x32_bf16 v[116:119], v[154:157], v[186:189], v[116:119]
	v_mfma_f32_16x16x32_bf16 v[104:107], v[146:149], v[194:197], v[104:107]
	v_mfma_f32_16x16x32_bf16 v[100:103], v[154:157], v[194:197], v[100:103]
	v_mfma_f32_16x16x32_bf16 v[88:91], v[146:149], v[214:217], v[88:91]
	v_mfma_f32_16x16x32_bf16 v[84:87], v[154:157], v[214:217], v[84:87]
	v_mfma_f32_16x16x32_bf16 v[112:115], v[158:161], v[174:177], v[112:115]
	v_mfma_f32_16x16x32_bf16 v[108:111], v[166:169], v[174:177], v[108:111]
	v_mfma_f32_16x16x32_bf16 v[96:99], v[158:161], v[182:185], v[96:99]
	v_mfma_f32_16x16x32_bf16 v[92:95], v[166:169], v[182:185], v[92:95]
	v_mfma_f32_16x16x32_bf16 v[80:83], v[158:161], v[190:193], v[80:83]
	v_mfma_f32_16x16x32_bf16 v[76:79], v[166:169], v[190:193], v[76:79]
	v_mfma_f32_16x16x32_bf16 v[72:75], v[158:161], v[210:213], v[72:75]
	v_mfma_f32_16x16x32_bf16 v[68:71], v[166:169], v[210:213], v[68:71]
	v_mfma_f32_16x16x32_bf16 v[112:115], v[162:165], v[178:181], v[112:115]
	v_mfma_f32_16x16x32_bf16 v[108:111], v[170:173], v[178:181], v[108:111]
	v_mfma_f32_16x16x32_bf16 v[96:99], v[162:165], v[186:189], v[96:99]
	v_mfma_f32_16x16x32_bf16 v[92:95], v[170:173], v[186:189], v[92:95]
	v_mfma_f32_16x16x32_bf16 v[80:83], v[162:165], v[194:197], v[80:83]
	v_mfma_f32_16x16x32_bf16 v[76:79], v[170:173], v[194:197], v[76:79]
	v_mfma_f32_16x16x32_bf16 v[72:75], v[162:165], v[214:217], v[72:75]
	v_mfma_f32_16x16x32_bf16 v[68:71], v[170:173], v[214:217], v[68:71]
	s_setprio 0
	s_barrier
	s_mov_b32 m0, s83
	v_lshl_add_u64 v[198:199], s[54:55], 0, v[134:135]
	ds_read_b128 v[174:177], v140 offset:16384
	ds_read_b128 v[178:181], v140 offset:17408
	ds_read_b128 v[182:185], v140 offset:18432
	ds_read_b128 v[186:189], v140 offset:19456
	ds_read_b128 v[190:193], v140 offset:20480
	ds_read_b128 v[194:197], v140 offset:21504
	ds_read_b128 v[210:213], v140 offset:22528
	ds_read_b128 v[214:217], v140 offset:23552
	global_load_lds_dwordx4 v[198:199], off
	v_lshl_add_u64 v[218:219], s[54:55], 0, v[0:1]
	s_mov_b32 m0, s80
	v_lshl_add_u64 v[220:221], s[56:57], 0, v[134:135]
	global_load_lds_dwordx4 v[218:219], off
	s_mov_b32 m0, s82
	v_lshl_add_u64 v[222:223], s[52:53], 0, v[132:133]
	global_load_lds_dwordx4 v[220:221], off
	v_lshl_add_u64 v[220:221], s[56:57], 0, v[0:1]
	s_mov_b32 m0, s81
	s_nop 0
	global_load_lds_dwordx4 v[220:221], off
	v_lshl_add_u64 v[220:221], s[52:53], 0, v[136:137]
	s_mov_b32 m0, s65
	s_nop 0
	global_load_lds_dwordx4 v[220:221], off
	s_mov_b32 m0, s66
	s_nop 0
	global_load_lds_dwordx4 v[222:223], off
	s_waitcnt vmcnt(8)
	s_waitcnt lgkmcnt(0)
	s_barrier
; #define PG8_STAGE(bufoff, gbase, voff) do { _Pragma("unroll") for (int _i = 0; _i < 2; ++_i) \
;         __builtin_amdgcn_global_load_lds((const unsigned*)((const char*)(gbase) + (voff)[_i]), (LAS unsigned*)(lds + (bufoff) + ldsw + _i * 8192), 16, 0, 0); } while (0)
; #define PG8_LDA(dst, b, h) do { _Pragma("unroll") for (int m = 0; m < 4; ++m) _Pragma("unroll") for (int k = 0; k < 2; ++k) dst[m][k] = *(const LAS bf16x8*)(lds + PG8_SA(b, h) + aoff + m * 2048 + k * 1024); } while (0)
; #define PG8_LDB(dst, b, h) do { _Pragma("unroll") for (int n = 0; n < 2; ++n) _Pragma("unroll") for (int k = 0; k < 2; ++k) dst[n][k] = *(const LAS bf16x8*)(lds + PG8_SB(b, h) + boff + n * 2048 + k * 1024); } while (0)
; #define PG8_MMA(ai, bj, At, Bt) do { __builtin_amdgcn_s_setprio(1); _Pragma("unroll") for (int m = 0; m < 4; ++m) _Pragma("unroll") for (int n = 0; n < 2; ++n) _Pragma("unroll") for (int k = 0; k < 2; ++k) \
;         acc[ai][bj][m][n] = __builtin_amdgcn_mfma_f32_16x16x32_bf16(Bt[n][k], At[m][k], acc[ai][bj][m][n], 0, 0, 0); __builtin_amdgcn_s_setprio(0); } while (0)
; #define PG8_WAIT_V(n) asm volatile("s_waitcnt vmcnt(" #n ")" ::: "memory")
; #define PG8_WAIT_L(n) asm volatile("s_waitcnt lgkmcnt(" #n ")" ::: "memory")
; #define PG8_BAR __builtin_amdgcn_s_barrier()
; #define PG8_SCHED __builtin_amdgcn_sched_barrier(0)
; template <class Epi>
; __device__ __forceinline__ void gemm_phase(LAS unsigned char* lds, const Gemm g, const StaticOrder& S, const Epi& E) {
;     ...
;             PG8_WAIT_V(8); PG8_WAIT_L(0); PG8_BAR; PG8_MMA(1, 0, At, B0); PG8_MMA(1, 1, At, B1); PG8_BAR; PG8_SCHED;
;             PG8_LDB(B0, 1, 0); PG8_LDB(B1, 1, 1); PG8_SCHED; PG8_LDA(At, 1, 0); PG8_STAGE(PG8_SA(0, 1), a2 + hstepA, voffA);
;             PG8_WAIT_V(8); PG8_WAIT_L(0); PG8_BAR; PG8_MMA(0, 0, At, B0); PG8_MMA(0, 1, At, B1); PG8_BAR; PG8_SCHED;
	s_setprio 1
	v_mfma_f32_16x16x32_bf16 v[64:67], v[142:145], v[174:177], v[64:67]
	v_mfma_f32_16x16x32_bf16 v[60:63], v[150:153], v[174:177], v[60:63]
	v_mfma_f32_16x16x32_bf16 v[56:59], v[142:145], v[182:185], v[56:59]
	v_mfma_f32_16x16x32_bf16 v[52:55], v[150:153], v[182:185], v[52:55]
	v_mfma_f32_16x16x32_bf16 v[40:43], v[142:145], v[190:193], v[40:43]
	v_mfma_f32_16x16x32_bf16 v[36:39], v[150:153], v[190:193], v[36:39]
	v_mfma_f32_16x16x32_bf16 v[24:27], v[142:145], v[210:213], v[24:27]
	v_mfma_f32_16x16x32_bf16 v[20:23], v[150:153], v[210:213], v[20:23]
	v_mfma_f32_16x16x32_bf16 v[64:67], v[146:149], v[178:181], v[64:67]
	v_mfma_f32_16x16x32_bf16 v[60:63], v[154:157], v[178:181], v[60:63]
	v_mfma_f32_16x16x32_bf16 v[56:59], v[146:149], v[186:189], v[56:59]
	v_mfma_f32_16x16x32_bf16 v[52:55], v[154:157], v[186:189], v[52:55]
	v_mfma_f32_16x16x32_bf16 v[40:43], v[146:149], v[194:197], v[40:43]
	v_mfma_f32_16x16x32_bf16 v[36:39], v[154:157], v[194:197], v[36:39]
	v_mfma_f32_16x16x32_bf16 v[24:27], v[146:149], v[214:217], v[24:27]
	v_mfma_f32_16x16x32_bf16 v[20:23], v[154:157], v[214:217], v[20:23]
	v_mfma_f32_16x16x32_bf16 v[48:51], v[158:161], v[174:177], v[48:51]
	v_mfma_f32_16x16x32_bf16 v[44:47], v[166:169], v[174:177], v[44:47]
	v_mfma_f32_16x16x32_bf16 v[32:35], v[158:161], v[182:185], v[32:35]
	v_mfma_f32_16x16x32_bf16 v[28:31], v[166:169], v[182:185], v[28:31]
	v_mfma_f32_16x16x32_bf16 v[16:19], v[158:161], v[190:193], v[16:19]
	v_mfma_f32_16x16x32_bf16 v[12:15], v[166:169], v[190:193], v[12:15]
	v_mfma_f32_16x16x32_bf16 v[8:11], v[158:161], v[210:213], v[8:11]
	v_mfma_f32_16x16x32_bf16 v[4:7], v[166:169], v[210:213], v[4:7]
	v_mfma_f32_16x16x32_bf16 v[48:51], v[162:165], v[178:181], v[48:51]
	v_mfma_f32_16x16x32_bf16 v[44:47], v[170:173], v[178:181], v[44:47]
	v_mfma_f32_16x16x32_bf16 v[32:35], v[162:165], v[186:189], v[32:35]
	v_mfma_f32_16x16x32_bf16 v[28:31], v[170:173], v[186:189], v[28:31]
	v_mfma_f32_16x16x32_bf16 v[16:19], v[162:165], v[194:197], v[16:19]
	v_mfma_f32_16x16x32_bf16 v[12:15], v[170:173], v[194:197], v[12:15]
	v_mfma_f32_16x16x32_bf16 v[8:11], v[162:165], v[214:217], v[8:11]
	v_mfma_f32_16x16x32_bf16 v[4:7], v[170:173], v[214:217], v[4:7]
	s_setprio 0
	s_barrier
	v_add_u32_e32 v141, s79, v138
	ds_read_b128 v[142:145], v141
	ds_read_b128 v[146:149], v141 offset:1024
	ds_read_b128 v[150:153], v141 offset:2048
	ds_read_b128 v[154:157], v141 offset:3072
	v_add_u32_e32 v141, s78, v138
	ds_read_b128 v[158:161], v141
	ds_read_b128 v[162:165], v141 offset:1024
	ds_read_b128 v[166:169], v141 offset:2048
	ds_read_b128 v[170:173], v141 offset:3072
	s_mov_b32 m0, s67
	v_lshl_add_u64 v[224:225], s[22:23], 0, v[136:137]
	ds_read_b128 v[174:177], v140 offset:32768
	ds_read_b128 v[178:181], v140 offset:33792
	ds_read_b128 v[182:185], v140 offset:34816
	ds_read_b128 v[186:189], v140 offset:35840
	ds_read_b128 v[190:193], v140 offset:36864
	ds_read_b128 v[194:197], v140 offset:37888
	ds_read_b128 v[210:213], v140 offset:38912
	ds_read_b128 v[214:217], v140 offset:39936
	global_load_lds_dwordx4 v[224:225], off
	v_lshl_add_u64 v[224:225], s[22:23], 0, v[132:133]
	s_mov_b32 m0, s68
	s_nop 0
	global_load_lds_dwordx4 v[224:225], off
	s_waitcnt vmcnt(8)
	s_waitcnt lgkmcnt(0)
	s_barrier
	s_setprio 1
	v_mfma_f32_16x16x32_bf16 v[128:131], v[142:145], v[174:177], v[128:131]
	v_mfma_f32_16x16x32_bf16 v[124:127], v[150:153], v[174:177], v[124:127]
	v_mfma_f32_16x16x32_bf16 v[120:123], v[142:145], v[182:185], v[120:123]
	v_mfma_f32_16x16x32_bf16 v[116:119], v[150:153], v[182:185], v[116:119]
	v_mfma_f32_16x16x32_bf16 v[104:107], v[142:145], v[190:193], v[104:107]
	v_mfma_f32_16x16x32_bf16 v[100:103], v[150:153], v[190:193], v[100:103]
	v_mfma_f32_16x16x32_bf16 v[88:91], v[142:145], v[210:213], v[88:91]
	v_mfma_f32_16x16x32_bf16 v[84:87], v[150:153], v[210:213], v[84:87]
	v_mfma_f32_16x16x32_bf16 v[128:131], v[146:149], v[178:181], v[128:131]
	v_mfma_f32_16x16x32_bf16 v[124:127], v[154:157], v[178:181], v[124:127]
	v_mfma_f32_16x16x32_bf16 v[120:123], v[146:149], v[186:189], v[120:123]
	v_mfma_f32_16x16x32_bf16 v[116:119], v[154:157], v[186:189], v[116:119]
	v_mfma_f32_16x16x32_bf16 v[104:107], v[146:149], v[194:197], v[104:107]
	v_mfma_f32_16x16x32_bf16 v[100:103], v[154:157], v[194:197], v[100:103]
	v_mfma_f32_16x16x32_bf16 v[88:91], v[146:149], v[214:217], v[88:91]
	v_mfma_f32_16x16x32_bf16 v[84:87], v[154:157], v[214:217], v[84:87]
	v_mfma_f32_16x16x32_bf16 v[112:115], v[158:161], v[174:177], v[112:115]
	v_mfma_f32_16x16x32_bf16 v[108:111], v[166:169], v[174:177], v[108:111]
	v_mfma_f32_16x16x32_bf16 v[96:99], v[158:161], v[182:185], v[96:99]
	v_mfma_f32_16x16x32_bf16 v[92:95], v[166:169], v[182:185], v[92:95]
	v_mfma_f32_16x16x32_bf16 v[80:83], v[158:161], v[190:193], v[80:83]
	v_mfma_f32_16x16x32_bf16 v[76:79], v[166:169], v[190:193], v[76:79]
	v_mfma_f32_16x16x32_bf16 v[72:75], v[158:161], v[210:213], v[72:75]
	v_mfma_f32_16x16x32_bf16 v[68:71], v[166:169], v[210:213], v[68:71]
	v_mfma_f32_16x16x32_bf16 v[112:115], v[162:165], v[178:181], v[112:115]
	v_mfma_f32_16x16x32_bf16 v[108:111], v[170:173], v[178:181], v[108:111]
	v_mfma_f32_16x16x32_bf16 v[96:99], v[162:165], v[186:189], v[96:99]
	v_mfma_f32_16x16x32_bf16 v[92:95], v[170:173], v[186:189], v[92:95]
	v_mfma_f32_16x16x32_bf16 v[80:83], v[162:165], v[194:197], v[80:83]
	v_mfma_f32_16x16x32_bf16 v[76:79], v[170:173], v[194:197], v[76:79]
	v_mfma_f32_16x16x32_bf16 v[72:75], v[162:165], v[214:217], v[72:75]
	v_mfma_f32_16x16x32_bf16 v[68:71], v[170:173], v[214:217], v[68:71]
	s_setprio 0
	s_barrier
; #define PG8_STAGE(bufoff, gbase, voff) do { _Pragma("unroll") for (int _i = 0; _i < 2; ++_i) \
;         __builtin_amdgcn_global_load_lds((const unsigned*)((const char*)(gbase) + (voff)[_i]), (LAS unsigned*)(lds + (bufoff) + ldsw + _i * 8192), 16, 0, 0); } while (0)
; #define PG8_LDA(dst, b, h) do { _Pragma("unroll") for (int m = 0; m < 4; ++m) _Pragma("unroll") for (int k = 0; k < 2; ++k) dst[m][k] = *(const LAS bf16x8*)(lds + PG8_SA(b, h) + aoff + m * 2048 + k * 1024); } while (0)
; #define PG8_MMA(ai, bj, At, Bt) do { __builtin_amdgcn_s_setprio(1); _Pragma("unroll") for (int m = 0; m < 4; ++m) _Pragma("unroll") for (int n = 0; n < 2; ++n) _Pragma("unroll") for (int k = 0; k < 2; ++k) \
;         acc[ai][bj][m][n] = __builtin_amdgcn_mfma_f32_16x16x32_bf16(Bt[n][k], At[m][k], acc[ai][bj][m][n], 0, 0, 0); __builtin_amdgcn_s_setprio(0); } while (0)
; #define PG8_WAIT_V(n) asm volatile("s_waitcnt vmcnt(" #n ")" ::: "memory")
; #define PG8_WAIT_L(n) asm volatile("s_waitcnt lgkmcnt(" #n ")" ::: "memory")
; #define PG8_BAR __builtin_amdgcn_s_barrier()
; #define PG8_SCHED __builtin_amdgcn_sched_barrier(0)
; template <class Epi>
; __device__ __forceinline__ void gemm_phase(LAS unsigned char* lds, const Gemm g, const StaticOrder& S, const Epi& E) {
;     ...
;             PG8_LDA(At, 1, 1); PG8_STAGE(PG8_SB(1, 0), b3, voffB); PG8_STAGE(PG8_SB(1, 1), b3 + hstepB, voffB); PG8_STAGE(PG8_SA(1, 0), a3, voffA);
;             PG8_WAIT_V(8); PG8_WAIT_L(0); PG8_BAR; PG8_MMA(1, 0, At, B0); PG8_MMA(1, 1, At, B1); PG8_BAR; PG8_SCHED;
;         }
;         if (wr == 0) PG8_BAR;
	s_mov_b32 m0, s77
	v_lshl_add_u64 v[198:199], v[198:199], 0, s[30:31]
	ds_read_b128 v[174:177], v140 offset:49152
	ds_read_b128 v[178:181], v140 offset:50176
	ds_read_b128 v[182:185], v140 offset:51200
	ds_read_b128 v[186:189], v140 offset:52224
	ds_read_b128 v[190:193], v140 offset:53248
	ds_read_b128 v[194:197], v140 offset:54272
	ds_read_b128 v[210:213], v140 offset:55296
	ds_read_b128 v[214:217], v140 offset:56320
	global_load_lds_dwordx4 v[198:199], off
	v_lshl_add_u64 v[198:199], v[218:219], 0, s[30:31]
	s_mov_b32 m0, s76
	s_nop 0
	global_load_lds_dwordx4 v[198:199], off
	v_lshl_add_u64 v[198:199], s[50:51], 0, v[134:135]
	s_mov_b32 m0, s85
	s_nop 0
	global_load_lds_dwordx4 v[198:199], off
	v_lshl_add_u64 v[198:199], s[50:51], 0, v[0:1]
	s_mov_b32 m0, s84
	s_nop 0
	global_load_lds_dwordx4 v[198:199], off
	v_lshl_add_u64 v[198:199], v[220:221], 0, s[30:31]
	s_mov_b32 m0, s69
	s_nop 0
	global_load_lds_dwordx4 v[198:199], off
	v_lshl_add_u64 v[198:199], v[222:223], 0, s[30:31]
	s_mov_b32 m0, s70
	s_nop 0
	global_load_lds_dwordx4 v[198:199], off
	s_waitcnt vmcnt(8)
	s_waitcnt lgkmcnt(0)
	s_barrier
	s_setprio 1
	v_mfma_f32_16x16x32_bf16 v[64:67], v[142:145], v[174:177], v[64:67]
	v_mfma_f32_16x16x32_bf16 v[60:63], v[150:153], v[174:177], v[60:63]
	v_mfma_f32_16x16x32_bf16 v[56:59], v[142:145], v[182:185], v[56:59]
	v_mfma_f32_16x16x32_bf16 v[52:55], v[150:153], v[182:185], v[52:55]
	v_mfma_f32_16x16x32_bf16 v[40:43], v[142:145], v[190:193], v[40:43]
	v_mfma_f32_16x16x32_bf16 v[36:39], v[150:153], v[190:193], v[36:39]
	v_mfma_f32_16x16x32_bf16 v[24:27], v[142:145], v[210:213], v[24:27]
	v_mfma_f32_16x16x32_bf16 v[20:23], v[150:153], v[210:213], v[20:23]
	v_mfma_f32_16x16x32_bf16 v[64:67], v[146:149], v[178:181], v[64:67]
	v_mfma_f32_16x16x32_bf16 v[60:63], v[154:157], v[178:181], v[60:63]
	v_mfma_f32_16x16x32_bf16 v[56:59], v[146:149], v[186:189], v[56:59]
	v_mfma_f32_16x16x32_bf16 v[52:55], v[154:157], v[186:189], v[52:55]
	v_mfma_f32_16x16x32_bf16 v[40:43], v[146:149], v[194:197], v[40:43]
	v_mfma_f32_16x16x32_bf16 v[36:39], v[154:157], v[194:197], v[36:39]
	v_mfma_f32_16x16x32_bf16 v[24:27], v[146:149], v[214:217], v[24:27]
	v_mfma_f32_16x16x32_bf16 v[20:23], v[154:157], v[214:217], v[20:23]
	v_mfma_f32_16x16x32_bf16 v[48:51], v[158:161], v[174:177], v[48:51]
	v_mfma_f32_16x16x32_bf16 v[44:47], v[166:169], v[174:177], v[44:47]
	v_mfma_f32_16x16x32_bf16 v[32:35], v[158:161], v[182:185], v[32:35]
	v_mfma_f32_16x16x32_bf16 v[28:31], v[166:169], v[182:185], v[28:31]
	v_mfma_f32_16x16x32_bf16 v[16:19], v[158:161], v[190:193], v[16:19]
	v_mfma_f32_16x16x32_bf16 v[12:15], v[166:169], v[190:193], v[12:15]
	v_mfma_f32_16x16x32_bf16 v[8:11], v[158:161], v[210:213], v[8:11]
	v_mfma_f32_16x16x32_bf16 v[4:7], v[166:169], v[210:213], v[4:7]
	v_mfma_f32_16x16x32_bf16 v[48:51], v[162:165], v[178:181], v[48:51]
	v_mfma_f32_16x16x32_bf16 v[44:47], v[170:173], v[178:181], v[44:47]
	v_mfma_f32_16x16x32_bf16 v[32:35], v[162:165], v[186:189], v[32:35]
	v_mfma_f32_16x16x32_bf16 v[28:31], v[170:173], v[186:189], v[28:31]
	v_mfma_f32_16x16x32_bf16 v[16:19], v[162:165], v[194:197], v[16:19]
	v_mfma_f32_16x16x32_bf16 v[12:15], v[170:173], v[194:197], v[12:15]
	v_mfma_f32_16x16x32_bf16 v[8:11], v[162:165], v[214:217], v[8:11]
	v_mfma_f32_16x16x32_bf16 v[4:7], v[170:173], v[214:217], v[4:7]
	s_setprio 0
	s_barrier
	s_movk_i32 s22, 0x100
	s_andn2_b64 vcc, exec, s[48:49]
	s_mov_b64 s[50:51], -1
	s_mov_b64 s[48:49], 0
	s_cbranch_vccz .LBB0_1250
	s_and_b64 vcc, exec, s[10:11]
	s_cbranch_vccz .LBB0_1253
	s_barrier

; #define PG8_STAGE(bufoff, gbase, voff) do { _Pragma("unroll") for (int _i = 0; _i < 2; ++_i) \
;         __builtin_amdgcn_global_load_lds((const unsigned*)((const char*)(gbase) + (voff)[_i]), (LAS unsigned*)(lds + (bufoff) + ldsw + _i * 8192), 16, 0, 0); } while (0)
; #define PG8_LDA(dst, b, h) do { _Pragma("unroll") for (int m = 0; m < 4; ++m) _Pragma("unroll") for (int k = 0; k < 2; ++k) dst[m][k] = *(const LAS bf16x8*)(lds + PG8_SA(b, h) + aoff + m * 2048 + k * 1024); } while (0)
; #define PG8_LDB(dst, b, h) do { _Pragma("unroll") for (int n = 0; n < 2; ++n) _Pragma("unroll") for (int k = 0; k < 2; ++k) dst[n][k] = *(const LAS bf16x8*)(lds + PG8_SB(b, h) + boff + n * 2048 + k * 1024); } while (0)
; #define PG8_MMA(ai, bj, At, Bt) do { __builtin_amdgcn_s_setprio(1); _Pragma("unroll") for (int m = 0; m < 4; ++m) _Pragma("unroll") for (int n = 0; n < 2; ++n) _Pragma("unroll") for (int k = 0; k < 2; ++k) \
;         acc[ai][bj][m][n] = __builtin_amdgcn_mfma_f32_16x16x32_bf16(Bt[n][k], At[m][k], acc[ai][bj][m][n], 0, 0, 0); __builtin_amdgcn_s_setprio(0); } while (0)
; #define PG8_WAIT_V(n) asm volatile("s_waitcnt vmcnt(" #n ")" ::: "memory")
; #define PG8_WAIT_L(n) asm volatile("s_waitcnt lgkmcnt(" #n ")" ::: "memory")
; #define PG8_BAR __builtin_amdgcn_s_barrier()
; #define PG8_SCHED __builtin_amdgcn_sched_barrier(0)
; template <class Epi>
; __device__ __forceinline__ void gemm_phase(LAS unsigned char* lds, const Gemm g, const StaticOrder& S, const Epi& E) {
;     ...
;         for (int t = 0; t < nt; t += 2) {
;             const bool last = (t == nt - 2);
;             const char* a1 = cA + (size_t)(t + 1) * kstep;
;             const char* a2 = last ? nA : cA + (size_t)(t + 2) * kstep; const char* b2 = last ? nB : cB + (size_t)(t + 2) * kstep;
;             const char* a3 = a2 + kstep; const char* b3 = b2 + kstep;
;             PG8_LDB(B0, 0, 0); PG8_LDB(B1, 0, 1); PG8_SCHED; PG8_LDA(At, 0, 0); PG8_STAGE(PG8_SA(1, 1), a1 + hstepA, voffA);
;             PG8_WAIT_V(8); PG8_WAIT_L(0); PG8_BAR; PG8_MMA(0, 0, At, B0); PG8_MMA(0, 1, At, B1); PG8_BAR; PG8_SCHED;
;             PG8_LDA(At, 0, 1); PG8_STAGE(PG8_SB(0, 0), b2, voffB); PG8_STAGE(PG8_SB(0, 1), b2 + hstepB, voffB); PG8_STAGE(PG8_SA(0, 0), a2, voffA);
.LBB0_1270:
	s_add_u32 s22, s56, 0xfffc0080
	s_addc_u32 s23, s57, -1
	s_add_i32 s74, 0, 0x10000
	s_cmp_eq_u32 s73, 12
	s_cselect_b32 s59, s47, s23
	s_cselect_b32 s58, s69, s22
	s_cselect_b32 s23, s45, s72
	s_cselect_b32 s22, s70, s71
	s_add_i32 s76, 0, 0x14000
	v_add_u32_e32 v144, s74, v180
	v_add_u32_e32 v170, s76, v180
	ds_read_b128 v[132:135], v144
	ds_read_b128 v[136:139], v144 offset:1024
	ds_read_b128 v[140:143], v144 offset:2048
	ds_read_b128 v[144:147], v144 offset:3072
	ds_read_b128 v[148:151], v170
	ds_read_b128 v[152:155], v170 offset:1024
	ds_read_b128 v[166:169], v170 offset:2048
	ds_read_b128 v[170:173], v170 offset:3072
	v_lshl_add_u64 v[178:179], s[56:57], 0, v[162:163]
	s_add_i32 m0, s53, 0xc000
	ds_read_b128 v[174:177], v182
	ds_read_b128 v[184:187], v182 offset:1024
	ds_read_b128 v[188:191], v182 offset:2048
	ds_read_b128 v[192:195], v182 offset:3072
	ds_read_b128 v[196:199], v182 offset:4096
	ds_read_b128 v[210:213], v182 offset:5120
	ds_read_b128 v[214:217], v182 offset:6144
	ds_read_b128 v[218:221], v182 offset:7168
	global_load_lds_dwordx4 v[178:179], off
	v_lshl_add_u64 v[178:179], s[56:57], 0, v[164:165]
	s_add_i32 m0, s53, 0xe000
	s_nop 0
	global_load_lds_dwordx4 v[178:179], off
	s_waitcnt vmcnt(8)
	s_waitcnt lgkmcnt(0)
	s_barrier
	s_setprio 1
	v_mfma_f32_16x16x32_bf16 v[128:131], v[132:135], v[174:177], v[128:131]
	v_mfma_f32_16x16x32_bf16 v[124:127], v[140:143], v[174:177], v[124:127]
	v_mfma_f32_16x16x32_bf16 v[112:115], v[132:135], v[188:191], v[112:115]
	v_mfma_f32_16x16x32_bf16 v[108:111], v[140:143], v[188:191], v[108:111]
	v_mfma_f32_16x16x32_bf16 v[96:99], v[132:135], v[196:199], v[96:99]
	v_mfma_f32_16x16x32_bf16 v[92:95], v[140:143], v[196:199], v[92:95]
	v_mfma_f32_16x16x32_bf16 v[80:83], v[132:135], v[214:217], v[80:83]
	v_mfma_f32_16x16x32_bf16 v[76:79], v[140:143], v[214:217], v[76:79]
	v_mfma_f32_16x16x32_bf16 v[128:131], v[136:139], v[184:187], v[128:131]
	v_mfma_f32_16x16x32_bf16 v[124:127], v[144:147], v[184:187], v[124:127]
	v_mfma_f32_16x16x32_bf16 v[112:115], v[136:139], v[192:195], v[112:115]
	v_mfma_f32_16x16x32_bf16 v[108:111], v[144:147], v[192:195], v[108:111]
	v_mfma_f32_16x16x32_bf16 v[96:99], v[136:139], v[210:213], v[96:99]
	v_mfma_f32_16x16x32_bf16 v[92:95], v[144:147], v[210:213], v[92:95]
	v_mfma_f32_16x16x32_bf16 v[80:83], v[136:139], v[218:221], v[80:83]
	v_mfma_f32_16x16x32_bf16 v[76:79], v[144:147], v[218:221], v[76:79]
	v_mfma_f32_16x16x32_bf16 v[120:123], v[148:151], v[174:177], v[120:123]
	v_mfma_f32_16x16x32_bf16 v[116:119], v[166:169], v[174:177], v[116:119]
	v_mfma_f32_16x16x32_bf16 v[104:107], v[148:151], v[188:191], v[104:107]
	v_mfma_f32_16x16x32_bf16 v[100:103], v[166:169], v[188:191], v[100:103]
	v_mfma_f32_16x16x32_bf16 v[88:91], v[148:151], v[196:199], v[88:91]
	v_mfma_f32_16x16x32_bf16 v[84:87], v[166:169], v[196:199], v[84:87]
	v_mfma_f32_16x16x32_bf16 v[72:75], v[148:151], v[214:217], v[72:75]
	v_mfma_f32_16x16x32_bf16 v[68:71], v[166:169], v[214:217], v[68:71]
	v_mfma_f32_16x16x32_bf16 v[120:123], v[152:155], v[184:187], v[120:123]
	v_mfma_f32_16x16x32_bf16 v[116:119], v[170:173], v[184:187], v[116:119]
	v_mfma_f32_16x16x32_bf16 v[104:107], v[152:155], v[192:195], v[104:107]
	v_mfma_f32_16x16x32_bf16 v[100:103], v[170:173], v[192:195], v[100:103]
	v_mfma_f32_16x16x32_bf16 v[88:91], v[152:155], v[210:213], v[88:91]
	v_mfma_f32_16x16x32_bf16 v[84:87], v[170:173], v[210:213], v[84:87]
	v_mfma_f32_16x16x32_bf16 v[72:75], v[152:155], v[218:221], v[72:75]
	v_mfma_f32_16x16x32_bf16 v[68:71], v[170:173], v[218:221], v[68:71]
	s_setprio 0
	s_barrier
	s_add_i32 s74, s74, s64
	v_lshl_add_u64 v[178:179], s[22:23], 0, v[158:159]
	s_mov_b32 m0, s74
	ds_read_b128 v[174:177], v182 offset:16384
	ds_read_b128 v[184:187], v182 offset:17408
	ds_read_b128 v[188:191], v182 offset:18432
	ds_read_b128 v[192:195], v182 offset:19456
	ds_read_b128 v[196:199], v182 offset:20480
	ds_read_b128 v[210:213], v182 offset:21504
	ds_read_b128 v[214:217], v182 offset:22528
	ds_read_b128 v[218:221], v182 offset:23552
	global_load_lds_dwordx4 v[178:179], off
	s_add_i32 m0, s74, 0x2000
	s_add_u32 s74, s22, 0x10000
	v_lshl_add_u64 v[222:223], s[22:23], 0, v[0:1]
	s_addc_u32 s75, s23, 0
	s_add_i32 s76, s76, s64
	global_load_lds_dwordx4 v[222:223], off
	v_lshl_add_u64 v[224:225], s[74:75], 0, v[158:159]
	s_mov_b32 m0, s76
	v_lshl_add_u64 v[226:227], s[58:59], 0, v[156:157]
	global_load_lds_dwordx4 v[224:225], off
	v_lshl_add_u64 v[224:225], s[74:75], 0, v[0:1]
	s_add_i32 m0, s76, 0x2000
	s_nop 0
	global_load_lds_dwordx4 v[224:225], off
	v_lshl_add_u64 v[224:225], s[58:59], 0, v[160:161]
	s_mov_b32 m0, s53
	s_nop 0
	global_load_lds_dwordx4 v[224:225], off
	s_mov_b32 m0, s55
	s_nop 0
	global_load_lds_dwordx4 v[226:227], off
	s_waitcnt vmcnt(8)
	s_waitcnt lgkmcnt(0)
	s_barrier
; #define PG8_STAGE(bufoff, gbase, voff) do { _Pragma("unroll") for (int _i = 0; _i < 2; ++_i) \
;         __builtin_amdgcn_global_load_lds((const unsigned*)((const char*)(gbase) + (voff)[_i]), (LAS unsigned*)(lds + (bufoff) + ldsw + _i * 8192), 16, 0, 0); } while (0)
; #define PG8_LDA(dst, b, h) do { _Pragma("unroll") for (int m = 0; m < 4; ++m) _Pragma("unroll") for (int k = 0; k < 2; ++k) dst[m][k] = *(const LAS bf16x8*)(lds + PG8_SA(b, h) + aoff + m * 2048 + k * 1024); } while (0)
; #define PG8_LDB(dst, b, h) do { _Pragma("unroll") for (int n = 0; n < 2; ++n) _Pragma("unroll") for (int k = 0; k < 2; ++k) dst[n][k] = *(const LAS bf16x8*)(lds + PG8_SB(b, h) + boff + n * 2048 + k * 1024); } while (0)
; #define PG8_MMA(ai, bj, At, Bt) do { __builtin_amdgcn_s_setprio(1); _Pragma("unroll") for (int m = 0; m < 4; ++m) _Pragma("unroll") for (int n = 0; n < 2; ++n) _Pragma("unroll") for (int k = 0; k < 2; ++k) \
;         acc[ai][bj][m][n] = __builtin_amdgcn_mfma_f32_16x16x32_bf16(Bt[n][k], At[m][k], acc[ai][bj][m][n], 0, 0, 0); __builtin_amdgcn_s_setprio(0); } while (0)
; #define PG8_WAIT_V(n) asm volatile("s_waitcnt vmcnt(" #n ")" ::: "memory")
; #define PG8_WAIT_L(n) asm volatile("s_waitcnt lgkmcnt(" #n ")" ::: "memory")
; #define PG8_BAR __builtin_amdgcn_s_barrier()
; #define PG8_SCHED __builtin_amdgcn_sched_barrier(0)
; template <class Epi>
; __device__ __forceinline__ void gemm_phase(LAS unsigned char* lds, const Gemm g, const StaticOrder& S, const Epi& E) {
;     ...
;             PG8_WAIT_V(8); PG8_WAIT_L(0); PG8_BAR; PG8_MMA(1, 0, At, B0); PG8_MMA(1, 1, At, B1); PG8_BAR; PG8_SCHED;
;             PG8_LDB(B0, 1, 0); PG8_LDB(B1, 1, 1); PG8_SCHED; PG8_LDA(At, 1, 0); PG8_STAGE(PG8_SA(0, 1), a2 + hstepA, voffA);
;             PG8_WAIT_V(8); PG8_WAIT_L(0); PG8_BAR; PG8_MMA(0, 0, At, B0); PG8_MMA(0, 1, At, B1); PG8_BAR; PG8_SCHED;
	s_setprio 1
	v_mfma_f32_16x16x32_bf16 v[64:67], v[132:135], v[174:177], v[64:67]
	v_mfma_f32_16x16x32_bf16 v[60:63], v[140:143], v[174:177], v[60:63]
	v_mfma_f32_16x16x32_bf16 v[48:51], v[132:135], v[188:191], v[48:51]
	v_mfma_f32_16x16x32_bf16 v[44:47], v[140:143], v[188:191], v[44:47]
	v_mfma_f32_16x16x32_bf16 v[32:35], v[132:135], v[196:199], v[32:35]
	v_mfma_f32_16x16x32_bf16 v[28:31], v[140:143], v[196:199], v[28:31]
	v_mfma_f32_16x16x32_bf16 v[16:19], v[132:135], v[214:217], v[16:19]
	v_mfma_f32_16x16x32_bf16 v[12:15], v[140:143], v[214:217], v[12:15]
	v_mfma_f32_16x16x32_bf16 v[64:67], v[136:139], v[184:187], v[64:67]
	v_mfma_f32_16x16x32_bf16 v[60:63], v[144:147], v[184:187], v[60:63]
	v_mfma_f32_16x16x32_bf16 v[48:51], v[136:139], v[192:195], v[48:51]
	v_mfma_f32_16x16x32_bf16 v[44:47], v[144:147], v[192:195], v[44:47]
	v_mfma_f32_16x16x32_bf16 v[32:35], v[136:139], v[210:213], v[32:35]
	v_mfma_f32_16x16x32_bf16 v[28:31], v[144:147], v[210:213], v[28:31]
	v_mfma_f32_16x16x32_bf16 v[16:19], v[136:139], v[218:221], v[16:19]
	v_mfma_f32_16x16x32_bf16 v[12:15], v[144:147], v[218:221], v[12:15]
	v_mfma_f32_16x16x32_bf16 v[56:59], v[148:151], v[174:177], v[56:59]
	v_mfma_f32_16x16x32_bf16 v[52:55], v[166:169], v[174:177], v[52:55]
	v_mfma_f32_16x16x32_bf16 v[40:43], v[148:151], v[188:191], v[40:43]
	v_mfma_f32_16x16x32_bf16 v[36:39], v[166:169], v[188:191], v[36:39]
	v_mfma_f32_16x16x32_bf16 v[24:27], v[148:151], v[196:199], v[24:27]
	v_mfma_f32_16x16x32_bf16 v[20:23], v[166:169], v[196:199], v[20:23]
	v_mfma_f32_16x16x32_bf16 v[8:11], v[148:151], v[214:217], v[8:11]
	v_mfma_f32_16x16x32_bf16 v[4:7], v[166:169], v[214:217], v[4:7]
	v_mfma_f32_16x16x32_bf16 v[56:59], v[152:155], v[184:187], v[56:59]
	v_mfma_f32_16x16x32_bf16 v[52:55], v[170:173], v[184:187], v[52:55]
	v_mfma_f32_16x16x32_bf16 v[40:43], v[152:155], v[192:195], v[40:43]
	v_mfma_f32_16x16x32_bf16 v[36:39], v[170:173], v[192:195], v[36:39]
	v_mfma_f32_16x16x32_bf16 v[24:27], v[152:155], v[210:213], v[24:27]
	v_mfma_f32_16x16x32_bf16 v[20:23], v[170:173], v[210:213], v[20:23]
	v_mfma_f32_16x16x32_bf16 v[8:11], v[152:155], v[218:221], v[8:11]
	v_mfma_f32_16x16x32_bf16 v[4:7], v[170:173], v[218:221], v[4:7]
	s_setprio 0
	s_barrier
	s_add_i32 s74, 0, 0x18000
	s_add_i32 s75, 0, 0x1c000
	v_add_u32_e32 v144, s74, v180
	v_add_u32_e32 v170, s75, v180
	ds_read_b128 v[132:135], v144
	ds_read_b128 v[136:139], v144 offset:1024
	ds_read_b128 v[140:143], v144 offset:2048
	ds_read_b128 v[144:147], v144 offset:3072
	ds_read_b128 v[148:151], v170
	ds_read_b128 v[152:155], v170 offset:1024
	ds_read_b128 v[166:169], v170 offset:2048
	ds_read_b128 v[170:173], v170 offset:3072
	s_add_u32 s58, s58, 0x40000
	s_addc_u32 s59, s59, 0
	s_mov_b32 m0, s65
	v_lshl_add_u64 v[228:229], s[58:59], 0, v[160:161]
	ds_read_b128 v[174:177], v182 offset:32768
	ds_read_b128 v[184:187], v182 offset:33792
	ds_read_b128 v[188:191], v182 offset:34816
	ds_read_b128 v[192:195], v182 offset:35840
	ds_read_b128 v[196:199], v182 offset:36864
	ds_read_b128 v[210:213], v182 offset:37888
	ds_read_b128 v[214:217], v182 offset:38912
	ds_read_b128 v[218:221], v182 offset:39936
	global_load_lds_dwordx4 v[228:229], off
	v_lshl_add_u64 v[228:229], s[58:59], 0, v[156:157]
	s_mov_b32 m0, s66
	s_nop 0
	global_load_lds_dwordx4 v[228:229], off
	s_waitcnt vmcnt(8)
	s_waitcnt lgkmcnt(0)
	s_barrier
	s_setprio 1
	v_mfma_f32_16x16x32_bf16 v[128:131], v[132:135], v[174:177], v[128:131]
	v_mfma_f32_16x16x32_bf16 v[124:127], v[140:143], v[174:177], v[124:127]
	v_mfma_f32_16x16x32_bf16 v[112:115], v[132:135], v[188:191], v[112:115]
	v_mfma_f32_16x16x32_bf16 v[108:111], v[140:143], v[188:191], v[108:111]
	v_mfma_f32_16x16x32_bf16 v[96:99], v[132:135], v[196:199], v[96:99]
	v_mfma_f32_16x16x32_bf16 v[92:95], v[140:143], v[196:199], v[92:95]
	v_mfma_f32_16x16x32_bf16 v[80:83], v[132:135], v[214:217], v[80:83]
	v_mfma_f32_16x16x32_bf16 v[76:79], v[140:143], v[214:217], v[76:79]
	v_mfma_f32_16x16x32_bf16 v[128:131], v[136:139], v[184:187], v[128:131]
	v_mfma_f32_16x16x32_bf16 v[124:127], v[144:147], v[184:187], v[124:127]
	v_mfma_f32_16x16x32_bf16 v[112:115], v[136:139], v[192:195], v[112:115]
	v_mfma_f32_16x16x32_bf16 v[108:111], v[144:147], v[192:195], v[108:111]
	v_mfma_f32_16x16x32_bf16 v[96:99], v[136:139], v[210:213], v[96:99]
	v_mfma_f32_16x16x32_bf16 v[92:95], v[144:147], v[210:213], v[92:95]
	v_mfma_f32_16x16x32_bf16 v[80:83], v[136:139], v[218:221], v[80:83]
	v_mfma_f32_16x16x32_bf16 v[76:79], v[144:147], v[218:221], v[76:79]
	v_mfma_f32_16x16x32_bf16 v[120:123], v[148:151], v[174:177], v[120:123]
	v_mfma_f32_16x16x32_bf16 v[116:119], v[166:169], v[174:177], v[116:119]
	v_mfma_f32_16x16x32_bf16 v[104:107], v[148:151], v[188:191], v[104:107]
	v_mfma_f32_16x16x32_bf16 v[100:103], v[166:169], v[188:191], v[100:103]
	v_mfma_f32_16x16x32_bf16 v[88:91], v[148:151], v[196:199], v[88:91]
	v_mfma_f32_16x16x32_bf16 v[84:87], v[166:169], v[196:199], v[84:87]
	v_mfma_f32_16x16x32_bf16 v[72:75], v[148:151], v[214:217], v[72:75]
	v_mfma_f32_16x16x32_bf16 v[68:71], v[166:169], v[214:217], v[68:71]
	v_mfma_f32_16x16x32_bf16 v[120:123], v[152:155], v[184:187], v[120:123]
	v_mfma_f32_16x16x32_bf16 v[116:119], v[170:173], v[184:187], v[116:119]
	v_mfma_f32_16x16x32_bf16 v[104:107], v[152:155], v[192:195], v[104:107]
	v_mfma_f32_16x16x32_bf16 v[100:103], v[170:173], v[192:195], v[100:103]
	v_mfma_f32_16x16x32_bf16 v[88:91], v[152:155], v[210:213], v[88:91]
	v_mfma_f32_16x16x32_bf16 v[84:87], v[170:173], v[210:213], v[84:87]
	v_mfma_f32_16x16x32_bf16 v[72:75], v[152:155], v[218:221], v[72:75]
	v_mfma_f32_16x16x32_bf16 v[68:71], v[170:173], v[218:221], v[68:71]
	s_setprio 0
	s_barrier
; #define PG8_STAGE(bufoff, gbase, voff) do { _Pragma("unroll") for (int _i = 0; _i < 2; ++_i) \
;         __builtin_amdgcn_global_load_lds((const unsigned*)((const char*)(gbase) + (voff)[_i]), (LAS unsigned*)(lds + (bufoff) + ldsw + _i * 8192), 16, 0, 0); } while (0)
; #define PG8_LDA(dst, b, h) do { _Pragma("unroll") for (int m = 0; m < 4; ++m) _Pragma("unroll") for (int k = 0; k < 2; ++k) dst[m][k] = *(const LAS bf16x8*)(lds + PG8_SA(b, h) + aoff + m * 2048 + k * 1024); } while (0)
; #define PG8_MMA(ai, bj, At, Bt) do { __builtin_amdgcn_s_setprio(1); _Pragma("unroll") for (int m = 0; m < 4; ++m) _Pragma("unroll") for (int n = 0; n < 2; ++n) _Pragma("unroll") for (int k = 0; k < 2; ++k) \
;         acc[ai][bj][m][n] = __builtin_amdgcn_mfma_f32_16x16x32_bf16(Bt[n][k], At[m][k], acc[ai][bj][m][n], 0, 0, 0); __builtin_amdgcn_s_setprio(0); } while (0)
; #define PG8_WAIT_V(n) asm volatile("s_waitcnt vmcnt(" #n ")" ::: "memory")
; #define PG8_WAIT_L(n) asm volatile("s_waitcnt lgkmcnt(" #n ")" ::: "memory")
; #define PG8_BAR __builtin_amdgcn_s_barrier()
; #define PG8_SCHED __builtin_amdgcn_sched_barrier(0)
; template <class Epi>
; __device__ __forceinline__ void gemm_phase(LAS unsigned char* lds, const Gemm g, const StaticOrder& S, const Epi& E) {
;     ...
;             PG8_LDA(At, 1, 1); PG8_STAGE(PG8_SB(1, 0), b3, voffB); PG8_STAGE(PG8_SB(1, 1), b3 + hstepB, voffB); PG8_STAGE(PG8_SA(1, 0), a3, voffA);
;             PG8_WAIT_V(8); PG8_WAIT_L(0); PG8_BAR; PG8_MMA(1, 0, At, B0); PG8_MMA(1, 1, At, B1); PG8_BAR; PG8_SCHED;
;         }
;         if (wr == 0) PG8_BAR;
	s_add_i32 s58, s74, s64
	v_lshl_add_u64 v[178:179], v[178:179], 0, s[30:31]
	s_mov_b32 m0, s58
	ds_read_b128 v[174:177], v182 offset:49152
	ds_read_b128 v[184:187], v182 offset:50176
	ds_read_b128 v[188:191], v182 offset:51200
	ds_read_b128 v[192:195], v182 offset:52224
	ds_read_b128 v[196:199], v182 offset:53248
	ds_read_b128 v[210:213], v182 offset:54272
	ds_read_b128 v[214:217], v182 offset:55296
	ds_read_b128 v[218:221], v182 offset:56320
	global_load_lds_dwordx4 v[178:179], off
	s_add_i32 m0, s58, 0x2000
	s_add_u32 s22, s22, 0x10080
	v_lshl_add_u64 v[178:179], v[222:223], 0, s[30:31]
	s_addc_u32 s23, s23, 0
	s_add_i32 s58, s75, s64
	global_load_lds_dwordx4 v[178:179], off
	v_lshl_add_u64 v[178:179], s[22:23], 0, v[158:159]
	s_mov_b32 m0, s58
	s_nop 0
	global_load_lds_dwordx4 v[178:179], off
	v_lshl_add_u64 v[178:179], s[22:23], 0, v[0:1]
	s_add_i32 m0, s58, 0x2000
	s_nop 0
	global_load_lds_dwordx4 v[178:179], off
	v_lshl_add_u64 v[178:179], v[224:225], 0, s[30:31]
	s_mov_b32 m0, s28
	s_nop 0
	global_load_lds_dwordx4 v[178:179], off
	v_lshl_add_u64 v[178:179], v[226:227], 0, s[30:31]
	s_mov_b32 m0, s67
	s_nop 0
	global_load_lds_dwordx4 v[178:179], off
	s_waitcnt vmcnt(8)
	s_waitcnt lgkmcnt(0)
	s_barrier
	s_setprio 1
	v_mfma_f32_16x16x32_bf16 v[64:67], v[132:135], v[174:177], v[64:67]
	v_mfma_f32_16x16x32_bf16 v[60:63], v[140:143], v[174:177], v[60:63]
	v_mfma_f32_16x16x32_bf16 v[48:51], v[132:135], v[188:191], v[48:51]
	v_mfma_f32_16x16x32_bf16 v[44:47], v[140:143], v[188:191], v[44:47]
	v_mfma_f32_16x16x32_bf16 v[32:35], v[132:135], v[196:199], v[32:35]
	v_mfma_f32_16x16x32_bf16 v[28:31], v[140:143], v[196:199], v[28:31]
	v_mfma_f32_16x16x32_bf16 v[16:19], v[132:135], v[214:217], v[16:19]
	v_mfma_f32_16x16x32_bf16 v[12:15], v[140:143], v[214:217], v[12:15]
	v_mfma_f32_16x16x32_bf16 v[64:67], v[136:139], v[184:187], v[64:67]
	v_mfma_f32_16x16x32_bf16 v[60:63], v[144:147], v[184:187], v[60:63]
	v_mfma_f32_16x16x32_bf16 v[48:51], v[136:139], v[192:195], v[48:51]
	v_mfma_f32_16x16x32_bf16 v[44:47], v[144:147], v[192:195], v[44:47]
	v_mfma_f32_16x16x32_bf16 v[32:35], v[136:139], v[210:213], v[32:35]
	v_mfma_f32_16x16x32_bf16 v[28:31], v[144:147], v[210:213], v[28:31]
	v_mfma_f32_16x16x32_bf16 v[16:19], v[136:139], v[218:221], v[16:19]
	v_mfma_f32_16x16x32_bf16 v[12:15], v[144:147], v[218:221], v[12:15]
	v_mfma_f32_16x16x32_bf16 v[56:59], v[148:151], v[174:177], v[56:59]
	v_mfma_f32_16x16x32_bf16 v[52:55], v[166:169], v[174:177], v[52:55]
	v_mfma_f32_16x16x32_bf16 v[40:43], v[148:151], v[188:191], v[40:43]
	v_mfma_f32_16x16x32_bf16 v[36:39], v[166:169], v[188:191], v[36:39]
	v_mfma_f32_16x16x32_bf16 v[24:27], v[148:151], v[196:199], v[24:27]
	v_mfma_f32_16x16x32_bf16 v[20:23], v[166:169], v[196:199], v[20:23]
	v_mfma_f32_16x16x32_bf16 v[8:11], v[148:151], v[214:217], v[8:11]
	v_mfma_f32_16x16x32_bf16 v[4:7], v[166:169], v[214:217], v[4:7]
	v_mfma_f32_16x16x32_bf16 v[56:59], v[152:155], v[184:187], v[56:59]
	v_mfma_f32_16x16x32_bf16 v[52:55], v[170:173], v[184:187], v[52:55]
	v_mfma_f32_16x16x32_bf16 v[40:43], v[152:155], v[192:195], v[40:43]
	v_mfma_f32_16x16x32_bf16 v[36:39], v[170:173], v[192:195], v[36:39]
	v_mfma_f32_16x16x32_bf16 v[24:27], v[152:155], v[210:213], v[24:27]
	v_mfma_f32_16x16x32_bf16 v[20:23], v[170:173], v[210:213], v[20:23]
	v_mfma_f32_16x16x32_bf16 v[8:11], v[152:155], v[218:221], v[8:11]
	v_mfma_f32_16x16x32_bf16 v[4:7], v[170:173], v[218:221], v[4:7]
	s_setprio 0
	s_barrier
	s_add_i32 s73, s73, 2
	s_add_u32 s56, s56, 0x100
	s_addc_u32 s57, s57, 0
	s_add_u32 s71, s71, 0x100
	s_addc_u32 s72, s72, 0
	s_cmp_gt_u32 s73, 13
	s_cbranch_scc0 .LBB0_1270
	s_and_b64 vcc, exec, s[38:39]
	s_cbranch_vccz .LBB0_1273
	s_barrier
